# speedup vs baseline: 1.0188x; 1.0019x over previous
; #define WAIT_L(n) asm volatile("s_waitcnt lgkmcnt(" #n ")" ::: "memory")
; #define BAR __builtin_amdgcn_s_barrier()
; #define SCHED __builtin_amdgcn_sched_barrier(0)
; #define LDA(dst, b, h)                                                                            \
;   _Pragma("unroll") for (int m = 0; m < 4; ++m) _Pragma("unroll") for (int k = 0; k < 2; ++k)                                         \
;     dst[m][k] = *reinterpret_cast<const bf16x8*>((char*)SA(b, h) + lds_byte(wr * 64 + m * 16 + fr, k * 32 + fq * 8))
; #define LDB(dst, b, h)                                                                            \
;   _Pragma("unroll") for (int n = 0; n < 2; ++n) _Pragma("unroll") for (int k = 0; k < 2; ++k)                                         \
;     dst[n][k] = *reinterpret_cast<const bf16x8*>((char*)SB(b, h) + lds_byte(wc * 32 + n * 16 + fr, k * 32 + fq * 8))
; template <int K, bool SWAP>
; __device__ __forceinline__ void gemm_kloop(const bf16* __restrict__ A, const bf16* __restrict__ Bt,
;                                            f32x4 (&acc)[2][2][4][2], bool pref = false) {
;     ...
;     LDB(B0, 0, 0); SCHED; LDA(At, 0, 0); STAGE(SA(1, 1), A, HALF, t + 1);
;     WAIT_L(8); BAR; WAIT_L(0); MMA(0, 0, At, B0); BAR; SCHED;
;     LDB(B1, 0, 1); STAGE(SB(0, 0), Bt, 0, t + 2);
;     BAR; WAIT_L(0); MMA(0, 1, At, B1); BAR;
;     LDA(At, 0, 1); STAGE(SA(0, 0), A, 0, t + 2);
;     BAR; WAIT_L(0); MMA(1, 0, At, B0); BAR; SCHED;
.LBB0_271:
	ds_read_b128 v[162:165], v159
	ds_read_b128 v[166:169], v159 offset:1024
	ds_read_b128 v[170:173], v159 offset:2048
	ds_read_b128 v[174:177], v159 offset:3072
	v_add_u32_e32 v160, 0xc000, v146
	v_lshl_add_u64 v[178:179], s[58:59], 0, v[140:141]
	v_readfirstlane_b32 s5, v160
	v_lshl_add_u64 v[188:189], v[178:179], 0, s[42:43]
	s_mov_b32 m0, s5
	v_add_u32_e32 v161, 0xe000, v146
	ds_read_b128 v[198:201], v151
	ds_read_b128 v[202:205], v151 offset:1024
	ds_read_b128 v[206:209], v150
	ds_read_b128 v[210:213], v150 offset:1024
	ds_read_b128 v[214:217], v149
	ds_read_b128 v[218:221], v149 offset:1024
	ds_read_b128 v[222:225], v148
	ds_read_b128 v[226:229], v148 offset:1024
	global_load_lds_dwordx4 v[188:189], off
	v_lshl_add_u64 v[188:189], s[58:59], 0, v[142:143]
	v_readfirstlane_b32 s5, v161
	v_lshl_add_u64 v[230:231], v[188:189], 0, s[42:43]
	s_mov_b32 m0, s5
	s_nop 0
	global_load_lds_dwordx4 v[230:231], off
	s_waitcnt lgkmcnt(8)
	s_barrier
	s_waitcnt lgkmcnt(0)
	v_mfma_f32_16x16x32_bf16 v[124:127], v[198:201], v[162:165], v[124:127]
	v_mfma_f32_16x16x32_bf16 v[120:123], v[198:201], v[170:173], v[120:123]
	v_mfma_f32_16x16x32_bf16 v[112:115], v[206:209], v[170:173], v[112:115]
	v_mfma_f32_16x16x32_bf16 v[116:119], v[206:209], v[162:165], v[116:119]
	v_mfma_f32_16x16x32_bf16 v[108:111], v[214:217], v[162:165], v[108:111]
	v_mfma_f32_16x16x32_bf16 v[104:107], v[214:217], v[170:173], v[104:107]
	v_mfma_f32_16x16x32_bf16 v[96:99], v[222:225], v[170:173], v[96:99]
	v_mfma_f32_16x16x32_bf16 v[100:103], v[222:225], v[162:165], v[100:103]
	v_mfma_f32_16x16x32_bf16 v[124:127], v[202:205], v[166:169], v[124:127]
	v_mfma_f32_16x16x32_bf16 v[120:123], v[202:205], v[174:177], v[120:123]
	v_mfma_f32_16x16x32_bf16 v[112:115], v[210:213], v[174:177], v[112:115]
	v_mfma_f32_16x16x32_bf16 v[116:119], v[210:213], v[166:169], v[116:119]
	v_mfma_f32_16x16x32_bf16 v[108:111], v[218:221], v[166:169], v[108:111]
	v_mfma_f32_16x16x32_bf16 v[104:107], v[218:221], v[174:177], v[104:107]
	v_mfma_f32_16x16x32_bf16 v[96:99], v[226:229], v[174:177], v[96:99]
	v_mfma_f32_16x16x32_bf16 v[100:103], v[226:229], v[166:169], v[100:103]
	s_barrier
	v_add_u32_e32 v186, s7, v145
	v_lshl_add_u64 v[246:247], s[58:59], 0, v[136:137]
	v_readfirstlane_b32 s5, v186
	v_lshl_add_u64 v[248:249], v[246:247], 0, s[44:45]
	s_mov_b32 m0, s5
	v_add_u32_e32 v186, 0x2000, v186
	ds_read_b128 v[230:233], v158
	ds_read_b128 v[234:237], v158 offset:1024
	ds_read_b128 v[238:241], v158 offset:2048
	ds_read_b128 v[242:245], v158 offset:3072
	global_load_lds_dwordx4 v[248:249], off
	v_lshl_add_u64 v[248:249], s[58:59], 0, v[138:139]
	v_readfirstlane_b32 s5, v186
	v_lshl_add_u64 v[250:251], v[248:249], 0, s[44:45]
	s_mov_b32 m0, s5
	s_nop 0
	global_load_lds_dwordx4 v[250:251], off
	s_barrier
	s_waitcnt lgkmcnt(0)
	v_mfma_f32_16x16x32_bf16 v[92:95], v[198:201], v[230:233], v[92:95]
	v_mfma_f32_16x16x32_bf16 v[88:91], v[198:201], v[238:241], v[88:91]
	v_mfma_f32_16x16x32_bf16 v[80:83], v[206:209], v[238:241], v[80:83]
	v_mfma_f32_16x16x32_bf16 v[84:87], v[206:209], v[230:233], v[84:87]
	v_mfma_f32_16x16x32_bf16 v[76:79], v[214:217], v[230:233], v[76:79]
	v_mfma_f32_16x16x32_bf16 v[72:75], v[214:217], v[238:241], v[72:75]
	v_mfma_f32_16x16x32_bf16 v[64:67], v[222:225], v[238:241], v[64:67]
	v_mfma_f32_16x16x32_bf16 v[68:71], v[222:225], v[230:233], v[68:71]
	v_mfma_f32_16x16x32_bf16 v[92:95], v[202:205], v[234:237], v[92:95]
	v_mfma_f32_16x16x32_bf16 v[88:91], v[202:205], v[242:245], v[88:91]
	v_mfma_f32_16x16x32_bf16 v[80:83], v[210:213], v[242:245], v[80:83]
	v_mfma_f32_16x16x32_bf16 v[84:87], v[210:213], v[234:237], v[84:87]
	v_mfma_f32_16x16x32_bf16 v[76:79], v[218:221], v[234:237], v[76:79]
	v_mfma_f32_16x16x32_bf16 v[72:75], v[218:221], v[242:245], v[72:75]
	v_mfma_f32_16x16x32_bf16 v[64:67], v[226:229], v[242:245], v[64:67]
	v_mfma_f32_16x16x32_bf16 v[68:71], v[226:229], v[234:237], v[68:71]
	v_readfirstlane_b32 s5, v146
	v_add_u32_e32 v186, 0x2000, v146
	v_lshl_add_u64 v[250:251], v[178:179], 0, s[46:47]
	s_mov_b32 m0, s5
	v_readfirstlane_b32 s5, v186
	s_barrier
	ds_read_b128 v[198:201], v151 offset:16384
	ds_read_b128 v[202:205], v151 offset:17408
	ds_read_b128 v[206:209], v150 offset:16384
	ds_read_b128 v[210:213], v150 offset:17408
	ds_read_b128 v[214:217], v149 offset:16384
	ds_read_b128 v[218:221], v149 offset:17408
	ds_read_b128 v[222:225], v148 offset:16384
	ds_read_b128 v[226:229], v148 offset:17408
	global_load_lds_dwordx4 v[250:251], off
	v_lshl_add_u64 v[250:251], v[188:189], 0, s[46:47]
	s_mov_b32 m0, s5
	s_nop 0
	global_load_lds_dwordx4 v[250:251], off
	s_barrier
	s_waitcnt lgkmcnt(0)
	v_mfma_f32_16x16x32_bf16 v[60:63], v[198:201], v[162:165], v[60:63]
	v_mfma_f32_16x16x32_bf16 v[56:59], v[198:201], v[170:173], v[56:59]
	v_mfma_f32_16x16x32_bf16 v[48:51], v[206:209], v[170:173], v[48:51]
	v_mfma_f32_16x16x32_bf16 v[52:55], v[206:209], v[162:165], v[52:55]
	v_mfma_f32_16x16x32_bf16 v[44:47], v[214:217], v[162:165], v[44:47]
	v_mfma_f32_16x16x32_bf16 v[40:43], v[214:217], v[170:173], v[40:43]
	v_mfma_f32_16x16x32_bf16 v[32:35], v[222:225], v[170:173], v[32:35]
	v_mfma_f32_16x16x32_bf16 v[36:39], v[222:225], v[162:165], v[36:39]
	v_mfma_f32_16x16x32_bf16 v[60:63], v[202:205], v[166:169], v[60:63]
	v_mfma_f32_16x16x32_bf16 v[56:59], v[202:205], v[174:177], v[56:59]
	v_mfma_f32_16x16x32_bf16 v[48:51], v[210:213], v[174:177], v[48:51]
	v_mfma_f32_16x16x32_bf16 v[52:55], v[210:213], v[166:169], v[52:55]
	v_mfma_f32_16x16x32_bf16 v[44:47], v[218:221], v[166:169], v[44:47]
	v_mfma_f32_16x16x32_bf16 v[40:43], v[218:221], v[174:177], v[40:43]
	v_mfma_f32_16x16x32_bf16 v[32:35], v[226:229], v[174:177], v[32:35]
	v_mfma_f32_16x16x32_bf16 v[36:39], v[226:229], v[166:169], v[36:39]
	s_barrier
; #define WAIT_V(n) asm volatile("s_waitcnt vmcnt(" #n ")" ::: "memory")
; #define WAIT_L(n) asm volatile("s_waitcnt lgkmcnt(" #n ")" ::: "memory")
; #define BAR __builtin_amdgcn_s_barrier()
; #define SCHED __builtin_amdgcn_sched_barrier(0)
; #define LDA(dst, b, h)                                                                            \
;   _Pragma("unroll") for (int m = 0; m < 4; ++m) _Pragma("unroll") for (int k = 0; k < 2; ++k)                                         \
;     dst[m][k] = *reinterpret_cast<const bf16x8*>((char*)SA(b, h) + lds_byte(wr * 64 + m * 16 + fr, k * 32 + fq * 8))
; #define LDB(dst, b, h)                                                                            \
;   _Pragma("unroll") for (int n = 0; n < 2; ++n) _Pragma("unroll") for (int k = 0; k < 2; ++k)                                         \
;     dst[n][k] = *reinterpret_cast<const bf16x8*>((char*)SB(b, h) + lds_byte(wc * 32 + n * 16 + fr, k * 32 + fq * 8))
; template <int K, bool SWAP>
; __device__ __forceinline__ void gemm_kloop(const bf16* __restrict__ A, const bf16* __restrict__ Bt,
;                                            f32x4 (&acc)[2][2][4][2], bool pref = false) {
;     ...
;     STAGE(SB(0, 1), Bt, HALF, t + 2);
;     WAIT_V(6); BAR; MMA(1, 1, At, B1); BAR;
;     LDB(B0, 1, 0); SCHED; LDA(At, 1, 0); STAGE(SA(0, 1), A, HALF, t + 2);
;     WAIT_L(8); BAR; WAIT_L(0); MMA(0, 0, At, B0); BAR; SCHED;
;     LDB(B1, 1, 1); STAGE(SB(1, 0), Bt, 0, t + 3);
;     BAR; WAIT_L(0); MMA(0, 1, At, B1); BAR;
;     LDA(At, 1, 1); STAGE(SA(1, 0), A, 0, t + 3);
	v_readfirstlane_b32 s5, v147
	v_add_u32_e32 v164, 0x2000, v147
	v_lshl_add_u64 v[162:163], v[246:247], 0, s[48:49]
	s_mov_b32 m0, s5
	v_readfirstlane_b32 s5, v164
	global_load_lds_dwordx4 v[162:163], off
	v_lshl_add_u64 v[162:163], v[248:249], 0, s[48:49]
	s_mov_b32 m0, s5
	s_nop 0
	global_load_lds_dwordx4 v[162:163], off
	s_waitcnt vmcnt(6)
	s_barrier
	v_mfma_f32_16x16x32_bf16 v[28:31], v[198:201], v[230:233], v[28:31]
	v_mfma_f32_16x16x32_bf16 v[24:27], v[198:201], v[238:241], v[24:27]
	v_mfma_f32_16x16x32_bf16 v[16:19], v[206:209], v[238:241], v[16:19]
	v_mfma_f32_16x16x32_bf16 v[20:23], v[206:209], v[230:233], v[20:23]
	v_mfma_f32_16x16x32_bf16 v[12:15], v[214:217], v[230:233], v[12:15]
	v_mfma_f32_16x16x32_bf16 v[8:11], v[214:217], v[238:241], v[8:11]
	v_mfma_f32_16x16x32_bf16 v[0:3], v[222:225], v[238:241], v[0:3]
	v_mfma_f32_16x16x32_bf16 v[4:7], v[222:225], v[230:233], v[4:7]
	v_mfma_f32_16x16x32_bf16 v[28:31], v[202:205], v[234:237], v[28:31]
	v_mfma_f32_16x16x32_bf16 v[24:27], v[202:205], v[242:245], v[24:27]
	v_mfma_f32_16x16x32_bf16 v[16:19], v[210:213], v[242:245], v[16:19]
	v_mfma_f32_16x16x32_bf16 v[20:23], v[210:213], v[234:237], v[20:23]
	v_mfma_f32_16x16x32_bf16 v[12:15], v[218:221], v[234:237], v[12:15]
	v_mfma_f32_16x16x32_bf16 v[8:11], v[218:221], v[242:245], v[8:11]
	v_mfma_f32_16x16x32_bf16 v[0:3], v[226:229], v[242:245], v[0:3]
	v_mfma_f32_16x16x32_bf16 v[4:7], v[226:229], v[234:237], v[4:7]
	s_barrier
	ds_read_b128 v[162:165], v153
	ds_read_b128 v[166:169], v153 offset:1024
	ds_read_b128 v[170:173], v153 offset:2048
	ds_read_b128 v[174:177], v153 offset:3072
	v_add_u32_e32 v186, 0x4000, v146
	v_lshl_add_u64 v[230:231], v[178:179], 0, s[50:51]
	v_readfirstlane_b32 s5, v186
	v_add_u32_e32 v186, 0x6000, v146
	s_mov_b32 m0, s5
	v_readfirstlane_b32 s5, v186
	ds_read_b128 v[198:201], v151 offset:32768
	ds_read_b128 v[202:205], v151 offset:33792
	ds_read_b128 v[206:209], v150 offset:32768
	ds_read_b128 v[210:213], v150 offset:33792
	ds_read_b128 v[214:217], v149 offset:32768
	ds_read_b128 v[218:221], v149 offset:33792
	ds_read_b128 v[222:225], v148 offset:32768
	ds_read_b128 v[226:229], v148 offset:33792
	global_load_lds_dwordx4 v[230:231], off
	v_lshl_add_u64 v[230:231], v[188:189], 0, s[50:51]
	s_mov_b32 m0, s5
	s_nop 0
	global_load_lds_dwordx4 v[230:231], off
	s_waitcnt lgkmcnt(8)
	s_barrier
	s_waitcnt lgkmcnt(0)
	v_mfma_f32_16x16x32_bf16 v[124:127], v[198:201], v[162:165], v[124:127]
	v_mfma_f32_16x16x32_bf16 v[120:123], v[198:201], v[170:173], v[120:123]
	v_mfma_f32_16x16x32_bf16 v[112:115], v[206:209], v[170:173], v[112:115]
	v_mfma_f32_16x16x32_bf16 v[116:119], v[206:209], v[162:165], v[116:119]
	v_mfma_f32_16x16x32_bf16 v[108:111], v[214:217], v[162:165], v[108:111]
	v_mfma_f32_16x16x32_bf16 v[104:107], v[214:217], v[170:173], v[104:107]
	v_mfma_f32_16x16x32_bf16 v[96:99], v[222:225], v[170:173], v[96:99]
	v_mfma_f32_16x16x32_bf16 v[100:103], v[222:225], v[162:165], v[100:103]
	v_mfma_f32_16x16x32_bf16 v[124:127], v[202:205], v[166:169], v[124:127]
	v_mfma_f32_16x16x32_bf16 v[120:123], v[202:205], v[174:177], v[120:123]
	v_mfma_f32_16x16x32_bf16 v[112:115], v[210:213], v[174:177], v[112:115]
	v_mfma_f32_16x16x32_bf16 v[116:119], v[210:213], v[166:169], v[116:119]
	v_mfma_f32_16x16x32_bf16 v[108:111], v[218:221], v[166:169], v[108:111]
	v_mfma_f32_16x16x32_bf16 v[104:107], v[218:221], v[174:177], v[104:107]
	v_mfma_f32_16x16x32_bf16 v[96:99], v[226:229], v[174:177], v[96:99]
	v_mfma_f32_16x16x32_bf16 v[100:103], v[226:229], v[166:169], v[100:103]
	s_barrier
	v_readfirstlane_b32 s5, v154
	v_add_u32_e32 v186, 0x2000, v154
	v_lshl_add_u64 v[250:251], v[246:247], 0, s[52:53]
	s_mov_b32 m0, s5
	v_readfirstlane_b32 s5, v186
	ds_read_b128 v[230:233], v152
	ds_read_b128 v[234:237], v152 offset:1024
	ds_read_b128 v[238:241], v152 offset:2048
	ds_read_b128 v[242:245], v152 offset:3072
	global_load_lds_dwordx4 v[250:251], off
	v_lshl_add_u64 v[250:251], v[248:249], 0, s[52:53]
	s_mov_b32 m0, s5
	s_nop 0
	global_load_lds_dwordx4 v[250:251], off
	s_barrier
	s_waitcnt lgkmcnt(0)
	v_mfma_f32_16x16x32_bf16 v[92:95], v[198:201], v[230:233], v[92:95]
	v_mfma_f32_16x16x32_bf16 v[88:91], v[198:201], v[238:241], v[88:91]
	v_mfma_f32_16x16x32_bf16 v[80:83], v[206:209], v[238:241], v[80:83]
	v_mfma_f32_16x16x32_bf16 v[84:87], v[206:209], v[230:233], v[84:87]
	v_mfma_f32_16x16x32_bf16 v[76:79], v[214:217], v[230:233], v[76:79]
	v_mfma_f32_16x16x32_bf16 v[72:75], v[214:217], v[238:241], v[72:75]
	v_mfma_f32_16x16x32_bf16 v[64:67], v[222:225], v[238:241], v[64:67]
	v_mfma_f32_16x16x32_bf16 v[68:71], v[222:225], v[230:233], v[68:71]
	v_mfma_f32_16x16x32_bf16 v[92:95], v[202:205], v[234:237], v[92:95]
	v_mfma_f32_16x16x32_bf16 v[88:91], v[202:205], v[242:245], v[88:91]
	v_mfma_f32_16x16x32_bf16 v[80:83], v[210:213], v[242:245], v[80:83]
	v_mfma_f32_16x16x32_bf16 v[84:87], v[210:213], v[234:237], v[84:87]
	v_mfma_f32_16x16x32_bf16 v[76:79], v[218:221], v[234:237], v[76:79]
	v_mfma_f32_16x16x32_bf16 v[72:75], v[218:221], v[242:245], v[72:75]
	v_mfma_f32_16x16x32_bf16 v[64:67], v[226:229], v[242:245], v[64:67]
	v_mfma_f32_16x16x32_bf16 v[68:71], v[226:229], v[234:237], v[68:71]
	v_readfirstlane_b32 s5, v155
	v_lshl_add_u64 v[178:179], v[178:179], 0, s[54:55]
	s_mov_b32 m0, s5
	v_readfirstlane_b32 s5, v156
	s_barrier
	ds_read_b128 v[198:201], v151 offset:49152
	ds_read_b128 v[202:205], v151 offset:50176
	ds_read_b128 v[206:209], v150 offset:49152
	ds_read_b128 v[210:213], v150 offset:50176
	ds_read_b128 v[214:217], v149 offset:49152
	ds_read_b128 v[218:221], v149 offset:50176
	ds_read_b128 v[222:225], v148 offset:49152
	ds_read_b128 v[226:229], v148 offset:50176
	global_load_lds_dwordx4 v[178:179], off
	v_lshl_add_u64 v[178:179], v[188:189], 0, s[54:55]
	s_mov_b32 m0, s5
	s_nop 0
	global_load_lds_dwordx4 v[178:179], off
	s_barrier
; #define WAIT_V(n) asm volatile("s_waitcnt vmcnt(" #n ")" ::: "memory")
; #define WAIT_L(n) asm volatile("s_waitcnt lgkmcnt(" #n ")" ::: "memory")
; #define BAR __builtin_amdgcn_s_barrier()
; #define SCHED __builtin_amdgcn_sched_barrier(0)
; #define LDA(dst, b, h)                                                                            \
;   _Pragma("unroll") for (int m = 0; m < 4; ++m) _Pragma("unroll") for (int k = 0; k < 2; ++k)                                         \
;     dst[m][k] = *reinterpret_cast<const bf16x8*>((char*)SA(b, h) + lds_byte(wr * 64 + m * 16 + fr, k * 32 + fq * 8))
; #define LDB(dst, b, h)                                                                            \
;   _Pragma("unroll") for (int n = 0; n < 2; ++n) _Pragma("unroll") for (int k = 0; k < 2; ++k)                                         \
;     dst[n][k] = *reinterpret_cast<const bf16x8*>((char*)SB(b, h) + lds_byte(wc * 32 + n * 16 + fr, k * 32 + fq * 8))
; template <int K, bool SWAP>
; __device__ __forceinline__ void gemm_kloop(const bf16* __restrict__ A, const bf16* __restrict__ Bt,
;                                            f32x4 (&acc)[2][2][4][2], bool pref = false) {
;     ...
;     BAR; WAIT_L(0); MMA(1, 0, At, B0); BAR; SCHED;
;     STAGE(SB(1, 1), Bt, HALF, t + 3);
;     WAIT_V(6); BAR; MMA(1, 1, At, B1); BAR;
;   }
;   { LDB(B0, 0, 0); LDA(At, 0, 0); STAGE(SA(1, 1), A, HALF, nt - 1);
;     BAR; WAIT_L(0); MMA(0, 0, At, B0); BAR;
;     LDB(B1, 0, 1); BAR; WAIT_L(0); MMA(0, 1, At, B1); BAR;
	s_waitcnt lgkmcnt(0)
	v_mfma_f32_16x16x32_bf16 v[60:63], v[198:201], v[162:165], v[60:63]
	v_mfma_f32_16x16x32_bf16 v[56:59], v[198:201], v[170:173], v[56:59]
	v_mfma_f32_16x16x32_bf16 v[48:51], v[206:209], v[170:173], v[48:51]
	v_mfma_f32_16x16x32_bf16 v[52:55], v[206:209], v[162:165], v[52:55]
	v_mfma_f32_16x16x32_bf16 v[44:47], v[214:217], v[162:165], v[44:47]
	v_mfma_f32_16x16x32_bf16 v[40:43], v[214:217], v[170:173], v[40:43]
	v_mfma_f32_16x16x32_bf16 v[32:35], v[222:225], v[170:173], v[32:35]
	v_mfma_f32_16x16x32_bf16 v[36:39], v[222:225], v[162:165], v[36:39]
	v_mfma_f32_16x16x32_bf16 v[60:63], v[202:205], v[166:169], v[60:63]
	v_mfma_f32_16x16x32_bf16 v[56:59], v[202:205], v[174:177], v[56:59]
	v_mfma_f32_16x16x32_bf16 v[48:51], v[210:213], v[174:177], v[48:51]
	v_mfma_f32_16x16x32_bf16 v[52:55], v[210:213], v[166:169], v[52:55]
	v_mfma_f32_16x16x32_bf16 v[44:47], v[218:221], v[166:169], v[44:47]
	v_mfma_f32_16x16x32_bf16 v[40:43], v[218:221], v[174:177], v[40:43]
	v_mfma_f32_16x16x32_bf16 v[32:35], v[226:229], v[174:177], v[32:35]
	v_mfma_f32_16x16x32_bf16 v[36:39], v[226:229], v[166:169], v[36:39]
	s_barrier
	v_readfirstlane_b32 s5, v157
	v_add_u32_e32 v164, 0x2000, v157
	v_lshl_add_u64 v[162:163], v[246:247], 0, s[56:57]
	s_mov_b32 m0, s5
	v_readfirstlane_b32 s5, v164
	global_load_lds_dwordx4 v[162:163], off
	v_lshl_add_u64 v[162:163], v[248:249], 0, s[56:57]
	s_mov_b32 m0, s5
	s_nop 0
	global_load_lds_dwordx4 v[162:163], off
	s_waitcnt vmcnt(6)
	s_barrier
	v_mfma_f32_16x16x32_bf16 v[28:31], v[198:201], v[230:233], v[28:31]
	v_mfma_f32_16x16x32_bf16 v[24:27], v[198:201], v[238:241], v[24:27]
	v_mfma_f32_16x16x32_bf16 v[16:19], v[206:209], v[238:241], v[16:19]
	v_mfma_f32_16x16x32_bf16 v[20:23], v[206:209], v[230:233], v[20:23]
	v_mfma_f32_16x16x32_bf16 v[12:15], v[214:217], v[230:233], v[12:15]
	v_mfma_f32_16x16x32_bf16 v[8:11], v[214:217], v[238:241], v[8:11]
	v_mfma_f32_16x16x32_bf16 v[0:3], v[222:225], v[238:241], v[0:3]
	v_mfma_f32_16x16x32_bf16 v[4:7], v[222:225], v[230:233], v[4:7]
	v_mfma_f32_16x16x32_bf16 v[28:31], v[202:205], v[234:237], v[28:31]
	v_mfma_f32_16x16x32_bf16 v[24:27], v[202:205], v[242:245], v[24:27]
	v_mfma_f32_16x16x32_bf16 v[16:19], v[210:213], v[242:245], v[16:19]
	v_mfma_f32_16x16x32_bf16 v[20:23], v[210:213], v[234:237], v[20:23]
	v_mfma_f32_16x16x32_bf16 v[12:15], v[218:221], v[234:237], v[12:15]
	v_mfma_f32_16x16x32_bf16 v[8:11], v[218:221], v[242:245], v[8:11]
	v_mfma_f32_16x16x32_bf16 v[0:3], v[226:229], v[242:245], v[0:3]
	v_mfma_f32_16x16x32_bf16 v[4:7], v[226:229], v[234:237], v[4:7]
	s_add_i32 s4, s4, 2
	v_lshl_add_u64 v[136:137], v[136:137], 0, s[44:45]
	v_lshl_add_u64 v[138:139], v[138:139], 0, s[44:45]
	v_lshl_add_u64 v[140:141], v[140:141], 0, s[44:45]
	s_cmp_lt_u32 s4, 12
	v_lshl_add_u64 v[142:143], v[142:143], 0, s[44:45]
	s_barrier
	s_cbranch_scc1 .LBB0_271
	s_add_u32 s0, s0, 0x40780
	s_addc_u32 s1, s1, 0
	v_lshl_add_u64 v[130:131], s[0:1], 0, v[130:131]
	v_readfirstlane_b32 s4, v160
	v_lshl_add_u64 v[128:129], v[128:129], 1, v[130:131]
	s_mov_b32 m0, s4
	ds_read_b128 v[136:139], v159
	ds_read_b128 v[140:143], v159 offset:1024
	ds_read_b128 v[154:157], v159 offset:2048
	ds_read_b128 v[162:165], v159 offset:3072
	ds_read_b128 v[166:169], v151
	ds_read_b128 v[170:173], v151 offset:1024
	ds_read_b128 v[174:177], v150
	ds_read_b128 v[198:201], v150 offset:1024
	ds_read_b128 v[202:205], v149
	ds_read_b128 v[206:209], v149 offset:1024
	ds_read_b128 v[210:213], v148
	ds_read_b128 v[214:217], v148 offset:1024
	global_load_lds_dwordx4 v[128:129], off
	v_lshl_add_u64 v[128:129], s[0:1], 0, v[134:135]
	v_readfirstlane_b32 s0, v161
	v_lshl_add_u64 v[128:129], v[132:133], 1, v[128:129]
	s_mov_b32 m0, s0
	s_nop 0
	global_load_lds_dwordx4 v[128:129], off
	s_barrier
	s_waitcnt lgkmcnt(0)
	v_mfma_f32_16x16x32_bf16 v[124:127], v[166:169], v[136:139], v[124:127]
	v_mfma_f32_16x16x32_bf16 v[116:119], v[174:177], v[136:139], v[116:119]
	v_mfma_f32_16x16x32_bf16 v[108:111], v[202:205], v[136:139], v[108:111]
	v_mfma_f32_16x16x32_bf16 v[100:103], v[210:213], v[136:139], v[100:103]
	v_mfma_f32_16x16x32_bf16 v[124:127], v[170:173], v[140:143], v[124:127]
	v_mfma_f32_16x16x32_bf16 v[120:123], v[166:169], v[154:157], v[120:123]
	v_mfma_f32_16x16x32_bf16 v[116:119], v[198:201], v[140:143], v[116:119]
	v_mfma_f32_16x16x32_bf16 v[112:115], v[174:177], v[154:157], v[112:115]
	v_mfma_f32_16x16x32_bf16 v[108:111], v[206:209], v[140:143], v[108:111]
	v_mfma_f32_16x16x32_bf16 v[104:107], v[202:205], v[154:157], v[104:107]
	v_mfma_f32_16x16x32_bf16 v[100:103], v[214:217], v[140:143], v[100:103]
	v_mfma_f32_16x16x32_bf16 v[96:99], v[210:213], v[154:157], v[96:99]
	v_mfma_f32_16x16x32_bf16 v[128:131], v[170:173], v[162:165], v[120:123]
	v_mfma_f32_16x16x32_bf16 v[132:135], v[198:201], v[162:165], v[112:115]
	v_mfma_f32_16x16x32_bf16 v[218:221], v[206:209], v[162:165], v[104:107]
	v_mfma_f32_16x16x32_bf16 v[222:225], v[214:217], v[162:165], v[96:99]
	s_barrier
	s_nop 1
	ds_read_b128 v[96:99], v158
	ds_read_b128 v[104:107], v158 offset:1024
	ds_read_b128 v[112:115], v158 offset:2048
	ds_read_b128 v[120:123], v158 offset:3072
	s_barrier
; #define WAIT_V(n) asm volatile("s_waitcnt vmcnt(" #n ")" ::: "memory")
; #define WAIT_L(n) asm volatile("s_waitcnt lgkmcnt(" #n ")" ::: "memory")
; #define BAR __builtin_amdgcn_s_barrier()
; #define LDA(dst, b, h)                                                                            \
;   _Pragma("unroll") for (int m = 0; m < 4; ++m) _Pragma("unroll") for (int k = 0; k < 2; ++k)                                         \
;     dst[m][k] = *reinterpret_cast<const bf16x8*>((char*)SA(b, h) + lds_byte(wr * 64 + m * 16 + fr, k * 32 + fq * 8))
; #define LDB(dst, b, h)                                                                            \
;   _Pragma("unroll") for (int n = 0; n < 2; ++n) _Pragma("unroll") for (int k = 0; k < 2; ++k)                                         \
;     dst[n][k] = *reinterpret_cast<const bf16x8*>((char*)SB(b, h) + lds_byte(wc * 32 + n * 16 + fr, k * 32 + fq * 8))
; template <int K, bool SWAP>
; __device__ __forceinline__ void gemm_kloop(const bf16* __restrict__ A, const bf16* __restrict__ Bt,
;                                            f32x4 (&acc)[2][2][4][2], bool pref = false) {
;     ...
;     LDB(B1, 0, 1); BAR; WAIT_L(0); MMA(0, 1, At, B1); BAR;
;     LDA(At, 0, 1); WAIT_V(4); BAR; WAIT_L(0); MMA(1, 0, At, B0); MMA(1, 1, At, B1); BAR; }
;   { LDB(B0, 1, 0); LDA(At, 1, 0); WAIT_V(2); BAR; WAIT_L(0); MMA(0, 0, At, B0); BAR;
	s_waitcnt lgkmcnt(0)
	v_mfma_f32_16x16x32_bf16 v[92:95], v[166:169], v[96:99], v[92:95]
	v_mfma_f32_16x16x32_bf16 v[84:87], v[174:177], v[96:99], v[84:87]
	v_mfma_f32_16x16x32_bf16 v[76:79], v[202:205], v[96:99], v[76:79]
	v_mfma_f32_16x16x32_bf16 v[68:71], v[210:213], v[96:99], v[68:71]
	v_mfma_f32_16x16x32_bf16 v[92:95], v[170:173], v[104:107], v[92:95]
	v_mfma_f32_16x16x32_bf16 v[88:91], v[166:169], v[112:115], v[88:91]
	v_mfma_f32_16x16x32_bf16 v[84:87], v[198:201], v[104:107], v[84:87]
	v_mfma_f32_16x16x32_bf16 v[80:83], v[174:177], v[112:115], v[80:83]
	v_mfma_f32_16x16x32_bf16 v[76:79], v[206:209], v[104:107], v[76:79]
	v_mfma_f32_16x16x32_bf16 v[72:75], v[202:205], v[112:115], v[72:75]
	v_mfma_f32_16x16x32_bf16 v[68:71], v[214:217], v[104:107], v[68:71]
	v_mfma_f32_16x16x32_bf16 v[64:67], v[210:213], v[112:115], v[64:67]
	v_mfma_f32_16x16x32_bf16 v[158:161], v[170:173], v[120:123], v[88:91]
	v_mfma_f32_16x16x32_bf16 v[166:169], v[198:201], v[120:123], v[80:83]
	v_mfma_f32_16x16x32_bf16 v[170:173], v[206:209], v[120:123], v[72:75]
	v_mfma_f32_16x16x32_bf16 v[174:177], v[214:217], v[120:123], v[64:67]
	s_barrier
	s_nop 1
	ds_read_b128 v[64:67], v151 offset:16384
	ds_read_b128 v[72:75], v151 offset:17408
	ds_read_b128 v[80:83], v150 offset:16384
	ds_read_b128 v[88:91], v150 offset:17408
	ds_read_b128 v[198:201], v149 offset:16384
	ds_read_b128 v[202:205], v149 offset:17408
	ds_read_b128 v[206:209], v148 offset:16384
	ds_read_b128 v[210:213], v148 offset:17408
	s_waitcnt vmcnt(4)
	s_barrier
	s_waitcnt lgkmcnt(0)
	v_mfma_f32_16x16x32_bf16 v[60:63], v[64:67], v[136:139], v[60:63]
	v_mfma_f32_16x16x32_bf16 v[52:55], v[80:83], v[136:139], v[52:55]
	v_mfma_f32_16x16x32_bf16 v[44:47], v[198:201], v[136:139], v[44:47]
	v_mfma_f32_16x16x32_bf16 v[36:39], v[206:209], v[136:139], v[36:39]
	v_mfma_f32_16x16x32_bf16 v[60:63], v[72:75], v[140:143], v[60:63]
	v_mfma_f32_16x16x32_bf16 v[56:59], v[64:67], v[154:157], v[56:59]
	v_mfma_f32_16x16x32_bf16 v[52:55], v[88:91], v[140:143], v[52:55]
	v_mfma_f32_16x16x32_bf16 v[48:51], v[80:83], v[154:157], v[48:51]
	v_mfma_f32_16x16x32_bf16 v[44:47], v[202:205], v[140:143], v[44:47]
	v_mfma_f32_16x16x32_bf16 v[40:43], v[198:201], v[154:157], v[40:43]
	v_mfma_f32_16x16x32_bf16 v[36:39], v[210:213], v[140:143], v[36:39]
	v_mfma_f32_16x16x32_bf16 v[32:35], v[206:209], v[154:157], v[32:35]
	v_mfma_f32_16x16x32_bf16 v[214:217], v[72:75], v[162:165], v[56:59]
	v_mfma_f32_16x16x32_bf16 v[226:229], v[88:91], v[162:165], v[48:51]
	v_mfma_f32_16x16x32_bf16 v[230:233], v[202:205], v[162:165], v[40:43]
	v_mfma_f32_16x16x32_bf16 v[136:139], v[210:213], v[162:165], v[32:35]
	v_mfma_f32_16x16x32_bf16 v[28:31], v[64:67], v[96:99], v[28:31]
	v_mfma_f32_16x16x32_bf16 v[20:23], v[80:83], v[96:99], v[20:23]
	v_mfma_f32_16x16x32_bf16 v[12:15], v[198:201], v[96:99], v[12:15]
	v_mfma_f32_16x16x32_bf16 v[4:7], v[206:209], v[96:99], v[4:7]
	v_mfma_f32_16x16x32_bf16 v[28:31], v[72:75], v[104:107], v[28:31]
	v_mfma_f32_16x16x32_bf16 v[24:27], v[64:67], v[112:115], v[24:27]
	v_mfma_f32_16x16x32_bf16 v[20:23], v[88:91], v[104:107], v[20:23]
	v_mfma_f32_16x16x32_bf16 v[16:19], v[80:83], v[112:115], v[16:19]
	v_mfma_f32_16x16x32_bf16 v[12:15], v[202:205], v[104:107], v[12:15]
	v_mfma_f32_16x16x32_bf16 v[8:11], v[198:201], v[112:115], v[8:11]
	v_mfma_f32_16x16x32_bf16 v[4:7], v[210:213], v[104:107], v[4:7]
	v_mfma_f32_16x16x32_bf16 v[0:3], v[206:209], v[112:115], v[0:3]
	v_mfma_f32_16x16x32_bf16 v[140:143], v[72:75], v[120:123], v[24:27]
	v_mfma_f32_16x16x32_bf16 v[154:157], v[88:91], v[120:123], v[16:19]
	v_mfma_f32_16x16x32_bf16 v[162:165], v[202:205], v[120:123], v[8:11]
	v_mfma_f32_16x16x32_bf16 v[198:201], v[210:213], v[120:123], v[0:3]
	s_barrier
	s_nop 1
	ds_read_b128 v[0:3], v153
	ds_read_b128 v[8:11], v153 offset:1024
	ds_read_b128 v[16:19], v153 offset:2048
	ds_read_b128 v[24:27], v153 offset:3072
	ds_read_b128 v[32:35], v151 offset:32768
	ds_read_b128 v[40:43], v151 offset:33792
	ds_read_b128 v[48:51], v150 offset:32768
	ds_read_b128 v[56:59], v150 offset:33792
	ds_read_b128 v[64:67], v149 offset:32768
	ds_read_b128 v[202:205], v149 offset:33792
	ds_read_b128 v[206:209], v148 offset:32768
	ds_read_b128 v[210:213], v148 offset:33792
	s_waitcnt vmcnt(2)
	s_barrier
; #define WAIT_V(n) asm volatile("s_waitcnt vmcnt(" #n ")" ::: "memory")
; #define WAIT_L(n) asm volatile("s_waitcnt lgkmcnt(" #n ")" ::: "memory")
; #define BAR __builtin_amdgcn_s_barrier()
; #define LDA(dst, b, h)                                                                            \
;   _Pragma("unroll") for (int m = 0; m < 4; ++m) _Pragma("unroll") for (int k = 0; k < 2; ++k)                                         \
;     dst[m][k] = *reinterpret_cast<const bf16x8*>((char*)SA(b, h) + lds_byte(wr * 64 + m * 16 + fr, k * 32 + fq * 8))
; #define LDB(dst, b, h)                                                                            \
;   _Pragma("unroll") for (int n = 0; n < 2; ++n) _Pragma("unroll") for (int k = 0; k < 2; ++k)                                         \
;     dst[n][k] = *reinterpret_cast<const bf16x8*>((char*)SB(b, h) + lds_byte(wc * 32 + n * 16 + fr, k * 32 + fq * 8))
; template <int K, bool SWAP>
; __device__ __forceinline__ void gemm_kloop(const bf16* __restrict__ A, const bf16* __restrict__ Bt,
;                                            f32x4 (&acc)[2][2][4][2], bool pref = false) {
;     ...
;   { LDB(B0, 1, 0); LDA(At, 1, 0); WAIT_V(2); BAR; WAIT_L(0); MMA(0, 0, At, B0); BAR;
;     LDB(B1, 1, 1); WAIT_V(0); BAR; WAIT_L(0); MMA(0, 1, At, B1); BAR;
;     LDA(At, 1, 1); BAR; WAIT_L(0); MMA(1, 0, At, B0); MMA(1, 1, At, B1); BAR; }
;   if (wr == 0) BAR;
	s_waitcnt lgkmcnt(0)
	v_mfma_f32_16x16x32_bf16 v[72:75], v[32:35], v[0:3], v[124:127]
	v_mfma_f32_16x16x32_bf16 v[120:123], v[40:43], v[8:11], v[72:75]
	v_mfma_f32_16x16x32_bf16 v[72:75], v[32:35], v[16:19], v[128:131]
	v_mfma_f32_16x16x32_bf16 v[124:127], v[40:43], v[24:27], v[72:75]
	v_mfma_f32_16x16x32_bf16 v[72:75], v[48:51], v[0:3], v[116:119]
	v_mfma_f32_16x16x32_bf16 v[112:115], v[56:59], v[8:11], v[72:75]
	v_mfma_f32_16x16x32_bf16 v[72:75], v[48:51], v[16:19], v[132:135]
	v_mfma_f32_16x16x32_bf16 v[116:119], v[56:59], v[24:27], v[72:75]
	v_mfma_f32_16x16x32_bf16 v[72:75], v[64:67], v[0:3], v[108:111]
	v_mfma_f32_16x16x32_bf16 v[104:107], v[202:205], v[8:11], v[72:75]
	v_mfma_f32_16x16x32_bf16 v[72:75], v[64:67], v[16:19], v[218:221]
	v_mfma_f32_16x16x32_bf16 v[108:111], v[202:205], v[24:27], v[72:75]
	v_mfma_f32_16x16x32_bf16 v[72:75], v[206:209], v[0:3], v[100:103]
	v_mfma_f32_16x16x32_bf16 v[96:99], v[210:213], v[8:11], v[72:75]
	v_mfma_f32_16x16x32_bf16 v[72:75], v[206:209], v[16:19], v[222:225]
	v_mfma_f32_16x16x32_bf16 v[100:103], v[210:213], v[24:27], v[72:75]
	s_barrier
	ds_read_b128 v[128:131], v152
	ds_read_b128 v[132:135], v152 offset:1024
	ds_read_b128 v[218:221], v152 offset:2048
	ds_read_b128 v[222:225], v152 offset:3072
	s_waitcnt vmcnt(0)
	s_barrier
	s_waitcnt lgkmcnt(0)
	v_mfma_f32_16x16x32_bf16 v[72:75], v[32:35], v[128:131], v[92:95]
	v_mfma_f32_16x16x32_bf16 v[32:35], v[32:35], v[218:221], v[158:161]
	v_mfma_f32_16x16x32_bf16 v[92:95], v[40:43], v[222:225], v[32:35]
	v_mfma_f32_16x16x32_bf16 v[32:35], v[48:51], v[128:131], v[84:87]
	v_mfma_f32_16x16x32_bf16 v[80:83], v[56:59], v[132:135], v[32:35]
	v_mfma_f32_16x16x32_bf16 v[32:35], v[48:51], v[218:221], v[166:169]
	v_mfma_f32_16x16x32_bf16 v[84:87], v[56:59], v[222:225], v[32:35]
	v_mfma_f32_16x16x32_bf16 v[32:35], v[64:67], v[128:131], v[76:79]
	v_mfma_f32_16x16x32_bf16 v[88:91], v[40:43], v[132:135], v[72:75]
	v_mfma_f32_16x16x32_bf16 v[72:75], v[202:205], v[132:135], v[32:35]
	v_mfma_f32_16x16x32_bf16 v[32:35], v[64:67], v[218:221], v[170:173]
	v_mfma_f32_16x16x32_bf16 v[76:79], v[202:205], v[222:225], v[32:35]
	v_mfma_f32_16x16x32_bf16 v[32:35], v[206:209], v[128:131], v[68:71]
	v_mfma_f32_16x16x32_bf16 v[64:67], v[210:213], v[132:135], v[32:35]
	v_mfma_f32_16x16x32_bf16 v[32:35], v[206:209], v[218:221], v[174:177]
	v_mfma_f32_16x16x32_bf16 v[68:71], v[210:213], v[222:225], v[32:35]
	s_barrier
	ds_read_b128 v[158:161], v151 offset:49152
	ds_read_b128 v[166:169], v151 offset:50176
	ds_read_b128 v[170:173], v150 offset:49152
	ds_read_b128 v[150:153], v150 offset:50176
	ds_read_b128 v[174:177], v149 offset:49152
	ds_read_b128 v[202:205], v149 offset:50176
	ds_read_b128 v[206:209], v148 offset:49152
	ds_read_b128 v[146:149], v148 offset:50176
	s_barrier
	s_waitcnt lgkmcnt(0)
	v_mfma_f32_16x16x32_bf16 v[32:35], v[158:161], v[0:3], v[60:63]
	v_mfma_f32_16x16x32_bf16 v[56:59], v[166:169], v[8:11], v[32:35]
	v_mfma_f32_16x16x32_bf16 v[32:35], v[158:161], v[16:19], v[214:217]
	v_mfma_f32_16x16x32_bf16 v[60:63], v[166:169], v[24:27], v[32:35]
	v_mfma_f32_16x16x32_bf16 v[32:35], v[170:173], v[0:3], v[52:55]
	v_mfma_f32_16x16x32_bf16 v[48:51], v[150:153], v[8:11], v[32:35]
	v_mfma_f32_16x16x32_bf16 v[32:35], v[170:173], v[16:19], v[226:229]
	v_mfma_f32_16x16x32_bf16 v[52:55], v[150:153], v[24:27], v[32:35]
	v_mfma_f32_16x16x32_bf16 v[32:35], v[174:177], v[0:3], v[44:47]
	v_mfma_f32_16x16x32_bf16 v[40:43], v[202:205], v[8:11], v[32:35]
	v_mfma_f32_16x16x32_bf16 v[32:35], v[174:177], v[16:19], v[230:233]
	v_mfma_f32_16x16x32_bf16 v[0:3], v[206:209], v[0:3], v[36:39]
	v_mfma_f32_16x16x32_bf16 v[44:47], v[202:205], v[24:27], v[32:35]
	v_mfma_f32_16x16x32_bf16 v[32:35], v[146:149], v[8:11], v[0:3]
	v_mfma_f32_16x16x32_bf16 v[0:3], v[206:209], v[16:19], v[136:139]
	v_mfma_f32_16x16x32_bf16 v[36:39], v[146:149], v[24:27], v[0:3]
	v_mfma_f32_16x16x32_bf16 v[0:3], v[158:161], v[128:131], v[28:31]
	v_mfma_f32_16x16x32_bf16 v[24:27], v[166:169], v[132:135], v[0:3]
	v_mfma_f32_16x16x32_bf16 v[0:3], v[158:161], v[218:221], v[140:143]
	v_mfma_f32_16x16x32_bf16 v[28:31], v[166:169], v[222:225], v[0:3]
	v_mfma_f32_16x16x32_bf16 v[0:3], v[170:173], v[128:131], v[20:23]
	v_mfma_f32_16x16x32_bf16 v[16:19], v[150:153], v[132:135], v[0:3]
	v_mfma_f32_16x16x32_bf16 v[0:3], v[170:173], v[218:221], v[154:157]
	v_mfma_f32_16x16x32_bf16 v[20:23], v[150:153], v[222:225], v[0:3]
	v_mfma_f32_16x16x32_bf16 v[0:3], v[174:177], v[128:131], v[12:15]
	v_mfma_f32_16x16x32_bf16 v[8:11], v[202:205], v[132:135], v[0:3]
	v_mfma_f32_16x16x32_bf16 v[0:3], v[174:177], v[218:221], v[162:165]
	v_mfma_f32_16x16x32_bf16 v[12:15], v[202:205], v[222:225], v[0:3]
	v_mfma_f32_16x16x32_bf16 v[0:3], v[206:209], v[128:131], v[4:7]
	v_mfma_f32_16x16x32_bf16 v[4:7], v[206:209], v[218:221], v[198:201]
	v_mfma_f32_16x16x32_bf16 v[0:3], v[146:149], v[132:135], v[0:3]
	v_mfma_f32_16x16x32_bf16 v[4:7], v[146:149], v[222:225], v[4:7]
	s_movk_i32 s0, 0x100
	v_cmp_gt_u32_e32 vcc, s0, v144
	s_barrier
	s_and_saveexec_b64 s[0:1], vcc
	s_cbranch_execz .LBB0_274
	s_barrier

; #define WAIT_L(n) asm volatile("s_waitcnt lgkmcnt(" #n ")" ::: "memory")
; #define BAR __builtin_amdgcn_s_barrier()
; #define SCHED __builtin_amdgcn_sched_barrier(0)
; #define LDA(dst, b, h)                                                                            \
;   _Pragma("unroll") for (int m = 0; m < 4; ++m) _Pragma("unroll") for (int k = 0; k < 2; ++k)                                         \
;     dst[m][k] = *reinterpret_cast<const bf16x8*>((char*)SA(b, h) + lds_byte(wr * 64 + m * 16 + fr, k * 32 + fq * 8))
; #define LDB(dst, b, h)                                                                            \
;   _Pragma("unroll") for (int n = 0; n < 2; ++n) _Pragma("unroll") for (int k = 0; k < 2; ++k)                                         \
;     dst[n][k] = *reinterpret_cast<const bf16x8*>((char*)SB(b, h) + lds_byte(wc * 32 + n * 16 + fr, k * 32 + fq * 8))
; template <int K, bool SWAP>
; __device__ __forceinline__ void gemm_kloop(const bf16* __restrict__ A, const bf16* __restrict__ Bt,
;                                            f32x4 (&acc)[2][2][4][2], bool pref = false) {
;     ...
;     LDB(B0, 0, 0); SCHED; LDA(At, 0, 0); STAGE(SA(1, 1), A, HALF, t + 1);
;     WAIT_L(8); BAR; WAIT_L(0); MMA(0, 0, At, B0); BAR; SCHED;
;     LDB(B1, 0, 1); STAGE(SB(0, 0), Bt, 0, t + 2);
;     BAR; WAIT_L(0); MMA(0, 1, At, B1); BAR;
;     LDA(At, 0, 1); STAGE(SA(0, 0), A, 0, t + 2);
;     BAR; WAIT_L(0); MMA(1, 0, At, B0); BAR; SCHED;
.LBB0_449:
	ds_read_b128 v[162:165], v159
	ds_read_b128 v[166:169], v159 offset:1024
	ds_read_b128 v[170:173], v159 offset:2048
	ds_read_b128 v[174:177], v159 offset:3072
	v_add_u32_e32 v160, 0xc000, v146
	v_lshl_add_u64 v[178:179], s[58:59], 0, v[140:141]
	v_readfirstlane_b32 s7, v160
	v_lshl_add_u64 v[188:189], v[178:179], 0, s[42:43]
	s_mov_b32 m0, s7
	v_add_u32_e32 v161, 0xe000, v146
	ds_read_b128 v[198:201], v151
	ds_read_b128 v[202:205], v151 offset:1024
	ds_read_b128 v[206:209], v150
	ds_read_b128 v[210:213], v150 offset:1024
	ds_read_b128 v[214:217], v149
	ds_read_b128 v[218:221], v149 offset:1024
	ds_read_b128 v[222:225], v148
	ds_read_b128 v[226:229], v148 offset:1024
	global_load_lds_dwordx4 v[188:189], off
	v_lshl_add_u64 v[188:189], s[58:59], 0, v[142:143]
	v_readfirstlane_b32 s7, v161
	v_lshl_add_u64 v[230:231], v[188:189], 0, s[42:43]
	s_mov_b32 m0, s7
	s_nop 0
	global_load_lds_dwordx4 v[230:231], off
	s_waitcnt lgkmcnt(8)
	s_barrier
	s_waitcnt lgkmcnt(0)
	v_mfma_f32_16x16x32_bf16 v[124:127], v[198:201], v[162:165], v[124:127]
	v_mfma_f32_16x16x32_bf16 v[120:123], v[198:201], v[170:173], v[120:123]
	v_mfma_f32_16x16x32_bf16 v[112:115], v[206:209], v[170:173], v[112:115]
	v_mfma_f32_16x16x32_bf16 v[116:119], v[206:209], v[162:165], v[116:119]
	v_mfma_f32_16x16x32_bf16 v[108:111], v[214:217], v[162:165], v[108:111]
	v_mfma_f32_16x16x32_bf16 v[104:107], v[214:217], v[170:173], v[104:107]
	v_mfma_f32_16x16x32_bf16 v[96:99], v[222:225], v[170:173], v[96:99]
	v_mfma_f32_16x16x32_bf16 v[100:103], v[222:225], v[162:165], v[100:103]
	v_mfma_f32_16x16x32_bf16 v[124:127], v[202:205], v[166:169], v[124:127]
	v_mfma_f32_16x16x32_bf16 v[120:123], v[202:205], v[174:177], v[120:123]
	v_mfma_f32_16x16x32_bf16 v[112:115], v[210:213], v[174:177], v[112:115]
	v_mfma_f32_16x16x32_bf16 v[116:119], v[210:213], v[166:169], v[116:119]
	v_mfma_f32_16x16x32_bf16 v[108:111], v[218:221], v[166:169], v[108:111]
	v_mfma_f32_16x16x32_bf16 v[104:107], v[218:221], v[174:177], v[104:107]
	v_mfma_f32_16x16x32_bf16 v[96:99], v[226:229], v[174:177], v[96:99]
	v_mfma_f32_16x16x32_bf16 v[100:103], v[226:229], v[166:169], v[100:103]
	s_barrier
	v_add_u32_e32 v186, s1, v145
	v_lshl_add_u64 v[246:247], s[58:59], 0, v[136:137]
	v_readfirstlane_b32 s7, v186
	v_lshl_add_u64 v[248:249], v[246:247], 0, s[44:45]
	s_mov_b32 m0, s7
	v_add_u32_e32 v186, 0x2000, v186
	ds_read_b128 v[230:233], v158
	ds_read_b128 v[234:237], v158 offset:1024
	ds_read_b128 v[238:241], v158 offset:2048
	ds_read_b128 v[242:245], v158 offset:3072
	global_load_lds_dwordx4 v[248:249], off
	v_lshl_add_u64 v[248:249], s[58:59], 0, v[138:139]
	v_readfirstlane_b32 s7, v186
	v_lshl_add_u64 v[250:251], v[248:249], 0, s[44:45]
	s_mov_b32 m0, s7
	s_nop 0
	global_load_lds_dwordx4 v[250:251], off
	s_barrier
	s_waitcnt lgkmcnt(0)
	v_mfma_f32_16x16x32_bf16 v[92:95], v[198:201], v[230:233], v[92:95]
	v_mfma_f32_16x16x32_bf16 v[88:91], v[198:201], v[238:241], v[88:91]
	v_mfma_f32_16x16x32_bf16 v[80:83], v[206:209], v[238:241], v[80:83]
	v_mfma_f32_16x16x32_bf16 v[84:87], v[206:209], v[230:233], v[84:87]
	v_mfma_f32_16x16x32_bf16 v[76:79], v[214:217], v[230:233], v[76:79]
	v_mfma_f32_16x16x32_bf16 v[72:75], v[214:217], v[238:241], v[72:75]
	v_mfma_f32_16x16x32_bf16 v[64:67], v[222:225], v[238:241], v[64:67]
	v_mfma_f32_16x16x32_bf16 v[68:71], v[222:225], v[230:233], v[68:71]
	v_mfma_f32_16x16x32_bf16 v[92:95], v[202:205], v[234:237], v[92:95]
	v_mfma_f32_16x16x32_bf16 v[88:91], v[202:205], v[242:245], v[88:91]
	v_mfma_f32_16x16x32_bf16 v[80:83], v[210:213], v[242:245], v[80:83]
	v_mfma_f32_16x16x32_bf16 v[84:87], v[210:213], v[234:237], v[84:87]
	v_mfma_f32_16x16x32_bf16 v[76:79], v[218:221], v[234:237], v[76:79]
	v_mfma_f32_16x16x32_bf16 v[72:75], v[218:221], v[242:245], v[72:75]
	v_mfma_f32_16x16x32_bf16 v[64:67], v[226:229], v[242:245], v[64:67]
	v_mfma_f32_16x16x32_bf16 v[68:71], v[226:229], v[234:237], v[68:71]
	v_readfirstlane_b32 s7, v146
	v_add_u32_e32 v186, 0x2000, v146
	v_lshl_add_u64 v[250:251], v[178:179], 0, s[46:47]
	s_mov_b32 m0, s7
	v_readfirstlane_b32 s7, v186
	s_barrier
	ds_read_b128 v[198:201], v151 offset:16384
	ds_read_b128 v[202:205], v151 offset:17408
	ds_read_b128 v[206:209], v150 offset:16384
	ds_read_b128 v[210:213], v150 offset:17408
	ds_read_b128 v[214:217], v149 offset:16384
	ds_read_b128 v[218:221], v149 offset:17408
	ds_read_b128 v[222:225], v148 offset:16384
	ds_read_b128 v[226:229], v148 offset:17408
	global_load_lds_dwordx4 v[250:251], off
	v_lshl_add_u64 v[250:251], v[188:189], 0, s[46:47]
	s_mov_b32 m0, s7
	s_nop 0
	global_load_lds_dwordx4 v[250:251], off
	s_barrier
	s_waitcnt lgkmcnt(0)
	v_mfma_f32_16x16x32_bf16 v[60:63], v[198:201], v[162:165], v[60:63]
	v_mfma_f32_16x16x32_bf16 v[56:59], v[198:201], v[170:173], v[56:59]
	v_mfma_f32_16x16x32_bf16 v[48:51], v[206:209], v[170:173], v[48:51]
	v_mfma_f32_16x16x32_bf16 v[52:55], v[206:209], v[162:165], v[52:55]
	v_mfma_f32_16x16x32_bf16 v[44:47], v[214:217], v[162:165], v[44:47]
	v_mfma_f32_16x16x32_bf16 v[40:43], v[214:217], v[170:173], v[40:43]
	v_mfma_f32_16x16x32_bf16 v[32:35], v[222:225], v[170:173], v[32:35]
	v_mfma_f32_16x16x32_bf16 v[36:39], v[222:225], v[162:165], v[36:39]
	v_mfma_f32_16x16x32_bf16 v[60:63], v[202:205], v[166:169], v[60:63]
	v_mfma_f32_16x16x32_bf16 v[56:59], v[202:205], v[174:177], v[56:59]
	v_mfma_f32_16x16x32_bf16 v[48:51], v[210:213], v[174:177], v[48:51]
	v_mfma_f32_16x16x32_bf16 v[52:55], v[210:213], v[166:169], v[52:55]
	v_mfma_f32_16x16x32_bf16 v[44:47], v[218:221], v[166:169], v[44:47]
	v_mfma_f32_16x16x32_bf16 v[40:43], v[218:221], v[174:177], v[40:43]
	v_mfma_f32_16x16x32_bf16 v[32:35], v[226:229], v[174:177], v[32:35]
	v_mfma_f32_16x16x32_bf16 v[36:39], v[226:229], v[166:169], v[36:39]
	s_barrier
; #define WAIT_V(n) asm volatile("s_waitcnt vmcnt(" #n ")" ::: "memory")
; #define WAIT_L(n) asm volatile("s_waitcnt lgkmcnt(" #n ")" ::: "memory")
; #define BAR __builtin_amdgcn_s_barrier()
; #define SCHED __builtin_amdgcn_sched_barrier(0)
; #define LDA(dst, b, h)                                                                            \
;   _Pragma("unroll") for (int m = 0; m < 4; ++m) _Pragma("unroll") for (int k = 0; k < 2; ++k)                                         \
;     dst[m][k] = *reinterpret_cast<const bf16x8*>((char*)SA(b, h) + lds_byte(wr * 64 + m * 16 + fr, k * 32 + fq * 8))
; #define LDB(dst, b, h)                                                                            \
;   _Pragma("unroll") for (int n = 0; n < 2; ++n) _Pragma("unroll") for (int k = 0; k < 2; ++k)                                         \
;     dst[n][k] = *reinterpret_cast<const bf16x8*>((char*)SB(b, h) + lds_byte(wc * 32 + n * 16 + fr, k * 32 + fq * 8))
; template <int K, bool SWAP>
; __device__ __forceinline__ void gemm_kloop(const bf16* __restrict__ A, const bf16* __restrict__ Bt,
;                                            f32x4 (&acc)[2][2][4][2], bool pref = false) {
;     ...
;     STAGE(SB(0, 1), Bt, HALF, t + 2);
;     WAIT_V(6); BAR; MMA(1, 1, At, B1); BAR;
;     LDB(B0, 1, 0); SCHED; LDA(At, 1, 0); STAGE(SA(0, 1), A, HALF, t + 2);
;     WAIT_L(8); BAR; WAIT_L(0); MMA(0, 0, At, B0); BAR; SCHED;
;     LDB(B1, 1, 1); STAGE(SB(1, 0), Bt, 0, t + 3);
;     BAR; WAIT_L(0); MMA(0, 1, At, B1); BAR;
;     LDA(At, 1, 1); STAGE(SA(1, 0), A, 0, t + 3);
	v_readfirstlane_b32 s7, v147
	v_add_u32_e32 v164, 0x2000, v147
	v_lshl_add_u64 v[162:163], v[246:247], 0, s[48:49]
	s_mov_b32 m0, s7
	v_readfirstlane_b32 s7, v164
	global_load_lds_dwordx4 v[162:163], off
	v_lshl_add_u64 v[162:163], v[248:249], 0, s[48:49]
	s_mov_b32 m0, s7
	s_nop 0
	global_load_lds_dwordx4 v[162:163], off
	s_waitcnt vmcnt(6)
	s_barrier
	v_mfma_f32_16x16x32_bf16 v[28:31], v[198:201], v[230:233], v[28:31]
	v_mfma_f32_16x16x32_bf16 v[24:27], v[198:201], v[238:241], v[24:27]
	v_mfma_f32_16x16x32_bf16 v[16:19], v[206:209], v[238:241], v[16:19]
	v_mfma_f32_16x16x32_bf16 v[20:23], v[206:209], v[230:233], v[20:23]
	v_mfma_f32_16x16x32_bf16 v[12:15], v[214:217], v[230:233], v[12:15]
	v_mfma_f32_16x16x32_bf16 v[8:11], v[214:217], v[238:241], v[8:11]
	v_mfma_f32_16x16x32_bf16 v[0:3], v[222:225], v[238:241], v[0:3]
	v_mfma_f32_16x16x32_bf16 v[4:7], v[222:225], v[230:233], v[4:7]
	v_mfma_f32_16x16x32_bf16 v[28:31], v[202:205], v[234:237], v[28:31]
	v_mfma_f32_16x16x32_bf16 v[24:27], v[202:205], v[242:245], v[24:27]
	v_mfma_f32_16x16x32_bf16 v[16:19], v[210:213], v[242:245], v[16:19]
	v_mfma_f32_16x16x32_bf16 v[20:23], v[210:213], v[234:237], v[20:23]
	v_mfma_f32_16x16x32_bf16 v[12:15], v[218:221], v[234:237], v[12:15]
	v_mfma_f32_16x16x32_bf16 v[8:11], v[218:221], v[242:245], v[8:11]
	v_mfma_f32_16x16x32_bf16 v[0:3], v[226:229], v[242:245], v[0:3]
	v_mfma_f32_16x16x32_bf16 v[4:7], v[226:229], v[234:237], v[4:7]
	s_barrier
	ds_read_b128 v[162:165], v153
	ds_read_b128 v[166:169], v153 offset:1024
	ds_read_b128 v[170:173], v153 offset:2048
	ds_read_b128 v[174:177], v153 offset:3072
	v_add_u32_e32 v186, 0x4000, v146
	v_lshl_add_u64 v[230:231], v[178:179], 0, s[50:51]
	v_readfirstlane_b32 s7, v186
	v_add_u32_e32 v186, 0x6000, v146
	s_mov_b32 m0, s7
	v_readfirstlane_b32 s7, v186
	ds_read_b128 v[198:201], v151 offset:32768
	ds_read_b128 v[202:205], v151 offset:33792
	ds_read_b128 v[206:209], v150 offset:32768
	ds_read_b128 v[210:213], v150 offset:33792
	ds_read_b128 v[214:217], v149 offset:32768
	ds_read_b128 v[218:221], v149 offset:33792
	ds_read_b128 v[222:225], v148 offset:32768
	ds_read_b128 v[226:229], v148 offset:33792
	global_load_lds_dwordx4 v[230:231], off
	v_lshl_add_u64 v[230:231], v[188:189], 0, s[50:51]
	s_mov_b32 m0, s7
	s_nop 0
	global_load_lds_dwordx4 v[230:231], off
	s_waitcnt lgkmcnt(8)
	s_barrier
	s_waitcnt lgkmcnt(0)
	v_mfma_f32_16x16x32_bf16 v[124:127], v[198:201], v[162:165], v[124:127]
	v_mfma_f32_16x16x32_bf16 v[120:123], v[198:201], v[170:173], v[120:123]
	v_mfma_f32_16x16x32_bf16 v[112:115], v[206:209], v[170:173], v[112:115]
	v_mfma_f32_16x16x32_bf16 v[116:119], v[206:209], v[162:165], v[116:119]
	v_mfma_f32_16x16x32_bf16 v[108:111], v[214:217], v[162:165], v[108:111]
	v_mfma_f32_16x16x32_bf16 v[104:107], v[214:217], v[170:173], v[104:107]
	v_mfma_f32_16x16x32_bf16 v[96:99], v[222:225], v[170:173], v[96:99]
	v_mfma_f32_16x16x32_bf16 v[100:103], v[222:225], v[162:165], v[100:103]
	v_mfma_f32_16x16x32_bf16 v[124:127], v[202:205], v[166:169], v[124:127]
	v_mfma_f32_16x16x32_bf16 v[120:123], v[202:205], v[174:177], v[120:123]
	v_mfma_f32_16x16x32_bf16 v[112:115], v[210:213], v[174:177], v[112:115]
	v_mfma_f32_16x16x32_bf16 v[116:119], v[210:213], v[166:169], v[116:119]
	v_mfma_f32_16x16x32_bf16 v[108:111], v[218:221], v[166:169], v[108:111]
	v_mfma_f32_16x16x32_bf16 v[104:107], v[218:221], v[174:177], v[104:107]
	v_mfma_f32_16x16x32_bf16 v[96:99], v[226:229], v[174:177], v[96:99]
	v_mfma_f32_16x16x32_bf16 v[100:103], v[226:229], v[166:169], v[100:103]
	s_barrier
	v_readfirstlane_b32 s7, v154
	v_add_u32_e32 v186, 0x2000, v154
	v_lshl_add_u64 v[250:251], v[246:247], 0, s[52:53]
	s_mov_b32 m0, s7
	v_readfirstlane_b32 s7, v186
	ds_read_b128 v[230:233], v152
	ds_read_b128 v[234:237], v152 offset:1024
	ds_read_b128 v[238:241], v152 offset:2048
	ds_read_b128 v[242:245], v152 offset:3072
	global_load_lds_dwordx4 v[250:251], off
	v_lshl_add_u64 v[250:251], v[248:249], 0, s[52:53]
	s_mov_b32 m0, s7
	s_nop 0
	global_load_lds_dwordx4 v[250:251], off
	s_barrier
	s_waitcnt lgkmcnt(0)
	v_mfma_f32_16x16x32_bf16 v[92:95], v[198:201], v[230:233], v[92:95]
	v_mfma_f32_16x16x32_bf16 v[88:91], v[198:201], v[238:241], v[88:91]
	v_mfma_f32_16x16x32_bf16 v[80:83], v[206:209], v[238:241], v[80:83]
	v_mfma_f32_16x16x32_bf16 v[84:87], v[206:209], v[230:233], v[84:87]
	v_mfma_f32_16x16x32_bf16 v[76:79], v[214:217], v[230:233], v[76:79]
	v_mfma_f32_16x16x32_bf16 v[72:75], v[214:217], v[238:241], v[72:75]
	v_mfma_f32_16x16x32_bf16 v[64:67], v[222:225], v[238:241], v[64:67]
	v_mfma_f32_16x16x32_bf16 v[68:71], v[222:225], v[230:233], v[68:71]
	v_mfma_f32_16x16x32_bf16 v[92:95], v[202:205], v[234:237], v[92:95]
	v_mfma_f32_16x16x32_bf16 v[88:91], v[202:205], v[242:245], v[88:91]
	v_mfma_f32_16x16x32_bf16 v[80:83], v[210:213], v[242:245], v[80:83]
	v_mfma_f32_16x16x32_bf16 v[84:87], v[210:213], v[234:237], v[84:87]
	v_mfma_f32_16x16x32_bf16 v[76:79], v[218:221], v[234:237], v[76:79]
	v_mfma_f32_16x16x32_bf16 v[72:75], v[218:221], v[242:245], v[72:75]
	v_mfma_f32_16x16x32_bf16 v[64:67], v[226:229], v[242:245], v[64:67]
	v_mfma_f32_16x16x32_bf16 v[68:71], v[226:229], v[234:237], v[68:71]
	v_readfirstlane_b32 s7, v155
	v_lshl_add_u64 v[178:179], v[178:179], 0, s[54:55]
	s_mov_b32 m0, s7
	v_readfirstlane_b32 s7, v156
	s_barrier
	ds_read_b128 v[198:201], v151 offset:49152
	ds_read_b128 v[202:205], v151 offset:50176
	ds_read_b128 v[206:209], v150 offset:49152
	ds_read_b128 v[210:213], v150 offset:50176
	ds_read_b128 v[214:217], v149 offset:49152
	ds_read_b128 v[218:221], v149 offset:50176
	ds_read_b128 v[222:225], v148 offset:49152
	ds_read_b128 v[226:229], v148 offset:50176
	global_load_lds_dwordx4 v[178:179], off
	v_lshl_add_u64 v[178:179], v[188:189], 0, s[54:55]
	s_mov_b32 m0, s7
	s_nop 0
	global_load_lds_dwordx4 v[178:179], off
	s_barrier
; #define WAIT_V(n) asm volatile("s_waitcnt vmcnt(" #n ")" ::: "memory")
; #define WAIT_L(n) asm volatile("s_waitcnt lgkmcnt(" #n ")" ::: "memory")
; #define BAR __builtin_amdgcn_s_barrier()
; #define SCHED __builtin_amdgcn_sched_barrier(0)
; #define LDA(dst, b, h)                                                                            \
;   _Pragma("unroll") for (int m = 0; m < 4; ++m) _Pragma("unroll") for (int k = 0; k < 2; ++k)                                         \
;     dst[m][k] = *reinterpret_cast<const bf16x8*>((char*)SA(b, h) + lds_byte(wr * 64 + m * 16 + fr, k * 32 + fq * 8))
; #define LDB(dst, b, h)                                                                            \
;   _Pragma("unroll") for (int n = 0; n < 2; ++n) _Pragma("unroll") for (int k = 0; k < 2; ++k)                                         \
;     dst[n][k] = *reinterpret_cast<const bf16x8*>((char*)SB(b, h) + lds_byte(wc * 32 + n * 16 + fr, k * 32 + fq * 8))
; template <int K, bool SWAP>
; __device__ __forceinline__ void gemm_kloop(const bf16* __restrict__ A, const bf16* __restrict__ Bt,
;                                            f32x4 (&acc)[2][2][4][2], bool pref = false) {
;     ...
;     BAR; WAIT_L(0); MMA(1, 0, At, B0); BAR; SCHED;
;     STAGE(SB(1, 1), Bt, HALF, t + 3);
;     WAIT_V(6); BAR; MMA(1, 1, At, B1); BAR;
;   }
;   { LDB(B0, 0, 0); LDA(At, 0, 0); STAGE(SA(1, 1), A, HALF, nt - 1);
;     BAR; WAIT_L(0); MMA(0, 0, At, B0); BAR;
;     LDB(B1, 0, 1); BAR; WAIT_L(0); MMA(0, 1, At, B1); BAR;
	s_waitcnt lgkmcnt(0)
	v_mfma_f32_16x16x32_bf16 v[60:63], v[198:201], v[162:165], v[60:63]
	v_mfma_f32_16x16x32_bf16 v[56:59], v[198:201], v[170:173], v[56:59]
	v_mfma_f32_16x16x32_bf16 v[48:51], v[206:209], v[170:173], v[48:51]
	v_mfma_f32_16x16x32_bf16 v[52:55], v[206:209], v[162:165], v[52:55]
	v_mfma_f32_16x16x32_bf16 v[44:47], v[214:217], v[162:165], v[44:47]
	v_mfma_f32_16x16x32_bf16 v[40:43], v[214:217], v[170:173], v[40:43]
	v_mfma_f32_16x16x32_bf16 v[32:35], v[222:225], v[170:173], v[32:35]
	v_mfma_f32_16x16x32_bf16 v[36:39], v[222:225], v[162:165], v[36:39]
	v_mfma_f32_16x16x32_bf16 v[60:63], v[202:205], v[166:169], v[60:63]
	v_mfma_f32_16x16x32_bf16 v[56:59], v[202:205], v[174:177], v[56:59]
	v_mfma_f32_16x16x32_bf16 v[48:51], v[210:213], v[174:177], v[48:51]
	v_mfma_f32_16x16x32_bf16 v[52:55], v[210:213], v[166:169], v[52:55]
	v_mfma_f32_16x16x32_bf16 v[44:47], v[218:221], v[166:169], v[44:47]
	v_mfma_f32_16x16x32_bf16 v[40:43], v[218:221], v[174:177], v[40:43]
	v_mfma_f32_16x16x32_bf16 v[32:35], v[226:229], v[174:177], v[32:35]
	v_mfma_f32_16x16x32_bf16 v[36:39], v[226:229], v[166:169], v[36:39]
	s_barrier
	v_readfirstlane_b32 s7, v157
	v_add_u32_e32 v164, 0x2000, v157
	v_lshl_add_u64 v[162:163], v[246:247], 0, s[56:57]
	s_mov_b32 m0, s7
	v_readfirstlane_b32 s7, v164
	global_load_lds_dwordx4 v[162:163], off
	v_lshl_add_u64 v[162:163], v[248:249], 0, s[56:57]
	s_mov_b32 m0, s7
	s_nop 0
	global_load_lds_dwordx4 v[162:163], off
	s_waitcnt vmcnt(6)
	s_barrier
	v_mfma_f32_16x16x32_bf16 v[28:31], v[198:201], v[230:233], v[28:31]
	v_mfma_f32_16x16x32_bf16 v[24:27], v[198:201], v[238:241], v[24:27]
	v_mfma_f32_16x16x32_bf16 v[16:19], v[206:209], v[238:241], v[16:19]
	v_mfma_f32_16x16x32_bf16 v[20:23], v[206:209], v[230:233], v[20:23]
	v_mfma_f32_16x16x32_bf16 v[12:15], v[214:217], v[230:233], v[12:15]
	v_mfma_f32_16x16x32_bf16 v[8:11], v[214:217], v[238:241], v[8:11]
	v_mfma_f32_16x16x32_bf16 v[0:3], v[222:225], v[238:241], v[0:3]
	v_mfma_f32_16x16x32_bf16 v[4:7], v[222:225], v[230:233], v[4:7]
	v_mfma_f32_16x16x32_bf16 v[28:31], v[202:205], v[234:237], v[28:31]
	v_mfma_f32_16x16x32_bf16 v[24:27], v[202:205], v[242:245], v[24:27]
	v_mfma_f32_16x16x32_bf16 v[16:19], v[210:213], v[242:245], v[16:19]
	v_mfma_f32_16x16x32_bf16 v[20:23], v[210:213], v[234:237], v[20:23]
	v_mfma_f32_16x16x32_bf16 v[12:15], v[218:221], v[234:237], v[12:15]
	v_mfma_f32_16x16x32_bf16 v[8:11], v[218:221], v[242:245], v[8:11]
	v_mfma_f32_16x16x32_bf16 v[0:3], v[226:229], v[242:245], v[0:3]
	v_mfma_f32_16x16x32_bf16 v[4:7], v[226:229], v[234:237], v[4:7]
	s_add_i32 s6, s6, 2
	v_lshl_add_u64 v[136:137], v[136:137], 0, s[44:45]
	v_lshl_add_u64 v[138:139], v[138:139], 0, s[44:45]
	v_lshl_add_u64 v[140:141], v[140:141], 0, s[44:45]
	s_cmp_lt_u32 s6, 12
	v_lshl_add_u64 v[142:143], v[142:143], 0, s[44:45]
	s_barrier
	s_cbranch_scc1 .LBB0_449
	s_add_u32 s4, s4, 0x40780
	s_addc_u32 s5, s5, 0
	v_lshl_add_u64 v[130:131], s[4:5], 0, v[130:131]
	v_readfirstlane_b32 s6, v160
	v_lshl_add_u64 v[128:129], v[128:129], 1, v[130:131]
	s_mov_b32 m0, s6
	ds_read_b128 v[136:139], v159
	ds_read_b128 v[140:143], v159 offset:1024
	ds_read_b128 v[154:157], v159 offset:2048
	ds_read_b128 v[162:165], v159 offset:3072
	ds_read_b128 v[166:169], v151
	ds_read_b128 v[170:173], v151 offset:1024
	ds_read_b128 v[174:177], v150
	ds_read_b128 v[198:201], v150 offset:1024
	ds_read_b128 v[202:205], v149
	ds_read_b128 v[206:209], v149 offset:1024
	ds_read_b128 v[210:213], v148
	ds_read_b128 v[214:217], v148 offset:1024
	global_load_lds_dwordx4 v[128:129], off
	v_lshl_add_u64 v[128:129], s[4:5], 0, v[134:135]
	v_readfirstlane_b32 s4, v161
	v_lshl_add_u64 v[128:129], v[132:133], 1, v[128:129]
	s_mov_b32 m0, s4
	s_nop 0
	global_load_lds_dwordx4 v[128:129], off
	s_barrier
	s_waitcnt lgkmcnt(0)
	v_mfma_f32_16x16x32_bf16 v[124:127], v[166:169], v[136:139], v[124:127]
	v_mfma_f32_16x16x32_bf16 v[116:119], v[174:177], v[136:139], v[116:119]
	v_mfma_f32_16x16x32_bf16 v[108:111], v[202:205], v[136:139], v[108:111]
	v_mfma_f32_16x16x32_bf16 v[100:103], v[210:213], v[136:139], v[100:103]
	v_mfma_f32_16x16x32_bf16 v[124:127], v[170:173], v[140:143], v[124:127]
	v_mfma_f32_16x16x32_bf16 v[120:123], v[166:169], v[154:157], v[120:123]
	v_mfma_f32_16x16x32_bf16 v[116:119], v[198:201], v[140:143], v[116:119]
	v_mfma_f32_16x16x32_bf16 v[112:115], v[174:177], v[154:157], v[112:115]
	v_mfma_f32_16x16x32_bf16 v[108:111], v[206:209], v[140:143], v[108:111]
	v_mfma_f32_16x16x32_bf16 v[104:107], v[202:205], v[154:157], v[104:107]
	v_mfma_f32_16x16x32_bf16 v[100:103], v[214:217], v[140:143], v[100:103]
	v_mfma_f32_16x16x32_bf16 v[96:99], v[210:213], v[154:157], v[96:99]
	v_mfma_f32_16x16x32_bf16 v[128:131], v[170:173], v[162:165], v[120:123]
	v_mfma_f32_16x16x32_bf16 v[132:135], v[198:201], v[162:165], v[112:115]
	v_mfma_f32_16x16x32_bf16 v[218:221], v[206:209], v[162:165], v[104:107]
	v_mfma_f32_16x16x32_bf16 v[222:225], v[214:217], v[162:165], v[96:99]
	s_barrier
	s_nop 1
	ds_read_b128 v[96:99], v158
	ds_read_b128 v[104:107], v158 offset:1024
	ds_read_b128 v[112:115], v158 offset:2048
	ds_read_b128 v[120:123], v158 offset:3072
	s_barrier
; #define WAIT_V(n) asm volatile("s_waitcnt vmcnt(" #n ")" ::: "memory")
; #define WAIT_L(n) asm volatile("s_waitcnt lgkmcnt(" #n ")" ::: "memory")
; #define BAR __builtin_amdgcn_s_barrier()
; #define LDA(dst, b, h)                                                                            \
;   _Pragma("unroll") for (int m = 0; m < 4; ++m) _Pragma("unroll") for (int k = 0; k < 2; ++k)                                         \
;     dst[m][k] = *reinterpret_cast<const bf16x8*>((char*)SA(b, h) + lds_byte(wr * 64 + m * 16 + fr, k * 32 + fq * 8))
; #define LDB(dst, b, h)                                                                            \
;   _Pragma("unroll") for (int n = 0; n < 2; ++n) _Pragma("unroll") for (int k = 0; k < 2; ++k)                                         \
;     dst[n][k] = *reinterpret_cast<const bf16x8*>((char*)SB(b, h) + lds_byte(wc * 32 + n * 16 + fr, k * 32 + fq * 8))
; template <int K, bool SWAP>
; __device__ __forceinline__ void gemm_kloop(const bf16* __restrict__ A, const bf16* __restrict__ Bt,
;                                            f32x4 (&acc)[2][2][4][2], bool pref = false) {
;     ...
;     LDB(B1, 0, 1); BAR; WAIT_L(0); MMA(0, 1, At, B1); BAR;
;     LDA(At, 0, 1); WAIT_V(4); BAR; WAIT_L(0); MMA(1, 0, At, B0); MMA(1, 1, At, B1); BAR; }
;   { LDB(B0, 1, 0); LDA(At, 1, 0); WAIT_V(2); BAR; WAIT_L(0); MMA(0, 0, At, B0); BAR;
	s_waitcnt lgkmcnt(0)
	v_mfma_f32_16x16x32_bf16 v[92:95], v[166:169], v[96:99], v[92:95]
	v_mfma_f32_16x16x32_bf16 v[84:87], v[174:177], v[96:99], v[84:87]
	v_mfma_f32_16x16x32_bf16 v[76:79], v[202:205], v[96:99], v[76:79]
	v_mfma_f32_16x16x32_bf16 v[68:71], v[210:213], v[96:99], v[68:71]
	v_mfma_f32_16x16x32_bf16 v[92:95], v[170:173], v[104:107], v[92:95]
	v_mfma_f32_16x16x32_bf16 v[88:91], v[166:169], v[112:115], v[88:91]
	v_mfma_f32_16x16x32_bf16 v[84:87], v[198:201], v[104:107], v[84:87]
	v_mfma_f32_16x16x32_bf16 v[80:83], v[174:177], v[112:115], v[80:83]
	v_mfma_f32_16x16x32_bf16 v[76:79], v[206:209], v[104:107], v[76:79]
	v_mfma_f32_16x16x32_bf16 v[72:75], v[202:205], v[112:115], v[72:75]
	v_mfma_f32_16x16x32_bf16 v[68:71], v[214:217], v[104:107], v[68:71]
	v_mfma_f32_16x16x32_bf16 v[64:67], v[210:213], v[112:115], v[64:67]
	v_mfma_f32_16x16x32_bf16 v[158:161], v[170:173], v[120:123], v[88:91]
	v_mfma_f32_16x16x32_bf16 v[166:169], v[198:201], v[120:123], v[80:83]
	v_mfma_f32_16x16x32_bf16 v[170:173], v[206:209], v[120:123], v[72:75]
	v_mfma_f32_16x16x32_bf16 v[174:177], v[214:217], v[120:123], v[64:67]
	s_barrier
	s_nop 1
	ds_read_b128 v[64:67], v151 offset:16384
	ds_read_b128 v[72:75], v151 offset:17408
	ds_read_b128 v[80:83], v150 offset:16384
	ds_read_b128 v[88:91], v150 offset:17408
	ds_read_b128 v[198:201], v149 offset:16384
	ds_read_b128 v[202:205], v149 offset:17408
	ds_read_b128 v[206:209], v148 offset:16384
	ds_read_b128 v[210:213], v148 offset:17408
	s_waitcnt vmcnt(4)
	s_barrier
	s_waitcnt lgkmcnt(0)
	v_mfma_f32_16x16x32_bf16 v[60:63], v[64:67], v[136:139], v[60:63]
	v_mfma_f32_16x16x32_bf16 v[52:55], v[80:83], v[136:139], v[52:55]
	v_mfma_f32_16x16x32_bf16 v[44:47], v[198:201], v[136:139], v[44:47]
	v_mfma_f32_16x16x32_bf16 v[36:39], v[206:209], v[136:139], v[36:39]
	v_mfma_f32_16x16x32_bf16 v[60:63], v[72:75], v[140:143], v[60:63]
	v_mfma_f32_16x16x32_bf16 v[56:59], v[64:67], v[154:157], v[56:59]
	v_mfma_f32_16x16x32_bf16 v[52:55], v[88:91], v[140:143], v[52:55]
	v_mfma_f32_16x16x32_bf16 v[48:51], v[80:83], v[154:157], v[48:51]
	v_mfma_f32_16x16x32_bf16 v[44:47], v[202:205], v[140:143], v[44:47]
	v_mfma_f32_16x16x32_bf16 v[40:43], v[198:201], v[154:157], v[40:43]
	v_mfma_f32_16x16x32_bf16 v[36:39], v[210:213], v[140:143], v[36:39]
	v_mfma_f32_16x16x32_bf16 v[32:35], v[206:209], v[154:157], v[32:35]
	v_mfma_f32_16x16x32_bf16 v[214:217], v[72:75], v[162:165], v[56:59]
	v_mfma_f32_16x16x32_bf16 v[226:229], v[88:91], v[162:165], v[48:51]
	v_mfma_f32_16x16x32_bf16 v[230:233], v[202:205], v[162:165], v[40:43]
	v_mfma_f32_16x16x32_bf16 v[136:139], v[210:213], v[162:165], v[32:35]
	v_mfma_f32_16x16x32_bf16 v[28:31], v[64:67], v[96:99], v[28:31]
	v_mfma_f32_16x16x32_bf16 v[20:23], v[80:83], v[96:99], v[20:23]
	v_mfma_f32_16x16x32_bf16 v[12:15], v[198:201], v[96:99], v[12:15]
	v_mfma_f32_16x16x32_bf16 v[4:7], v[206:209], v[96:99], v[4:7]
	v_mfma_f32_16x16x32_bf16 v[28:31], v[72:75], v[104:107], v[28:31]
	v_mfma_f32_16x16x32_bf16 v[24:27], v[64:67], v[112:115], v[24:27]
	v_mfma_f32_16x16x32_bf16 v[20:23], v[88:91], v[104:107], v[20:23]
	v_mfma_f32_16x16x32_bf16 v[16:19], v[80:83], v[112:115], v[16:19]
	v_mfma_f32_16x16x32_bf16 v[12:15], v[202:205], v[104:107], v[12:15]
	v_mfma_f32_16x16x32_bf16 v[8:11], v[198:201], v[112:115], v[8:11]
	v_mfma_f32_16x16x32_bf16 v[4:7], v[210:213], v[104:107], v[4:7]
	v_mfma_f32_16x16x32_bf16 v[0:3], v[206:209], v[112:115], v[0:3]
	v_mfma_f32_16x16x32_bf16 v[140:143], v[72:75], v[120:123], v[24:27]
	v_mfma_f32_16x16x32_bf16 v[154:157], v[88:91], v[120:123], v[16:19]
	v_mfma_f32_16x16x32_bf16 v[162:165], v[202:205], v[120:123], v[8:11]
	v_mfma_f32_16x16x32_bf16 v[198:201], v[210:213], v[120:123], v[0:3]
	s_barrier
	ds_read_b128 v[202:205], v153
	ds_read_b128 v[206:209], v153 offset:1024
	ds_read_b128 v[210:213], v153 offset:2048
	ds_read_b128 v[234:237], v153 offset:3072
	ds_read_b128 v[0:3], v151 offset:32768
	ds_read_b128 v[8:11], v151 offset:33792
	ds_read_b128 v[16:19], v150 offset:32768
	ds_read_b128 v[24:27], v150 offset:33792
	ds_read_b128 v[238:241], v149 offset:32768
	ds_read_b128 v[242:245], v149 offset:33792
	ds_read_b128 v[246:249], v148 offset:32768
	ds_read_b128 v[250:253], v148 offset:33792
	s_waitcnt vmcnt(2)
	s_barrier
; #define WAIT_V(n) asm volatile("s_waitcnt vmcnt(" #n ")" ::: "memory")
; #define WAIT_L(n) asm volatile("s_waitcnt lgkmcnt(" #n ")" ::: "memory")
; #define BAR __builtin_amdgcn_s_barrier()
; #define LDA(dst, b, h)                                                                            \
;   _Pragma("unroll") for (int m = 0; m < 4; ++m) _Pragma("unroll") for (int k = 0; k < 2; ++k)                                         \
;     dst[m][k] = *reinterpret_cast<const bf16x8*>((char*)SA(b, h) + lds_byte(wr * 64 + m * 16 + fr, k * 32 + fq * 8))
; #define LDB(dst, b, h)                                                                            \
;   _Pragma("unroll") for (int n = 0; n < 2; ++n) _Pragma("unroll") for (int k = 0; k < 2; ++k)                                         \
;     dst[n][k] = *reinterpret_cast<const bf16x8*>((char*)SB(b, h) + lds_byte(wc * 32 + n * 16 + fr, k * 32 + fq * 8))
; template <int K, bool SWAP>
; __device__ __forceinline__ void gemm_kloop(const bf16* __restrict__ A, const bf16* __restrict__ Bt,
;                                            f32x4 (&acc)[2][2][4][2], bool pref = false) {
;     ...
;   { LDB(B0, 1, 0); LDA(At, 1, 0); WAIT_V(2); BAR; WAIT_L(0); MMA(0, 0, At, B0); BAR;
;     LDB(B1, 1, 1); WAIT_V(0); BAR; WAIT_L(0); MMA(0, 1, At, B1); BAR;
;     LDA(At, 1, 1); BAR; WAIT_L(0); MMA(1, 0, At, B0); MMA(1, 1, At, B1); BAR; }
;   if (wr == 0) BAR;
	s_waitcnt lgkmcnt(0)
	v_mfma_f32_16x16x32_bf16 v[32:35], v[0:3], v[202:205], v[124:127]
	v_mfma_f32_16x16x32_bf16 v[120:123], v[8:11], v[206:209], v[32:35]
	v_mfma_f32_16x16x32_bf16 v[32:35], v[0:3], v[210:213], v[128:131]
	v_mfma_f32_16x16x32_bf16 v[112:115], v[8:11], v[234:237], v[32:35]
	v_mfma_f32_16x16x32_bf16 v[32:35], v[16:19], v[202:205], v[116:119]
	v_mfma_f32_16x16x32_bf16 v[104:107], v[24:27], v[206:209], v[32:35]
	v_mfma_f32_16x16x32_bf16 v[32:35], v[16:19], v[210:213], v[132:135]
	v_mfma_f32_16x16x32_bf16 v[96:99], v[24:27], v[234:237], v[32:35]
	v_mfma_f32_16x16x32_bf16 v[32:35], v[238:241], v[202:205], v[108:111]
	v_mfma_f32_16x16x32_bf16 v[88:91], v[242:245], v[206:209], v[32:35]
	v_mfma_f32_16x16x32_bf16 v[32:35], v[238:241], v[210:213], v[218:221]
	v_mfma_f32_16x16x32_bf16 v[80:83], v[242:245], v[234:237], v[32:35]
	v_mfma_f32_16x16x32_bf16 v[32:35], v[246:249], v[202:205], v[100:103]
	v_mfma_f32_16x16x32_bf16 v[72:75], v[250:253], v[206:209], v[32:35]
	v_mfma_f32_16x16x32_bf16 v[32:35], v[246:249], v[210:213], v[222:225]
	v_mfma_f32_16x16x32_bf16 v[64:67], v[250:253], v[234:237], v[32:35]
	s_barrier
	ds_read_b128 v[128:131], v152
	ds_read_b128 v[132:135], v152 offset:1024
	ds_read_b128 v[218:221], v152 offset:2048
	ds_read_b128 v[222:225], v152 offset:3072
	s_waitcnt vmcnt(0)
	s_barrier
	s_waitcnt lgkmcnt(0)
	v_mfma_f32_16x16x32_bf16 v[32:35], v[0:3], v[128:131], v[92:95]
	v_mfma_f32_16x16x32_bf16 v[0:3], v[0:3], v[218:221], v[158:161]
	v_mfma_f32_16x16x32_bf16 v[48:51], v[8:11], v[222:225], v[0:3]
	v_mfma_f32_16x16x32_bf16 v[0:3], v[16:19], v[128:131], v[84:87]
	v_mfma_f32_16x16x32_bf16 v[40:43], v[24:27], v[132:135], v[0:3]
	v_mfma_f32_16x16x32_bf16 v[0:3], v[16:19], v[218:221], v[166:169]
	v_mfma_f32_16x16x32_bf16 v[56:59], v[8:11], v[132:135], v[32:35]
	v_mfma_f32_16x16x32_bf16 v[32:35], v[24:27], v[222:225], v[0:3]
	v_mfma_f32_16x16x32_bf16 v[0:3], v[238:241], v[128:131], v[76:79]
	v_mfma_f32_16x16x32_bf16 v[24:27], v[242:245], v[132:135], v[0:3]
	v_mfma_f32_16x16x32_bf16 v[0:3], v[238:241], v[218:221], v[170:173]
	v_mfma_f32_16x16x32_bf16 v[16:19], v[242:245], v[222:225], v[0:3]
	v_mfma_f32_16x16x32_bf16 v[0:3], v[246:249], v[128:131], v[68:71]
	v_mfma_f32_16x16x32_bf16 v[8:11], v[250:253], v[132:135], v[0:3]
	v_mfma_f32_16x16x32_bf16 v[0:3], v[246:249], v[218:221], v[174:177]
	v_mfma_f32_16x16x32_bf16 v[0:3], v[250:253], v[222:225], v[0:3]
	s_barrier
	ds_read_b128 v[158:161], v151 offset:49152
	ds_read_b128 v[166:169], v151 offset:50176
	ds_read_b128 v[170:173], v150 offset:49152
	ds_read_b128 v[150:153], v150 offset:50176
	ds_read_b128 v[174:177], v149 offset:49152
	ds_read_b128 v[238:241], v149 offset:50176
	ds_read_b128 v[242:245], v148 offset:49152
	ds_read_b128 v[146:149], v148 offset:50176
	s_barrier
	s_waitcnt lgkmcnt(0)
	v_mfma_f32_16x16x32_bf16 v[60:63], v[158:161], v[202:205], v[60:63]
	v_mfma_f32_16x16x32_bf16 v[52:55], v[170:173], v[202:205], v[52:55]
	v_mfma_f32_16x16x32_bf16 v[44:47], v[174:177], v[202:205], v[44:47]
	v_mfma_f32_16x16x32_bf16 v[36:39], v[242:245], v[202:205], v[36:39]
	v_mfma_f32_16x16x32_bf16 v[124:127], v[166:169], v[206:209], v[60:63]
	v_mfma_f32_16x16x32_bf16 v[60:63], v[158:161], v[210:213], v[214:217]
	v_mfma_f32_16x16x32_bf16 v[108:111], v[150:153], v[206:209], v[52:55]
	v_mfma_f32_16x16x32_bf16 v[52:55], v[170:173], v[210:213], v[226:229]
	v_mfma_f32_16x16x32_bf16 v[92:95], v[238:241], v[206:209], v[44:47]
	v_mfma_f32_16x16x32_bf16 v[44:47], v[174:177], v[210:213], v[230:233]
	v_mfma_f32_16x16x32_bf16 v[76:79], v[146:149], v[206:209], v[36:39]
	v_mfma_f32_16x16x32_bf16 v[36:39], v[242:245], v[210:213], v[136:139]
	v_mfma_f32_16x16x32_bf16 v[116:119], v[166:169], v[234:237], v[60:63]
	v_mfma_f32_16x16x32_bf16 v[100:103], v[150:153], v[234:237], v[52:55]
	v_mfma_f32_16x16x32_bf16 v[84:87], v[238:241], v[234:237], v[44:47]
	v_mfma_f32_16x16x32_bf16 v[68:71], v[146:149], v[234:237], v[36:39]
	v_mfma_f32_16x16x32_bf16 v[28:31], v[158:161], v[128:131], v[28:31]
	v_mfma_f32_16x16x32_bf16 v[60:63], v[166:169], v[132:135], v[28:31]
	v_mfma_f32_16x16x32_bf16 v[28:31], v[158:161], v[218:221], v[140:143]
	v_mfma_f32_16x16x32_bf16 v[20:23], v[170:173], v[128:131], v[20:23]
	v_mfma_f32_16x16x32_bf16 v[12:15], v[174:177], v[128:131], v[12:15]
	v_mfma_f32_16x16x32_bf16 v[52:55], v[166:169], v[222:225], v[28:31]
	v_mfma_f32_16x16x32_bf16 v[44:47], v[150:153], v[132:135], v[20:23]
	v_mfma_f32_16x16x32_bf16 v[20:23], v[170:173], v[218:221], v[154:157]
	v_mfma_f32_16x16x32_bf16 v[28:31], v[238:241], v[132:135], v[12:15]
	v_mfma_f32_16x16x32_bf16 v[12:15], v[174:177], v[218:221], v[162:165]
	v_mfma_f32_16x16x32_bf16 v[4:7], v[242:245], v[128:131], v[4:7]
	v_mfma_f32_16x16x32_bf16 v[36:39], v[150:153], v[222:225], v[20:23]
	v_mfma_f32_16x16x32_bf16 v[20:23], v[238:241], v[222:225], v[12:15]
	v_mfma_f32_16x16x32_bf16 v[12:15], v[146:149], v[132:135], v[4:7]
	v_mfma_f32_16x16x32_bf16 v[4:7], v[242:245], v[218:221], v[198:201]
	v_mfma_f32_16x16x32_bf16 v[4:7], v[146:149], v[222:225], v[4:7]
	s_movk_i32 s4, 0x100
	v_cmp_gt_u32_e32 vcc, s4, v144
	s_barrier
	s_and_saveexec_b64 s[4:5], vcc
	s_cbranch_execz .LBB0_452
	s_barrier

; #define WAIT_L(n) asm volatile("s_waitcnt lgkmcnt(" #n ")" ::: "memory")
; #define BAR __builtin_amdgcn_s_barrier()
; #define SCHED __builtin_amdgcn_sched_barrier(0)
; #define LDA(dst, b, h)                                                                            \
;   _Pragma("unroll") for (int m = 0; m < 4; ++m) _Pragma("unroll") for (int k = 0; k < 2; ++k)                                         \
;     dst[m][k] = *reinterpret_cast<const bf16x8*>((char*)SA(b, h) + lds_byte(wr * 64 + m * 16 + fr, k * 32 + fq * 8))
; #define LDB(dst, b, h)                                                                            \
;   _Pragma("unroll") for (int n = 0; n < 2; ++n) _Pragma("unroll") for (int k = 0; k < 2; ++k)                                         \
;     dst[n][k] = *reinterpret_cast<const bf16x8*>((char*)SB(b, h) + lds_byte(wc * 32 + n * 16 + fr, k * 32 + fq * 8))
; template <int K, bool SWAP>
; __device__ __forceinline__ void gemm_kloop(const bf16* __restrict__ A, const bf16* __restrict__ Bt,
;                                            f32x4 (&acc)[2][2][4][2], bool pref = false) {
;     ...
;     LDB(B0, 0, 0); SCHED; LDA(At, 0, 0); STAGE(SA(1, 1), A, HALF, t + 1);
;     WAIT_L(8); BAR; WAIT_L(0); MMA(0, 0, At, B0); BAR; SCHED;
;     LDB(B1, 0, 1); STAGE(SB(0, 0), Bt, 0, t + 2);
;     BAR; WAIT_L(0); MMA(0, 1, At, B1); BAR;
;     LDA(At, 0, 1); STAGE(SA(0, 0), A, 0, t + 2);
;     BAR; WAIT_L(0); MMA(1, 0, At, B0); BAR; SCHED;
.LBB0_514:
	ds_read_b128 v[162:165], v159
	ds_read_b128 v[166:169], v159 offset:1024
	ds_read_b128 v[170:173], v159 offset:2048
	ds_read_b128 v[174:177], v159 offset:3072
	v_add_u32_e32 v160, 0xc000, v146
	v_lshl_add_u64 v[178:179], s[58:59], 0, v[140:141]
	v_readfirstlane_b32 s9, v160
	v_lshl_add_u64 v[188:189], v[178:179], 0, s[42:43]
	s_mov_b32 m0, s9
	v_add_u32_e32 v161, 0xe000, v146
	ds_read_b128 v[198:201], v151
	ds_read_b128 v[202:205], v151 offset:1024
	ds_read_b128 v[206:209], v150
	ds_read_b128 v[210:213], v150 offset:1024
	ds_read_b128 v[214:217], v149
	ds_read_b128 v[218:221], v149 offset:1024
	ds_read_b128 v[222:225], v148
	ds_read_b128 v[226:229], v148 offset:1024
	global_load_lds_dwordx4 v[188:189], off
	v_lshl_add_u64 v[188:189], s[58:59], 0, v[142:143]
	v_readfirstlane_b32 s9, v161
	v_lshl_add_u64 v[230:231], v[188:189], 0, s[42:43]
	s_mov_b32 m0, s9
	s_nop 0
	global_load_lds_dwordx4 v[230:231], off
	s_waitcnt lgkmcnt(8)
	s_barrier
	s_waitcnt lgkmcnt(0)
	v_mfma_f32_16x16x32_bf16 v[124:127], v[162:165], v[198:201], v[124:127]
	v_mfma_f32_16x16x32_bf16 v[120:123], v[170:173], v[198:201], v[120:123]
	v_mfma_f32_16x16x32_bf16 v[112:115], v[170:173], v[206:209], v[112:115]
	v_mfma_f32_16x16x32_bf16 v[116:119], v[162:165], v[206:209], v[116:119]
	v_mfma_f32_16x16x32_bf16 v[108:111], v[162:165], v[214:217], v[108:111]
	v_mfma_f32_16x16x32_bf16 v[104:107], v[170:173], v[214:217], v[104:107]
	v_mfma_f32_16x16x32_bf16 v[96:99], v[170:173], v[222:225], v[96:99]
	v_mfma_f32_16x16x32_bf16 v[100:103], v[162:165], v[222:225], v[100:103]
	v_mfma_f32_16x16x32_bf16 v[124:127], v[166:169], v[202:205], v[124:127]
	v_mfma_f32_16x16x32_bf16 v[120:123], v[174:177], v[202:205], v[120:123]
	v_mfma_f32_16x16x32_bf16 v[112:115], v[174:177], v[210:213], v[112:115]
	v_mfma_f32_16x16x32_bf16 v[116:119], v[166:169], v[210:213], v[116:119]
	v_mfma_f32_16x16x32_bf16 v[108:111], v[166:169], v[218:221], v[108:111]
	v_mfma_f32_16x16x32_bf16 v[104:107], v[174:177], v[218:221], v[104:107]
	v_mfma_f32_16x16x32_bf16 v[96:99], v[174:177], v[226:229], v[96:99]
	v_mfma_f32_16x16x32_bf16 v[100:103], v[166:169], v[226:229], v[100:103]
	s_barrier
	v_add_u32_e32 v186, s7, v145
	v_lshl_add_u64 v[246:247], s[58:59], 0, v[136:137]
	v_readfirstlane_b32 s9, v186
	v_lshl_add_u64 v[248:249], v[246:247], 0, s[44:45]
	s_mov_b32 m0, s9
	v_add_u32_e32 v186, 0x2000, v186
	ds_read_b128 v[230:233], v158
	ds_read_b128 v[234:237], v158 offset:1024
	ds_read_b128 v[238:241], v158 offset:2048
	ds_read_b128 v[242:245], v158 offset:3072
	global_load_lds_dwordx4 v[248:249], off
	v_lshl_add_u64 v[248:249], s[58:59], 0, v[138:139]
	v_readfirstlane_b32 s9, v186
	v_lshl_add_u64 v[250:251], v[248:249], 0, s[44:45]
	s_mov_b32 m0, s9
	s_nop 0
	global_load_lds_dwordx4 v[250:251], off
	s_barrier
	s_waitcnt lgkmcnt(0)
	v_mfma_f32_16x16x32_bf16 v[92:95], v[230:233], v[198:201], v[92:95]
	v_mfma_f32_16x16x32_bf16 v[88:91], v[238:241], v[198:201], v[88:91]
	v_mfma_f32_16x16x32_bf16 v[72:75], v[238:241], v[206:209], v[72:75]
	v_mfma_f32_16x16x32_bf16 v[84:87], v[230:233], v[206:209], v[84:87]
	v_mfma_f32_16x16x32_bf16 v[60:63], v[230:233], v[214:217], v[60:63]
	v_mfma_f32_16x16x32_bf16 v[56:59], v[238:241], v[214:217], v[56:59]
	v_mfma_f32_16x16x32_bf16 v[48:51], v[238:241], v[222:225], v[48:51]
	v_mfma_f32_16x16x32_bf16 v[52:55], v[230:233], v[222:225], v[52:55]
	v_mfma_f32_16x16x32_bf16 v[92:95], v[234:237], v[202:205], v[92:95]
	v_mfma_f32_16x16x32_bf16 v[88:91], v[242:245], v[202:205], v[88:91]
	v_mfma_f32_16x16x32_bf16 v[72:75], v[242:245], v[210:213], v[72:75]
	v_mfma_f32_16x16x32_bf16 v[84:87], v[234:237], v[210:213], v[84:87]
	v_mfma_f32_16x16x32_bf16 v[60:63], v[234:237], v[218:221], v[60:63]
	v_mfma_f32_16x16x32_bf16 v[56:59], v[242:245], v[218:221], v[56:59]
	v_mfma_f32_16x16x32_bf16 v[48:51], v[242:245], v[226:229], v[48:51]
	v_mfma_f32_16x16x32_bf16 v[52:55], v[234:237], v[226:229], v[52:55]
	v_readfirstlane_b32 s9, v146
	v_add_u32_e32 v186, 0x2000, v146
	v_lshl_add_u64 v[250:251], v[178:179], 0, s[46:47]
	s_mov_b32 m0, s9
	v_readfirstlane_b32 s9, v186
	s_barrier
	ds_read_b128 v[198:201], v151 offset:16384
	ds_read_b128 v[202:205], v151 offset:17408
	ds_read_b128 v[206:209], v150 offset:16384
	ds_read_b128 v[210:213], v150 offset:17408
	ds_read_b128 v[214:217], v149 offset:16384
	ds_read_b128 v[218:221], v149 offset:17408
	ds_read_b128 v[222:225], v148 offset:16384
	ds_read_b128 v[226:229], v148 offset:17408
	global_load_lds_dwordx4 v[250:251], off
	v_lshl_add_u64 v[250:251], v[188:189], 0, s[46:47]
	s_mov_b32 m0, s9
	s_nop 0
	global_load_lds_dwordx4 v[250:251], off
	s_barrier
	s_waitcnt lgkmcnt(0)
	v_mfma_f32_16x16x32_bf16 v[44:47], v[162:165], v[198:201], v[44:47]
	v_mfma_f32_16x16x32_bf16 v[40:43], v[170:173], v[198:201], v[40:43]
	v_mfma_f32_16x16x32_bf16 v[32:35], v[170:173], v[206:209], v[32:35]
	v_mfma_f32_16x16x32_bf16 v[36:39], v[162:165], v[206:209], v[36:39]
	v_mfma_f32_16x16x32_bf16 v[28:31], v[162:165], v[214:217], v[28:31]
	v_mfma_f32_16x16x32_bf16 v[24:27], v[170:173], v[214:217], v[24:27]
	v_mfma_f32_16x16x32_bf16 v[16:19], v[170:173], v[222:225], v[16:19]
	v_mfma_f32_16x16x32_bf16 v[20:23], v[162:165], v[222:225], v[20:23]
	v_mfma_f32_16x16x32_bf16 v[44:47], v[166:169], v[202:205], v[44:47]
	v_mfma_f32_16x16x32_bf16 v[40:43], v[174:177], v[202:205], v[40:43]
	v_mfma_f32_16x16x32_bf16 v[32:35], v[174:177], v[210:213], v[32:35]
	v_mfma_f32_16x16x32_bf16 v[36:39], v[166:169], v[210:213], v[36:39]
	v_mfma_f32_16x16x32_bf16 v[28:31], v[166:169], v[218:221], v[28:31]
	v_mfma_f32_16x16x32_bf16 v[24:27], v[174:177], v[218:221], v[24:27]
	v_mfma_f32_16x16x32_bf16 v[16:19], v[174:177], v[226:229], v[16:19]
	v_mfma_f32_16x16x32_bf16 v[20:23], v[166:169], v[226:229], v[20:23]
	s_barrier
; #define WAIT_V(n) asm volatile("s_waitcnt vmcnt(" #n ")" ::: "memory")
; #define WAIT_L(n) asm volatile("s_waitcnt lgkmcnt(" #n ")" ::: "memory")
; #define BAR __builtin_amdgcn_s_barrier()
; #define SCHED __builtin_amdgcn_sched_barrier(0)
; #define LDA(dst, b, h)                                                                            \
;   _Pragma("unroll") for (int m = 0; m < 4; ++m) _Pragma("unroll") for (int k = 0; k < 2; ++k)                                         \
;     dst[m][k] = *reinterpret_cast<const bf16x8*>((char*)SA(b, h) + lds_byte(wr * 64 + m * 16 + fr, k * 32 + fq * 8))
; #define LDB(dst, b, h)                                                                            \
;   _Pragma("unroll") for (int n = 0; n < 2; ++n) _Pragma("unroll") for (int k = 0; k < 2; ++k)                                         \
;     dst[n][k] = *reinterpret_cast<const bf16x8*>((char*)SB(b, h) + lds_byte(wc * 32 + n * 16 + fr, k * 32 + fq * 8))
; template <int K, bool SWAP>
; __device__ __forceinline__ void gemm_kloop(const bf16* __restrict__ A, const bf16* __restrict__ Bt,
;                                            f32x4 (&acc)[2][2][4][2], bool pref = false) {
;     ...
;     STAGE(SB(0, 1), Bt, HALF, t + 2);
;     WAIT_V(6); BAR; MMA(1, 1, At, B1); BAR;
;     LDB(B0, 1, 0); SCHED; LDA(At, 1, 0); STAGE(SA(0, 1), A, HALF, t + 2);
;     WAIT_L(8); BAR; WAIT_L(0); MMA(0, 0, At, B0); BAR; SCHED;
;     LDB(B1, 1, 1); STAGE(SB(1, 0), Bt, 0, t + 3);
;     BAR; WAIT_L(0); MMA(0, 1, At, B1); BAR;
;     LDA(At, 1, 1); STAGE(SA(1, 0), A, 0, t + 3);
	v_readfirstlane_b32 s9, v147
	v_add_u32_e32 v164, 0x2000, v147
	v_lshl_add_u64 v[162:163], v[246:247], 0, s[48:49]
	s_mov_b32 m0, s9
	v_readfirstlane_b32 s9, v164
	global_load_lds_dwordx4 v[162:163], off
	v_lshl_add_u64 v[162:163], v[248:249], 0, s[48:49]
	s_mov_b32 m0, s9
	s_nop 0
	global_load_lds_dwordx4 v[162:163], off
	s_waitcnt vmcnt(6)
	s_barrier
	v_mfma_f32_16x16x32_bf16 v[12:15], v[230:233], v[198:201], v[12:15]
	v_mfma_f32_16x16x32_bf16 v[8:11], v[238:241], v[198:201], v[8:11]
	v_mfma_f32_16x16x32_bf16 v[0:3], v[238:241], v[206:209], v[0:3]
	v_mfma_f32_16x16x32_bf16 v[4:7], v[230:233], v[206:209], v[4:7]
	v_mfma_f32_16x16x32_bf16 v[64:67], v[230:233], v[214:217], v[64:67]
	v_mfma_f32_16x16x32_bf16 v[68:71], v[238:241], v[214:217], v[68:71]
	v_mfma_f32_16x16x32_bf16 v[80:83], v[238:241], v[222:225], v[80:83]
	v_mfma_f32_16x16x32_bf16 v[76:79], v[230:233], v[222:225], v[76:79]
	v_mfma_f32_16x16x32_bf16 v[12:15], v[234:237], v[202:205], v[12:15]
	v_mfma_f32_16x16x32_bf16 v[8:11], v[242:245], v[202:205], v[8:11]
	v_mfma_f32_16x16x32_bf16 v[0:3], v[242:245], v[210:213], v[0:3]
	v_mfma_f32_16x16x32_bf16 v[4:7], v[234:237], v[210:213], v[4:7]
	v_mfma_f32_16x16x32_bf16 v[64:67], v[234:237], v[218:221], v[64:67]
	v_mfma_f32_16x16x32_bf16 v[68:71], v[242:245], v[218:221], v[68:71]
	v_mfma_f32_16x16x32_bf16 v[80:83], v[242:245], v[226:229], v[80:83]
	v_mfma_f32_16x16x32_bf16 v[76:79], v[234:237], v[226:229], v[76:79]
	s_barrier
	ds_read_b128 v[162:165], v153
	ds_read_b128 v[166:169], v153 offset:1024
	ds_read_b128 v[170:173], v153 offset:2048
	ds_read_b128 v[174:177], v153 offset:3072
	v_add_u32_e32 v186, 0x4000, v146
	v_lshl_add_u64 v[230:231], v[178:179], 0, s[50:51]
	v_readfirstlane_b32 s9, v186
	v_add_u32_e32 v186, 0x6000, v146
	s_mov_b32 m0, s9
	v_readfirstlane_b32 s9, v186
	ds_read_b128 v[198:201], v151 offset:32768
	ds_read_b128 v[202:205], v151 offset:33792
	ds_read_b128 v[206:209], v150 offset:32768
	ds_read_b128 v[210:213], v150 offset:33792
	ds_read_b128 v[214:217], v149 offset:32768
	ds_read_b128 v[218:221], v149 offset:33792
	ds_read_b128 v[222:225], v148 offset:32768
	ds_read_b128 v[226:229], v148 offset:33792
	global_load_lds_dwordx4 v[230:231], off
	v_lshl_add_u64 v[230:231], v[188:189], 0, s[50:51]
	s_mov_b32 m0, s9
	s_nop 0
	global_load_lds_dwordx4 v[230:231], off
	s_waitcnt lgkmcnt(8)
	s_barrier
	s_waitcnt lgkmcnt(0)
	v_mfma_f32_16x16x32_bf16 v[124:127], v[162:165], v[198:201], v[124:127]
	v_mfma_f32_16x16x32_bf16 v[120:123], v[170:173], v[198:201], v[120:123]
	v_mfma_f32_16x16x32_bf16 v[112:115], v[170:173], v[206:209], v[112:115]
	v_mfma_f32_16x16x32_bf16 v[116:119], v[162:165], v[206:209], v[116:119]
	v_mfma_f32_16x16x32_bf16 v[108:111], v[162:165], v[214:217], v[108:111]
	v_mfma_f32_16x16x32_bf16 v[104:107], v[170:173], v[214:217], v[104:107]
	v_mfma_f32_16x16x32_bf16 v[96:99], v[170:173], v[222:225], v[96:99]
	v_mfma_f32_16x16x32_bf16 v[100:103], v[162:165], v[222:225], v[100:103]
	v_mfma_f32_16x16x32_bf16 v[124:127], v[166:169], v[202:205], v[124:127]
	v_mfma_f32_16x16x32_bf16 v[120:123], v[174:177], v[202:205], v[120:123]
	v_mfma_f32_16x16x32_bf16 v[112:115], v[174:177], v[210:213], v[112:115]
	v_mfma_f32_16x16x32_bf16 v[116:119], v[166:169], v[210:213], v[116:119]
	v_mfma_f32_16x16x32_bf16 v[108:111], v[166:169], v[218:221], v[108:111]
	v_mfma_f32_16x16x32_bf16 v[104:107], v[174:177], v[218:221], v[104:107]
	v_mfma_f32_16x16x32_bf16 v[96:99], v[174:177], v[226:229], v[96:99]
	v_mfma_f32_16x16x32_bf16 v[100:103], v[166:169], v[226:229], v[100:103]
	s_barrier
	v_readfirstlane_b32 s9, v154
	v_add_u32_e32 v186, 0x2000, v154
	v_lshl_add_u64 v[250:251], v[246:247], 0, s[52:53]
	s_mov_b32 m0, s9
	v_readfirstlane_b32 s9, v186
	ds_read_b128 v[230:233], v152
	ds_read_b128 v[234:237], v152 offset:1024
	ds_read_b128 v[238:241], v152 offset:2048
	ds_read_b128 v[242:245], v152 offset:3072
	global_load_lds_dwordx4 v[250:251], off
	v_lshl_add_u64 v[250:251], v[248:249], 0, s[52:53]
	s_mov_b32 m0, s9
	s_nop 0
	global_load_lds_dwordx4 v[250:251], off
	s_barrier
	s_waitcnt lgkmcnt(0)
	v_mfma_f32_16x16x32_bf16 v[92:95], v[230:233], v[198:201], v[92:95]
	v_mfma_f32_16x16x32_bf16 v[88:91], v[238:241], v[198:201], v[88:91]
	v_mfma_f32_16x16x32_bf16 v[72:75], v[238:241], v[206:209], v[72:75]
	v_mfma_f32_16x16x32_bf16 v[84:87], v[230:233], v[206:209], v[84:87]
	v_mfma_f32_16x16x32_bf16 v[60:63], v[230:233], v[214:217], v[60:63]
	v_mfma_f32_16x16x32_bf16 v[56:59], v[238:241], v[214:217], v[56:59]
	v_mfma_f32_16x16x32_bf16 v[48:51], v[238:241], v[222:225], v[48:51]
	v_mfma_f32_16x16x32_bf16 v[52:55], v[230:233], v[222:225], v[52:55]
	v_mfma_f32_16x16x32_bf16 v[92:95], v[234:237], v[202:205], v[92:95]
	v_mfma_f32_16x16x32_bf16 v[88:91], v[242:245], v[202:205], v[88:91]
	v_mfma_f32_16x16x32_bf16 v[72:75], v[242:245], v[210:213], v[72:75]
	v_mfma_f32_16x16x32_bf16 v[84:87], v[234:237], v[210:213], v[84:87]
	v_mfma_f32_16x16x32_bf16 v[60:63], v[234:237], v[218:221], v[60:63]
	v_mfma_f32_16x16x32_bf16 v[56:59], v[242:245], v[218:221], v[56:59]
	v_mfma_f32_16x16x32_bf16 v[48:51], v[242:245], v[226:229], v[48:51]
	v_mfma_f32_16x16x32_bf16 v[52:55], v[234:237], v[226:229], v[52:55]
	v_readfirstlane_b32 s9, v155
	v_lshl_add_u64 v[178:179], v[178:179], 0, s[54:55]
	s_mov_b32 m0, s9
	v_readfirstlane_b32 s9, v156
	s_barrier
	ds_read_b128 v[198:201], v151 offset:49152
	ds_read_b128 v[202:205], v151 offset:50176
	ds_read_b128 v[206:209], v150 offset:49152
	ds_read_b128 v[210:213], v150 offset:50176
	ds_read_b128 v[214:217], v149 offset:49152
	ds_read_b128 v[218:221], v149 offset:50176
	ds_read_b128 v[222:225], v148 offset:49152
	ds_read_b128 v[226:229], v148 offset:50176
	global_load_lds_dwordx4 v[178:179], off
	v_lshl_add_u64 v[178:179], v[188:189], 0, s[54:55]
	s_mov_b32 m0, s9
	s_nop 0
	global_load_lds_dwordx4 v[178:179], off
	s_barrier
; #define WAIT_V(n) asm volatile("s_waitcnt vmcnt(" #n ")" ::: "memory")
; #define WAIT_L(n) asm volatile("s_waitcnt lgkmcnt(" #n ")" ::: "memory")
; #define BAR __builtin_amdgcn_s_barrier()
; #define SCHED __builtin_amdgcn_sched_barrier(0)
; #define LDA(dst, b, h)                                                                            \
;   _Pragma("unroll") for (int m = 0; m < 4; ++m) _Pragma("unroll") for (int k = 0; k < 2; ++k)                                         \
;     dst[m][k] = *reinterpret_cast<const bf16x8*>((char*)SA(b, h) + lds_byte(wr * 64 + m * 16 + fr, k * 32 + fq * 8))
; #define LDB(dst, b, h)                                                                            \
;   _Pragma("unroll") for (int n = 0; n < 2; ++n) _Pragma("unroll") for (int k = 0; k < 2; ++k)                                         \
;     dst[n][k] = *reinterpret_cast<const bf16x8*>((char*)SB(b, h) + lds_byte(wc * 32 + n * 16 + fr, k * 32 + fq * 8))
; template <int K, bool SWAP>
; __device__ __forceinline__ void gemm_kloop(const bf16* __restrict__ A, const bf16* __restrict__ Bt,
;                                            f32x4 (&acc)[2][2][4][2], bool pref = false) {
;     ...
;     BAR; WAIT_L(0); MMA(1, 0, At, B0); BAR; SCHED;
;     STAGE(SB(1, 1), Bt, HALF, t + 3);
;     WAIT_V(6); BAR; MMA(1, 1, At, B1); BAR;
;   }
;   { LDB(B0, 0, 0); LDA(At, 0, 0); STAGE(SA(1, 1), A, HALF, nt - 1);
;     BAR; WAIT_L(0); MMA(0, 0, At, B0); BAR;
;     LDB(B1, 0, 1); BAR; WAIT_L(0); MMA(0, 1, At, B1); BAR;
	s_waitcnt lgkmcnt(0)
	v_mfma_f32_16x16x32_bf16 v[44:47], v[162:165], v[198:201], v[44:47]
	v_mfma_f32_16x16x32_bf16 v[40:43], v[170:173], v[198:201], v[40:43]
	v_mfma_f32_16x16x32_bf16 v[32:35], v[170:173], v[206:209], v[32:35]
	v_mfma_f32_16x16x32_bf16 v[36:39], v[162:165], v[206:209], v[36:39]
	v_mfma_f32_16x16x32_bf16 v[28:31], v[162:165], v[214:217], v[28:31]
	v_mfma_f32_16x16x32_bf16 v[24:27], v[170:173], v[214:217], v[24:27]
	v_mfma_f32_16x16x32_bf16 v[16:19], v[170:173], v[222:225], v[16:19]
	v_mfma_f32_16x16x32_bf16 v[20:23], v[162:165], v[222:225], v[20:23]
	v_mfma_f32_16x16x32_bf16 v[44:47], v[166:169], v[202:205], v[44:47]
	v_mfma_f32_16x16x32_bf16 v[40:43], v[174:177], v[202:205], v[40:43]
	v_mfma_f32_16x16x32_bf16 v[32:35], v[174:177], v[210:213], v[32:35]
	v_mfma_f32_16x16x32_bf16 v[36:39], v[166:169], v[210:213], v[36:39]
	v_mfma_f32_16x16x32_bf16 v[28:31], v[166:169], v[218:221], v[28:31]
	v_mfma_f32_16x16x32_bf16 v[24:27], v[174:177], v[218:221], v[24:27]
	v_mfma_f32_16x16x32_bf16 v[16:19], v[174:177], v[226:229], v[16:19]
	v_mfma_f32_16x16x32_bf16 v[20:23], v[166:169], v[226:229], v[20:23]
	s_barrier
	v_readfirstlane_b32 s9, v157
	v_add_u32_e32 v164, 0x2000, v157
	v_lshl_add_u64 v[162:163], v[246:247], 0, s[56:57]
	s_mov_b32 m0, s9
	v_readfirstlane_b32 s9, v164
	global_load_lds_dwordx4 v[162:163], off
	v_lshl_add_u64 v[162:163], v[248:249], 0, s[56:57]
	s_mov_b32 m0, s9
	s_nop 0
	global_load_lds_dwordx4 v[162:163], off
	s_waitcnt vmcnt(6)
	s_barrier
	v_mfma_f32_16x16x32_bf16 v[12:15], v[230:233], v[198:201], v[12:15]
	v_mfma_f32_16x16x32_bf16 v[8:11], v[238:241], v[198:201], v[8:11]
	v_mfma_f32_16x16x32_bf16 v[0:3], v[238:241], v[206:209], v[0:3]
	v_mfma_f32_16x16x32_bf16 v[4:7], v[230:233], v[206:209], v[4:7]
	v_mfma_f32_16x16x32_bf16 v[64:67], v[230:233], v[214:217], v[64:67]
	v_mfma_f32_16x16x32_bf16 v[68:71], v[238:241], v[214:217], v[68:71]
	v_mfma_f32_16x16x32_bf16 v[80:83], v[238:241], v[222:225], v[80:83]
	v_mfma_f32_16x16x32_bf16 v[76:79], v[230:233], v[222:225], v[76:79]
	v_mfma_f32_16x16x32_bf16 v[12:15], v[234:237], v[202:205], v[12:15]
	v_mfma_f32_16x16x32_bf16 v[8:11], v[242:245], v[202:205], v[8:11]
	v_mfma_f32_16x16x32_bf16 v[0:3], v[242:245], v[210:213], v[0:3]
	v_mfma_f32_16x16x32_bf16 v[4:7], v[234:237], v[210:213], v[4:7]
	v_mfma_f32_16x16x32_bf16 v[64:67], v[234:237], v[218:221], v[64:67]
	v_mfma_f32_16x16x32_bf16 v[68:71], v[242:245], v[218:221], v[68:71]
	v_mfma_f32_16x16x32_bf16 v[80:83], v[242:245], v[226:229], v[80:83]
	v_mfma_f32_16x16x32_bf16 v[76:79], v[234:237], v[226:229], v[76:79]
	s_add_i32 s8, s8, 2
	v_lshl_add_u64 v[136:137], v[136:137], 0, s[44:45]
	v_lshl_add_u64 v[138:139], v[138:139], 0, s[44:45]
	v_lshl_add_u64 v[140:141], v[140:141], 0, s[44:45]
	s_cmp_lt_u32 s8, 12
	v_lshl_add_u64 v[142:143], v[142:143], 0, s[44:45]
	s_barrier
	s_cbranch_scc1 .LBB0_514
	s_add_u32 s4, s4, 0x40780
	s_addc_u32 s5, s5, 0
	v_lshl_add_u64 v[130:131], s[4:5], 0, v[130:131]
	v_readfirstlane_b32 s8, v160
	v_lshl_add_u64 v[128:129], v[128:129], 1, v[130:131]
	s_mov_b32 m0, s8
	ds_read_b128 v[136:139], v159
	ds_read_b128 v[140:143], v159 offset:1024
	ds_read_b128 v[154:157], v159 offset:2048
	ds_read_b128 v[162:165], v159 offset:3072
	ds_read_b128 v[166:169], v151
	ds_read_b128 v[170:173], v151 offset:1024
	ds_read_b128 v[174:177], v150
	ds_read_b128 v[198:201], v150 offset:1024
	ds_read_b128 v[202:205], v149
	ds_read_b128 v[206:209], v149 offset:1024
	ds_read_b128 v[210:213], v148
	ds_read_b128 v[214:217], v148 offset:1024
	global_load_lds_dwordx4 v[128:129], off
	v_lshl_add_u64 v[128:129], s[4:5], 0, v[134:135]
	v_readfirstlane_b32 s4, v161
	v_lshl_add_u64 v[128:129], v[132:133], 1, v[128:129]
	s_mov_b32 m0, s4
	s_nop 0
	global_load_lds_dwordx4 v[128:129], off
	s_barrier
	s_waitcnt lgkmcnt(0)
	v_mfma_f32_16x16x32_bf16 v[124:127], v[136:139], v[166:169], v[124:127]
	v_mfma_f32_16x16x32_bf16 v[120:123], v[154:157], v[166:169], v[120:123]
	v_mfma_f32_16x16x32_bf16 v[112:115], v[154:157], v[174:177], v[112:115]
	v_mfma_f32_16x16x32_bf16 v[116:119], v[136:139], v[174:177], v[116:119]
	v_mfma_f32_16x16x32_bf16 v[108:111], v[136:139], v[202:205], v[108:111]
	v_mfma_f32_16x16x32_bf16 v[104:107], v[154:157], v[202:205], v[104:107]
	v_mfma_f32_16x16x32_bf16 v[96:99], v[154:157], v[210:213], v[96:99]
	v_mfma_f32_16x16x32_bf16 v[100:103], v[136:139], v[210:213], v[100:103]
	v_mfma_f32_16x16x32_bf16 v[124:127], v[140:143], v[170:173], v[124:127]
	v_mfma_f32_16x16x32_bf16 v[120:123], v[162:165], v[170:173], v[120:123]
	v_mfma_f32_16x16x32_bf16 v[112:115], v[162:165], v[198:201], v[112:115]
	v_mfma_f32_16x16x32_bf16 v[116:119], v[140:143], v[198:201], v[116:119]
	v_mfma_f32_16x16x32_bf16 v[108:111], v[140:143], v[206:209], v[108:111]
	v_mfma_f32_16x16x32_bf16 v[104:107], v[162:165], v[206:209], v[104:107]
	v_mfma_f32_16x16x32_bf16 v[96:99], v[162:165], v[214:217], v[96:99]
	v_mfma_f32_16x16x32_bf16 v[100:103], v[140:143], v[214:217], v[100:103]
	s_barrier
	ds_read_b128 v[128:131], v158
	ds_read_b128 v[132:135], v158 offset:1024
	ds_read_b128 v[218:221], v158 offset:2048
	ds_read_b128 v[158:161], v158 offset:3072
	s_barrier
; #define WAIT_V(n) asm volatile("s_waitcnt vmcnt(" #n ")" ::: "memory")
; #define WAIT_L(n) asm volatile("s_waitcnt lgkmcnt(" #n ")" ::: "memory")
; #define BAR __builtin_amdgcn_s_barrier()
; #define LDA(dst, b, h)                                                                            \
;   _Pragma("unroll") for (int m = 0; m < 4; ++m) _Pragma("unroll") for (int k = 0; k < 2; ++k)                                         \
;     dst[m][k] = *reinterpret_cast<const bf16x8*>((char*)SA(b, h) + lds_byte(wr * 64 + m * 16 + fr, k * 32 + fq * 8))
; #define LDB(dst, b, h)                                                                            \
;   _Pragma("unroll") for (int n = 0; n < 2; ++n) _Pragma("unroll") for (int k = 0; k < 2; ++k)                                         \
;     dst[n][k] = *reinterpret_cast<const bf16x8*>((char*)SB(b, h) + lds_byte(wc * 32 + n * 16 + fr, k * 32 + fq * 8))
; template <int K, bool SWAP>
; __device__ __forceinline__ void gemm_kloop(const bf16* __restrict__ A, const bf16* __restrict__ Bt,
;                                            f32x4 (&acc)[2][2][4][2], bool pref = false) {
;     ...
;     LDB(B1, 0, 1); BAR; WAIT_L(0); MMA(0, 1, At, B1); BAR;
;     LDA(At, 0, 1); WAIT_V(4); BAR; WAIT_L(0); MMA(1, 0, At, B0); MMA(1, 1, At, B1); BAR; }
;   { LDB(B0, 1, 0); LDA(At, 1, 0); WAIT_V(2); BAR; WAIT_L(0); MMA(0, 0, At, B0); BAR;
	s_waitcnt lgkmcnt(0)
	v_mfma_f32_16x16x32_bf16 v[92:95], v[128:131], v[166:169], v[92:95]
	v_mfma_f32_16x16x32_bf16 v[88:91], v[218:221], v[166:169], v[88:91]
	v_mfma_f32_16x16x32_bf16 v[72:75], v[218:221], v[174:177], v[72:75]
	v_mfma_f32_16x16x32_bf16 v[84:87], v[128:131], v[174:177], v[84:87]
	v_mfma_f32_16x16x32_bf16 v[60:63], v[128:131], v[202:205], v[60:63]
	v_mfma_f32_16x16x32_bf16 v[56:59], v[218:221], v[202:205], v[56:59]
	v_mfma_f32_16x16x32_bf16 v[48:51], v[218:221], v[210:213], v[48:51]
	v_mfma_f32_16x16x32_bf16 v[52:55], v[128:131], v[210:213], v[52:55]
	v_mfma_f32_16x16x32_bf16 v[92:95], v[132:135], v[170:173], v[92:95]
	v_mfma_f32_16x16x32_bf16 v[88:91], v[158:161], v[170:173], v[88:91]
	v_mfma_f32_16x16x32_bf16 v[72:75], v[158:161], v[198:201], v[72:75]
	v_mfma_f32_16x16x32_bf16 v[84:87], v[132:135], v[198:201], v[84:87]
	v_mfma_f32_16x16x32_bf16 v[60:63], v[132:135], v[206:209], v[60:63]
	v_mfma_f32_16x16x32_bf16 v[56:59], v[158:161], v[206:209], v[56:59]
	v_mfma_f32_16x16x32_bf16 v[48:51], v[158:161], v[214:217], v[48:51]
	v_mfma_f32_16x16x32_bf16 v[52:55], v[132:135], v[214:217], v[52:55]
	s_barrier
	ds_read_b128 v[166:169], v151 offset:16384
	ds_read_b128 v[170:173], v151 offset:17408
	ds_read_b128 v[174:177], v150 offset:16384
	ds_read_b128 v[198:201], v150 offset:17408
	ds_read_b128 v[202:205], v149 offset:16384
	ds_read_b128 v[206:209], v149 offset:17408
	ds_read_b128 v[210:213], v148 offset:16384
	ds_read_b128 v[214:217], v148 offset:17408
	s_waitcnt vmcnt(4)
	s_barrier
	s_waitcnt lgkmcnt(0)
	v_mfma_f32_16x16x32_bf16 v[44:47], v[136:139], v[166:169], v[44:47]
	v_mfma_f32_16x16x32_bf16 v[40:43], v[154:157], v[166:169], v[40:43]
	v_mfma_f32_16x16x32_bf16 v[32:35], v[154:157], v[174:177], v[32:35]
	v_mfma_f32_16x16x32_bf16 v[36:39], v[136:139], v[174:177], v[36:39]
	v_mfma_f32_16x16x32_bf16 v[28:31], v[136:139], v[202:205], v[28:31]
	v_mfma_f32_16x16x32_bf16 v[24:27], v[154:157], v[202:205], v[24:27]
	v_mfma_f32_16x16x32_bf16 v[16:19], v[154:157], v[210:213], v[16:19]
	v_mfma_f32_16x16x32_bf16 v[20:23], v[136:139], v[210:213], v[20:23]
	v_mfma_f32_16x16x32_bf16 v[44:47], v[140:143], v[170:173], v[44:47]
	v_mfma_f32_16x16x32_bf16 v[40:43], v[162:165], v[170:173], v[40:43]
	v_mfma_f32_16x16x32_bf16 v[32:35], v[162:165], v[198:201], v[32:35]
	v_mfma_f32_16x16x32_bf16 v[36:39], v[140:143], v[198:201], v[36:39]
	v_mfma_f32_16x16x32_bf16 v[28:31], v[140:143], v[206:209], v[28:31]
	v_mfma_f32_16x16x32_bf16 v[24:27], v[162:165], v[206:209], v[24:27]
	v_mfma_f32_16x16x32_bf16 v[16:19], v[162:165], v[214:217], v[16:19]
	v_mfma_f32_16x16x32_bf16 v[20:23], v[140:143], v[214:217], v[20:23]
	v_mfma_f32_16x16x32_bf16 v[64:67], v[128:131], v[202:205], v[64:67]
	v_mfma_f32_16x16x32_bf16 v[136:139], v[132:135], v[206:209], v[64:67]
	v_mfma_f32_16x16x32_bf16 v[64:67], v[218:221], v[202:205], v[68:71]
	v_mfma_f32_16x16x32_bf16 v[12:15], v[128:131], v[166:169], v[12:15]
	v_mfma_f32_16x16x32_bf16 v[8:11], v[218:221], v[166:169], v[8:11]
	v_mfma_f32_16x16x32_bf16 v[4:7], v[128:131], v[174:177], v[4:7]
	v_mfma_f32_16x16x32_bf16 v[0:3], v[218:221], v[174:177], v[0:3]
	v_mfma_f32_16x16x32_bf16 v[140:143], v[158:161], v[206:209], v[64:67]
	v_mfma_f32_16x16x32_bf16 v[64:67], v[128:131], v[210:213], v[76:79]
	v_mfma_f32_16x16x32_bf16 v[12:15], v[132:135], v[170:173], v[12:15]
	v_mfma_f32_16x16x32_bf16 v[8:11], v[158:161], v[170:173], v[8:11]
	v_mfma_f32_16x16x32_bf16 v[4:7], v[132:135], v[198:201], v[4:7]
	v_mfma_f32_16x16x32_bf16 v[0:3], v[158:161], v[198:201], v[0:3]
	v_mfma_f32_16x16x32_bf16 v[128:131], v[132:135], v[214:217], v[64:67]
	v_mfma_f32_16x16x32_bf16 v[64:67], v[218:221], v[210:213], v[80:83]
	v_mfma_f32_16x16x32_bf16 v[132:135], v[158:161], v[214:217], v[64:67]
	s_barrier
	ds_read_b128 v[154:157], v153
	ds_read_b128 v[158:161], v153 offset:1024
	ds_read_b128 v[162:165], v153 offset:2048
	ds_read_b128 v[166:169], v153 offset:3072
	s_nop 0
	ds_read_b128 v[64:67], v151 offset:32768
	ds_read_b128 v[68:71], v151 offset:33792
	ds_read_b128 v[76:79], v150 offset:32768
	ds_read_b128 v[80:83], v150 offset:33792
	ds_read_b128 v[170:173], v149 offset:32768
	ds_read_b128 v[174:177], v149 offset:33792
	ds_read_b128 v[198:201], v148 offset:32768
	ds_read_b128 v[202:205], v148 offset:33792
	s_waitcnt vmcnt(2)
	s_barrier
; #define WAIT_V(n) asm volatile("s_waitcnt vmcnt(" #n ")" ::: "memory")
; #define WAIT_L(n) asm volatile("s_waitcnt lgkmcnt(" #n ")" ::: "memory")
; #define BAR __builtin_amdgcn_s_barrier()
; #define LDA(dst, b, h)                                                                            \
;   _Pragma("unroll") for (int m = 0; m < 4; ++m) _Pragma("unroll") for (int k = 0; k < 2; ++k)                                         \
;     dst[m][k] = *reinterpret_cast<const bf16x8*>((char*)SA(b, h) + lds_byte(wr * 64 + m * 16 + fr, k * 32 + fq * 8))
; #define LDB(dst, b, h)                                                                            \
;   _Pragma("unroll") for (int n = 0; n < 2; ++n) _Pragma("unroll") for (int k = 0; k < 2; ++k)                                         \
;     dst[n][k] = *reinterpret_cast<const bf16x8*>((char*)SB(b, h) + lds_byte(wc * 32 + n * 16 + fr, k * 32 + fq * 8))
; template <int K, bool SWAP>
; __device__ __forceinline__ void gemm_kloop(const bf16* __restrict__ A, const bf16* __restrict__ Bt,
;                                            f32x4 (&acc)[2][2][4][2], bool pref = false) {
;     ...
;   { LDB(B0, 1, 0); LDA(At, 1, 0); WAIT_V(2); BAR; WAIT_L(0); MMA(0, 0, At, B0); BAR;
;     LDB(B1, 1, 1); WAIT_V(0); BAR; WAIT_L(0); MMA(0, 1, At, B1); BAR;
;     LDA(At, 1, 1); BAR; WAIT_L(0); MMA(1, 0, At, B0); MMA(1, 1, At, B1); BAR; }
;   if (wr == 0) BAR;
	s_waitcnt lgkmcnt(0)
	v_mfma_f32_16x16x32_bf16 v[124:127], v[154:157], v[64:67], v[124:127]
	v_mfma_f32_16x16x32_bf16 v[120:123], v[162:165], v[64:67], v[120:123]
	v_mfma_f32_16x16x32_bf16 v[112:115], v[162:165], v[76:79], v[112:115]
	v_mfma_f32_16x16x32_bf16 v[116:119], v[154:157], v[76:79], v[116:119]
	v_mfma_f32_16x16x32_bf16 v[108:111], v[154:157], v[170:173], v[108:111]
	v_mfma_f32_16x16x32_bf16 v[104:107], v[162:165], v[170:173], v[104:107]
	v_mfma_f32_16x16x32_bf16 v[96:99], v[162:165], v[198:201], v[96:99]
	v_mfma_f32_16x16x32_bf16 v[100:103], v[154:157], v[198:201], v[100:103]
	v_mfma_f32_16x16x32_bf16 v[124:127], v[158:161], v[68:71], v[124:127]
	v_mfma_f32_16x16x32_bf16 v[120:123], v[166:169], v[68:71], v[120:123]
	v_mfma_f32_16x16x32_bf16 v[112:115], v[166:169], v[80:83], v[112:115]
	v_mfma_f32_16x16x32_bf16 v[116:119], v[158:161], v[80:83], v[116:119]
	v_mfma_f32_16x16x32_bf16 v[108:111], v[158:161], v[174:177], v[108:111]
	v_mfma_f32_16x16x32_bf16 v[104:107], v[166:169], v[174:177], v[104:107]
	v_mfma_f32_16x16x32_bf16 v[96:99], v[166:169], v[202:205], v[96:99]
	v_mfma_f32_16x16x32_bf16 v[100:103], v[158:161], v[202:205], v[100:103]
	s_barrier
	ds_read_b128 v[206:209], v152
	ds_read_b128 v[210:213], v152 offset:1024
	ds_read_b128 v[214:217], v152 offset:2048
	ds_read_b128 v[218:221], v152 offset:3072
	s_waitcnt vmcnt(0)
	s_barrier
	s_waitcnt lgkmcnt(0)
	v_mfma_f32_16x16x32_bf16 v[92:95], v[206:209], v[64:67], v[92:95]
	v_mfma_f32_16x16x32_bf16 v[64:67], v[214:217], v[64:67], v[88:91]
	v_mfma_f32_16x16x32_bf16 v[88:91], v[218:221], v[68:71], v[64:67]
	v_mfma_f32_16x16x32_bf16 v[64:67], v[206:209], v[76:79], v[84:87]
	v_mfma_f32_16x16x32_bf16 v[84:87], v[210:213], v[80:83], v[64:67]
	v_mfma_f32_16x16x32_bf16 v[64:67], v[214:217], v[76:79], v[72:75]
	v_mfma_f32_16x16x32_bf16 v[60:63], v[206:209], v[170:173], v[60:63]
	v_mfma_f32_16x16x32_bf16 v[56:59], v[214:217], v[170:173], v[56:59]
	v_mfma_f32_16x16x32_bf16 v[52:55], v[206:209], v[198:201], v[52:55]
	v_mfma_f32_16x16x32_bf16 v[48:51], v[214:217], v[198:201], v[48:51]
	v_mfma_f32_16x16x32_bf16 v[92:95], v[210:213], v[68:71], v[92:95]
	v_mfma_f32_16x16x32_bf16 v[80:83], v[218:221], v[80:83], v[64:67]
	v_mfma_f32_16x16x32_bf16 v[76:79], v[210:213], v[174:177], v[60:63]
	v_mfma_f32_16x16x32_bf16 v[72:75], v[218:221], v[174:177], v[56:59]
	v_mfma_f32_16x16x32_bf16 v[68:71], v[210:213], v[202:205], v[52:55]
	v_mfma_f32_16x16x32_bf16 v[64:67], v[218:221], v[202:205], v[48:51]
	s_barrier
	ds_read_b128 v[170:173], v151 offset:49152
	ds_read_b128 v[174:177], v151 offset:50176
	ds_read_b128 v[198:201], v150 offset:49152
	ds_read_b128 v[150:153], v150 offset:50176
	ds_read_b128 v[202:205], v149 offset:49152
	ds_read_b128 v[222:225], v149 offset:50176
	ds_read_b128 v[226:229], v148 offset:49152
	ds_read_b128 v[146:149], v148 offset:50176
	s_barrier
	s_waitcnt lgkmcnt(0)
	v_mfma_f32_16x16x32_bf16 v[44:47], v[154:157], v[170:173], v[44:47]
	v_mfma_f32_16x16x32_bf16 v[40:43], v[162:165], v[170:173], v[40:43]
	v_mfma_f32_16x16x32_bf16 v[36:39], v[154:157], v[198:201], v[36:39]
	v_mfma_f32_16x16x32_bf16 v[32:35], v[162:165], v[198:201], v[32:35]
	v_mfma_f32_16x16x32_bf16 v[28:31], v[154:157], v[202:205], v[28:31]
	v_mfma_f32_16x16x32_bf16 v[24:27], v[162:165], v[202:205], v[24:27]
	v_mfma_f32_16x16x32_bf16 v[20:23], v[154:157], v[226:229], v[20:23]
	v_mfma_f32_16x16x32_bf16 v[16:19], v[162:165], v[226:229], v[16:19]
	v_mfma_f32_16x16x32_bf16 v[60:63], v[158:161], v[174:177], v[44:47]
	v_mfma_f32_16x16x32_bf16 v[56:59], v[166:169], v[174:177], v[40:43]
	v_mfma_f32_16x16x32_bf16 v[52:55], v[158:161], v[150:153], v[36:39]
	v_mfma_f32_16x16x32_bf16 v[48:51], v[166:169], v[150:153], v[32:35]
	v_mfma_f32_16x16x32_bf16 v[44:47], v[158:161], v[222:225], v[28:31]
	v_mfma_f32_16x16x32_bf16 v[40:43], v[166:169], v[222:225], v[24:27]
	v_mfma_f32_16x16x32_bf16 v[36:39], v[158:161], v[146:149], v[20:23]
	v_mfma_f32_16x16x32_bf16 v[32:35], v[166:169], v[146:149], v[16:19]
	v_mfma_f32_16x16x32_bf16 v[0:3], v[214:217], v[198:201], v[0:3]
	v_mfma_f32_16x16x32_bf16 v[12:15], v[206:209], v[170:173], v[12:15]
	v_mfma_f32_16x16x32_bf16 v[16:19], v[218:221], v[150:153], v[0:3]
	v_mfma_f32_16x16x32_bf16 v[0:3], v[206:209], v[202:205], v[136:139]
	v_mfma_f32_16x16x32_bf16 v[28:31], v[210:213], v[174:177], v[12:15]
	v_mfma_f32_16x16x32_bf16 v[8:11], v[214:217], v[170:173], v[8:11]
	v_mfma_f32_16x16x32_bf16 v[12:15], v[210:213], v[222:225], v[0:3]
	v_mfma_f32_16x16x32_bf16 v[0:3], v[214:217], v[202:205], v[140:143]
	v_mfma_f32_16x16x32_bf16 v[24:27], v[218:221], v[174:177], v[8:11]
	v_mfma_f32_16x16x32_bf16 v[4:7], v[206:209], v[198:201], v[4:7]
	v_mfma_f32_16x16x32_bf16 v[8:11], v[218:221], v[222:225], v[0:3]
	v_mfma_f32_16x16x32_bf16 v[0:3], v[206:209], v[226:229], v[128:131]
	v_mfma_f32_16x16x32_bf16 v[20:23], v[210:213], v[150:153], v[4:7]
	v_mfma_f32_16x16x32_bf16 v[4:7], v[210:213], v[146:149], v[0:3]
	v_mfma_f32_16x16x32_bf16 v[0:3], v[214:217], v[226:229], v[132:135]
	v_mfma_f32_16x16x32_bf16 v[0:3], v[218:221], v[146:149], v[0:3]
	s_movk_i32 s4, 0x100
	v_cmp_gt_u32_e32 vcc, s4, v144
	s_barrier
	s_and_saveexec_b64 s[4:5], vcc
	s_cbranch_execz .LBB0_517
	s_barrier

; #define WAIT_L(n) asm volatile("s_waitcnt lgkmcnt(" #n ")" ::: "memory")
; #define BAR __builtin_amdgcn_s_barrier()
; #define SCHED __builtin_amdgcn_sched_barrier(0)
; #define LDA(dst, b, h)                                                                            \
;   _Pragma("unroll") for (int m = 0; m < 4; ++m) _Pragma("unroll") for (int k = 0; k < 2; ++k)                                         \
;     dst[m][k] = *reinterpret_cast<const bf16x8*>((char*)SA(b, h) + lds_byte(wr * 64 + m * 16 + fr, k * 32 + fq * 8))
; #define LDB(dst, b, h)                                                                            \
;   _Pragma("unroll") for (int n = 0; n < 2; ++n) _Pragma("unroll") for (int k = 0; k < 2; ++k)                                         \
;     dst[n][k] = *reinterpret_cast<const bf16x8*>((char*)SB(b, h) + lds_byte(wc * 32 + n * 16 + fr, k * 32 + fq * 8))
; template <int K, bool SWAP>
; __device__ __forceinline__ void gemm_kloop(const bf16* __restrict__ A, const bf16* __restrict__ Bt,
;                                            f32x4 (&acc)[2][2][4][2], bool pref = false) {
;     ...
;     LDB(B0, 0, 0); SCHED; LDA(At, 0, 0); STAGE(SA(1, 1), A, HALF, t + 1);
;     WAIT_L(8); BAR; WAIT_L(0); MMA(0, 0, At, B0); BAR; SCHED;
;     LDB(B1, 0, 1); STAGE(SB(0, 0), Bt, 0, t + 2);
;     BAR; WAIT_L(0); MMA(0, 1, At, B1); BAR;
;     LDA(At, 0, 1); STAGE(SA(0, 0), A, 0, t + 2);
;     BAR; WAIT_L(0); MMA(1, 0, At, B0); BAR; SCHED;
.LBB0_527:
	ds_read_b128 v[162:165], v159
	ds_read_b128 v[166:169], v159 offset:1024
	ds_read_b128 v[170:173], v159 offset:2048
	ds_read_b128 v[174:177], v159 offset:3072
	v_add_u32_e32 v160, 0xc000, v146
	v_lshl_add_u64 v[178:179], s[58:59], 0, v[140:141]
	v_readfirstlane_b32 s9, v160
	v_lshl_add_u64 v[188:189], v[178:179], 0, s[42:43]
	s_mov_b32 m0, s9
	v_add_u32_e32 v161, 0xe000, v146
	ds_read_b128 v[198:201], v151
	ds_read_b128 v[202:205], v151 offset:1024
	ds_read_b128 v[206:209], v150
	ds_read_b128 v[210:213], v150 offset:1024
	ds_read_b128 v[214:217], v149
	ds_read_b128 v[218:221], v149 offset:1024
	ds_read_b128 v[222:225], v148
	ds_read_b128 v[226:229], v148 offset:1024
	global_load_lds_dwordx4 v[188:189], off
	v_lshl_add_u64 v[188:189], s[58:59], 0, v[142:143]
	v_readfirstlane_b32 s9, v161
	v_lshl_add_u64 v[230:231], v[188:189], 0, s[42:43]
	s_mov_b32 m0, s9
	s_nop 0
	global_load_lds_dwordx4 v[230:231], off
	s_waitcnt lgkmcnt(8)
	s_barrier
	s_waitcnt lgkmcnt(0)
	v_mfma_f32_16x16x32_bf16 v[124:127], v[162:165], v[198:201], v[124:127]
	v_mfma_f32_16x16x32_bf16 v[120:123], v[170:173], v[198:201], v[120:123]
	v_mfma_f32_16x16x32_bf16 v[112:115], v[170:173], v[206:209], v[112:115]
	v_mfma_f32_16x16x32_bf16 v[116:119], v[162:165], v[206:209], v[116:119]
	v_mfma_f32_16x16x32_bf16 v[108:111], v[162:165], v[214:217], v[108:111]
	v_mfma_f32_16x16x32_bf16 v[104:107], v[170:173], v[214:217], v[104:107]
	v_mfma_f32_16x16x32_bf16 v[96:99], v[170:173], v[222:225], v[96:99]
	v_mfma_f32_16x16x32_bf16 v[100:103], v[162:165], v[222:225], v[100:103]
	v_mfma_f32_16x16x32_bf16 v[124:127], v[166:169], v[202:205], v[124:127]
	v_mfma_f32_16x16x32_bf16 v[120:123], v[174:177], v[202:205], v[120:123]
	v_mfma_f32_16x16x32_bf16 v[112:115], v[174:177], v[210:213], v[112:115]
	v_mfma_f32_16x16x32_bf16 v[116:119], v[166:169], v[210:213], v[116:119]
	v_mfma_f32_16x16x32_bf16 v[108:111], v[166:169], v[218:221], v[108:111]
	v_mfma_f32_16x16x32_bf16 v[104:107], v[174:177], v[218:221], v[104:107]
	v_mfma_f32_16x16x32_bf16 v[96:99], v[174:177], v[226:229], v[96:99]
	v_mfma_f32_16x16x32_bf16 v[100:103], v[166:169], v[226:229], v[100:103]
	s_barrier
	v_add_u32_e32 v186, s7, v145
	v_lshl_add_u64 v[246:247], s[58:59], 0, v[136:137]
	v_readfirstlane_b32 s9, v186
	v_lshl_add_u64 v[248:249], v[246:247], 0, s[44:45]
	s_mov_b32 m0, s9
	v_add_u32_e32 v186, 0x2000, v186
	ds_read_b128 v[230:233], v158
	ds_read_b128 v[234:237], v158 offset:1024
	ds_read_b128 v[238:241], v158 offset:2048
	ds_read_b128 v[242:245], v158 offset:3072
	global_load_lds_dwordx4 v[248:249], off
	v_lshl_add_u64 v[248:249], s[58:59], 0, v[138:139]
	v_readfirstlane_b32 s9, v186
	v_lshl_add_u64 v[250:251], v[248:249], 0, s[44:45]
	s_mov_b32 m0, s9
	s_nop 0
	global_load_lds_dwordx4 v[250:251], off
	s_barrier
	s_waitcnt lgkmcnt(0)
	v_mfma_f32_16x16x32_bf16 v[92:95], v[230:233], v[198:201], v[92:95]
	v_mfma_f32_16x16x32_bf16 v[88:91], v[238:241], v[198:201], v[88:91]
	v_mfma_f32_16x16x32_bf16 v[80:83], v[238:241], v[206:209], v[80:83]
	v_mfma_f32_16x16x32_bf16 v[84:87], v[230:233], v[206:209], v[84:87]
	v_mfma_f32_16x16x32_bf16 v[76:79], v[230:233], v[214:217], v[76:79]
	v_mfma_f32_16x16x32_bf16 v[72:75], v[238:241], v[214:217], v[72:75]
	v_mfma_f32_16x16x32_bf16 v[64:67], v[238:241], v[222:225], v[64:67]
	v_mfma_f32_16x16x32_bf16 v[68:71], v[230:233], v[222:225], v[68:71]
	v_mfma_f32_16x16x32_bf16 v[92:95], v[234:237], v[202:205], v[92:95]
	v_mfma_f32_16x16x32_bf16 v[88:91], v[242:245], v[202:205], v[88:91]
	v_mfma_f32_16x16x32_bf16 v[80:83], v[242:245], v[210:213], v[80:83]
	v_mfma_f32_16x16x32_bf16 v[84:87], v[234:237], v[210:213], v[84:87]
	v_mfma_f32_16x16x32_bf16 v[76:79], v[234:237], v[218:221], v[76:79]
	v_mfma_f32_16x16x32_bf16 v[72:75], v[242:245], v[218:221], v[72:75]
	v_mfma_f32_16x16x32_bf16 v[64:67], v[242:245], v[226:229], v[64:67]
	v_mfma_f32_16x16x32_bf16 v[68:71], v[234:237], v[226:229], v[68:71]
	v_readfirstlane_b32 s9, v146
	v_add_u32_e32 v186, 0x2000, v146
	v_lshl_add_u64 v[250:251], v[178:179], 0, s[46:47]
	s_mov_b32 m0, s9
	v_readfirstlane_b32 s9, v186
	s_barrier
	ds_read_b128 v[198:201], v151 offset:16384
	ds_read_b128 v[202:205], v151 offset:17408
	ds_read_b128 v[206:209], v150 offset:16384
	ds_read_b128 v[210:213], v150 offset:17408
	ds_read_b128 v[214:217], v149 offset:16384
	ds_read_b128 v[218:221], v149 offset:17408
	ds_read_b128 v[222:225], v148 offset:16384
	ds_read_b128 v[226:229], v148 offset:17408
	global_load_lds_dwordx4 v[250:251], off
	v_lshl_add_u64 v[250:251], v[188:189], 0, s[46:47]
	s_mov_b32 m0, s9
	s_nop 0
	global_load_lds_dwordx4 v[250:251], off
	s_barrier
	s_waitcnt lgkmcnt(0)
	v_mfma_f32_16x16x32_bf16 v[60:63], v[162:165], v[198:201], v[60:63]
	v_mfma_f32_16x16x32_bf16 v[56:59], v[170:173], v[198:201], v[56:59]
	v_mfma_f32_16x16x32_bf16 v[48:51], v[170:173], v[206:209], v[48:51]
	v_mfma_f32_16x16x32_bf16 v[52:55], v[162:165], v[206:209], v[52:55]
	v_mfma_f32_16x16x32_bf16 v[44:47], v[162:165], v[214:217], v[44:47]
	v_mfma_f32_16x16x32_bf16 v[40:43], v[170:173], v[214:217], v[40:43]
	v_mfma_f32_16x16x32_bf16 v[32:35], v[170:173], v[222:225], v[32:35]
	v_mfma_f32_16x16x32_bf16 v[36:39], v[162:165], v[222:225], v[36:39]
	v_mfma_f32_16x16x32_bf16 v[60:63], v[166:169], v[202:205], v[60:63]
	v_mfma_f32_16x16x32_bf16 v[56:59], v[174:177], v[202:205], v[56:59]
	v_mfma_f32_16x16x32_bf16 v[48:51], v[174:177], v[210:213], v[48:51]
	v_mfma_f32_16x16x32_bf16 v[52:55], v[166:169], v[210:213], v[52:55]
	v_mfma_f32_16x16x32_bf16 v[44:47], v[166:169], v[218:221], v[44:47]
	v_mfma_f32_16x16x32_bf16 v[40:43], v[174:177], v[218:221], v[40:43]
	v_mfma_f32_16x16x32_bf16 v[32:35], v[174:177], v[226:229], v[32:35]
	v_mfma_f32_16x16x32_bf16 v[36:39], v[166:169], v[226:229], v[36:39]
	s_barrier
; #define WAIT_V(n) asm volatile("s_waitcnt vmcnt(" #n ")" ::: "memory")
; #define WAIT_L(n) asm volatile("s_waitcnt lgkmcnt(" #n ")" ::: "memory")
; #define BAR __builtin_amdgcn_s_barrier()
; #define SCHED __builtin_amdgcn_sched_barrier(0)
; #define LDA(dst, b, h)                                                                            \
;   _Pragma("unroll") for (int m = 0; m < 4; ++m) _Pragma("unroll") for (int k = 0; k < 2; ++k)                                         \
;     dst[m][k] = *reinterpret_cast<const bf16x8*>((char*)SA(b, h) + lds_byte(wr * 64 + m * 16 + fr, k * 32 + fq * 8))
; #define LDB(dst, b, h)                                                                            \
;   _Pragma("unroll") for (int n = 0; n < 2; ++n) _Pragma("unroll") for (int k = 0; k < 2; ++k)                                         \
;     dst[n][k] = *reinterpret_cast<const bf16x8*>((char*)SB(b, h) + lds_byte(wc * 32 + n * 16 + fr, k * 32 + fq * 8))
; template <int K, bool SWAP>
; __device__ __forceinline__ void gemm_kloop(const bf16* __restrict__ A, const bf16* __restrict__ Bt,
;                                            f32x4 (&acc)[2][2][4][2], bool pref = false) {
;     ...
;     STAGE(SB(0, 1), Bt, HALF, t + 2);
;     WAIT_V(6); BAR; MMA(1, 1, At, B1); BAR;
;     LDB(B0, 1, 0); SCHED; LDA(At, 1, 0); STAGE(SA(0, 1), A, HALF, t + 2);
;     WAIT_L(8); BAR; WAIT_L(0); MMA(0, 0, At, B0); BAR; SCHED;
;     LDB(B1, 1, 1); STAGE(SB(1, 0), Bt, 0, t + 3);
;     BAR; WAIT_L(0); MMA(0, 1, At, B1); BAR;
;     LDA(At, 1, 1); STAGE(SA(1, 0), A, 0, t + 3);
	v_readfirstlane_b32 s9, v147
	v_add_u32_e32 v164, 0x2000, v147
	v_lshl_add_u64 v[162:163], v[246:247], 0, s[48:49]
	s_mov_b32 m0, s9
	v_readfirstlane_b32 s9, v164
	global_load_lds_dwordx4 v[162:163], off
	v_lshl_add_u64 v[162:163], v[248:249], 0, s[48:49]
	s_mov_b32 m0, s9
	s_nop 0
	global_load_lds_dwordx4 v[162:163], off
	s_waitcnt vmcnt(6)
	s_barrier
	v_mfma_f32_16x16x32_bf16 v[28:31], v[230:233], v[198:201], v[28:31]
	v_mfma_f32_16x16x32_bf16 v[24:27], v[238:241], v[198:201], v[24:27]
	v_mfma_f32_16x16x32_bf16 v[16:19], v[238:241], v[206:209], v[16:19]
	v_mfma_f32_16x16x32_bf16 v[20:23], v[230:233], v[206:209], v[20:23]
	v_mfma_f32_16x16x32_bf16 v[12:15], v[230:233], v[214:217], v[12:15]
	v_mfma_f32_16x16x32_bf16 v[8:11], v[238:241], v[214:217], v[8:11]
	v_mfma_f32_16x16x32_bf16 v[0:3], v[238:241], v[222:225], v[0:3]
	v_mfma_f32_16x16x32_bf16 v[4:7], v[230:233], v[222:225], v[4:7]
	v_mfma_f32_16x16x32_bf16 v[28:31], v[234:237], v[202:205], v[28:31]
	v_mfma_f32_16x16x32_bf16 v[24:27], v[242:245], v[202:205], v[24:27]
	v_mfma_f32_16x16x32_bf16 v[16:19], v[242:245], v[210:213], v[16:19]
	v_mfma_f32_16x16x32_bf16 v[20:23], v[234:237], v[210:213], v[20:23]
	v_mfma_f32_16x16x32_bf16 v[12:15], v[234:237], v[218:221], v[12:15]
	v_mfma_f32_16x16x32_bf16 v[8:11], v[242:245], v[218:221], v[8:11]
	v_mfma_f32_16x16x32_bf16 v[0:3], v[242:245], v[226:229], v[0:3]
	v_mfma_f32_16x16x32_bf16 v[4:7], v[234:237], v[226:229], v[4:7]
	s_barrier
	ds_read_b128 v[162:165], v153
	ds_read_b128 v[166:169], v153 offset:1024
	ds_read_b128 v[170:173], v153 offset:2048
	ds_read_b128 v[174:177], v153 offset:3072
	v_add_u32_e32 v186, 0x4000, v146
	v_lshl_add_u64 v[230:231], v[178:179], 0, s[50:51]
	v_readfirstlane_b32 s9, v186
	v_add_u32_e32 v186, 0x6000, v146
	s_mov_b32 m0, s9
	v_readfirstlane_b32 s9, v186
	ds_read_b128 v[198:201], v151 offset:32768
	ds_read_b128 v[202:205], v151 offset:33792
	ds_read_b128 v[206:209], v150 offset:32768
	ds_read_b128 v[210:213], v150 offset:33792
	ds_read_b128 v[214:217], v149 offset:32768
	ds_read_b128 v[218:221], v149 offset:33792
	ds_read_b128 v[222:225], v148 offset:32768
	ds_read_b128 v[226:229], v148 offset:33792
	global_load_lds_dwordx4 v[230:231], off
	v_lshl_add_u64 v[230:231], v[188:189], 0, s[50:51]
	s_mov_b32 m0, s9
	s_nop 0
	global_load_lds_dwordx4 v[230:231], off
	s_waitcnt lgkmcnt(8)
	s_barrier
	s_waitcnt lgkmcnt(0)
	v_mfma_f32_16x16x32_bf16 v[124:127], v[162:165], v[198:201], v[124:127]
	v_mfma_f32_16x16x32_bf16 v[120:123], v[170:173], v[198:201], v[120:123]
	v_mfma_f32_16x16x32_bf16 v[112:115], v[170:173], v[206:209], v[112:115]
	v_mfma_f32_16x16x32_bf16 v[116:119], v[162:165], v[206:209], v[116:119]
	v_mfma_f32_16x16x32_bf16 v[108:111], v[162:165], v[214:217], v[108:111]
	v_mfma_f32_16x16x32_bf16 v[104:107], v[170:173], v[214:217], v[104:107]
	v_mfma_f32_16x16x32_bf16 v[96:99], v[170:173], v[222:225], v[96:99]
	v_mfma_f32_16x16x32_bf16 v[100:103], v[162:165], v[222:225], v[100:103]
	v_mfma_f32_16x16x32_bf16 v[124:127], v[166:169], v[202:205], v[124:127]
	v_mfma_f32_16x16x32_bf16 v[120:123], v[174:177], v[202:205], v[120:123]
	v_mfma_f32_16x16x32_bf16 v[112:115], v[174:177], v[210:213], v[112:115]
	v_mfma_f32_16x16x32_bf16 v[116:119], v[166:169], v[210:213], v[116:119]
	v_mfma_f32_16x16x32_bf16 v[108:111], v[166:169], v[218:221], v[108:111]
	v_mfma_f32_16x16x32_bf16 v[104:107], v[174:177], v[218:221], v[104:107]
	v_mfma_f32_16x16x32_bf16 v[96:99], v[174:177], v[226:229], v[96:99]
	v_mfma_f32_16x16x32_bf16 v[100:103], v[166:169], v[226:229], v[100:103]
	s_barrier
	v_readfirstlane_b32 s9, v154
	v_add_u32_e32 v186, 0x2000, v154
	v_lshl_add_u64 v[250:251], v[246:247], 0, s[52:53]
	s_mov_b32 m0, s9
	v_readfirstlane_b32 s9, v186
	ds_read_b128 v[230:233], v152
	ds_read_b128 v[234:237], v152 offset:1024
	ds_read_b128 v[238:241], v152 offset:2048
	ds_read_b128 v[242:245], v152 offset:3072
	global_load_lds_dwordx4 v[250:251], off
	v_lshl_add_u64 v[250:251], v[248:249], 0, s[52:53]
	s_mov_b32 m0, s9
	s_nop 0
	global_load_lds_dwordx4 v[250:251], off
	s_barrier
	s_waitcnt lgkmcnt(0)
	v_mfma_f32_16x16x32_bf16 v[92:95], v[230:233], v[198:201], v[92:95]
	v_mfma_f32_16x16x32_bf16 v[88:91], v[238:241], v[198:201], v[88:91]
	v_mfma_f32_16x16x32_bf16 v[80:83], v[238:241], v[206:209], v[80:83]
	v_mfma_f32_16x16x32_bf16 v[84:87], v[230:233], v[206:209], v[84:87]
	v_mfma_f32_16x16x32_bf16 v[76:79], v[230:233], v[214:217], v[76:79]
	v_mfma_f32_16x16x32_bf16 v[72:75], v[238:241], v[214:217], v[72:75]
	v_mfma_f32_16x16x32_bf16 v[64:67], v[238:241], v[222:225], v[64:67]
	v_mfma_f32_16x16x32_bf16 v[68:71], v[230:233], v[222:225], v[68:71]
	v_mfma_f32_16x16x32_bf16 v[92:95], v[234:237], v[202:205], v[92:95]
	v_mfma_f32_16x16x32_bf16 v[88:91], v[242:245], v[202:205], v[88:91]
	v_mfma_f32_16x16x32_bf16 v[80:83], v[242:245], v[210:213], v[80:83]
	v_mfma_f32_16x16x32_bf16 v[84:87], v[234:237], v[210:213], v[84:87]
	v_mfma_f32_16x16x32_bf16 v[76:79], v[234:237], v[218:221], v[76:79]
	v_mfma_f32_16x16x32_bf16 v[72:75], v[242:245], v[218:221], v[72:75]
	v_mfma_f32_16x16x32_bf16 v[64:67], v[242:245], v[226:229], v[64:67]
	v_mfma_f32_16x16x32_bf16 v[68:71], v[234:237], v[226:229], v[68:71]
	v_readfirstlane_b32 s9, v155
	v_lshl_add_u64 v[178:179], v[178:179], 0, s[54:55]
	s_mov_b32 m0, s9
	v_readfirstlane_b32 s9, v156
	s_barrier
	ds_read_b128 v[198:201], v151 offset:49152
	ds_read_b128 v[202:205], v151 offset:50176
	ds_read_b128 v[206:209], v150 offset:49152
	ds_read_b128 v[210:213], v150 offset:50176
	ds_read_b128 v[214:217], v149 offset:49152
	ds_read_b128 v[218:221], v149 offset:50176
	ds_read_b128 v[222:225], v148 offset:49152
	ds_read_b128 v[226:229], v148 offset:50176
	global_load_lds_dwordx4 v[178:179], off
	v_lshl_add_u64 v[178:179], v[188:189], 0, s[54:55]
	s_mov_b32 m0, s9
	s_nop 0
	global_load_lds_dwordx4 v[178:179], off
	s_barrier
; #define WAIT_V(n) asm volatile("s_waitcnt vmcnt(" #n ")" ::: "memory")
; #define WAIT_L(n) asm volatile("s_waitcnt lgkmcnt(" #n ")" ::: "memory")
; #define BAR __builtin_amdgcn_s_barrier()
; #define SCHED __builtin_amdgcn_sched_barrier(0)
; #define LDA(dst, b, h)                                                                            \
;   _Pragma("unroll") for (int m = 0; m < 4; ++m) _Pragma("unroll") for (int k = 0; k < 2; ++k)                                         \
;     dst[m][k] = *reinterpret_cast<const bf16x8*>((char*)SA(b, h) + lds_byte(wr * 64 + m * 16 + fr, k * 32 + fq * 8))
; #define LDB(dst, b, h)                                                                            \
;   _Pragma("unroll") for (int n = 0; n < 2; ++n) _Pragma("unroll") for (int k = 0; k < 2; ++k)                                         \
;     dst[n][k] = *reinterpret_cast<const bf16x8*>((char*)SB(b, h) + lds_byte(wc * 32 + n * 16 + fr, k * 32 + fq * 8))
; template <int K, bool SWAP>
; __device__ __forceinline__ void gemm_kloop(const bf16* __restrict__ A, const bf16* __restrict__ Bt,
;                                            f32x4 (&acc)[2][2][4][2], bool pref = false) {
;     ...
;     BAR; WAIT_L(0); MMA(1, 0, At, B0); BAR; SCHED;
;     STAGE(SB(1, 1), Bt, HALF, t + 3);
;     WAIT_V(6); BAR; MMA(1, 1, At, B1); BAR;
;   }
;   { LDB(B0, 0, 0); LDA(At, 0, 0); STAGE(SA(1, 1), A, HALF, nt - 1);
;     BAR; WAIT_L(0); MMA(0, 0, At, B0); BAR;
;     LDB(B1, 0, 1); BAR; WAIT_L(0); MMA(0, 1, At, B1); BAR;
	s_waitcnt lgkmcnt(0)
	v_mfma_f32_16x16x32_bf16 v[60:63], v[162:165], v[198:201], v[60:63]
	v_mfma_f32_16x16x32_bf16 v[56:59], v[170:173], v[198:201], v[56:59]
	v_mfma_f32_16x16x32_bf16 v[48:51], v[170:173], v[206:209], v[48:51]
	v_mfma_f32_16x16x32_bf16 v[52:55], v[162:165], v[206:209], v[52:55]
	v_mfma_f32_16x16x32_bf16 v[44:47], v[162:165], v[214:217], v[44:47]
	v_mfma_f32_16x16x32_bf16 v[40:43], v[170:173], v[214:217], v[40:43]
	v_mfma_f32_16x16x32_bf16 v[32:35], v[170:173], v[222:225], v[32:35]
	v_mfma_f32_16x16x32_bf16 v[36:39], v[162:165], v[222:225], v[36:39]
	v_mfma_f32_16x16x32_bf16 v[60:63], v[166:169], v[202:205], v[60:63]
	v_mfma_f32_16x16x32_bf16 v[56:59], v[174:177], v[202:205], v[56:59]
	v_mfma_f32_16x16x32_bf16 v[48:51], v[174:177], v[210:213], v[48:51]
	v_mfma_f32_16x16x32_bf16 v[52:55], v[166:169], v[210:213], v[52:55]
	v_mfma_f32_16x16x32_bf16 v[44:47], v[166:169], v[218:221], v[44:47]
	v_mfma_f32_16x16x32_bf16 v[40:43], v[174:177], v[218:221], v[40:43]
	v_mfma_f32_16x16x32_bf16 v[32:35], v[174:177], v[226:229], v[32:35]
	v_mfma_f32_16x16x32_bf16 v[36:39], v[166:169], v[226:229], v[36:39]
	s_barrier
	v_readfirstlane_b32 s9, v157
	v_add_u32_e32 v164, 0x2000, v157
	v_lshl_add_u64 v[162:163], v[246:247], 0, s[56:57]
	s_mov_b32 m0, s9
	v_readfirstlane_b32 s9, v164
	global_load_lds_dwordx4 v[162:163], off
	v_lshl_add_u64 v[162:163], v[248:249], 0, s[56:57]
	s_mov_b32 m0, s9
	s_nop 0
	global_load_lds_dwordx4 v[162:163], off
	s_waitcnt vmcnt(6)
	s_barrier
	v_mfma_f32_16x16x32_bf16 v[28:31], v[230:233], v[198:201], v[28:31]
	v_mfma_f32_16x16x32_bf16 v[24:27], v[238:241], v[198:201], v[24:27]
	v_mfma_f32_16x16x32_bf16 v[16:19], v[238:241], v[206:209], v[16:19]
	v_mfma_f32_16x16x32_bf16 v[20:23], v[230:233], v[206:209], v[20:23]
	v_mfma_f32_16x16x32_bf16 v[12:15], v[230:233], v[214:217], v[12:15]
	v_mfma_f32_16x16x32_bf16 v[8:11], v[238:241], v[214:217], v[8:11]
	v_mfma_f32_16x16x32_bf16 v[0:3], v[238:241], v[222:225], v[0:3]
	v_mfma_f32_16x16x32_bf16 v[4:7], v[230:233], v[222:225], v[4:7]
	v_mfma_f32_16x16x32_bf16 v[28:31], v[234:237], v[202:205], v[28:31]
	v_mfma_f32_16x16x32_bf16 v[24:27], v[242:245], v[202:205], v[24:27]
	v_mfma_f32_16x16x32_bf16 v[16:19], v[242:245], v[210:213], v[16:19]
	v_mfma_f32_16x16x32_bf16 v[20:23], v[234:237], v[210:213], v[20:23]
	v_mfma_f32_16x16x32_bf16 v[12:15], v[234:237], v[218:221], v[12:15]
	v_mfma_f32_16x16x32_bf16 v[8:11], v[242:245], v[218:221], v[8:11]
	v_mfma_f32_16x16x32_bf16 v[0:3], v[242:245], v[226:229], v[0:3]
	v_mfma_f32_16x16x32_bf16 v[4:7], v[234:237], v[226:229], v[4:7]
	s_add_i32 s8, s8, 2
	v_lshl_add_u64 v[136:137], v[136:137], 0, s[44:45]
	v_lshl_add_u64 v[138:139], v[138:139], 0, s[44:45]
	v_lshl_add_u64 v[140:141], v[140:141], 0, s[44:45]
	s_cmp_lt_u32 s8, 12
	v_lshl_add_u64 v[142:143], v[142:143], 0, s[44:45]
	s_barrier
	s_cbranch_scc1 .LBB0_527
	s_add_u32 s0, s0, 0x40780
	s_addc_u32 s1, s1, 0
	v_lshl_add_u64 v[130:131], s[0:1], 0, v[130:131]
	v_readfirstlane_b32 s8, v160
	v_lshl_add_u64 v[128:129], v[128:129], 1, v[130:131]
	s_mov_b32 m0, s8
	ds_read_b128 v[136:139], v159
	ds_read_b128 v[140:143], v159 offset:1024
	ds_read_b128 v[154:157], v159 offset:2048
	ds_read_b128 v[162:165], v159 offset:3072
	ds_read_b128 v[166:169], v151
	ds_read_b128 v[170:173], v151 offset:1024
	ds_read_b128 v[174:177], v150
	ds_read_b128 v[198:201], v150 offset:1024
	ds_read_b128 v[202:205], v149
	ds_read_b128 v[206:209], v149 offset:1024
	ds_read_b128 v[210:213], v148
	ds_read_b128 v[214:217], v148 offset:1024
	global_load_lds_dwordx4 v[128:129], off
	v_lshl_add_u64 v[128:129], s[0:1], 0, v[134:135]
	v_readfirstlane_b32 s0, v161
	v_lshl_add_u64 v[128:129], v[132:133], 1, v[128:129]
	s_mov_b32 m0, s0
	s_nop 0
	global_load_lds_dwordx4 v[128:129], off
	s_barrier
	s_waitcnt lgkmcnt(0)
	v_mfma_f32_16x16x32_bf16 v[124:127], v[136:139], v[166:169], v[124:127]
	v_mfma_f32_16x16x32_bf16 v[120:123], v[154:157], v[166:169], v[120:123]
	v_mfma_f32_16x16x32_bf16 v[112:115], v[154:157], v[174:177], v[112:115]
	v_mfma_f32_16x16x32_bf16 v[116:119], v[136:139], v[174:177], v[116:119]
	v_mfma_f32_16x16x32_bf16 v[108:111], v[136:139], v[202:205], v[108:111]
	v_mfma_f32_16x16x32_bf16 v[104:107], v[154:157], v[202:205], v[104:107]
	v_mfma_f32_16x16x32_bf16 v[96:99], v[154:157], v[210:213], v[96:99]
	v_mfma_f32_16x16x32_bf16 v[100:103], v[136:139], v[210:213], v[100:103]
	v_mfma_f32_16x16x32_bf16 v[124:127], v[140:143], v[170:173], v[124:127]
	v_mfma_f32_16x16x32_bf16 v[120:123], v[162:165], v[170:173], v[120:123]
	v_mfma_f32_16x16x32_bf16 v[112:115], v[162:165], v[198:201], v[112:115]
	v_mfma_f32_16x16x32_bf16 v[116:119], v[140:143], v[198:201], v[116:119]
	v_mfma_f32_16x16x32_bf16 v[108:111], v[140:143], v[206:209], v[108:111]
	v_mfma_f32_16x16x32_bf16 v[104:107], v[162:165], v[206:209], v[104:107]
	v_mfma_f32_16x16x32_bf16 v[96:99], v[162:165], v[214:217], v[96:99]
	v_mfma_f32_16x16x32_bf16 v[100:103], v[140:143], v[214:217], v[100:103]
	s_barrier
	ds_read_b128 v[128:131], v158
	ds_read_b128 v[132:135], v158 offset:1024
	ds_read_b128 v[218:221], v158 offset:2048
	ds_read_b128 v[158:161], v158 offset:3072
	s_barrier
; #define WAIT_V(n) asm volatile("s_waitcnt vmcnt(" #n ")" ::: "memory")
; #define WAIT_L(n) asm volatile("s_waitcnt lgkmcnt(" #n ")" ::: "memory")
; #define BAR __builtin_amdgcn_s_barrier()
; #define LDA(dst, b, h)                                                                            \
;   _Pragma("unroll") for (int m = 0; m < 4; ++m) _Pragma("unroll") for (int k = 0; k < 2; ++k)                                         \
;     dst[m][k] = *reinterpret_cast<const bf16x8*>((char*)SA(b, h) + lds_byte(wr * 64 + m * 16 + fr, k * 32 + fq * 8))
; #define LDB(dst, b, h)                                                                            \
;   _Pragma("unroll") for (int n = 0; n < 2; ++n) _Pragma("unroll") for (int k = 0; k < 2; ++k)                                         \
;     dst[n][k] = *reinterpret_cast<const bf16x8*>((char*)SB(b, h) + lds_byte(wc * 32 + n * 16 + fr, k * 32 + fq * 8))
; template <int K, bool SWAP>
; __device__ __forceinline__ void gemm_kloop(const bf16* __restrict__ A, const bf16* __restrict__ Bt,
;                                            f32x4 (&acc)[2][2][4][2], bool pref = false) {
;     ...
;     LDB(B1, 0, 1); BAR; WAIT_L(0); MMA(0, 1, At, B1); BAR;
;     LDA(At, 0, 1); WAIT_V(4); BAR; WAIT_L(0); MMA(1, 0, At, B0); MMA(1, 1, At, B1); BAR; }
;   { LDB(B0, 1, 0); LDA(At, 1, 0); WAIT_V(2); BAR; WAIT_L(0); MMA(0, 0, At, B0); BAR;
	s_waitcnt lgkmcnt(0)
	v_mfma_f32_16x16x32_bf16 v[92:95], v[128:131], v[166:169], v[92:95]
	v_mfma_f32_16x16x32_bf16 v[88:91], v[218:221], v[166:169], v[88:91]
	v_mfma_f32_16x16x32_bf16 v[80:83], v[218:221], v[174:177], v[80:83]
	v_mfma_f32_16x16x32_bf16 v[76:79], v[128:131], v[202:205], v[76:79]
	v_mfma_f32_16x16x32_bf16 v[92:95], v[132:135], v[170:173], v[92:95]
	v_mfma_f32_16x16x32_bf16 v[88:91], v[158:161], v[170:173], v[88:91]
	v_mfma_f32_16x16x32_bf16 v[84:87], v[128:131], v[174:177], v[84:87]
	v_mfma_f32_16x16x32_bf16 v[80:83], v[158:161], v[198:201], v[80:83]
	v_mfma_f32_16x16x32_bf16 v[76:79], v[132:135], v[206:209], v[76:79]
	v_mfma_f32_16x16x32_bf16 v[72:75], v[218:221], v[202:205], v[72:75]
	v_mfma_f32_16x16x32_bf16 v[68:71], v[128:131], v[210:213], v[68:71]
	v_mfma_f32_16x16x32_bf16 v[64:67], v[218:221], v[210:213], v[64:67]
	v_mfma_f32_16x16x32_bf16 v[166:169], v[132:135], v[198:201], v[84:87]
	v_mfma_f32_16x16x32_bf16 v[170:173], v[158:161], v[206:209], v[72:75]
	v_mfma_f32_16x16x32_bf16 v[174:177], v[132:135], v[214:217], v[68:71]
	v_mfma_f32_16x16x32_bf16 v[198:201], v[158:161], v[214:217], v[64:67]
	s_barrier
	s_nop 1
	ds_read_b128 v[64:67], v151 offset:16384
	ds_read_b128 v[68:71], v151 offset:17408
	ds_read_b128 v[72:75], v150 offset:16384
	ds_read_b128 v[84:87], v150 offset:17408
	ds_read_b128 v[202:205], v149 offset:16384
	ds_read_b128 v[206:209], v149 offset:17408
	ds_read_b128 v[210:213], v148 offset:16384
	ds_read_b128 v[214:217], v148 offset:17408
	s_waitcnt vmcnt(4)
	s_barrier
	s_waitcnt lgkmcnt(0)
	v_mfma_f32_16x16x32_bf16 v[60:63], v[136:139], v[64:67], v[60:63]
	v_mfma_f32_16x16x32_bf16 v[52:55], v[136:139], v[72:75], v[52:55]
	v_mfma_f32_16x16x32_bf16 v[40:43], v[154:157], v[202:205], v[40:43]
	v_mfma_f32_16x16x32_bf16 v[60:63], v[140:143], v[68:71], v[60:63]
	v_mfma_f32_16x16x32_bf16 v[56:59], v[154:157], v[64:67], v[56:59]
	v_mfma_f32_16x16x32_bf16 v[52:55], v[140:143], v[84:87], v[52:55]
	v_mfma_f32_16x16x32_bf16 v[48:51], v[154:157], v[72:75], v[48:51]
	v_mfma_f32_16x16x32_bf16 v[44:47], v[136:139], v[202:205], v[44:47]
	v_mfma_f32_16x16x32_bf16 v[40:43], v[162:165], v[206:209], v[40:43]
	v_mfma_f32_16x16x32_bf16 v[36:39], v[136:139], v[210:213], v[36:39]
	v_mfma_f32_16x16x32_bf16 v[32:35], v[154:157], v[210:213], v[32:35]
	v_mfma_f32_16x16x32_bf16 v[222:225], v[162:165], v[68:71], v[56:59]
	v_mfma_f32_16x16x32_bf16 v[226:229], v[162:165], v[84:87], v[48:51]
	v_mfma_f32_16x16x32_bf16 v[230:233], v[140:143], v[206:209], v[44:47]
	v_mfma_f32_16x16x32_bf16 v[136:139], v[140:143], v[214:217], v[36:39]
	v_mfma_f32_16x16x32_bf16 v[140:143], v[162:165], v[214:217], v[32:35]
	v_mfma_f32_16x16x32_bf16 v[20:23], v[128:131], v[72:75], v[20:23]
	v_mfma_f32_16x16x32_bf16 v[0:3], v[218:221], v[210:213], v[0:3]
	v_mfma_f32_16x16x32_bf16 v[28:31], v[128:131], v[64:67], v[28:31]
	v_mfma_f32_16x16x32_bf16 v[24:27], v[218:221], v[64:67], v[24:27]
	v_mfma_f32_16x16x32_bf16 v[20:23], v[132:135], v[84:87], v[20:23]
	v_mfma_f32_16x16x32_bf16 v[16:19], v[218:221], v[72:75], v[16:19]
	v_mfma_f32_16x16x32_bf16 v[12:15], v[128:131], v[202:205], v[12:15]
	v_mfma_f32_16x16x32_bf16 v[8:11], v[218:221], v[202:205], v[8:11]
	v_mfma_f32_16x16x32_bf16 v[4:7], v[128:131], v[210:213], v[4:7]
	v_mfma_f32_16x16x32_bf16 v[0:3], v[158:161], v[214:217], v[0:3]
	v_mfma_f32_16x16x32_bf16 v[154:157], v[132:135], v[68:71], v[28:31]
	v_mfma_f32_16x16x32_bf16 v[162:165], v[158:161], v[68:71], v[24:27]
	v_mfma_f32_16x16x32_bf16 v[234:237], v[158:161], v[84:87], v[16:19]
	v_mfma_f32_16x16x32_bf16 v[238:241], v[132:135], v[206:209], v[12:15]
	v_mfma_f32_16x16x32_bf16 v[202:205], v[158:161], v[206:209], v[8:11]
	v_mfma_f32_16x16x32_bf16 v[128:131], v[132:135], v[214:217], v[4:7]
	s_barrier
	s_nop 0
	ds_read_b128 v[4:7], v153
	ds_read_b128 v[8:11], v153 offset:1024
	ds_read_b128 v[12:15], v153 offset:2048
	ds_read_b128 v[16:19], v153 offset:3072
	ds_read_b128 v[24:27], v151 offset:32768
	ds_read_b128 v[28:31], v151 offset:33792
	ds_read_b128 v[32:35], v150 offset:32768
	ds_read_b128 v[36:39], v150 offset:33792
	ds_read_b128 v[44:47], v149 offset:32768
	ds_read_b128 v[132:135], v149 offset:33792
	ds_read_b128 v[158:161], v148 offset:32768
	ds_read_b128 v[206:209], v148 offset:33792
	s_waitcnt vmcnt(2)
	s_barrier
; #define WAIT_V(n) asm volatile("s_waitcnt vmcnt(" #n ")" ::: "memory")
; #define WAIT_L(n) asm volatile("s_waitcnt lgkmcnt(" #n ")" ::: "memory")
; #define BAR __builtin_amdgcn_s_barrier()
; #define LDA(dst, b, h)                                                                            \
;   _Pragma("unroll") for (int m = 0; m < 4; ++m) _Pragma("unroll") for (int k = 0; k < 2; ++k)                                         \
;     dst[m][k] = *reinterpret_cast<const bf16x8*>((char*)SA(b, h) + lds_byte(wr * 64 + m * 16 + fr, k * 32 + fq * 8))
; #define LDB(dst, b, h)                                                                            \
;   _Pragma("unroll") for (int n = 0; n < 2; ++n) _Pragma("unroll") for (int k = 0; k < 2; ++k)                                         \
;     dst[n][k] = *reinterpret_cast<const bf16x8*>((char*)SB(b, h) + lds_byte(wc * 32 + n * 16 + fr, k * 32 + fq * 8))
; template <int K, bool SWAP>
; __device__ __forceinline__ void gemm_kloop(const bf16* __restrict__ A, const bf16* __restrict__ Bt,
;                                            f32x4 (&acc)[2][2][4][2], bool pref = false) {
;     ...
;   { LDB(B0, 1, 0); LDA(At, 1, 0); WAIT_V(2); BAR; WAIT_L(0); MMA(0, 0, At, B0); BAR;
;     LDB(B1, 1, 1); WAIT_V(0); BAR; WAIT_L(0); MMA(0, 1, At, B1); BAR;
;     LDA(At, 1, 1); BAR; WAIT_L(0); MMA(1, 0, At, B0); MMA(1, 1, At, B1); BAR; }
;   if (wr == 0) BAR;
	s_waitcnt lgkmcnt(0)
	v_mfma_f32_16x16x32_bf16 v[48:51], v[4:7], v[24:27], v[124:127]
	v_mfma_f32_16x16x32_bf16 v[124:127], v[8:11], v[28:31], v[48:51]
	v_mfma_f32_16x16x32_bf16 v[48:51], v[12:15], v[24:27], v[120:123]
	v_mfma_f32_16x16x32_bf16 v[84:87], v[16:19], v[28:31], v[48:51]
	v_mfma_f32_16x16x32_bf16 v[48:51], v[4:7], v[32:35], v[116:119]
	v_mfma_f32_16x16x32_bf16 v[120:123], v[8:11], v[36:39], v[48:51]
	v_mfma_f32_16x16x32_bf16 v[48:51], v[12:15], v[32:35], v[112:115]
	v_mfma_f32_16x16x32_bf16 v[72:75], v[16:19], v[36:39], v[48:51]
	v_mfma_f32_16x16x32_bf16 v[48:51], v[4:7], v[44:47], v[108:111]
	v_mfma_f32_16x16x32_bf16 v[112:115], v[8:11], v[132:135], v[48:51]
	v_mfma_f32_16x16x32_bf16 v[48:51], v[12:15], v[44:47], v[104:107]
	v_mfma_f32_16x16x32_bf16 v[68:71], v[16:19], v[132:135], v[48:51]
	v_mfma_f32_16x16x32_bf16 v[48:51], v[4:7], v[158:161], v[100:103]
	v_mfma_f32_16x16x32_bf16 v[104:107], v[8:11], v[206:209], v[48:51]
	v_mfma_f32_16x16x32_bf16 v[48:51], v[12:15], v[158:161], v[96:99]
	v_mfma_f32_16x16x32_bf16 v[64:67], v[16:19], v[206:209], v[48:51]
	s_barrier
	ds_read_b128 v[210:213], v152
	ds_read_b128 v[214:217], v152 offset:1024
	ds_read_b128 v[218:221], v152 offset:2048
	ds_read_b128 v[242:245], v152 offset:3072
	s_waitcnt vmcnt(0)
	s_barrier
	s_waitcnt lgkmcnt(0)
	v_mfma_f32_16x16x32_bf16 v[48:51], v[210:213], v[24:27], v[92:95]
	v_mfma_f32_16x16x32_bf16 v[24:27], v[218:221], v[24:27], v[88:91]
	v_mfma_f32_16x16x32_bf16 v[56:59], v[242:245], v[28:31], v[24:27]
	v_mfma_f32_16x16x32_bf16 v[24:27], v[210:213], v[32:35], v[166:169]
	v_mfma_f32_16x16x32_bf16 v[108:111], v[214:217], v[36:39], v[24:27]
	v_mfma_f32_16x16x32_bf16 v[24:27], v[218:221], v[32:35], v[80:83]
	v_mfma_f32_16x16x32_bf16 v[116:119], v[214:217], v[28:31], v[48:51]
	v_mfma_f32_16x16x32_bf16 v[48:51], v[242:245], v[36:39], v[24:27]
	v_mfma_f32_16x16x32_bf16 v[24:27], v[210:213], v[44:47], v[76:79]
	v_mfma_f32_16x16x32_bf16 v[100:103], v[214:217], v[132:135], v[24:27]
	v_mfma_f32_16x16x32_bf16 v[24:27], v[218:221], v[44:47], v[170:173]
	v_mfma_f32_16x16x32_bf16 v[44:47], v[242:245], v[132:135], v[24:27]
	v_mfma_f32_16x16x32_bf16 v[24:27], v[210:213], v[158:161], v[174:177]
	v_mfma_f32_16x16x32_bf16 v[96:99], v[214:217], v[206:209], v[24:27]
	v_mfma_f32_16x16x32_bf16 v[24:27], v[218:221], v[158:161], v[198:201]
	v_mfma_f32_16x16x32_bf16 v[36:39], v[242:245], v[206:209], v[24:27]
	s_barrier
	ds_read_b128 v[132:135], v151 offset:49152
	ds_read_b128 v[158:161], v151 offset:50176
	ds_read_b128 v[166:169], v150 offset:49152
	ds_read_b128 v[150:153], v150 offset:50176
	ds_read_b128 v[170:173], v149 offset:49152
	ds_read_b128 v[174:177], v149 offset:50176
	ds_read_b128 v[198:201], v148 offset:49152
	ds_read_b128 v[146:149], v148 offset:50176
	s_barrier
	s_waitcnt lgkmcnt(0)
	v_mfma_f32_16x16x32_bf16 v[24:27], v[4:7], v[132:135], v[60:63]
	v_mfma_f32_16x16x32_bf16 v[92:95], v[8:11], v[158:161], v[24:27]
	v_mfma_f32_16x16x32_bf16 v[24:27], v[12:15], v[132:135], v[222:225]
	v_mfma_f32_16x16x32_bf16 v[32:35], v[16:19], v[158:161], v[24:27]
	v_mfma_f32_16x16x32_bf16 v[24:27], v[4:7], v[166:169], v[52:55]
	v_mfma_f32_16x16x32_bf16 v[88:91], v[8:11], v[150:153], v[24:27]
	v_mfma_f32_16x16x32_bf16 v[24:27], v[12:15], v[166:169], v[226:229]
	v_mfma_f32_16x16x32_bf16 v[28:31], v[16:19], v[150:153], v[24:27]
	v_mfma_f32_16x16x32_bf16 v[24:27], v[4:7], v[170:173], v[230:233]
	v_mfma_f32_16x16x32_bf16 v[4:7], v[4:7], v[198:201], v[136:139]
	v_mfma_f32_16x16x32_bf16 v[76:79], v[8:11], v[174:177], v[24:27]
	v_mfma_f32_16x16x32_bf16 v[24:27], v[12:15], v[170:173], v[40:43]
	v_mfma_f32_16x16x32_bf16 v[52:55], v[8:11], v[146:149], v[4:7]
	v_mfma_f32_16x16x32_bf16 v[4:7], v[12:15], v[198:201], v[140:143]
	v_mfma_f32_16x16x32_bf16 v[24:27], v[16:19], v[174:177], v[24:27]
	v_mfma_f32_16x16x32_bf16 v[16:19], v[16:19], v[146:149], v[4:7]
	v_mfma_f32_16x16x32_bf16 v[4:7], v[210:213], v[132:135], v[154:157]
	v_mfma_f32_16x16x32_bf16 v[80:83], v[214:217], v[158:161], v[4:7]
	v_mfma_f32_16x16x32_bf16 v[4:7], v[218:221], v[132:135], v[162:165]
	v_mfma_f32_16x16x32_bf16 v[12:15], v[242:245], v[158:161], v[4:7]
	v_mfma_f32_16x16x32_bf16 v[4:7], v[210:213], v[166:169], v[20:23]
	v_mfma_f32_16x16x32_bf16 v[60:63], v[214:217], v[150:153], v[4:7]
	v_mfma_f32_16x16x32_bf16 v[4:7], v[218:221], v[166:169], v[234:237]
	v_mfma_f32_16x16x32_bf16 v[8:11], v[242:245], v[150:153], v[4:7]
	v_mfma_f32_16x16x32_bf16 v[4:7], v[210:213], v[170:173], v[238:241]
	v_mfma_f32_16x16x32_bf16 v[40:43], v[214:217], v[174:177], v[4:7]
	v_mfma_f32_16x16x32_bf16 v[4:7], v[218:221], v[170:173], v[202:205]
	v_mfma_f32_16x16x32_bf16 v[20:23], v[210:213], v[198:201], v[128:131]
	v_mfma_f32_16x16x32_bf16 v[0:3], v[218:221], v[198:201], v[0:3]
	v_mfma_f32_16x16x32_bf16 v[4:7], v[242:245], v[174:177], v[4:7]
	v_mfma_f32_16x16x32_bf16 v[20:23], v[214:217], v[146:149], v[20:23]
	v_mfma_f32_16x16x32_bf16 v[0:3], v[242:245], v[146:149], v[0:3]
	s_movk_i32 s0, 0x100
	v_cmp_gt_u32_e32 vcc, s0, v144
	s_barrier
	s_and_saveexec_b64 s[0:1], vcc
	s_cbranch_execz .LBB0_530
	s_barrier

; #define WAIT_L(n) asm volatile("s_waitcnt lgkmcnt(" #n ")" ::: "memory")
; #define BAR __builtin_amdgcn_s_barrier()
; #define SCHED __builtin_amdgcn_sched_barrier(0)
; #define LDA(dst, b, h)                                                                            \
;   _Pragma("unroll") for (int m = 0; m < 4; ++m) _Pragma("unroll") for (int k = 0; k < 2; ++k)                                         \
;     dst[m][k] = *reinterpret_cast<const bf16x8*>((char*)SA(b, h) + lds_byte(wr * 64 + m * 16 + fr, k * 32 + fq * 8))
; #define LDB(dst, b, h)                                                                            \
;   _Pragma("unroll") for (int n = 0; n < 2; ++n) _Pragma("unroll") for (int k = 0; k < 2; ++k)                                         \
;     dst[n][k] = *reinterpret_cast<const bf16x8*>((char*)SB(b, h) + lds_byte(wc * 32 + n * 16 + fr, k * 32 + fq * 8))
; template <int K, bool SWAP>
; __device__ __forceinline__ void gemm_kloop(const bf16* __restrict__ A, const bf16* __restrict__ Bt,
;                                            f32x4 (&acc)[2][2][4][2], bool pref = false) {
;     ...
;     LDB(B0, 0, 0); SCHED; LDA(At, 0, 0); STAGE(SA(1, 1), A, HALF, t + 1);
;     WAIT_L(8); BAR; WAIT_L(0); MMA(0, 0, At, B0); BAR; SCHED;
;     LDB(B1, 0, 1); STAGE(SB(0, 0), Bt, 0, t + 2);
;     BAR; WAIT_L(0); MMA(0, 1, At, B1); BAR;
;     LDA(At, 0, 1); STAGE(SA(0, 0), A, 0, t + 2);
;     BAR; WAIT_L(0); MMA(1, 0, At, B0); BAR; SCHED;
.LBB0_542:
	ds_read_b128 v[162:165], v159
	ds_read_b128 v[166:169], v159 offset:1024
	ds_read_b128 v[170:173], v159 offset:2048
	ds_read_b128 v[174:177], v159 offset:3072
	v_add_u32_e32 v160, 0xc000, v146
	v_lshl_add_u64 v[178:179], s[58:59], 0, v[140:141]
	v_readfirstlane_b32 s5, v160
	v_lshl_add_u64 v[188:189], v[178:179], 0, s[42:43]
	s_mov_b32 m0, s5
	v_add_u32_e32 v161, 0xe000, v146
	ds_read_b128 v[198:201], v151
	ds_read_b128 v[202:205], v151 offset:1024
	ds_read_b128 v[206:209], v150
	ds_read_b128 v[210:213], v150 offset:1024
	ds_read_b128 v[214:217], v149
	ds_read_b128 v[218:221], v149 offset:1024
	ds_read_b128 v[222:225], v148
	ds_read_b128 v[226:229], v148 offset:1024
	global_load_lds_dwordx4 v[188:189], off
	v_lshl_add_u64 v[188:189], s[58:59], 0, v[142:143]
	v_readfirstlane_b32 s5, v161
	v_lshl_add_u64 v[230:231], v[188:189], 0, s[42:43]
	s_mov_b32 m0, s5
	s_nop 0
	global_load_lds_dwordx4 v[230:231], off
	s_waitcnt lgkmcnt(8)
	s_barrier
	s_waitcnt lgkmcnt(0)
	v_mfma_f32_16x16x32_bf16 v[124:127], v[162:165], v[198:201], v[124:127]
	v_mfma_f32_16x16x32_bf16 v[120:123], v[170:173], v[198:201], v[120:123]
	v_mfma_f32_16x16x32_bf16 v[112:115], v[170:173], v[206:209], v[112:115]
	v_mfma_f32_16x16x32_bf16 v[116:119], v[162:165], v[206:209], v[116:119]
	v_mfma_f32_16x16x32_bf16 v[108:111], v[162:165], v[214:217], v[108:111]
	v_mfma_f32_16x16x32_bf16 v[104:107], v[170:173], v[214:217], v[104:107]
	v_mfma_f32_16x16x32_bf16 v[96:99], v[170:173], v[222:225], v[96:99]
	v_mfma_f32_16x16x32_bf16 v[100:103], v[162:165], v[222:225], v[100:103]
	v_mfma_f32_16x16x32_bf16 v[124:127], v[166:169], v[202:205], v[124:127]
	v_mfma_f32_16x16x32_bf16 v[120:123], v[174:177], v[202:205], v[120:123]
	v_mfma_f32_16x16x32_bf16 v[112:115], v[174:177], v[210:213], v[112:115]
	v_mfma_f32_16x16x32_bf16 v[116:119], v[166:169], v[210:213], v[116:119]
	v_mfma_f32_16x16x32_bf16 v[108:111], v[166:169], v[218:221], v[108:111]
	v_mfma_f32_16x16x32_bf16 v[104:107], v[174:177], v[218:221], v[104:107]
	v_mfma_f32_16x16x32_bf16 v[96:99], v[174:177], v[226:229], v[96:99]
	v_mfma_f32_16x16x32_bf16 v[100:103], v[166:169], v[226:229], v[100:103]
	s_barrier
	v_add_u32_e32 v186, s8, v145
	v_lshl_add_u64 v[246:247], s[58:59], 0, v[136:137]
	v_readfirstlane_b32 s5, v186
	v_lshl_add_u64 v[248:249], v[246:247], 0, s[44:45]
	s_mov_b32 m0, s5
	v_add_u32_e32 v186, 0x2000, v186
	ds_read_b128 v[230:233], v158
	ds_read_b128 v[234:237], v158 offset:1024
	ds_read_b128 v[238:241], v158 offset:2048
	ds_read_b128 v[242:245], v158 offset:3072
	global_load_lds_dwordx4 v[248:249], off
	v_lshl_add_u64 v[248:249], s[58:59], 0, v[138:139]
	v_readfirstlane_b32 s5, v186
	v_lshl_add_u64 v[250:251], v[248:249], 0, s[44:45]
	s_mov_b32 m0, s5
	s_nop 0
	global_load_lds_dwordx4 v[250:251], off
	s_barrier
	s_waitcnt lgkmcnt(0)
	v_mfma_f32_16x16x32_bf16 v[92:95], v[230:233], v[198:201], v[92:95]
	v_mfma_f32_16x16x32_bf16 v[88:91], v[238:241], v[198:201], v[88:91]
	v_mfma_f32_16x16x32_bf16 v[80:83], v[238:241], v[206:209], v[80:83]
	v_mfma_f32_16x16x32_bf16 v[84:87], v[230:233], v[206:209], v[84:87]
	v_mfma_f32_16x16x32_bf16 v[76:79], v[230:233], v[214:217], v[76:79]
	v_mfma_f32_16x16x32_bf16 v[72:75], v[238:241], v[214:217], v[72:75]
	v_mfma_f32_16x16x32_bf16 v[64:67], v[238:241], v[222:225], v[64:67]
	v_mfma_f32_16x16x32_bf16 v[68:71], v[230:233], v[222:225], v[68:71]
	v_mfma_f32_16x16x32_bf16 v[92:95], v[234:237], v[202:205], v[92:95]
	v_mfma_f32_16x16x32_bf16 v[88:91], v[242:245], v[202:205], v[88:91]
	v_mfma_f32_16x16x32_bf16 v[80:83], v[242:245], v[210:213], v[80:83]
	v_mfma_f32_16x16x32_bf16 v[84:87], v[234:237], v[210:213], v[84:87]
	v_mfma_f32_16x16x32_bf16 v[76:79], v[234:237], v[218:221], v[76:79]
	v_mfma_f32_16x16x32_bf16 v[72:75], v[242:245], v[218:221], v[72:75]
	v_mfma_f32_16x16x32_bf16 v[64:67], v[242:245], v[226:229], v[64:67]
	v_mfma_f32_16x16x32_bf16 v[68:71], v[234:237], v[226:229], v[68:71]
	v_readfirstlane_b32 s5, v146
	v_add_u32_e32 v186, 0x2000, v146
	v_lshl_add_u64 v[250:251], v[178:179], 0, s[46:47]
	s_mov_b32 m0, s5
	v_readfirstlane_b32 s5, v186
	s_barrier
	ds_read_b128 v[198:201], v151 offset:16384
	ds_read_b128 v[202:205], v151 offset:17408
	ds_read_b128 v[206:209], v150 offset:16384
	ds_read_b128 v[210:213], v150 offset:17408
	ds_read_b128 v[214:217], v149 offset:16384
	ds_read_b128 v[218:221], v149 offset:17408
	ds_read_b128 v[222:225], v148 offset:16384
	ds_read_b128 v[226:229], v148 offset:17408
	global_load_lds_dwordx4 v[250:251], off
	v_lshl_add_u64 v[250:251], v[188:189], 0, s[46:47]
	s_mov_b32 m0, s5
	s_nop 0
	global_load_lds_dwordx4 v[250:251], off
	s_barrier
	s_waitcnt lgkmcnt(0)
	v_mfma_f32_16x16x32_bf16 v[60:63], v[162:165], v[198:201], v[60:63]
	v_mfma_f32_16x16x32_bf16 v[56:59], v[170:173], v[198:201], v[56:59]
	v_mfma_f32_16x16x32_bf16 v[48:51], v[170:173], v[206:209], v[48:51]
	v_mfma_f32_16x16x32_bf16 v[52:55], v[162:165], v[206:209], v[52:55]
	v_mfma_f32_16x16x32_bf16 v[44:47], v[162:165], v[214:217], v[44:47]
	v_mfma_f32_16x16x32_bf16 v[40:43], v[170:173], v[214:217], v[40:43]
	v_mfma_f32_16x16x32_bf16 v[32:35], v[170:173], v[222:225], v[32:35]
	v_mfma_f32_16x16x32_bf16 v[36:39], v[162:165], v[222:225], v[36:39]
	v_mfma_f32_16x16x32_bf16 v[60:63], v[166:169], v[202:205], v[60:63]
	v_mfma_f32_16x16x32_bf16 v[56:59], v[174:177], v[202:205], v[56:59]
	v_mfma_f32_16x16x32_bf16 v[48:51], v[174:177], v[210:213], v[48:51]
	v_mfma_f32_16x16x32_bf16 v[52:55], v[166:169], v[210:213], v[52:55]
	v_mfma_f32_16x16x32_bf16 v[44:47], v[166:169], v[218:221], v[44:47]
	v_mfma_f32_16x16x32_bf16 v[40:43], v[174:177], v[218:221], v[40:43]
	v_mfma_f32_16x16x32_bf16 v[32:35], v[174:177], v[226:229], v[32:35]
	v_mfma_f32_16x16x32_bf16 v[36:39], v[166:169], v[226:229], v[36:39]
	s_barrier
; #define WAIT_V(n) asm volatile("s_waitcnt vmcnt(" #n ")" ::: "memory")
; #define WAIT_L(n) asm volatile("s_waitcnt lgkmcnt(" #n ")" ::: "memory")
; #define BAR __builtin_amdgcn_s_barrier()
; #define SCHED __builtin_amdgcn_sched_barrier(0)
; #define LDA(dst, b, h)                                                                            \
;   _Pragma("unroll") for (int m = 0; m < 4; ++m) _Pragma("unroll") for (int k = 0; k < 2; ++k)                                         \
;     dst[m][k] = *reinterpret_cast<const bf16x8*>((char*)SA(b, h) + lds_byte(wr * 64 + m * 16 + fr, k * 32 + fq * 8))
; #define LDB(dst, b, h)                                                                            \
;   _Pragma("unroll") for (int n = 0; n < 2; ++n) _Pragma("unroll") for (int k = 0; k < 2; ++k)                                         \
;     dst[n][k] = *reinterpret_cast<const bf16x8*>((char*)SB(b, h) + lds_byte(wc * 32 + n * 16 + fr, k * 32 + fq * 8))
; template <int K, bool SWAP>
; __device__ __forceinline__ void gemm_kloop(const bf16* __restrict__ A, const bf16* __restrict__ Bt,
;                                            f32x4 (&acc)[2][2][4][2], bool pref = false) {
;     ...
;     STAGE(SB(0, 1), Bt, HALF, t + 2);
;     WAIT_V(6); BAR; MMA(1, 1, At, B1); BAR;
;     LDB(B0, 1, 0); SCHED; LDA(At, 1, 0); STAGE(SA(0, 1), A, HALF, t + 2);
;     WAIT_L(8); BAR; WAIT_L(0); MMA(0, 0, At, B0); BAR; SCHED;
;     LDB(B1, 1, 1); STAGE(SB(1, 0), Bt, 0, t + 3);
;     BAR; WAIT_L(0); MMA(0, 1, At, B1); BAR;
;     LDA(At, 1, 1); STAGE(SA(1, 0), A, 0, t + 3);
	v_readfirstlane_b32 s5, v147
	v_add_u32_e32 v164, 0x2000, v147
	v_lshl_add_u64 v[162:163], v[246:247], 0, s[48:49]
	s_mov_b32 m0, s5
	v_readfirstlane_b32 s5, v164
	global_load_lds_dwordx4 v[162:163], off
	v_lshl_add_u64 v[162:163], v[248:249], 0, s[48:49]
	s_mov_b32 m0, s5
	s_nop 0
	global_load_lds_dwordx4 v[162:163], off
	s_waitcnt vmcnt(6)
	s_barrier
	v_mfma_f32_16x16x32_bf16 v[28:31], v[230:233], v[198:201], v[28:31]
	v_mfma_f32_16x16x32_bf16 v[24:27], v[238:241], v[198:201], v[24:27]
	v_mfma_f32_16x16x32_bf16 v[16:19], v[238:241], v[206:209], v[16:19]
	v_mfma_f32_16x16x32_bf16 v[20:23], v[230:233], v[206:209], v[20:23]
	v_mfma_f32_16x16x32_bf16 v[12:15], v[230:233], v[214:217], v[12:15]
	v_mfma_f32_16x16x32_bf16 v[8:11], v[238:241], v[214:217], v[8:11]
	v_mfma_f32_16x16x32_bf16 v[0:3], v[238:241], v[222:225], v[0:3]
	v_mfma_f32_16x16x32_bf16 v[4:7], v[230:233], v[222:225], v[4:7]
	v_mfma_f32_16x16x32_bf16 v[28:31], v[234:237], v[202:205], v[28:31]
	v_mfma_f32_16x16x32_bf16 v[24:27], v[242:245], v[202:205], v[24:27]
	v_mfma_f32_16x16x32_bf16 v[16:19], v[242:245], v[210:213], v[16:19]
	v_mfma_f32_16x16x32_bf16 v[20:23], v[234:237], v[210:213], v[20:23]
	v_mfma_f32_16x16x32_bf16 v[12:15], v[234:237], v[218:221], v[12:15]
	v_mfma_f32_16x16x32_bf16 v[8:11], v[242:245], v[218:221], v[8:11]
	v_mfma_f32_16x16x32_bf16 v[0:3], v[242:245], v[226:229], v[0:3]
	v_mfma_f32_16x16x32_bf16 v[4:7], v[234:237], v[226:229], v[4:7]
	s_barrier
	ds_read_b128 v[162:165], v153
	ds_read_b128 v[166:169], v153 offset:1024
	ds_read_b128 v[170:173], v153 offset:2048
	ds_read_b128 v[174:177], v153 offset:3072
	v_add_u32_e32 v186, 0x4000, v146
	v_lshl_add_u64 v[230:231], v[178:179], 0, s[50:51]
	v_readfirstlane_b32 s5, v186
	v_add_u32_e32 v186, 0x6000, v146
	s_mov_b32 m0, s5
	v_readfirstlane_b32 s5, v186
	ds_read_b128 v[198:201], v151 offset:32768
	ds_read_b128 v[202:205], v151 offset:33792
	ds_read_b128 v[206:209], v150 offset:32768
	ds_read_b128 v[210:213], v150 offset:33792
	ds_read_b128 v[214:217], v149 offset:32768
	ds_read_b128 v[218:221], v149 offset:33792
	ds_read_b128 v[222:225], v148 offset:32768
	ds_read_b128 v[226:229], v148 offset:33792
	global_load_lds_dwordx4 v[230:231], off
	v_lshl_add_u64 v[230:231], v[188:189], 0, s[50:51]
	s_mov_b32 m0, s5
	s_nop 0
	global_load_lds_dwordx4 v[230:231], off
	s_waitcnt lgkmcnt(8)
	s_barrier
	s_waitcnt lgkmcnt(0)
	v_mfma_f32_16x16x32_bf16 v[124:127], v[162:165], v[198:201], v[124:127]
	v_mfma_f32_16x16x32_bf16 v[120:123], v[170:173], v[198:201], v[120:123]
	v_mfma_f32_16x16x32_bf16 v[112:115], v[170:173], v[206:209], v[112:115]
	v_mfma_f32_16x16x32_bf16 v[116:119], v[162:165], v[206:209], v[116:119]
	v_mfma_f32_16x16x32_bf16 v[108:111], v[162:165], v[214:217], v[108:111]
	v_mfma_f32_16x16x32_bf16 v[104:107], v[170:173], v[214:217], v[104:107]
	v_mfma_f32_16x16x32_bf16 v[96:99], v[170:173], v[222:225], v[96:99]
	v_mfma_f32_16x16x32_bf16 v[100:103], v[162:165], v[222:225], v[100:103]
	v_mfma_f32_16x16x32_bf16 v[124:127], v[166:169], v[202:205], v[124:127]
	v_mfma_f32_16x16x32_bf16 v[120:123], v[174:177], v[202:205], v[120:123]
	v_mfma_f32_16x16x32_bf16 v[112:115], v[174:177], v[210:213], v[112:115]
	v_mfma_f32_16x16x32_bf16 v[116:119], v[166:169], v[210:213], v[116:119]
	v_mfma_f32_16x16x32_bf16 v[108:111], v[166:169], v[218:221], v[108:111]
	v_mfma_f32_16x16x32_bf16 v[104:107], v[174:177], v[218:221], v[104:107]
	v_mfma_f32_16x16x32_bf16 v[96:99], v[174:177], v[226:229], v[96:99]
	v_mfma_f32_16x16x32_bf16 v[100:103], v[166:169], v[226:229], v[100:103]
	s_barrier
	v_readfirstlane_b32 s5, v154
	v_add_u32_e32 v186, 0x2000, v154
	v_lshl_add_u64 v[250:251], v[246:247], 0, s[52:53]
	s_mov_b32 m0, s5
	v_readfirstlane_b32 s5, v186
	ds_read_b128 v[230:233], v152
	ds_read_b128 v[234:237], v152 offset:1024
	ds_read_b128 v[238:241], v152 offset:2048
	ds_read_b128 v[242:245], v152 offset:3072
	global_load_lds_dwordx4 v[250:251], off
	v_lshl_add_u64 v[250:251], v[248:249], 0, s[52:53]
	s_mov_b32 m0, s5
	s_nop 0
	global_load_lds_dwordx4 v[250:251], off
	s_barrier
	s_waitcnt lgkmcnt(0)
	v_mfma_f32_16x16x32_bf16 v[92:95], v[230:233], v[198:201], v[92:95]
	v_mfma_f32_16x16x32_bf16 v[88:91], v[238:241], v[198:201], v[88:91]
	v_mfma_f32_16x16x32_bf16 v[80:83], v[238:241], v[206:209], v[80:83]
	v_mfma_f32_16x16x32_bf16 v[84:87], v[230:233], v[206:209], v[84:87]
	v_mfma_f32_16x16x32_bf16 v[76:79], v[230:233], v[214:217], v[76:79]
	v_mfma_f32_16x16x32_bf16 v[72:75], v[238:241], v[214:217], v[72:75]
	v_mfma_f32_16x16x32_bf16 v[64:67], v[238:241], v[222:225], v[64:67]
	v_mfma_f32_16x16x32_bf16 v[68:71], v[230:233], v[222:225], v[68:71]
	v_mfma_f32_16x16x32_bf16 v[92:95], v[234:237], v[202:205], v[92:95]
	v_mfma_f32_16x16x32_bf16 v[88:91], v[242:245], v[202:205], v[88:91]
	v_mfma_f32_16x16x32_bf16 v[80:83], v[242:245], v[210:213], v[80:83]
	v_mfma_f32_16x16x32_bf16 v[84:87], v[234:237], v[210:213], v[84:87]
	v_mfma_f32_16x16x32_bf16 v[76:79], v[234:237], v[218:221], v[76:79]
	v_mfma_f32_16x16x32_bf16 v[72:75], v[242:245], v[218:221], v[72:75]
	v_mfma_f32_16x16x32_bf16 v[64:67], v[242:245], v[226:229], v[64:67]
	v_mfma_f32_16x16x32_bf16 v[68:71], v[234:237], v[226:229], v[68:71]
	v_readfirstlane_b32 s5, v155
	v_lshl_add_u64 v[178:179], v[178:179], 0, s[54:55]
	s_mov_b32 m0, s5
	v_readfirstlane_b32 s5, v156
	s_barrier
	ds_read_b128 v[198:201], v151 offset:49152
	ds_read_b128 v[202:205], v151 offset:50176
	ds_read_b128 v[206:209], v150 offset:49152
	ds_read_b128 v[210:213], v150 offset:50176
	ds_read_b128 v[214:217], v149 offset:49152
	ds_read_b128 v[218:221], v149 offset:50176
	ds_read_b128 v[222:225], v148 offset:49152
	ds_read_b128 v[226:229], v148 offset:50176
	global_load_lds_dwordx4 v[178:179], off
	v_lshl_add_u64 v[178:179], v[188:189], 0, s[54:55]
	s_mov_b32 m0, s5
	s_nop 0
	global_load_lds_dwordx4 v[178:179], off
	s_barrier
; #define WAIT_V(n) asm volatile("s_waitcnt vmcnt(" #n ")" ::: "memory")
; #define WAIT_L(n) asm volatile("s_waitcnt lgkmcnt(" #n ")" ::: "memory")
; #define BAR __builtin_amdgcn_s_barrier()
; #define SCHED __builtin_amdgcn_sched_barrier(0)
; #define LDA(dst, b, h)                                                                            \
;   _Pragma("unroll") for (int m = 0; m < 4; ++m) _Pragma("unroll") for (int k = 0; k < 2; ++k)                                         \
;     dst[m][k] = *reinterpret_cast<const bf16x8*>((char*)SA(b, h) + lds_byte(wr * 64 + m * 16 + fr, k * 32 + fq * 8))
; #define LDB(dst, b, h)                                                                            \
;   _Pragma("unroll") for (int n = 0; n < 2; ++n) _Pragma("unroll") for (int k = 0; k < 2; ++k)                                         \
;     dst[n][k] = *reinterpret_cast<const bf16x8*>((char*)SB(b, h) + lds_byte(wc * 32 + n * 16 + fr, k * 32 + fq * 8))
; template <int K, bool SWAP>
; __device__ __forceinline__ void gemm_kloop(const bf16* __restrict__ A, const bf16* __restrict__ Bt,
;                                            f32x4 (&acc)[2][2][4][2], bool pref = false) {
;     ...
;     BAR; WAIT_L(0); MMA(1, 0, At, B0); BAR; SCHED;
;     STAGE(SB(1, 1), Bt, HALF, t + 3);
;     WAIT_V(6); BAR; MMA(1, 1, At, B1); BAR;
;   }
;   { LDB(B0, 0, 0); LDA(At, 0, 0); STAGE(SA(1, 1), A, HALF, nt - 1);
;     BAR; WAIT_L(0); MMA(0, 0, At, B0); BAR;
;     LDB(B1, 0, 1); BAR; WAIT_L(0); MMA(0, 1, At, B1); BAR;
	s_waitcnt lgkmcnt(0)
	v_mfma_f32_16x16x32_bf16 v[60:63], v[162:165], v[198:201], v[60:63]
	v_mfma_f32_16x16x32_bf16 v[56:59], v[170:173], v[198:201], v[56:59]
	v_mfma_f32_16x16x32_bf16 v[48:51], v[170:173], v[206:209], v[48:51]
	v_mfma_f32_16x16x32_bf16 v[52:55], v[162:165], v[206:209], v[52:55]
	v_mfma_f32_16x16x32_bf16 v[44:47], v[162:165], v[214:217], v[44:47]
	v_mfma_f32_16x16x32_bf16 v[40:43], v[170:173], v[214:217], v[40:43]
	v_mfma_f32_16x16x32_bf16 v[32:35], v[170:173], v[222:225], v[32:35]
	v_mfma_f32_16x16x32_bf16 v[36:39], v[162:165], v[222:225], v[36:39]
	v_mfma_f32_16x16x32_bf16 v[60:63], v[166:169], v[202:205], v[60:63]
	v_mfma_f32_16x16x32_bf16 v[56:59], v[174:177], v[202:205], v[56:59]
	v_mfma_f32_16x16x32_bf16 v[48:51], v[174:177], v[210:213], v[48:51]
	v_mfma_f32_16x16x32_bf16 v[52:55], v[166:169], v[210:213], v[52:55]
	v_mfma_f32_16x16x32_bf16 v[44:47], v[166:169], v[218:221], v[44:47]
	v_mfma_f32_16x16x32_bf16 v[40:43], v[174:177], v[218:221], v[40:43]
	v_mfma_f32_16x16x32_bf16 v[32:35], v[174:177], v[226:229], v[32:35]
	v_mfma_f32_16x16x32_bf16 v[36:39], v[166:169], v[226:229], v[36:39]
	s_barrier
	v_readfirstlane_b32 s5, v157
	v_add_u32_e32 v164, 0x2000, v157
	v_lshl_add_u64 v[162:163], v[246:247], 0, s[56:57]
	s_mov_b32 m0, s5
	v_readfirstlane_b32 s5, v164
	global_load_lds_dwordx4 v[162:163], off
	v_lshl_add_u64 v[162:163], v[248:249], 0, s[56:57]
	s_mov_b32 m0, s5
	s_nop 0
	global_load_lds_dwordx4 v[162:163], off
	s_waitcnt vmcnt(6)
	s_barrier
	v_mfma_f32_16x16x32_bf16 v[28:31], v[230:233], v[198:201], v[28:31]
	v_mfma_f32_16x16x32_bf16 v[24:27], v[238:241], v[198:201], v[24:27]
	v_mfma_f32_16x16x32_bf16 v[16:19], v[238:241], v[206:209], v[16:19]
	v_mfma_f32_16x16x32_bf16 v[20:23], v[230:233], v[206:209], v[20:23]
	v_mfma_f32_16x16x32_bf16 v[12:15], v[230:233], v[214:217], v[12:15]
	v_mfma_f32_16x16x32_bf16 v[8:11], v[238:241], v[214:217], v[8:11]
	v_mfma_f32_16x16x32_bf16 v[0:3], v[238:241], v[222:225], v[0:3]
	v_mfma_f32_16x16x32_bf16 v[4:7], v[230:233], v[222:225], v[4:7]
	v_mfma_f32_16x16x32_bf16 v[28:31], v[234:237], v[202:205], v[28:31]
	v_mfma_f32_16x16x32_bf16 v[24:27], v[242:245], v[202:205], v[24:27]
	v_mfma_f32_16x16x32_bf16 v[16:19], v[242:245], v[210:213], v[16:19]
	v_mfma_f32_16x16x32_bf16 v[20:23], v[234:237], v[210:213], v[20:23]
	v_mfma_f32_16x16x32_bf16 v[12:15], v[234:237], v[218:221], v[12:15]
	v_mfma_f32_16x16x32_bf16 v[8:11], v[242:245], v[218:221], v[8:11]
	v_mfma_f32_16x16x32_bf16 v[0:3], v[242:245], v[226:229], v[0:3]
	v_mfma_f32_16x16x32_bf16 v[4:7], v[234:237], v[226:229], v[4:7]
	s_add_i32 s4, s4, 2
	v_lshl_add_u64 v[136:137], v[136:137], 0, s[44:45]
	v_lshl_add_u64 v[138:139], v[138:139], 0, s[44:45]
	v_lshl_add_u64 v[140:141], v[140:141], 0, s[44:45]
	s_cmp_lt_u32 s4, 12
	v_lshl_add_u64 v[142:143], v[142:143], 0, s[44:45]
	s_barrier
	s_cbranch_scc1 .LBB0_542
	s_add_u32 s0, s0, 0x40780
	s_addc_u32 s1, s1, 0
	v_lshl_add_u64 v[130:131], s[0:1], 0, v[130:131]
	v_readfirstlane_b32 s4, v160
	v_lshl_add_u64 v[128:129], v[128:129], 1, v[130:131]
	s_mov_b32 m0, s4
	ds_read_b128 v[136:139], v159
	ds_read_b128 v[140:143], v159 offset:1024
	ds_read_b128 v[154:157], v159 offset:2048
	ds_read_b128 v[162:165], v159 offset:3072
	ds_read_b128 v[166:169], v151
	ds_read_b128 v[170:173], v151 offset:1024
	ds_read_b128 v[174:177], v150
	ds_read_b128 v[198:201], v150 offset:1024
	ds_read_b128 v[202:205], v149
	ds_read_b128 v[206:209], v149 offset:1024
	ds_read_b128 v[210:213], v148
	ds_read_b128 v[214:217], v148 offset:1024
	global_load_lds_dwordx4 v[128:129], off
	v_lshl_add_u64 v[128:129], s[0:1], 0, v[134:135]
	v_readfirstlane_b32 s0, v161
	v_lshl_add_u64 v[128:129], v[132:133], 1, v[128:129]
	s_mov_b32 m0, s0
	s_nop 0
	global_load_lds_dwordx4 v[128:129], off
	s_barrier
	s_waitcnt lgkmcnt(0)
	v_mfma_f32_16x16x32_bf16 v[124:127], v[136:139], v[166:169], v[124:127]
	v_mfma_f32_16x16x32_bf16 v[120:123], v[154:157], v[166:169], v[120:123]
	v_mfma_f32_16x16x32_bf16 v[112:115], v[154:157], v[174:177], v[112:115]
	v_mfma_f32_16x16x32_bf16 v[116:119], v[136:139], v[174:177], v[116:119]
	v_mfma_f32_16x16x32_bf16 v[108:111], v[136:139], v[202:205], v[108:111]
	v_mfma_f32_16x16x32_bf16 v[104:107], v[154:157], v[202:205], v[104:107]
	v_mfma_f32_16x16x32_bf16 v[96:99], v[154:157], v[210:213], v[96:99]
	v_mfma_f32_16x16x32_bf16 v[100:103], v[136:139], v[210:213], v[100:103]
	v_mfma_f32_16x16x32_bf16 v[124:127], v[140:143], v[170:173], v[124:127]
	v_mfma_f32_16x16x32_bf16 v[120:123], v[162:165], v[170:173], v[120:123]
	v_mfma_f32_16x16x32_bf16 v[112:115], v[162:165], v[198:201], v[112:115]
	v_mfma_f32_16x16x32_bf16 v[116:119], v[140:143], v[198:201], v[116:119]
	v_mfma_f32_16x16x32_bf16 v[108:111], v[140:143], v[206:209], v[108:111]
	v_mfma_f32_16x16x32_bf16 v[104:107], v[162:165], v[206:209], v[104:107]
	v_mfma_f32_16x16x32_bf16 v[96:99], v[162:165], v[214:217], v[96:99]
	v_mfma_f32_16x16x32_bf16 v[100:103], v[140:143], v[214:217], v[100:103]
	s_barrier
	ds_read_b128 v[128:131], v158
	ds_read_b128 v[132:135], v158 offset:1024
	ds_read_b128 v[218:221], v158 offset:2048
	ds_read_b128 v[158:161], v158 offset:3072
	s_barrier
; #define WAIT_V(n) asm volatile("s_waitcnt vmcnt(" #n ")" ::: "memory")
; #define WAIT_L(n) asm volatile("s_waitcnt lgkmcnt(" #n ")" ::: "memory")
; #define BAR __builtin_amdgcn_s_barrier()
; #define LDA(dst, b, h)                                                                            \
;   _Pragma("unroll") for (int m = 0; m < 4; ++m) _Pragma("unroll") for (int k = 0; k < 2; ++k)                                         \
;     dst[m][k] = *reinterpret_cast<const bf16x8*>((char*)SA(b, h) + lds_byte(wr * 64 + m * 16 + fr, k * 32 + fq * 8))
; #define LDB(dst, b, h)                                                                            \
;   _Pragma("unroll") for (int n = 0; n < 2; ++n) _Pragma("unroll") for (int k = 0; k < 2; ++k)                                         \
;     dst[n][k] = *reinterpret_cast<const bf16x8*>((char*)SB(b, h) + lds_byte(wc * 32 + n * 16 + fr, k * 32 + fq * 8))
; template <int K, bool SWAP>
; __device__ __forceinline__ void gemm_kloop(const bf16* __restrict__ A, const bf16* __restrict__ Bt,
;                                            f32x4 (&acc)[2][2][4][2], bool pref = false) {
;     ...
;     LDB(B1, 0, 1); BAR; WAIT_L(0); MMA(0, 1, At, B1); BAR;
;     LDA(At, 0, 1); WAIT_V(4); BAR; WAIT_L(0); MMA(1, 0, At, B0); MMA(1, 1, At, B1); BAR; }
;   { LDB(B0, 1, 0); LDA(At, 1, 0); WAIT_V(2); BAR; WAIT_L(0); MMA(0, 0, At, B0); BAR;
	s_waitcnt lgkmcnt(0)
	v_mfma_f32_16x16x32_bf16 v[92:95], v[128:131], v[166:169], v[92:95]
	v_mfma_f32_16x16x32_bf16 v[88:91], v[218:221], v[166:169], v[88:91]
	v_mfma_f32_16x16x32_bf16 v[76:79], v[128:131], v[202:205], v[76:79]
	v_mfma_f32_16x16x32_bf16 v[72:75], v[218:221], v[202:205], v[72:75]
	v_mfma_f32_16x16x32_bf16 v[68:71], v[128:131], v[210:213], v[68:71]
	v_mfma_f32_16x16x32_bf16 v[64:67], v[218:221], v[210:213], v[64:67]
	v_mfma_f32_16x16x32_bf16 v[92:95], v[132:135], v[170:173], v[92:95]
	v_mfma_f32_16x16x32_bf16 v[88:91], v[158:161], v[170:173], v[88:91]
	v_mfma_f32_16x16x32_bf16 v[84:87], v[128:131], v[174:177], v[84:87]
	v_mfma_f32_16x16x32_bf16 v[80:83], v[218:221], v[174:177], v[80:83]
	v_mfma_f32_16x16x32_bf16 v[76:79], v[132:135], v[206:209], v[76:79]
	v_mfma_f32_16x16x32_bf16 v[72:75], v[158:161], v[206:209], v[72:75]
	v_mfma_f32_16x16x32_bf16 v[68:71], v[132:135], v[214:217], v[68:71]
	v_mfma_f32_16x16x32_bf16 v[64:67], v[158:161], v[214:217], v[64:67]
	v_mfma_f32_16x16x32_bf16 v[84:87], v[132:135], v[198:201], v[84:87]
	v_mfma_f32_16x16x32_bf16 v[80:83], v[158:161], v[198:201], v[80:83]
	s_barrier
	ds_read_b128 v[166:169], v151 offset:16384
	ds_read_b128 v[170:173], v151 offset:17408
	ds_read_b128 v[174:177], v150 offset:16384
	ds_read_b128 v[198:201], v150 offset:17408
	ds_read_b128 v[202:205], v149 offset:16384
	ds_read_b128 v[206:209], v149 offset:17408
	ds_read_b128 v[210:213], v148 offset:16384
	ds_read_b128 v[214:217], v148 offset:17408
	s_waitcnt vmcnt(4)
	s_barrier
	s_waitcnt lgkmcnt(0)
	v_mfma_f32_16x16x32_bf16 v[60:63], v[136:139], v[166:169], v[60:63]
	v_mfma_f32_16x16x32_bf16 v[56:59], v[154:157], v[166:169], v[56:59]
	v_mfma_f32_16x16x32_bf16 v[52:55], v[136:139], v[174:177], v[52:55]
	v_mfma_f32_16x16x32_bf16 v[48:51], v[154:157], v[174:177], v[48:51]
	v_mfma_f32_16x16x32_bf16 v[44:47], v[136:139], v[202:205], v[44:47]
	v_mfma_f32_16x16x32_bf16 v[36:39], v[136:139], v[210:213], v[36:39]
	v_mfma_f32_16x16x32_bf16 v[60:63], v[140:143], v[170:173], v[60:63]
	v_mfma_f32_16x16x32_bf16 v[56:59], v[162:165], v[170:173], v[56:59]
	v_mfma_f32_16x16x32_bf16 v[52:55], v[140:143], v[198:201], v[52:55]
	v_mfma_f32_16x16x32_bf16 v[48:51], v[162:165], v[198:201], v[48:51]
	v_mfma_f32_16x16x32_bf16 v[44:47], v[140:143], v[206:209], v[44:47]
	v_mfma_f32_16x16x32_bf16 v[40:43], v[154:157], v[202:205], v[40:43]
	v_mfma_f32_16x16x32_bf16 v[36:39], v[140:143], v[214:217], v[36:39]
	v_mfma_f32_16x16x32_bf16 v[32:35], v[154:157], v[210:213], v[32:35]
	v_mfma_f32_16x16x32_bf16 v[40:43], v[162:165], v[206:209], v[40:43]
	v_mfma_f32_16x16x32_bf16 v[32:35], v[162:165], v[214:217], v[32:35]
	v_mfma_f32_16x16x32_bf16 v[28:31], v[128:131], v[166:169], v[28:31]
	v_mfma_f32_16x16x32_bf16 v[24:27], v[218:221], v[166:169], v[24:27]
	v_mfma_f32_16x16x32_bf16 v[16:19], v[218:221], v[174:177], v[16:19]
	v_mfma_f32_16x16x32_bf16 v[20:23], v[128:131], v[174:177], v[20:23]
	v_mfma_f32_16x16x32_bf16 v[12:15], v[128:131], v[202:205], v[12:15]
	v_mfma_f32_16x16x32_bf16 v[8:11], v[218:221], v[202:205], v[8:11]
	v_mfma_f32_16x16x32_bf16 v[0:3], v[218:221], v[210:213], v[0:3]
	v_mfma_f32_16x16x32_bf16 v[4:7], v[128:131], v[210:213], v[4:7]
	v_mfma_f32_16x16x32_bf16 v[28:31], v[132:135], v[170:173], v[28:31]
	v_mfma_f32_16x16x32_bf16 v[24:27], v[158:161], v[170:173], v[24:27]
	v_mfma_f32_16x16x32_bf16 v[16:19], v[158:161], v[198:201], v[16:19]
	v_mfma_f32_16x16x32_bf16 v[20:23], v[132:135], v[198:201], v[20:23]
	v_mfma_f32_16x16x32_bf16 v[12:15], v[132:135], v[206:209], v[12:15]
	v_mfma_f32_16x16x32_bf16 v[8:11], v[158:161], v[206:209], v[8:11]
	v_mfma_f32_16x16x32_bf16 v[0:3], v[158:161], v[214:217], v[0:3]
	v_mfma_f32_16x16x32_bf16 v[4:7], v[132:135], v[214:217], v[4:7]
	s_barrier
	ds_read_b128 v[154:157], v153
	ds_read_b128 v[158:161], v153 offset:1024
	ds_read_b128 v[162:165], v153 offset:2048
	ds_read_b128 v[166:169], v153 offset:3072
	ds_read_b128 v[170:173], v151 offset:32768
	ds_read_b128 v[174:177], v151 offset:33792
	ds_read_b128 v[198:201], v150 offset:32768
	ds_read_b128 v[202:205], v150 offset:33792
	ds_read_b128 v[206:209], v149 offset:32768
	ds_read_b128 v[210:213], v149 offset:33792
	ds_read_b128 v[214:217], v148 offset:32768
	ds_read_b128 v[218:221], v148 offset:33792
	s_waitcnt vmcnt(2)
	s_barrier
; #define WAIT_V(n) asm volatile("s_waitcnt vmcnt(" #n ")" ::: "memory")
; #define WAIT_L(n) asm volatile("s_waitcnt lgkmcnt(" #n ")" ::: "memory")
; #define BAR __builtin_amdgcn_s_barrier()
; #define LDA(dst, b, h)                                                                            \
;   _Pragma("unroll") for (int m = 0; m < 4; ++m) _Pragma("unroll") for (int k = 0; k < 2; ++k)                                         \
;     dst[m][k] = *reinterpret_cast<const bf16x8*>((char*)SA(b, h) + lds_byte(wr * 64 + m * 16 + fr, k * 32 + fq * 8))
; #define LDB(dst, b, h)                                                                            \
;   _Pragma("unroll") for (int n = 0; n < 2; ++n) _Pragma("unroll") for (int k = 0; k < 2; ++k)                                         \
;     dst[n][k] = *reinterpret_cast<const bf16x8*>((char*)SB(b, h) + lds_byte(wc * 32 + n * 16 + fr, k * 32 + fq * 8))
; template <int K, bool SWAP>
; __device__ __forceinline__ void gemm_kloop(const bf16* __restrict__ A, const bf16* __restrict__ Bt,
;                                            f32x4 (&acc)[2][2][4][2], bool pref = false) {
;     ...
;   { LDB(B0, 1, 0); LDA(At, 1, 0); WAIT_V(2); BAR; WAIT_L(0); MMA(0, 0, At, B0); BAR;
;     LDB(B1, 1, 1); WAIT_V(0); BAR; WAIT_L(0); MMA(0, 1, At, B1); BAR;
;     LDA(At, 1, 1); BAR; WAIT_L(0); MMA(1, 0, At, B0); MMA(1, 1, At, B1); BAR; }
;   if (wr == 0) BAR;
	s_waitcnt lgkmcnt(0)
	v_mfma_f32_16x16x32_bf16 v[124:127], v[154:157], v[170:173], v[124:127]
	v_mfma_f32_16x16x32_bf16 v[120:123], v[162:165], v[170:173], v[120:123]
	v_mfma_f32_16x16x32_bf16 v[116:119], v[154:157], v[198:201], v[116:119]
	v_mfma_f32_16x16x32_bf16 v[112:115], v[162:165], v[198:201], v[112:115]
	v_mfma_f32_16x16x32_bf16 v[108:111], v[154:157], v[206:209], v[108:111]
	v_mfma_f32_16x16x32_bf16 v[104:107], v[162:165], v[206:209], v[104:107]
	v_mfma_f32_16x16x32_bf16 v[100:103], v[154:157], v[214:217], v[100:103]
	v_mfma_f32_16x16x32_bf16 v[96:99], v[162:165], v[214:217], v[96:99]
	v_mfma_f32_16x16x32_bf16 v[140:143], v[158:161], v[174:177], v[124:127]
	v_mfma_f32_16x16x32_bf16 v[136:139], v[166:169], v[174:177], v[120:123]
	v_mfma_f32_16x16x32_bf16 v[132:135], v[158:161], v[202:205], v[116:119]
	v_mfma_f32_16x16x32_bf16 v[128:131], v[166:169], v[202:205], v[112:115]
	v_mfma_f32_16x16x32_bf16 v[124:127], v[158:161], v[210:213], v[108:111]
	v_mfma_f32_16x16x32_bf16 v[120:123], v[166:169], v[210:213], v[104:107]
	v_mfma_f32_16x16x32_bf16 v[116:119], v[158:161], v[218:221], v[100:103]
	v_mfma_f32_16x16x32_bf16 v[112:115], v[166:169], v[218:221], v[96:99]
	s_barrier
	ds_read_b128 v[222:225], v152
	ds_read_b128 v[226:229], v152 offset:1024
	ds_read_b128 v[230:233], v152 offset:2048
	ds_read_b128 v[234:237], v152 offset:3072
	s_waitcnt vmcnt(0)
	s_barrier
	s_waitcnt lgkmcnt(0)
	v_mfma_f32_16x16x32_bf16 v[92:95], v[222:225], v[170:173], v[92:95]
	v_mfma_f32_16x16x32_bf16 v[88:91], v[230:233], v[170:173], v[88:91]
	v_mfma_f32_16x16x32_bf16 v[84:87], v[222:225], v[198:201], v[84:87]
	v_mfma_f32_16x16x32_bf16 v[80:83], v[230:233], v[198:201], v[80:83]
	v_mfma_f32_16x16x32_bf16 v[76:79], v[222:225], v[206:209], v[76:79]
	v_mfma_f32_16x16x32_bf16 v[72:75], v[230:233], v[206:209], v[72:75]
	v_mfma_f32_16x16x32_bf16 v[68:71], v[222:225], v[214:217], v[68:71]
	v_mfma_f32_16x16x32_bf16 v[64:67], v[230:233], v[214:217], v[64:67]
	v_mfma_f32_16x16x32_bf16 v[108:111], v[226:229], v[174:177], v[92:95]
	v_mfma_f32_16x16x32_bf16 v[104:107], v[234:237], v[174:177], v[88:91]
	v_mfma_f32_16x16x32_bf16 v[100:103], v[226:229], v[202:205], v[84:87]
	v_mfma_f32_16x16x32_bf16 v[96:99], v[234:237], v[202:205], v[80:83]
	v_mfma_f32_16x16x32_bf16 v[92:95], v[226:229], v[210:213], v[76:79]
	v_mfma_f32_16x16x32_bf16 v[88:91], v[234:237], v[210:213], v[72:75]
	v_mfma_f32_16x16x32_bf16 v[76:79], v[226:229], v[218:221], v[68:71]
	v_mfma_f32_16x16x32_bf16 v[72:75], v[234:237], v[218:221], v[64:67]
	s_barrier
	ds_read_b128 v[80:83], v151 offset:49152
	ds_read_b128 v[84:87], v151 offset:50176
	ds_read_b128 v[170:173], v150 offset:49152
	ds_read_b128 v[150:153], v150 offset:50176
	ds_read_b128 v[174:177], v149 offset:49152
	ds_read_b128 v[198:201], v149 offset:50176
	ds_read_b128 v[202:205], v148 offset:49152
	ds_read_b128 v[146:149], v148 offset:50176
	s_barrier
	s_waitcnt lgkmcnt(0)
	v_mfma_f32_16x16x32_bf16 v[60:63], v[154:157], v[80:83], v[60:63]
	v_mfma_f32_16x16x32_bf16 v[56:59], v[162:165], v[80:83], v[56:59]
	v_mfma_f32_16x16x32_bf16 v[52:55], v[154:157], v[170:173], v[52:55]
	v_mfma_f32_16x16x32_bf16 v[48:51], v[162:165], v[170:173], v[48:51]
	v_mfma_f32_16x16x32_bf16 v[44:47], v[154:157], v[174:177], v[44:47]
	v_mfma_f32_16x16x32_bf16 v[40:43], v[162:165], v[174:177], v[40:43]
	v_mfma_f32_16x16x32_bf16 v[36:39], v[154:157], v[202:205], v[36:39]
	v_mfma_f32_16x16x32_bf16 v[32:35], v[162:165], v[202:205], v[32:35]
	v_mfma_f32_16x16x32_bf16 v[68:71], v[158:161], v[84:87], v[60:63]
	v_mfma_f32_16x16x32_bf16 v[64:67], v[166:169], v[84:87], v[56:59]
	v_mfma_f32_16x16x32_bf16 v[60:63], v[158:161], v[150:153], v[52:55]
	v_mfma_f32_16x16x32_bf16 v[56:59], v[166:169], v[150:153], v[48:51]
	v_mfma_f32_16x16x32_bf16 v[52:55], v[158:161], v[198:201], v[44:47]
	v_mfma_f32_16x16x32_bf16 v[48:51], v[166:169], v[198:201], v[40:43]
	v_mfma_f32_16x16x32_bf16 v[44:47], v[158:161], v[146:149], v[36:39]
	v_mfma_f32_16x16x32_bf16 v[36:39], v[166:169], v[146:149], v[32:35]
	v_mfma_f32_16x16x32_bf16 v[28:31], v[222:225], v[80:83], v[28:31]
	v_mfma_f32_16x16x32_bf16 v[24:27], v[230:233], v[80:83], v[24:27]
	v_mfma_f32_16x16x32_bf16 v[16:19], v[230:233], v[170:173], v[16:19]
	v_mfma_f32_16x16x32_bf16 v[20:23], v[222:225], v[170:173], v[20:23]
	v_mfma_f32_16x16x32_bf16 v[12:15], v[222:225], v[174:177], v[12:15]
	v_mfma_f32_16x16x32_bf16 v[8:11], v[230:233], v[174:177], v[8:11]
	v_mfma_f32_16x16x32_bf16 v[0:3], v[230:233], v[202:205], v[0:3]
	v_mfma_f32_16x16x32_bf16 v[4:7], v[222:225], v[202:205], v[4:7]
	v_mfma_f32_16x16x32_bf16 v[28:31], v[226:229], v[84:87], v[28:31]
	v_mfma_f32_16x16x32_bf16 v[24:27], v[234:237], v[84:87], v[24:27]
	v_mfma_f32_16x16x32_bf16 v[16:19], v[234:237], v[150:153], v[16:19]
	v_mfma_f32_16x16x32_bf16 v[20:23], v[226:229], v[150:153], v[20:23]
	v_mfma_f32_16x16x32_bf16 v[12:15], v[226:229], v[198:201], v[12:15]
	v_mfma_f32_16x16x32_bf16 v[8:11], v[234:237], v[198:201], v[8:11]
	v_mfma_f32_16x16x32_bf16 v[0:3], v[234:237], v[146:149], v[0:3]
	v_mfma_f32_16x16x32_bf16 v[4:7], v[226:229], v[146:149], v[4:7]
	s_movk_i32 s0, 0x100
	v_cmp_gt_u32_e32 vcc, s0, v144
	s_barrier
	s_and_saveexec_b64 s[0:1], vcc
	s_cbranch_execz .LBB0_545
	s_barrier

; #define WAIT_L(n) asm volatile("s_waitcnt lgkmcnt(" #n ")" ::: "memory")
; #define BAR __builtin_amdgcn_s_barrier()
; #define SCHED __builtin_amdgcn_sched_barrier(0)
; #define LDA(dst, b, h)                                                                            \
;   _Pragma("unroll") for (int m = 0; m < 4; ++m) _Pragma("unroll") for (int k = 0; k < 2; ++k)                                         \
;     dst[m][k] = *reinterpret_cast<const bf16x8*>((char*)SA(b, h) + lds_byte(wr * 64 + m * 16 + fr, k * 32 + fq * 8))
; #define LDB(dst, b, h)                                                                            \
;   _Pragma("unroll") for (int n = 0; n < 2; ++n) _Pragma("unroll") for (int k = 0; k < 2; ++k)                                         \
;     dst[n][k] = *reinterpret_cast<const bf16x8*>((char*)SB(b, h) + lds_byte(wc * 32 + n * 16 + fr, k * 32 + fq * 8))
; template <int K, bool SWAP>
; __device__ __forceinline__ void gemm_kloop(const bf16* __restrict__ A, const bf16* __restrict__ Bt,
;                                            f32x4 (&acc)[2][2][4][2], bool pref = false) {
;     ...
;     LDB(B0, 0, 0); SCHED; LDA(At, 0, 0); STAGE(SA(1, 1), A, HALF, t + 1);
;     WAIT_L(8); BAR; WAIT_L(0); MMA(0, 0, At, B0); BAR; SCHED;
;     LDB(B1, 0, 1); STAGE(SB(0, 0), Bt, 0, t + 2);
;     BAR; WAIT_L(0); MMA(0, 1, At, B1); BAR;
;     LDA(At, 0, 1); STAGE(SA(0, 0), A, 0, t + 2);
;     BAR; WAIT_L(0); MMA(1, 0, At, B0); BAR; SCHED;
.LBB0_590:
	ds_read_b128 v[162:165], v159
	ds_read_b128 v[166:169], v159 offset:1024
	ds_read_b128 v[170:173], v159 offset:2048
	ds_read_b128 v[174:177], v159 offset:3072
	v_add_u32_e32 v160, 0xc000, v146
	v_lshl_add_u64 v[178:179], s[6:7], 0, v[140:141]
	v_readfirstlane_b32 s14, v160
	v_lshl_add_u64 v[188:189], v[178:179], 0, s[22:23]
	s_mov_b32 m0, s14
	v_add_u32_e32 v161, 0xe000, v146
	ds_read_b128 v[198:201], v151
	ds_read_b128 v[202:205], v151 offset:1024
	ds_read_b128 v[206:209], v150
	ds_read_b128 v[210:213], v150 offset:1024
	ds_read_b128 v[214:217], v149
	ds_read_b128 v[218:221], v149 offset:1024
	ds_read_b128 v[222:225], v148
	ds_read_b128 v[226:229], v148 offset:1024
	global_load_lds_dwordx4 v[188:189], off
	v_lshl_add_u64 v[188:189], s[6:7], 0, v[142:143]
	v_readfirstlane_b32 s14, v161
	v_lshl_add_u64 v[230:231], v[188:189], 0, s[22:23]
	s_mov_b32 m0, s14
	s_nop 0
	global_load_lds_dwordx4 v[230:231], off
	s_waitcnt lgkmcnt(8)
	s_barrier
	s_waitcnt lgkmcnt(0)
	v_mfma_f32_16x16x32_bf16 v[124:127], v[162:165], v[198:201], v[124:127]
	v_mfma_f32_16x16x32_bf16 v[120:123], v[170:173], v[198:201], v[120:123]
	v_mfma_f32_16x16x32_bf16 v[112:115], v[170:173], v[206:209], v[112:115]
	v_mfma_f32_16x16x32_bf16 v[116:119], v[162:165], v[206:209], v[116:119]
	v_mfma_f32_16x16x32_bf16 v[108:111], v[162:165], v[214:217], v[108:111]
	v_mfma_f32_16x16x32_bf16 v[104:107], v[170:173], v[214:217], v[104:107]
	v_mfma_f32_16x16x32_bf16 v[96:99], v[170:173], v[222:225], v[96:99]
	v_mfma_f32_16x16x32_bf16 v[100:103], v[162:165], v[222:225], v[100:103]
	v_mfma_f32_16x16x32_bf16 v[124:127], v[166:169], v[202:205], v[124:127]
	v_mfma_f32_16x16x32_bf16 v[120:123], v[174:177], v[202:205], v[120:123]
	v_mfma_f32_16x16x32_bf16 v[112:115], v[174:177], v[210:213], v[112:115]
	v_mfma_f32_16x16x32_bf16 v[116:119], v[166:169], v[210:213], v[116:119]
	v_mfma_f32_16x16x32_bf16 v[108:111], v[166:169], v[218:221], v[108:111]
	v_mfma_f32_16x16x32_bf16 v[104:107], v[174:177], v[218:221], v[104:107]
	v_mfma_f32_16x16x32_bf16 v[96:99], v[174:177], v[226:229], v[96:99]
	v_mfma_f32_16x16x32_bf16 v[100:103], v[166:169], v[226:229], v[100:103]
	s_barrier
	v_add_u32_e32 v186, s1, v145
	v_lshl_add_u64 v[246:247], s[6:7], 0, v[136:137]
	v_readfirstlane_b32 s14, v186
	v_lshl_add_u64 v[248:249], v[246:247], 0, s[40:41]
	s_mov_b32 m0, s14
	v_add_u32_e32 v186, 0x2000, v186
	ds_read_b128 v[230:233], v156
	ds_read_b128 v[234:237], v156 offset:1024
	ds_read_b128 v[238:241], v156 offset:2048
	ds_read_b128 v[242:245], v156 offset:3072
	global_load_lds_dwordx4 v[248:249], off
	v_lshl_add_u64 v[248:249], s[6:7], 0, v[138:139]
	v_readfirstlane_b32 s14, v186
	v_lshl_add_u64 v[250:251], v[248:249], 0, s[40:41]
	s_mov_b32 m0, s14
	s_nop 0
	global_load_lds_dwordx4 v[250:251], off
	s_barrier
	s_waitcnt lgkmcnt(0)
	v_mfma_f32_16x16x32_bf16 v[92:95], v[230:233], v[198:201], v[92:95]
	v_mfma_f32_16x16x32_bf16 v[88:91], v[238:241], v[198:201], v[88:91]
	v_mfma_f32_16x16x32_bf16 v[80:83], v[238:241], v[206:209], v[80:83]
	v_mfma_f32_16x16x32_bf16 v[84:87], v[230:233], v[206:209], v[84:87]
	v_mfma_f32_16x16x32_bf16 v[76:79], v[230:233], v[214:217], v[76:79]
	v_mfma_f32_16x16x32_bf16 v[72:75], v[238:241], v[214:217], v[72:75]
	v_mfma_f32_16x16x32_bf16 v[64:67], v[238:241], v[222:225], v[64:67]
	v_mfma_f32_16x16x32_bf16 v[68:71], v[230:233], v[222:225], v[68:71]
	v_mfma_f32_16x16x32_bf16 v[92:95], v[234:237], v[202:205], v[92:95]
	v_mfma_f32_16x16x32_bf16 v[88:91], v[242:245], v[202:205], v[88:91]
	v_mfma_f32_16x16x32_bf16 v[80:83], v[242:245], v[210:213], v[80:83]
	v_mfma_f32_16x16x32_bf16 v[84:87], v[234:237], v[210:213], v[84:87]
	v_mfma_f32_16x16x32_bf16 v[76:79], v[234:237], v[218:221], v[76:79]
	v_mfma_f32_16x16x32_bf16 v[72:75], v[242:245], v[218:221], v[72:75]
	v_mfma_f32_16x16x32_bf16 v[64:67], v[242:245], v[226:229], v[64:67]
	v_mfma_f32_16x16x32_bf16 v[68:71], v[234:237], v[226:229], v[68:71]
	v_readfirstlane_b32 s14, v146
	v_add_u32_e32 v186, 0x2000, v146
	v_lshl_add_u64 v[250:251], v[178:179], 0, s[58:59]
	s_mov_b32 m0, s14
	v_readfirstlane_b32 s14, v186
	s_barrier
	ds_read_b128 v[198:201], v151 offset:16384
	ds_read_b128 v[202:205], v151 offset:17408
	ds_read_b128 v[206:209], v150 offset:16384
	ds_read_b128 v[210:213], v150 offset:17408
	ds_read_b128 v[214:217], v149 offset:16384
	ds_read_b128 v[218:221], v149 offset:17408
	ds_read_b128 v[222:225], v148 offset:16384
	ds_read_b128 v[226:229], v148 offset:17408
	global_load_lds_dwordx4 v[250:251], off
	v_lshl_add_u64 v[250:251], v[188:189], 0, s[58:59]
	s_mov_b32 m0, s14
	s_nop 0
	global_load_lds_dwordx4 v[250:251], off
	s_barrier
	s_waitcnt lgkmcnt(0)
	v_mfma_f32_16x16x32_bf16 v[60:63], v[162:165], v[198:201], v[60:63]
	v_mfma_f32_16x16x32_bf16 v[56:59], v[170:173], v[198:201], v[56:59]
	v_mfma_f32_16x16x32_bf16 v[48:51], v[170:173], v[206:209], v[48:51]
	v_mfma_f32_16x16x32_bf16 v[52:55], v[162:165], v[206:209], v[52:55]
	v_mfma_f32_16x16x32_bf16 v[44:47], v[162:165], v[214:217], v[44:47]
	v_mfma_f32_16x16x32_bf16 v[40:43], v[170:173], v[214:217], v[40:43]
	v_mfma_f32_16x16x32_bf16 v[32:35], v[170:173], v[222:225], v[32:35]
	v_mfma_f32_16x16x32_bf16 v[36:39], v[162:165], v[222:225], v[36:39]
	v_mfma_f32_16x16x32_bf16 v[60:63], v[166:169], v[202:205], v[60:63]
	v_mfma_f32_16x16x32_bf16 v[56:59], v[174:177], v[202:205], v[56:59]
	v_mfma_f32_16x16x32_bf16 v[48:51], v[174:177], v[210:213], v[48:51]
	v_mfma_f32_16x16x32_bf16 v[52:55], v[166:169], v[210:213], v[52:55]
	v_mfma_f32_16x16x32_bf16 v[44:47], v[166:169], v[218:221], v[44:47]
	v_mfma_f32_16x16x32_bf16 v[40:43], v[174:177], v[218:221], v[40:43]
	v_mfma_f32_16x16x32_bf16 v[32:35], v[174:177], v[226:229], v[32:35]
	v_mfma_f32_16x16x32_bf16 v[36:39], v[166:169], v[226:229], v[36:39]
	s_barrier
; #define WAIT_V(n) asm volatile("s_waitcnt vmcnt(" #n ")" ::: "memory")
; #define WAIT_L(n) asm volatile("s_waitcnt lgkmcnt(" #n ")" ::: "memory")
; #define BAR __builtin_amdgcn_s_barrier()
; #define SCHED __builtin_amdgcn_sched_barrier(0)
; #define LDA(dst, b, h)                                                                            \
;   _Pragma("unroll") for (int m = 0; m < 4; ++m) _Pragma("unroll") for (int k = 0; k < 2; ++k)                                         \
;     dst[m][k] = *reinterpret_cast<const bf16x8*>((char*)SA(b, h) + lds_byte(wr * 64 + m * 16 + fr, k * 32 + fq * 8))
; #define LDB(dst, b, h)                                                                            \
;   _Pragma("unroll") for (int n = 0; n < 2; ++n) _Pragma("unroll") for (int k = 0; k < 2; ++k)                                         \
;     dst[n][k] = *reinterpret_cast<const bf16x8*>((char*)SB(b, h) + lds_byte(wc * 32 + n * 16 + fr, k * 32 + fq * 8))
; template <int K, bool SWAP>
; __device__ __forceinline__ void gemm_kloop(const bf16* __restrict__ A, const bf16* __restrict__ Bt,
;                                            f32x4 (&acc)[2][2][4][2], bool pref = false) {
;     ...
;     STAGE(SB(0, 1), Bt, HALF, t + 2);
;     WAIT_V(6); BAR; MMA(1, 1, At, B1); BAR;
;     LDB(B0, 1, 0); SCHED; LDA(At, 1, 0); STAGE(SA(0, 1), A, HALF, t + 2);
;     WAIT_L(8); BAR; WAIT_L(0); MMA(0, 0, At, B0); BAR; SCHED;
;     LDB(B1, 1, 1); STAGE(SB(1, 0), Bt, 0, t + 3);
;     BAR; WAIT_L(0); MMA(0, 1, At, B1); BAR;
;     LDA(At, 1, 1); STAGE(SA(1, 0), A, 0, t + 3);
	v_readfirstlane_b32 s14, v147
	v_add_u32_e32 v164, 0x2000, v147
	v_lshl_add_u64 v[162:163], v[246:247], 0, s[60:61]
	s_mov_b32 m0, s14
	v_readfirstlane_b32 s14, v164
	global_load_lds_dwordx4 v[162:163], off
	v_lshl_add_u64 v[162:163], v[248:249], 0, s[60:61]
	s_mov_b32 m0, s14
	s_nop 0
	global_load_lds_dwordx4 v[162:163], off
	s_waitcnt vmcnt(6)
	s_barrier
	v_mfma_f32_16x16x32_bf16 v[28:31], v[230:233], v[198:201], v[28:31]
	v_mfma_f32_16x16x32_bf16 v[24:27], v[238:241], v[198:201], v[24:27]
	v_mfma_f32_16x16x32_bf16 v[16:19], v[238:241], v[206:209], v[16:19]
	v_mfma_f32_16x16x32_bf16 v[20:23], v[230:233], v[206:209], v[20:23]
	v_mfma_f32_16x16x32_bf16 v[12:15], v[230:233], v[214:217], v[12:15]
	v_mfma_f32_16x16x32_bf16 v[8:11], v[238:241], v[214:217], v[8:11]
	v_mfma_f32_16x16x32_bf16 v[0:3], v[238:241], v[222:225], v[0:3]
	v_mfma_f32_16x16x32_bf16 v[4:7], v[230:233], v[222:225], v[4:7]
	v_mfma_f32_16x16x32_bf16 v[28:31], v[234:237], v[202:205], v[28:31]
	v_mfma_f32_16x16x32_bf16 v[24:27], v[242:245], v[202:205], v[24:27]
	v_mfma_f32_16x16x32_bf16 v[16:19], v[242:245], v[210:213], v[16:19]
	v_mfma_f32_16x16x32_bf16 v[20:23], v[234:237], v[210:213], v[20:23]
	v_mfma_f32_16x16x32_bf16 v[12:15], v[234:237], v[218:221], v[12:15]
	v_mfma_f32_16x16x32_bf16 v[8:11], v[242:245], v[218:221], v[8:11]
	v_mfma_f32_16x16x32_bf16 v[0:3], v[242:245], v[226:229], v[0:3]
	v_mfma_f32_16x16x32_bf16 v[4:7], v[234:237], v[226:229], v[4:7]
	s_barrier
	ds_read_b128 v[162:165], v153
	ds_read_b128 v[166:169], v153 offset:1024
	ds_read_b128 v[170:173], v153 offset:2048
	ds_read_b128 v[174:177], v153 offset:3072
	v_add_u32_e32 v186, 0x4000, v146
	v_lshl_add_u64 v[230:231], v[178:179], 0, s[72:73]
	v_readfirstlane_b32 s14, v186
	v_add_u32_e32 v186, 0x6000, v146
	s_mov_b32 m0, s14
	v_readfirstlane_b32 s14, v186
	ds_read_b128 v[198:201], v151 offset:32768
	ds_read_b128 v[202:205], v151 offset:33792
	ds_read_b128 v[206:209], v150 offset:32768
	ds_read_b128 v[210:213], v150 offset:33792
	ds_read_b128 v[214:217], v149 offset:32768
	ds_read_b128 v[218:221], v149 offset:33792
	ds_read_b128 v[222:225], v148 offset:32768
	ds_read_b128 v[226:229], v148 offset:33792
	global_load_lds_dwordx4 v[230:231], off
	v_lshl_add_u64 v[230:231], v[188:189], 0, s[72:73]
	s_mov_b32 m0, s14
	s_nop 0
	global_load_lds_dwordx4 v[230:231], off
	s_waitcnt lgkmcnt(8)
	s_barrier
	s_waitcnt lgkmcnt(0)
	v_mfma_f32_16x16x32_bf16 v[124:127], v[162:165], v[198:201], v[124:127]
	v_mfma_f32_16x16x32_bf16 v[120:123], v[170:173], v[198:201], v[120:123]
	v_mfma_f32_16x16x32_bf16 v[112:115], v[170:173], v[206:209], v[112:115]
	v_mfma_f32_16x16x32_bf16 v[116:119], v[162:165], v[206:209], v[116:119]
	v_mfma_f32_16x16x32_bf16 v[108:111], v[162:165], v[214:217], v[108:111]
	v_mfma_f32_16x16x32_bf16 v[104:107], v[170:173], v[214:217], v[104:107]
	v_mfma_f32_16x16x32_bf16 v[96:99], v[170:173], v[222:225], v[96:99]
	v_mfma_f32_16x16x32_bf16 v[100:103], v[162:165], v[222:225], v[100:103]
	v_mfma_f32_16x16x32_bf16 v[124:127], v[166:169], v[202:205], v[124:127]
	v_mfma_f32_16x16x32_bf16 v[120:123], v[174:177], v[202:205], v[120:123]
	v_mfma_f32_16x16x32_bf16 v[112:115], v[174:177], v[210:213], v[112:115]
	v_mfma_f32_16x16x32_bf16 v[116:119], v[166:169], v[210:213], v[116:119]
	v_mfma_f32_16x16x32_bf16 v[108:111], v[166:169], v[218:221], v[108:111]
	v_mfma_f32_16x16x32_bf16 v[104:107], v[174:177], v[218:221], v[104:107]
	v_mfma_f32_16x16x32_bf16 v[96:99], v[174:177], v[226:229], v[96:99]
	v_mfma_f32_16x16x32_bf16 v[100:103], v[166:169], v[226:229], v[100:103]
	s_barrier
	v_readfirstlane_b32 s14, v154
	v_add_u32_e32 v186, 0x2000, v154
	v_lshl_add_u64 v[250:251], v[246:247], 0, vcc
	s_mov_b32 m0, s14
	v_readfirstlane_b32 s14, v186
	ds_read_b128 v[230:233], v152
	ds_read_b128 v[234:237], v152 offset:1024
	ds_read_b128 v[238:241], v152 offset:2048
	ds_read_b128 v[242:245], v152 offset:3072
	global_load_lds_dwordx4 v[250:251], off
	v_lshl_add_u64 v[250:251], v[248:249], 0, vcc
	s_mov_b32 m0, s14
	s_nop 0
	global_load_lds_dwordx4 v[250:251], off
	s_barrier
	s_waitcnt lgkmcnt(0)
	v_mfma_f32_16x16x32_bf16 v[92:95], v[230:233], v[198:201], v[92:95]
	v_mfma_f32_16x16x32_bf16 v[88:91], v[238:241], v[198:201], v[88:91]
	v_mfma_f32_16x16x32_bf16 v[80:83], v[238:241], v[206:209], v[80:83]
	v_mfma_f32_16x16x32_bf16 v[84:87], v[230:233], v[206:209], v[84:87]
	v_mfma_f32_16x16x32_bf16 v[76:79], v[230:233], v[214:217], v[76:79]
	v_mfma_f32_16x16x32_bf16 v[72:75], v[238:241], v[214:217], v[72:75]
	v_mfma_f32_16x16x32_bf16 v[64:67], v[238:241], v[222:225], v[64:67]
	v_mfma_f32_16x16x32_bf16 v[68:71], v[230:233], v[222:225], v[68:71]
	v_mfma_f32_16x16x32_bf16 v[92:95], v[234:237], v[202:205], v[92:95]
	v_mfma_f32_16x16x32_bf16 v[88:91], v[242:245], v[202:205], v[88:91]
	v_mfma_f32_16x16x32_bf16 v[80:83], v[242:245], v[210:213], v[80:83]
	v_mfma_f32_16x16x32_bf16 v[84:87], v[234:237], v[210:213], v[84:87]
	v_mfma_f32_16x16x32_bf16 v[76:79], v[234:237], v[218:221], v[76:79]
	v_mfma_f32_16x16x32_bf16 v[72:75], v[242:245], v[218:221], v[72:75]
	v_mfma_f32_16x16x32_bf16 v[64:67], v[242:245], v[226:229], v[64:67]
	v_mfma_f32_16x16x32_bf16 v[68:71], v[234:237], v[226:229], v[68:71]
	v_readfirstlane_b32 s14, v155
	v_lshl_add_u64 v[178:179], v[178:179], 0, s[64:65]
	s_mov_b32 m0, s14
	v_readfirstlane_b32 s14, v157
	s_barrier
	ds_read_b128 v[198:201], v151 offset:49152
	ds_read_b128 v[202:205], v151 offset:50176
	ds_read_b128 v[206:209], v150 offset:49152
	ds_read_b128 v[210:213], v150 offset:50176
	ds_read_b128 v[214:217], v149 offset:49152
	ds_read_b128 v[218:221], v149 offset:50176
	ds_read_b128 v[222:225], v148 offset:49152
	ds_read_b128 v[226:229], v148 offset:50176
	global_load_lds_dwordx4 v[178:179], off
	v_lshl_add_u64 v[178:179], v[188:189], 0, s[64:65]
	s_mov_b32 m0, s14
	s_nop 0
	global_load_lds_dwordx4 v[178:179], off
	s_barrier
; #define WAIT_V(n) asm volatile("s_waitcnt vmcnt(" #n ")" ::: "memory")
; #define WAIT_L(n) asm volatile("s_waitcnt lgkmcnt(" #n ")" ::: "memory")
; #define BAR __builtin_amdgcn_s_barrier()
; #define SCHED __builtin_amdgcn_sched_barrier(0)
; #define LDA(dst, b, h)                                                                            \
;   _Pragma("unroll") for (int m = 0; m < 4; ++m) _Pragma("unroll") for (int k = 0; k < 2; ++k)                                         \
;     dst[m][k] = *reinterpret_cast<const bf16x8*>((char*)SA(b, h) + lds_byte(wr * 64 + m * 16 + fr, k * 32 + fq * 8))
; #define LDB(dst, b, h)                                                                            \
;   _Pragma("unroll") for (int n = 0; n < 2; ++n) _Pragma("unroll") for (int k = 0; k < 2; ++k)                                         \
;     dst[n][k] = *reinterpret_cast<const bf16x8*>((char*)SB(b, h) + lds_byte(wc * 32 + n * 16 + fr, k * 32 + fq * 8))
; template <int K, bool SWAP>
; __device__ __forceinline__ void gemm_kloop(const bf16* __restrict__ A, const bf16* __restrict__ Bt,
;                                            f32x4 (&acc)[2][2][4][2], bool pref = false) {
;     ...
;     BAR; WAIT_L(0); MMA(1, 0, At, B0); BAR; SCHED;
;     STAGE(SB(1, 1), Bt, HALF, t + 3);
;     WAIT_V(6); BAR; MMA(1, 1, At, B1); BAR;
;   }
;   { LDB(B0, 0, 0); LDA(At, 0, 0); STAGE(SA(1, 1), A, HALF, nt - 1);
;     BAR; WAIT_L(0); MMA(0, 0, At, B0); BAR;
;     LDB(B1, 0, 1); BAR; WAIT_L(0); MMA(0, 1, At, B1); BAR;
	s_waitcnt lgkmcnt(0)
	v_mfma_f32_16x16x32_bf16 v[60:63], v[162:165], v[198:201], v[60:63]
	v_mfma_f32_16x16x32_bf16 v[56:59], v[170:173], v[198:201], v[56:59]
	v_mfma_f32_16x16x32_bf16 v[48:51], v[170:173], v[206:209], v[48:51]
	v_mfma_f32_16x16x32_bf16 v[52:55], v[162:165], v[206:209], v[52:55]
	v_mfma_f32_16x16x32_bf16 v[44:47], v[162:165], v[214:217], v[44:47]
	v_mfma_f32_16x16x32_bf16 v[40:43], v[170:173], v[214:217], v[40:43]
	v_mfma_f32_16x16x32_bf16 v[32:35], v[170:173], v[222:225], v[32:35]
	v_mfma_f32_16x16x32_bf16 v[36:39], v[162:165], v[222:225], v[36:39]
	v_mfma_f32_16x16x32_bf16 v[60:63], v[166:169], v[202:205], v[60:63]
	v_mfma_f32_16x16x32_bf16 v[56:59], v[174:177], v[202:205], v[56:59]
	v_mfma_f32_16x16x32_bf16 v[48:51], v[174:177], v[210:213], v[48:51]
	v_mfma_f32_16x16x32_bf16 v[52:55], v[166:169], v[210:213], v[52:55]
	v_mfma_f32_16x16x32_bf16 v[44:47], v[166:169], v[218:221], v[44:47]
	v_mfma_f32_16x16x32_bf16 v[40:43], v[174:177], v[218:221], v[40:43]
	v_mfma_f32_16x16x32_bf16 v[32:35], v[174:177], v[226:229], v[32:35]
	v_mfma_f32_16x16x32_bf16 v[36:39], v[166:169], v[226:229], v[36:39]
	s_barrier
	v_readfirstlane_b32 s14, v158
	v_add_u32_e32 v164, 0x2000, v158
	v_lshl_add_u64 v[162:163], v[246:247], 0, s[70:71]
	s_mov_b32 m0, s14
	v_readfirstlane_b32 s14, v164
	global_load_lds_dwordx4 v[162:163], off
	v_lshl_add_u64 v[162:163], v[248:249], 0, s[70:71]
	s_mov_b32 m0, s14
	s_nop 0
	global_load_lds_dwordx4 v[162:163], off
	s_waitcnt vmcnt(6)
	s_barrier
	v_mfma_f32_16x16x32_bf16 v[28:31], v[230:233], v[198:201], v[28:31]
	v_mfma_f32_16x16x32_bf16 v[24:27], v[238:241], v[198:201], v[24:27]
	v_mfma_f32_16x16x32_bf16 v[16:19], v[238:241], v[206:209], v[16:19]
	v_mfma_f32_16x16x32_bf16 v[20:23], v[230:233], v[206:209], v[20:23]
	v_mfma_f32_16x16x32_bf16 v[12:15], v[230:233], v[214:217], v[12:15]
	v_mfma_f32_16x16x32_bf16 v[8:11], v[238:241], v[214:217], v[8:11]
	v_mfma_f32_16x16x32_bf16 v[0:3], v[238:241], v[222:225], v[0:3]
	v_mfma_f32_16x16x32_bf16 v[4:7], v[230:233], v[222:225], v[4:7]
	v_mfma_f32_16x16x32_bf16 v[28:31], v[234:237], v[202:205], v[28:31]
	v_mfma_f32_16x16x32_bf16 v[24:27], v[242:245], v[202:205], v[24:27]
	v_mfma_f32_16x16x32_bf16 v[16:19], v[242:245], v[210:213], v[16:19]
	v_mfma_f32_16x16x32_bf16 v[20:23], v[234:237], v[210:213], v[20:23]
	v_mfma_f32_16x16x32_bf16 v[12:15], v[234:237], v[218:221], v[12:15]
	v_mfma_f32_16x16x32_bf16 v[8:11], v[242:245], v[218:221], v[8:11]
	v_mfma_f32_16x16x32_bf16 v[0:3], v[242:245], v[226:229], v[0:3]
	v_mfma_f32_16x16x32_bf16 v[4:7], v[234:237], v[226:229], v[4:7]
	s_add_i32 s5, s5, 2
	v_lshl_add_u64 v[136:137], v[136:137], 0, s[44:45]
	v_lshl_add_u64 v[138:139], v[138:139], 0, s[44:45]
	v_lshl_add_u64 v[140:141], v[140:141], 0, s[44:45]
	s_cmp_lt_u32 s5, 60
	v_lshl_add_u64 v[142:143], v[142:143], 0, s[44:45]
	s_barrier
	s_cbranch_scc1 .LBB0_590
	s_add_u32 s12, s12, 0x101f80
	s_addc_u32 s13, s13, 0
	v_lshl_add_u64 v[130:131], s[12:13], 0, v[130:131]
	v_readfirstlane_b32 s5, v160
	v_lshl_add_u64 v[128:129], v[128:129], 1, v[130:131]
	s_mov_b32 m0, s5
	ds_read_b128 v[136:139], v159
	ds_read_b128 v[140:143], v159 offset:1024
	ds_read_b128 v[162:165], v159 offset:2048
	ds_read_b128 v[166:169], v159 offset:3072
	ds_read_b128 v[170:173], v151
	ds_read_b128 v[174:177], v151 offset:1024
	ds_read_b128 v[198:201], v150
	ds_read_b128 v[202:205], v150 offset:1024
	ds_read_b128 v[206:209], v149
	ds_read_b128 v[210:213], v149 offset:1024
	ds_read_b128 v[214:217], v148
	ds_read_b128 v[218:221], v148 offset:1024
	global_load_lds_dwordx4 v[128:129], off
	v_lshl_add_u64 v[128:129], s[12:13], 0, v[134:135]
	v_readfirstlane_b32 s5, v161
	v_lshl_add_u64 v[128:129], v[132:133], 1, v[128:129]
	s_mov_b32 m0, s5
	s_nop 0
	global_load_lds_dwordx4 v[128:129], off
	s_barrier
	s_waitcnt lgkmcnt(0)
	v_mfma_f32_16x16x32_bf16 v[124:127], v[136:139], v[170:173], v[124:127]
	v_mfma_f32_16x16x32_bf16 v[120:123], v[162:165], v[170:173], v[120:123]
	v_mfma_f32_16x16x32_bf16 v[112:115], v[162:165], v[198:201], v[112:115]
	v_mfma_f32_16x16x32_bf16 v[116:119], v[136:139], v[198:201], v[116:119]
	v_mfma_f32_16x16x32_bf16 v[108:111], v[136:139], v[206:209], v[108:111]
	v_mfma_f32_16x16x32_bf16 v[104:107], v[162:165], v[206:209], v[104:107]
	v_mfma_f32_16x16x32_bf16 v[96:99], v[162:165], v[214:217], v[96:99]
	v_mfma_f32_16x16x32_bf16 v[100:103], v[136:139], v[214:217], v[100:103]
	v_mfma_f32_16x16x32_bf16 v[124:127], v[140:143], v[174:177], v[124:127]
	v_mfma_f32_16x16x32_bf16 v[120:123], v[166:169], v[174:177], v[120:123]
	v_mfma_f32_16x16x32_bf16 v[112:115], v[166:169], v[202:205], v[112:115]
	v_mfma_f32_16x16x32_bf16 v[116:119], v[140:143], v[202:205], v[116:119]
	v_mfma_f32_16x16x32_bf16 v[108:111], v[140:143], v[210:213], v[108:111]
	v_mfma_f32_16x16x32_bf16 v[104:107], v[166:169], v[210:213], v[104:107]
	v_mfma_f32_16x16x32_bf16 v[96:99], v[166:169], v[218:221], v[96:99]
	v_mfma_f32_16x16x32_bf16 v[100:103], v[140:143], v[218:221], v[100:103]
	s_barrier
	ds_read_b128 v[128:131], v156
	ds_read_b128 v[132:135], v156 offset:1024
	ds_read_b128 v[158:161], v156 offset:2048
	ds_read_b128 v[154:157], v156 offset:3072
	s_barrier
; #define WAIT_V(n) asm volatile("s_waitcnt vmcnt(" #n ")" ::: "memory")
; #define WAIT_L(n) asm volatile("s_waitcnt lgkmcnt(" #n ")" ::: "memory")
; #define BAR __builtin_amdgcn_s_barrier()
; #define LDA(dst, b, h)                                                                            \
;   _Pragma("unroll") for (int m = 0; m < 4; ++m) _Pragma("unroll") for (int k = 0; k < 2; ++k)                                         \
;     dst[m][k] = *reinterpret_cast<const bf16x8*>((char*)SA(b, h) + lds_byte(wr * 64 + m * 16 + fr, k * 32 + fq * 8))
; #define LDB(dst, b, h)                                                                            \
;   _Pragma("unroll") for (int n = 0; n < 2; ++n) _Pragma("unroll") for (int k = 0; k < 2; ++k)                                         \
;     dst[n][k] = *reinterpret_cast<const bf16x8*>((char*)SB(b, h) + lds_byte(wc * 32 + n * 16 + fr, k * 32 + fq * 8))
; template <int K, bool SWAP>
; __device__ __forceinline__ void gemm_kloop(const bf16* __restrict__ A, const bf16* __restrict__ Bt,
;                                            f32x4 (&acc)[2][2][4][2], bool pref = false) {
;     ...
;     LDB(B1, 0, 1); BAR; WAIT_L(0); MMA(0, 1, At, B1); BAR;
;     LDA(At, 0, 1); WAIT_V(4); BAR; WAIT_L(0); MMA(1, 0, At, B0); MMA(1, 1, At, B1); BAR; }
;   { LDB(B0, 1, 0); LDA(At, 1, 0); WAIT_V(2); BAR; WAIT_L(0); MMA(0, 0, At, B0); BAR;
	s_waitcnt lgkmcnt(0)
	v_mfma_f32_16x16x32_bf16 v[92:95], v[128:131], v[170:173], v[92:95]
	v_mfma_f32_16x16x32_bf16 v[88:91], v[158:161], v[170:173], v[88:91]
	v_mfma_f32_16x16x32_bf16 v[80:83], v[158:161], v[198:201], v[80:83]
	v_mfma_f32_16x16x32_bf16 v[84:87], v[128:131], v[198:201], v[84:87]
	v_mfma_f32_16x16x32_bf16 v[76:79], v[128:131], v[206:209], v[76:79]
	v_mfma_f32_16x16x32_bf16 v[72:75], v[158:161], v[206:209], v[72:75]
	v_mfma_f32_16x16x32_bf16 v[64:67], v[158:161], v[214:217], v[64:67]
	v_mfma_f32_16x16x32_bf16 v[68:71], v[128:131], v[214:217], v[68:71]
	v_mfma_f32_16x16x32_bf16 v[92:95], v[132:135], v[174:177], v[92:95]
	v_mfma_f32_16x16x32_bf16 v[88:91], v[154:157], v[174:177], v[88:91]
	v_mfma_f32_16x16x32_bf16 v[80:83], v[154:157], v[202:205], v[80:83]
	v_mfma_f32_16x16x32_bf16 v[84:87], v[132:135], v[202:205], v[84:87]
	v_mfma_f32_16x16x32_bf16 v[76:79], v[132:135], v[210:213], v[76:79]
	v_mfma_f32_16x16x32_bf16 v[72:75], v[154:157], v[210:213], v[72:75]
	v_mfma_f32_16x16x32_bf16 v[64:67], v[154:157], v[218:221], v[64:67]
	v_mfma_f32_16x16x32_bf16 v[68:71], v[132:135], v[218:221], v[68:71]
	s_barrier
	ds_read_b128 v[170:173], v151 offset:16384
	ds_read_b128 v[174:177], v151 offset:17408
	ds_read_b128 v[198:201], v150 offset:16384
	ds_read_b128 v[202:205], v150 offset:17408
	ds_read_b128 v[206:209], v149 offset:16384
	ds_read_b128 v[210:213], v149 offset:17408
	ds_read_b128 v[214:217], v148 offset:16384
	ds_read_b128 v[218:221], v148 offset:17408
	s_waitcnt vmcnt(4)
	s_barrier
	s_waitcnt lgkmcnt(0)
	v_mfma_f32_16x16x32_bf16 v[60:63], v[136:139], v[170:173], v[60:63]
	v_mfma_f32_16x16x32_bf16 v[56:59], v[162:165], v[170:173], v[56:59]
	v_mfma_f32_16x16x32_bf16 v[48:51], v[162:165], v[198:201], v[48:51]
	v_mfma_f32_16x16x32_bf16 v[52:55], v[136:139], v[198:201], v[52:55]
	v_mfma_f32_16x16x32_bf16 v[44:47], v[136:139], v[206:209], v[44:47]
	v_mfma_f32_16x16x32_bf16 v[40:43], v[162:165], v[206:209], v[40:43]
	v_mfma_f32_16x16x32_bf16 v[32:35], v[162:165], v[214:217], v[32:35]
	v_mfma_f32_16x16x32_bf16 v[36:39], v[136:139], v[214:217], v[36:39]
	v_mfma_f32_16x16x32_bf16 v[60:63], v[140:143], v[174:177], v[60:63]
	v_mfma_f32_16x16x32_bf16 v[56:59], v[166:169], v[174:177], v[56:59]
	v_mfma_f32_16x16x32_bf16 v[48:51], v[166:169], v[202:205], v[48:51]
	v_mfma_f32_16x16x32_bf16 v[52:55], v[140:143], v[202:205], v[52:55]
	v_mfma_f32_16x16x32_bf16 v[44:47], v[140:143], v[210:213], v[44:47]
	v_mfma_f32_16x16x32_bf16 v[40:43], v[166:169], v[210:213], v[40:43]
	v_mfma_f32_16x16x32_bf16 v[32:35], v[166:169], v[218:221], v[32:35]
	v_mfma_f32_16x16x32_bf16 v[36:39], v[140:143], v[218:221], v[36:39]
	v_mfma_f32_16x16x32_bf16 v[28:31], v[128:131], v[170:173], v[28:31]
	v_mfma_f32_16x16x32_bf16 v[24:27], v[158:161], v[170:173], v[24:27]
	v_mfma_f32_16x16x32_bf16 v[16:19], v[158:161], v[198:201], v[16:19]
	v_mfma_f32_16x16x32_bf16 v[20:23], v[128:131], v[198:201], v[20:23]
	v_mfma_f32_16x16x32_bf16 v[12:15], v[128:131], v[206:209], v[12:15]
	v_mfma_f32_16x16x32_bf16 v[8:11], v[158:161], v[206:209], v[8:11]
	v_mfma_f32_16x16x32_bf16 v[0:3], v[158:161], v[214:217], v[0:3]
	v_mfma_f32_16x16x32_bf16 v[4:7], v[128:131], v[214:217], v[4:7]
	v_mfma_f32_16x16x32_bf16 v[28:31], v[132:135], v[174:177], v[28:31]
	v_mfma_f32_16x16x32_bf16 v[24:27], v[154:157], v[174:177], v[24:27]
	v_mfma_f32_16x16x32_bf16 v[16:19], v[154:157], v[202:205], v[16:19]
	v_mfma_f32_16x16x32_bf16 v[20:23], v[132:135], v[202:205], v[20:23]
	v_mfma_f32_16x16x32_bf16 v[12:15], v[132:135], v[210:213], v[12:15]
	v_mfma_f32_16x16x32_bf16 v[8:11], v[154:157], v[210:213], v[8:11]
	v_mfma_f32_16x16x32_bf16 v[0:3], v[154:157], v[218:221], v[0:3]
	v_mfma_f32_16x16x32_bf16 v[4:7], v[132:135], v[218:221], v[4:7]
	s_barrier
	ds_read_b128 v[128:131], v153
	ds_read_b128 v[132:135], v153 offset:1024
	ds_read_b128 v[136:139], v153 offset:2048
	ds_read_b128 v[140:143], v153 offset:3072
	ds_read_b128 v[154:157], v151 offset:32768
	ds_read_b128 v[158:161], v151 offset:33792
	ds_read_b128 v[162:165], v150 offset:32768
	ds_read_b128 v[166:169], v150 offset:33792
	ds_read_b128 v[170:173], v149 offset:32768
	ds_read_b128 v[174:177], v149 offset:33792
	ds_read_b128 v[198:201], v148 offset:32768
	ds_read_b128 v[202:205], v148 offset:33792
	s_waitcnt vmcnt(2)
	s_barrier
; #define WAIT_V(n) asm volatile("s_waitcnt vmcnt(" #n ")" ::: "memory")
; #define WAIT_L(n) asm volatile("s_waitcnt lgkmcnt(" #n ")" ::: "memory")
; #define BAR __builtin_amdgcn_s_barrier()
; #define LDA(dst, b, h)                                                                            \
;   _Pragma("unroll") for (int m = 0; m < 4; ++m) _Pragma("unroll") for (int k = 0; k < 2; ++k)                                         \
;     dst[m][k] = *reinterpret_cast<const bf16x8*>((char*)SA(b, h) + lds_byte(wr * 64 + m * 16 + fr, k * 32 + fq * 8))
; #define LDB(dst, b, h)                                                                            \
;   _Pragma("unroll") for (int n = 0; n < 2; ++n) _Pragma("unroll") for (int k = 0; k < 2; ++k)                                         \
;     dst[n][k] = *reinterpret_cast<const bf16x8*>((char*)SB(b, h) + lds_byte(wc * 32 + n * 16 + fr, k * 32 + fq * 8))
; template <int K, bool SWAP>
; __device__ __forceinline__ void gemm_kloop(const bf16* __restrict__ A, const bf16* __restrict__ Bt,
;                                            f32x4 (&acc)[2][2][4][2], bool pref = false) {
;     ...
;   { LDB(B0, 1, 0); LDA(At, 1, 0); WAIT_V(2); BAR; WAIT_L(0); MMA(0, 0, At, B0); BAR;
;     LDB(B1, 1, 1); WAIT_V(0); BAR; WAIT_L(0); MMA(0, 1, At, B1); BAR;
;     LDA(At, 1, 1); BAR; WAIT_L(0); MMA(1, 0, At, B0); MMA(1, 1, At, B1); BAR; }
;   if (wr == 0) BAR;
	s_waitcnt lgkmcnt(0)
	v_mfma_f32_16x16x32_bf16 v[124:127], v[128:131], v[154:157], v[124:127]
	v_mfma_f32_16x16x32_bf16 v[120:123], v[136:139], v[154:157], v[120:123]
	v_mfma_f32_16x16x32_bf16 v[112:115], v[136:139], v[162:165], v[112:115]
	v_mfma_f32_16x16x32_bf16 v[116:119], v[128:131], v[162:165], v[116:119]
	v_mfma_f32_16x16x32_bf16 v[108:111], v[128:131], v[170:173], v[108:111]
	v_mfma_f32_16x16x32_bf16 v[104:107], v[136:139], v[170:173], v[104:107]
	v_mfma_f32_16x16x32_bf16 v[96:99], v[136:139], v[198:201], v[96:99]
	v_mfma_f32_16x16x32_bf16 v[100:103], v[128:131], v[198:201], v[100:103]
	v_mfma_f32_16x16x32_bf16 v[124:127], v[132:135], v[158:161], v[124:127]
	v_mfma_f32_16x16x32_bf16 v[120:123], v[140:143], v[158:161], v[120:123]
	v_mfma_f32_16x16x32_bf16 v[112:115], v[140:143], v[166:169], v[112:115]
	v_mfma_f32_16x16x32_bf16 v[116:119], v[132:135], v[166:169], v[116:119]
	v_mfma_f32_16x16x32_bf16 v[108:111], v[132:135], v[174:177], v[108:111]
	v_mfma_f32_16x16x32_bf16 v[104:107], v[140:143], v[174:177], v[104:107]
	v_mfma_f32_16x16x32_bf16 v[96:99], v[140:143], v[202:205], v[96:99]
	v_mfma_f32_16x16x32_bf16 v[100:103], v[132:135], v[202:205], v[100:103]
	s_barrier
	ds_read_b128 v[206:209], v152
	ds_read_b128 v[210:213], v152 offset:1024
	ds_read_b128 v[214:217], v152 offset:2048
	ds_read_b128 v[218:221], v152 offset:3072
	s_waitcnt vmcnt(0)
	s_barrier
	s_waitcnt lgkmcnt(0)
	v_mfma_f32_16x16x32_bf16 v[92:95], v[206:209], v[154:157], v[92:95]
	v_mfma_f32_16x16x32_bf16 v[88:91], v[214:217], v[154:157], v[88:91]
	v_mfma_f32_16x16x32_bf16 v[80:83], v[214:217], v[162:165], v[80:83]
	v_mfma_f32_16x16x32_bf16 v[84:87], v[206:209], v[162:165], v[84:87]
	v_mfma_f32_16x16x32_bf16 v[76:79], v[206:209], v[170:173], v[76:79]
	v_mfma_f32_16x16x32_bf16 v[72:75], v[214:217], v[170:173], v[72:75]
	v_mfma_f32_16x16x32_bf16 v[64:67], v[214:217], v[198:201], v[64:67]
	v_mfma_f32_16x16x32_bf16 v[68:71], v[206:209], v[198:201], v[68:71]
	v_mfma_f32_16x16x32_bf16 v[92:95], v[210:213], v[158:161], v[92:95]
	v_mfma_f32_16x16x32_bf16 v[88:91], v[218:221], v[158:161], v[88:91]
	v_mfma_f32_16x16x32_bf16 v[80:83], v[218:221], v[166:169], v[80:83]
	v_mfma_f32_16x16x32_bf16 v[84:87], v[210:213], v[166:169], v[84:87]
	v_mfma_f32_16x16x32_bf16 v[76:79], v[210:213], v[174:177], v[76:79]
	v_mfma_f32_16x16x32_bf16 v[72:75], v[218:221], v[174:177], v[72:75]
	v_mfma_f32_16x16x32_bf16 v[64:67], v[218:221], v[202:205], v[64:67]
	v_mfma_f32_16x16x32_bf16 v[68:71], v[210:213], v[202:205], v[68:71]
	s_barrier
	ds_read_b128 v[152:155], v151 offset:49152
	ds_read_b128 v[156:159], v151 offset:50176
	ds_read_b128 v[160:163], v150 offset:49152
	ds_read_b128 v[164:167], v150 offset:50176
	ds_read_b128 v[168:171], v149 offset:49152
	ds_read_b128 v[172:175], v149 offset:50176
	ds_read_b128 v[176:179], v148 offset:49152
	ds_read_b128 v[146:149], v148 offset:50176
	s_barrier
	s_waitcnt lgkmcnt(0)
	v_mfma_f32_16x16x32_bf16 v[60:63], v[128:131], v[152:155], v[60:63]
	v_mfma_f32_16x16x32_bf16 v[56:59], v[136:139], v[152:155], v[56:59]
	v_mfma_f32_16x16x32_bf16 v[48:51], v[136:139], v[160:163], v[48:51]
	v_mfma_f32_16x16x32_bf16 v[52:55], v[128:131], v[160:163], v[52:55]
	v_mfma_f32_16x16x32_bf16 v[44:47], v[128:131], v[168:171], v[44:47]
	v_mfma_f32_16x16x32_bf16 v[40:43], v[136:139], v[168:171], v[40:43]
	v_mfma_f32_16x16x32_bf16 v[32:35], v[136:139], v[176:179], v[32:35]
	v_mfma_f32_16x16x32_bf16 v[36:39], v[128:131], v[176:179], v[36:39]
	v_mfma_f32_16x16x32_bf16 v[60:63], v[132:135], v[156:159], v[60:63]
	v_mfma_f32_16x16x32_bf16 v[56:59], v[140:143], v[156:159], v[56:59]
	v_mfma_f32_16x16x32_bf16 v[48:51], v[140:143], v[164:167], v[48:51]
	v_mfma_f32_16x16x32_bf16 v[52:55], v[132:135], v[164:167], v[52:55]
	v_mfma_f32_16x16x32_bf16 v[44:47], v[132:135], v[172:175], v[44:47]
	v_mfma_f32_16x16x32_bf16 v[40:43], v[140:143], v[172:175], v[40:43]
	v_mfma_f32_16x16x32_bf16 v[32:35], v[140:143], v[146:149], v[32:35]
	v_mfma_f32_16x16x32_bf16 v[36:39], v[132:135], v[146:149], v[36:39]
	v_mfma_f32_16x16x32_bf16 v[28:31], v[206:209], v[152:155], v[28:31]
	v_mfma_f32_16x16x32_bf16 v[24:27], v[214:217], v[152:155], v[24:27]
	v_mfma_f32_16x16x32_bf16 v[16:19], v[214:217], v[160:163], v[16:19]
	v_mfma_f32_16x16x32_bf16 v[20:23], v[206:209], v[160:163], v[20:23]
	v_mfma_f32_16x16x32_bf16 v[12:15], v[206:209], v[168:171], v[12:15]
	v_mfma_f32_16x16x32_bf16 v[8:11], v[214:217], v[168:171], v[8:11]
	v_mfma_f32_16x16x32_bf16 v[0:3], v[214:217], v[176:179], v[0:3]
	v_mfma_f32_16x16x32_bf16 v[4:7], v[206:209], v[176:179], v[4:7]
	v_mfma_f32_16x16x32_bf16 v[28:31], v[210:213], v[156:159], v[28:31]
	v_mfma_f32_16x16x32_bf16 v[24:27], v[218:221], v[156:159], v[24:27]
	v_mfma_f32_16x16x32_bf16 v[16:19], v[218:221], v[164:167], v[16:19]
	v_mfma_f32_16x16x32_bf16 v[20:23], v[210:213], v[164:167], v[20:23]
	v_mfma_f32_16x16x32_bf16 v[12:15], v[210:213], v[172:175], v[12:15]
	v_mfma_f32_16x16x32_bf16 v[8:11], v[218:221], v[172:175], v[8:11]
	v_mfma_f32_16x16x32_bf16 v[0:3], v[218:221], v[146:149], v[0:3]
	v_mfma_f32_16x16x32_bf16 v[4:7], v[210:213], v[146:149], v[4:7]
	s_movk_i32 s5, 0x100
	v_cmp_gt_u32_e32 vcc, s5, v144
	s_barrier
	s_and_saveexec_b64 s[12:13], vcc
	s_cbranch_execz .LBB0_593
	s_barrier

; #define WAIT_V(n) asm volatile("s_waitcnt vmcnt(" #n ")" ::: "memory")
; #define WAIT_L(n) asm volatile("s_waitcnt lgkmcnt(" #n ")" ::: "memory")
; #define BAR __builtin_amdgcn_s_barrier()
; #define SCHED __builtin_amdgcn_sched_barrier(0)
; #define LDA(dst, b, h)                                                                            \
;   _Pragma("unroll") for (int m = 0; m < 4; ++m) _Pragma("unroll") for (int k = 0; k < 2; ++k)                                         \
;     dst[m][k] = *reinterpret_cast<const bf16x8*>((char*)SA(b, h) + lds_byte(wr * 64 + m * 16 + fr, k * 32 + fq * 8))
; #define LDB(dst, b, h)                                                                            \
;   _Pragma("unroll") for (int n = 0; n < 2; ++n) _Pragma("unroll") for (int k = 0; k < 2; ++k)                                         \
;     dst[n][k] = *reinterpret_cast<const bf16x8*>((char*)SB(b, h) + lds_byte(wc * 32 + n * 16 + fr, k * 32 + fq * 8))
; template <int K, bool SWAP>
; __device__ __forceinline__ void gemm_kloop(const bf16* __restrict__ A, const bf16* __restrict__ Bt,
;                                            f32x4 (&acc)[2][2][4][2], bool pref = false) {
;     ...
;   if (wr == 1) BAR;
;   WAIT_V(4); BAR;
;   STAGE(SB(1, 0), Bt, 0, 1); STAGE(SA(1, 0), A, 0, 1); STAGE(SB(1, 1), Bt, HALF, 1);
;   WAIT_V(6); BAR;
;   for (int t = 0; t < nt - 2; t += 2) {
;     LDB(B0, 0, 0); SCHED; LDA(At, 0, 0); STAGE(SA(1, 1), A, HALF, t + 1);
;     WAIT_L(8); BAR; WAIT_L(0); MMA(0, 0, At, B0); BAR; SCHED;
;     LDB(B1, 0, 1); STAGE(SB(0, 0), Bt, 0, t + 2);
.LBB0_671:
	s_or_b64 exec, exec, s[0:1]
	v_add_u32_e32 v0, v15, v0
	v_and_b32_e32 v0, 0xfffffc00, v0
	v_sub_u32_e32 v0, v15, v0
	v_lshrrev_b32_e32 v2, 4, v0
	v_bitop3_b32 v2, v2, v0, 32 bitop3:0x6c
	v_ashrrev_i32_e32 v3, 31, v2
	v_add_u32_e32 v1, v128, v1
	v_lshrrev_b32_e32 v3, 26, v3
	v_ashrrev_i32_e32 v1, 6, v1
	v_add_u32_e32 v3, v2, v3
	v_lshlrev_b32_e32 v0, 3, v1
	v_ashrrev_i32_e32 v4, 6, v3
	v_and_b32_e32 v3, 0xc0, v3
	v_and_b32_e32 v0, -16, v0
	v_lshlrev_b32_e32 v1, 5, v1
	v_sub_u32_e32 v2, v2, v3
	v_add_u32_e32 v0, v4, v0
	v_and_b32_e32 v1, 32, v1
	v_ashrrev_i16_sdwa v2, v193, sext(v2) dst_sel:DWORD dst_unused:UNUSED_PAD src0_sel:DWORD src1_sel:BYTE_0
	v_add_u32_sdwa v2, v1, sext(v2) dst_sel:DWORD dst_unused:UNUSED_PAD src0_sel:DWORD src1_sel:WORD_0
	v_ashrrev_i32_e32 v1, 31, v0
	v_lshlrev_b64 v[0:1], 9, v[0:1]
	v_ashrrev_i32_e32 v3, 31, v2
	v_readlane_b32 s68, v254, 33
	v_lshl_add_u64 v[4:5], s[58:59], 0, v[0:1]
	v_lshlrev_b64 v[2:3], 1, v[2:3]
	v_add_u32_e32 v6, s68, v15
	v_lshl_add_u64 v[8:9], v[4:5], 0, v[2:3]
	s_mov_b64 s[0:1], 0x80
	v_readfirstlane_b32 s63, v6
	v_lshl_add_u64 v[4:5], v[8:9], 0, s[0:1]
	s_mov_b32 m0, s63
	s_waitcnt vmcnt(4)
	s_barrier
	global_load_lds_dwordx4 v[4:5], off
	v_ashrrev_i32_e32 v4, 31, v13
	v_lshrrev_b32_e32 v4, 22, v4
	v_add_u32_e32 v4, v13, v4
	v_ashrrev_i32_e32 v5, 10, v4
	v_mul_i32_i24_e32 v4, 0x400, v5
	v_sub_u32_e32 v4, v13, v4
	v_lshrrev_b32_e32 v6, 4, v4
	v_bitop3_b32 v6, v6, v4, 32 bitop3:0x6c
	v_ashrrev_i32_e32 v7, 31, v6
	v_lshrrev_b32_e32 v7, 26, v7
	v_add_u32_e32 v7, v6, v7
	v_lshlrev_b32_e32 v4, 3, v5
	v_ashrrev_i32_e32 v10, 6, v7
	v_and_b32_e32 v7, 0xc0, v7
	v_and_b32_e32 v4, -16, v4
	v_lshlrev_b32_e32 v5, 5, v5
	v_sub_u32_e32 v6, v6, v7
	v_add_u32_e32 v4, v10, v4
	v_and_b32_e32 v5, 32, v5
	v_ashrrev_i16_sdwa v6, v193, sext(v6) dst_sel:DWORD dst_unused:UNUSED_PAD src0_sel:DWORD src1_sel:BYTE_0
	v_add_u32_sdwa v6, v5, sext(v6) dst_sel:DWORD dst_unused:UNUSED_PAD src0_sel:DWORD src1_sel:WORD_0
	v_ashrrev_i32_e32 v5, 31, v4
	v_lshlrev_b64 v[4:5], 9, v[4:5]
	v_ashrrev_i32_e32 v7, 31, v6
	v_lshl_add_u64 v[10:11], s[58:59], 0, v[4:5]
	v_lshlrev_b64 v[6:7], 1, v[6:7]
	v_lshl_add_u64 v[10:11], v[10:11], 0, v[6:7]
	v_add_u32_e32 v17, s68, v13
	v_lshl_add_u64 v[18:19], v[10:11], 0, s[0:1]
	v_readfirstlane_b32 s67, v17
	v_readlane_b32 s0, v254, 50
	s_mov_b32 m0, s67
	v_readlane_b32 s1, v254, 51
	v_add_u32_e32 v17, 0x8000, v12
	global_load_lds_dwordx4 v[18:19], off
	v_lshl_add_u64 v[18:19], s[0:1], 0, v[0:1]
	v_readfirstlane_b32 s65, v17
	v_lshl_add_u64 v[18:19], v[18:19], 0, v[2:3]
	s_mov_b32 m0, s65
	v_add_u32_e32 v17, 0xa000, v12
	global_load_lds_dwordx4 v[18:19], off
	v_lshl_add_u64 v[18:19], s[0:1], 0, v[4:5]
	v_readfirstlane_b32 s61, v17
	s_add_u32 s0, s58, 0x10080
	v_readlane_b32 s69, v254, 34
	v_lshl_add_u64 v[18:19], v[18:19], 0, v[6:7]
	s_mov_b32 m0, s61
	s_addc_u32 s1, s59, 0
	v_add_u32_e32 v17, s69, v15
	global_load_lds_dwordx4 v[18:19], off
	v_lshl_add_u64 v[18:19], s[0:1], 0, v[0:1]
	v_readfirstlane_b32 s41, v17
	v_lshl_add_u64 v[18:19], v[18:19], 0, v[2:3]
	s_mov_b32 m0, s41
	v_add_u32_e32 v17, s69, v13
	global_load_lds_dwordx4 v[18:19], off
	v_lshl_add_u64 v[18:19], s[0:1], 0, v[4:5]
	v_readfirstlane_b32 s23, v17
	v_lshl_add_u64 v[18:19], v[18:19], 0, v[6:7]
	s_mov_b32 m0, s23
	v_and_b32_e32 v17, 15, v128
	global_load_lds_dwordx4 v[18:19], off
	v_lshlrev_b32_e32 v18, 2, v128
	v_and_b32_e32 v42, 48, v128
	v_lshlrev_b32_e32 v17, 6, v17
	v_and_b32_e32 v43, 32, v18
	v_bitop3_b32 v126, v17, v43, v42 bitop3:0x36
	v_lshlrev_b32_e32 v17, 6, v128
	s_add_i32 s40, 0, 0x10000
	v_and_b32_e32 v127, 0x3000, v17
	v_add3_u32 v129, s40, v126, v127
	s_waitcnt vmcnt(6)
	s_barrier
	ds_read_b128 v[18:21], v129
	ds_read_b128 v[22:25], v129 offset:1024
	ds_read_b128 v[26:29], v129 offset:2048
	ds_read_b128 v[30:33], v129 offset:3072
	s_add_u32 s0, s58, 0x10180
	s_addc_u32 s1, s59, 0
	v_and_b32_e32 v17, 0x3c0, v17
	v_lshlrev_b32_e32 v16, 13, v16
	v_bitop3_b32 v17, v17, v43, v42 bitop3:0x36
	s_mov_b64 s[70:71], s[72:73]
	v_add_u32_e32 v66, 0xc000, v12
	v_add3_u32 v178, 0, v126, v16
	v_add3_u32 v179, 0, v17, v16
	v_lshl_add_u64 v[16:17], s[70:71], 0, v[0:1]
	v_readfirstlane_b32 s66, v66
	v_lshl_add_u64 v[16:17], v[16:17], 0, v[2:3]
	s_mov_b32 m0, s66
	v_add_u32_e32 v66, 0xe000, v12
	ds_read_b128 v[34:37], v178
	ds_read_b128 v[38:41], v178 offset:1024
	ds_read_b128 v[42:45], v179 offset:2048
	ds_read_b128 v[46:49], v179 offset:3072
	ds_read_b128 v[50:53], v179 offset:4096
	ds_read_b128 v[54:57], v179 offset:5120
	ds_read_b128 v[58:61], v179 offset:6144
	ds_read_b128 v[62:65], v179 offset:7168
	global_load_lds_dwordx4 v[16:17], off
	v_lshl_add_u64 v[16:17], s[70:71], 0, v[4:5]
	v_readfirstlane_b32 s64, v66
	v_lshl_add_u64 v[16:17], v[16:17], 0, v[6:7]
	s_mov_b32 m0, s64
	s_add_u32 s58, s58, 0x10100
	global_load_lds_dwordx4 v[16:17], off
	s_waitcnt lgkmcnt(8)
	s_barrier
	s_waitcnt lgkmcnt(0)
	s_addc_u32 s59, s59, 0
	s_waitcnt lgkmcnt(0)
	v_mfma_f32_16x16x32_bf16 v[66:69], v[18:21], v[34:37], 0
	v_mfma_f32_16x16x32_bf16 v[70:73], v[26:29], v[34:37], 0
	v_mfma_f32_16x16x32_bf16 v[74:77], v[18:21], v[42:45], 0
	v_mfma_f32_16x16x32_bf16 v[78:81], v[26:29], v[42:45], 0
	v_mfma_f32_16x16x32_bf16 v[82:85], v[18:21], v[50:53], 0
	v_mfma_f32_16x16x32_bf16 v[86:89], v[26:29], v[50:53], 0
	v_mfma_f32_16x16x32_bf16 v[90:93], v[18:21], v[58:61], 0
	v_mfma_f32_16x16x32_bf16 v[94:97], v[26:29], v[58:61], 0
	v_mfma_f32_16x16x32_bf16 v[66:69], v[22:25], v[38:41], v[66:69]
	v_mfma_f32_16x16x32_bf16 v[70:73], v[30:33], v[38:41], v[70:73]
	v_mfma_f32_16x16x32_bf16 v[74:77], v[22:25], v[46:49], v[74:77]
	v_mfma_f32_16x16x32_bf16 v[78:81], v[30:33], v[46:49], v[78:81]
	v_mfma_f32_16x16x32_bf16 v[82:85], v[22:25], v[54:57], v[82:85]
	v_mfma_f32_16x16x32_bf16 v[86:89], v[30:33], v[54:57], v[86:89]
	v_mfma_f32_16x16x32_bf16 v[90:93], v[22:25], v[62:65], v[90:93]
	v_mfma_f32_16x16x32_bf16 v[94:97], v[30:33], v[62:65], v[94:97]
	s_barrier
; #define WAIT_V(n) asm volatile("s_waitcnt vmcnt(" #n ")" ::: "memory")
; #define WAIT_L(n) asm volatile("s_waitcnt lgkmcnt(" #n ")" ::: "memory")
; #define BAR __builtin_amdgcn_s_barrier()
; #define SCHED __builtin_amdgcn_sched_barrier(0)
; #define LDA(dst, b, h)                                                                            \
;   _Pragma("unroll") for (int m = 0; m < 4; ++m) _Pragma("unroll") for (int k = 0; k < 2; ++k)                                         \
;     dst[m][k] = *reinterpret_cast<const bf16x8*>((char*)SA(b, h) + lds_byte(wr * 64 + m * 16 + fr, k * 32 + fq * 8))
; #define LDB(dst, b, h)                                                                            \
;   _Pragma("unroll") for (int n = 0; n < 2; ++n) _Pragma("unroll") for (int k = 0; k < 2; ++k)                                         \
;     dst[n][k] = *reinterpret_cast<const bf16x8*>((char*)SB(b, h) + lds_byte(wc * 32 + n * 16 + fr, k * 32 + fq * 8))
; template <int K, bool SWAP>
; __device__ __forceinline__ void gemm_kloop(const bf16* __restrict__ A, const bf16* __restrict__ Bt,
;                                            f32x4 (&acc)[2][2][4][2], bool pref = false) {
;     ...
;     LDB(B0, 0, 0); SCHED; LDA(At, 0, 0); STAGE(SA(1, 1), A, HALF, t + 1);
;     WAIT_L(8); BAR; WAIT_L(0); MMA(0, 0, At, B0); BAR; SCHED;
;     LDB(B1, 0, 1); STAGE(SB(0, 0), Bt, 0, t + 2);
;     BAR; WAIT_L(0); MMA(0, 1, At, B1); BAR;
;     LDA(At, 0, 1); STAGE(SA(0, 0), A, 0, t + 2);
;     BAR; WAIT_L(0); MMA(1, 0, At, B0); BAR; SCHED;
;     STAGE(SB(0, 1), Bt, HALF, t + 2);
;     WAIT_V(6); BAR; MMA(1, 1, At, B1); BAR;
;     LDB(B0, 1, 0); SCHED; LDA(At, 1, 0); STAGE(SA(0, 1), A, HALF, t + 2);
	v_add_u32_e32 v15, s40, v15
	v_add3_u32 v186, s33, v126, v127
	v_readfirstlane_b32 s70, v15
	v_add_u32_e32 v15, s40, v13
	v_lshl_add_u64 v[16:17], v[8:9], 0, s[44:45]
	s_mov_b32 m0, s70
	v_readfirstlane_b32 s70, v15
	ds_read_b128 v[98:101], v186
	ds_read_b128 v[102:105], v186 offset:1024
	ds_read_b128 v[106:109], v186 offset:2048
	ds_read_b128 v[110:113], v186 offset:3072
	global_load_lds_dwordx4 v[16:17], off
	v_lshl_add_u64 v[16:17], v[10:11], 0, s[44:45]
	s_mov_b32 m0, s70
	s_nop 0
	global_load_lds_dwordx4 v[16:17], off
	s_barrier
	s_waitcnt lgkmcnt(0)
	v_mfma_f32_16x16x32_bf16 v[114:117], v[98:101], v[34:37], 0
	v_mfma_f32_16x16x32_bf16 v[34:37], v[106:109], v[34:37], 0
	v_mfma_f32_16x16x32_bf16 v[114:117], v[102:105], v[38:41], v[114:117]
	v_mfma_f32_16x16x32_bf16 v[34:37], v[110:113], v[38:41], v[34:37]
	v_mfma_f32_16x16x32_bf16 v[38:41], v[98:101], v[42:45], 0
	v_mfma_f32_16x16x32_bf16 v[42:45], v[106:109], v[42:45], 0
	v_mfma_f32_16x16x32_bf16 v[38:41], v[102:105], v[46:49], v[38:41]
	v_mfma_f32_16x16x32_bf16 v[42:45], v[110:113], v[46:49], v[42:45]
	v_mfma_f32_16x16x32_bf16 v[46:49], v[98:101], v[50:53], 0
	v_mfma_f32_16x16x32_bf16 v[50:53], v[106:109], v[50:53], 0
	v_mfma_f32_16x16x32_bf16 v[46:49], v[102:105], v[54:57], v[46:49]
	v_mfma_f32_16x16x32_bf16 v[50:53], v[110:113], v[54:57], v[50:53]
	v_mfma_f32_16x16x32_bf16 v[54:57], v[98:101], v[58:61], 0
	v_mfma_f32_16x16x32_bf16 v[58:61], v[106:109], v[58:61], 0
	v_mfma_f32_16x16x32_bf16 v[54:57], v[102:105], v[62:65], v[54:57]
	v_mfma_f32_16x16x32_bf16 v[58:61], v[110:113], v[62:65], v[58:61]
	v_lshl_add_u64 v[16:17], s[4:5], 0, v[0:1]
	v_readfirstlane_b32 s70, v12
	v_lshl_add_u64 v[16:17], v[16:17], 0, v[2:3]
	s_mov_b32 m0, s70
	v_add_u32_e32 v15, 0x2000, v12
	s_barrier
	ds_read_b128 v[62:65], v178 offset:16384
	ds_read_b128 v[118:121], v178 offset:17408
	ds_read_b128 v[122:125], v179 offset:18432
	ds_read_b128 v[130:133], v179 offset:19456
	ds_read_b128 v[134:137], v179 offset:20480
	ds_read_b128 v[138:141], v179 offset:21504
	ds_read_b128 v[142:145], v179 offset:22528
	ds_read_b128 v[146:149], v179 offset:23552
	global_load_lds_dwordx4 v[16:17], off
	v_lshl_add_u64 v[16:17], s[4:5], 0, v[4:5]
	v_readfirstlane_b32 s70, v15
	v_lshl_add_u64 v[16:17], v[16:17], 0, v[6:7]
	s_mov_b32 m0, s70
	s_nop 0
	global_load_lds_dwordx4 v[16:17], off
	s_barrier
	s_waitcnt lgkmcnt(0)
	v_mfma_f32_16x16x32_bf16 v[150:153], v[18:21], v[62:65], 0
	v_mfma_f32_16x16x32_bf16 v[158:161], v[18:21], v[122:125], 0
	v_mfma_f32_16x16x32_bf16 v[166:169], v[18:21], v[134:137], 0
	v_mfma_f32_16x16x32_bf16 v[16:19], v[18:21], v[142:145], 0
	v_mfma_f32_16x16x32_bf16 v[150:153], v[22:25], v[118:121], v[150:153]
	v_mfma_f32_16x16x32_bf16 v[158:161], v[22:25], v[130:133], v[158:161]
	v_mfma_f32_16x16x32_bf16 v[166:169], v[22:25], v[138:141], v[166:169]
	v_mfma_f32_16x16x32_bf16 v[16:19], v[22:25], v[146:149], v[16:19]
	v_mfma_f32_16x16x32_bf16 v[20:23], v[26:29], v[142:145], 0
	v_mfma_f32_16x16x32_bf16 v[154:157], v[26:29], v[62:65], 0
	v_mfma_f32_16x16x32_bf16 v[162:165], v[26:29], v[122:125], 0
	v_mfma_f32_16x16x32_bf16 v[170:173], v[26:29], v[134:137], 0
	v_mfma_f32_16x16x32_bf16 v[20:23], v[30:33], v[146:149], v[20:23]
	v_mfma_f32_16x16x32_bf16 v[154:157], v[30:33], v[118:121], v[154:157]
	v_mfma_f32_16x16x32_bf16 v[162:165], v[30:33], v[130:133], v[162:165]
	v_mfma_f32_16x16x32_bf16 v[170:173], v[30:33], v[138:141], v[170:173]
	s_barrier
	v_lshl_add_u64 v[24:25], s[58:59], 0, v[0:1]
	v_readfirstlane_b32 s70, v14
	v_add_u32_e32 v13, s33, v13
	v_lshl_add_u64 v[24:25], v[24:25], 0, v[2:3]
	s_mov_b32 m0, s70
	v_lshl_add_u64 v[14:15], s[58:59], 0, v[4:5]
	v_readfirstlane_b32 s58, v13
	global_load_lds_dwordx4 v[24:25], off
	v_lshl_add_u64 v[14:15], v[14:15], 0, v[6:7]
	s_mov_b32 m0, s58
	s_nop 0
	global_load_lds_dwordx4 v[14:15], off
	s_waitcnt vmcnt(6)
	s_barrier
	v_mfma_f32_16x16x32_bf16 v[24:27], v[98:101], v[62:65], 0
	v_mfma_f32_16x16x32_bf16 v[28:31], v[106:109], v[62:65], 0
	v_mfma_f32_16x16x32_bf16 v[24:27], v[102:105], v[118:121], v[24:27]
	v_mfma_f32_16x16x32_bf16 v[28:31], v[110:113], v[118:121], v[28:31]
	v_mfma_f32_16x16x32_bf16 v[62:65], v[98:101], v[122:125], 0
	v_mfma_f32_16x16x32_bf16 v[118:121], v[106:109], v[122:125], 0
	v_mfma_f32_16x16x32_bf16 v[122:125], v[98:101], v[134:137], 0
	v_mfma_f32_16x16x32_bf16 v[98:101], v[98:101], v[142:145], 0
	v_mfma_f32_16x16x32_bf16 v[62:65], v[102:105], v[130:133], v[62:65]
	v_mfma_f32_16x16x32_bf16 v[122:125], v[102:105], v[138:141], v[122:125]
	v_mfma_f32_16x16x32_bf16 v[98:101], v[102:105], v[146:149], v[98:101]
	v_mfma_f32_16x16x32_bf16 v[102:105], v[106:109], v[142:145], 0
	v_mfma_f32_16x16x32_bf16 v[118:121], v[110:113], v[130:133], v[118:121]
	v_mfma_f32_16x16x32_bf16 v[130:133], v[106:109], v[134:137], 0
	v_mfma_f32_16x16x32_bf16 v[102:105], v[110:113], v[146:149], v[102:105]
	v_mfma_f32_16x16x32_bf16 v[130:133], v[110:113], v[138:141], v[130:133]
	v_add3_u32 v188, s68, v126, v127
	s_barrier
	ds_read_b128 v[106:109], v188
	ds_read_b128 v[110:113], v188 offset:1024
	ds_read_b128 v[134:137], v188 offset:2048
	ds_read_b128 v[138:141], v188 offset:3072
	v_add_u32_e32 v13, 0x4000, v12
	v_lshl_add_u64 v[14:15], s[8:9], 0, v[0:1]
	v_readfirstlane_b32 s58, v13
	v_lshl_add_u64 v[14:15], v[14:15], 0, v[2:3]
	s_mov_b32 m0, s58
	v_add_u32_e32 v12, 0x6000, v12
	ds_read_b128 v[142:145], v178 offset:32768
	ds_read_b128 v[146:149], v178 offset:33792
	ds_read_b128 v[174:177], v179 offset:34816
	ds_read_b128 v[198:201], v179 offset:35840
	ds_read_b128 v[202:205], v179 offset:36864
	ds_read_b128 v[206:209], v179 offset:37888
	ds_read_b128 v[210:213], v179 offset:38912
	ds_read_b128 v[214:217], v179 offset:39936
	global_load_lds_dwordx4 v[14:15], off
	v_lshl_add_u64 v[14:15], s[8:9], 0, v[4:5]
	v_readfirstlane_b32 s58, v12
	v_lshl_add_u64 v[14:15], v[14:15], 0, v[6:7]
	s_mov_b32 m0, s58
	s_nop 0
	global_load_lds_dwordx4 v[14:15], off
	s_waitcnt lgkmcnt(8)
	s_barrier
; #define WAIT_V(n) asm volatile("s_waitcnt vmcnt(" #n ")" ::: "memory")
; #define WAIT_L(n) asm volatile("s_waitcnt lgkmcnt(" #n ")" ::: "memory")
; #define BAR __builtin_amdgcn_s_barrier()
; #define SCHED __builtin_amdgcn_sched_barrier(0)
; #define LDA(dst, b, h)                                                                            \
;   _Pragma("unroll") for (int m = 0; m < 4; ++m) _Pragma("unroll") for (int k = 0; k < 2; ++k)                                         \
;     dst[m][k] = *reinterpret_cast<const bf16x8*>((char*)SA(b, h) + lds_byte(wr * 64 + m * 16 + fr, k * 32 + fq * 8))
; #define LDB(dst, b, h)                                                                            \
;   _Pragma("unroll") for (int n = 0; n < 2; ++n) _Pragma("unroll") for (int k = 0; k < 2; ++k)                                         \
;     dst[n][k] = *reinterpret_cast<const bf16x8*>((char*)SB(b, h) + lds_byte(wc * 32 + n * 16 + fr, k * 32 + fq * 8))
; template <int K, bool SWAP>
; __device__ __forceinline__ void gemm_kloop(const bf16* __restrict__ A, const bf16* __restrict__ Bt,
;                                            f32x4 (&acc)[2][2][4][2], bool pref = false) {
;     ...
;     LDB(B0, 1, 0); SCHED; LDA(At, 1, 0); STAGE(SA(0, 1), A, HALF, t + 2);
;     WAIT_L(8); BAR; WAIT_L(0); MMA(0, 0, At, B0); BAR; SCHED;
;     LDB(B1, 1, 1); STAGE(SB(1, 0), Bt, 0, t + 3);
;     BAR; WAIT_L(0); MMA(0, 1, At, B1); BAR;
;     LDA(At, 1, 1); STAGE(SA(1, 0), A, 0, t + 3);
;     BAR; WAIT_L(0); MMA(1, 0, At, B0); BAR; SCHED;
;     STAGE(SB(1, 1), Bt, HALF, t + 3);
;     WAIT_V(6); BAR; MMA(1, 1, At, B1); BAR;
	s_waitcnt lgkmcnt(0)
	v_mfma_f32_16x16x32_bf16 v[12:15], v[106:109], v[142:145], v[66:69]
	v_mfma_f32_16x16x32_bf16 v[66:69], v[134:137], v[142:145], v[70:73]
	v_mfma_f32_16x16x32_bf16 v[70:73], v[106:109], v[174:177], v[74:77]
	v_mfma_f32_16x16x32_bf16 v[74:77], v[134:137], v[174:177], v[78:81]
	v_mfma_f32_16x16x32_bf16 v[78:81], v[106:109], v[202:205], v[82:85]
	v_mfma_f32_16x16x32_bf16 v[82:85], v[134:137], v[202:205], v[86:89]
	v_mfma_f32_16x16x32_bf16 v[86:89], v[106:109], v[210:213], v[90:93]
	v_mfma_f32_16x16x32_bf16 v[90:93], v[134:137], v[210:213], v[94:97]
	v_mfma_f32_16x16x32_bf16 v[12:15], v[110:113], v[146:149], v[12:15]
	v_mfma_f32_16x16x32_bf16 v[66:69], v[138:141], v[146:149], v[66:69]
	v_mfma_f32_16x16x32_bf16 v[70:73], v[110:113], v[198:201], v[70:73]
	v_mfma_f32_16x16x32_bf16 v[74:77], v[138:141], v[198:201], v[74:77]
	v_mfma_f32_16x16x32_bf16 v[78:81], v[110:113], v[206:209], v[78:81]
	v_mfma_f32_16x16x32_bf16 v[82:85], v[138:141], v[206:209], v[82:85]
	v_mfma_f32_16x16x32_bf16 v[86:89], v[110:113], v[214:217], v[86:89]
	v_mfma_f32_16x16x32_bf16 v[90:93], v[138:141], v[214:217], v[90:93]
	s_barrier
	s_mov_b32 m0, s63
	v_add3_u32 v189, s69, v126, v127
	v_lshl_add_u64 v[8:9], v[8:9], 0, s[52:53]
	ds_read_b128 v[94:97], v189
	ds_read_b128 v[218:221], v189 offset:1024
	ds_read_b128 v[222:225], v189 offset:2048
	ds_read_b128 v[226:229], v189 offset:3072
	global_load_lds_dwordx4 v[8:9], off
	v_lshl_add_u64 v[8:9], v[10:11], 0, s[52:53]
	s_mov_b32 m0, s67
	s_nop 0
	global_load_lds_dwordx4 v[8:9], off
	s_barrier
	s_waitcnt lgkmcnt(0)
	v_mfma_f32_16x16x32_bf16 v[8:11], v[94:97], v[142:145], v[114:117]
	v_mfma_f32_16x16x32_bf16 v[32:35], v[222:225], v[142:145], v[34:37]
	v_mfma_f32_16x16x32_bf16 v[36:39], v[94:97], v[174:177], v[38:41]
	v_mfma_f32_16x16x32_bf16 v[40:43], v[222:225], v[174:177], v[42:45]
	v_mfma_f32_16x16x32_bf16 v[44:47], v[94:97], v[202:205], v[46:49]
	v_mfma_f32_16x16x32_bf16 v[48:51], v[222:225], v[202:205], v[50:53]
	v_mfma_f32_16x16x32_bf16 v[52:55], v[94:97], v[210:213], v[54:57]
	v_mfma_f32_16x16x32_bf16 v[56:59], v[222:225], v[210:213], v[58:61]
	v_mfma_f32_16x16x32_bf16 v[8:11], v[218:221], v[146:149], v[8:11]
	v_mfma_f32_16x16x32_bf16 v[32:35], v[226:229], v[146:149], v[32:35]
	v_mfma_f32_16x16x32_bf16 v[36:39], v[218:221], v[198:201], v[36:39]
	v_mfma_f32_16x16x32_bf16 v[40:43], v[226:229], v[198:201], v[40:43]
	v_mfma_f32_16x16x32_bf16 v[44:47], v[218:221], v[206:209], v[44:47]
	v_mfma_f32_16x16x32_bf16 v[48:51], v[226:229], v[206:209], v[48:51]
	v_mfma_f32_16x16x32_bf16 v[52:55], v[218:221], v[214:217], v[52:55]
	v_mfma_f32_16x16x32_bf16 v[56:59], v[226:229], v[214:217], v[56:59]
	v_lshl_add_u64 v[60:61], s[14:15], 0, v[0:1]
	s_mov_b32 m0, s65
	v_lshl_add_u64 v[60:61], v[60:61], 0, v[2:3]
	s_barrier
	ds_read_b128 v[114:117], v178 offset:49152
	ds_read_b128 v[142:145], v178 offset:50176
	ds_read_b128 v[146:149], v179 offset:51200
	ds_read_b128 v[174:177], v179 offset:52224
	ds_read_b128 v[198:201], v179 offset:53248
	ds_read_b128 v[202:205], v179 offset:54272
	ds_read_b128 v[206:209], v179 offset:55296
	ds_read_b128 v[210:213], v179 offset:56320
	global_load_lds_dwordx4 v[60:61], off
	v_lshl_add_u64 v[60:61], s[14:15], 0, v[4:5]
	v_lshl_add_u64 v[60:61], v[60:61], 0, v[6:7]
	s_mov_b32 m0, s61
	s_nop 0
	global_load_lds_dwordx4 v[60:61], off
	s_barrier
	s_waitcnt lgkmcnt(0)
	v_mfma_f32_16x16x32_bf16 v[16:19], v[106:109], v[206:209], v[16:19]
	v_mfma_f32_16x16x32_bf16 v[20:23], v[134:137], v[206:209], v[20:23]
	v_mfma_f32_16x16x32_bf16 v[154:157], v[134:137], v[114:117], v[154:157]
	v_mfma_f32_16x16x32_bf16 v[150:153], v[106:109], v[114:117], v[150:153]
	v_mfma_f32_16x16x32_bf16 v[158:161], v[106:109], v[146:149], v[158:161]
	v_mfma_f32_16x16x32_bf16 v[162:165], v[134:137], v[146:149], v[162:165]
	v_mfma_f32_16x16x32_bf16 v[170:173], v[134:137], v[198:201], v[170:173]
	v_mfma_f32_16x16x32_bf16 v[166:169], v[106:109], v[198:201], v[166:169]
	v_mfma_f32_16x16x32_bf16 v[16:19], v[110:113], v[210:213], v[16:19]
	v_mfma_f32_16x16x32_bf16 v[20:23], v[138:141], v[210:213], v[20:23]
	v_mfma_f32_16x16x32_bf16 v[154:157], v[138:141], v[142:145], v[154:157]
	v_mfma_f32_16x16x32_bf16 v[150:153], v[110:113], v[142:145], v[150:153]
	v_mfma_f32_16x16x32_bf16 v[158:161], v[110:113], v[174:177], v[158:161]
	v_mfma_f32_16x16x32_bf16 v[162:165], v[138:141], v[174:177], v[162:165]
	v_mfma_f32_16x16x32_bf16 v[170:173], v[138:141], v[202:205], v[170:173]
	v_mfma_f32_16x16x32_bf16 v[166:169], v[110:113], v[202:205], v[166:169]
	s_barrier
	v_lshl_add_u64 v[60:61], s[0:1], 0, v[0:1]
	s_mov_b32 m0, s41
	v_lshl_add_u64 v[60:61], v[60:61], 0, v[2:3]
	global_load_lds_dwordx4 v[60:61], off
	v_lshl_add_u64 v[60:61], s[0:1], 0, v[4:5]
	v_lshl_add_u64 v[60:61], v[60:61], 0, v[6:7]
	s_mov_b32 m0, s23
	s_nop 0
	global_load_lds_dwordx4 v[60:61], off
	s_waitcnt vmcnt(6)
	s_barrier
	v_mfma_f32_16x16x32_bf16 v[24:27], v[94:97], v[114:117], v[24:27]
	v_mfma_f32_16x16x32_bf16 v[28:31], v[222:225], v[114:117], v[28:31]
	v_mfma_f32_16x16x32_bf16 v[60:63], v[94:97], v[146:149], v[62:65]
	v_mfma_f32_16x16x32_bf16 v[106:109], v[222:225], v[146:149], v[118:121]
	v_mfma_f32_16x16x32_bf16 v[110:113], v[94:97], v[198:201], v[122:125]
	v_mfma_f32_16x16x32_bf16 v[114:117], v[222:225], v[198:201], v[130:133]
	v_mfma_f32_16x16x32_bf16 v[94:97], v[94:97], v[206:209], v[98:101]
	v_mfma_f32_16x16x32_bf16 v[98:101], v[222:225], v[206:209], v[102:105]
	v_mfma_f32_16x16x32_bf16 v[24:27], v[218:221], v[142:145], v[24:27]
	v_mfma_f32_16x16x32_bf16 v[28:31], v[226:229], v[142:145], v[28:31]
	v_mfma_f32_16x16x32_bf16 v[60:63], v[218:221], v[174:177], v[60:63]
	v_mfma_f32_16x16x32_bf16 v[106:109], v[226:229], v[174:177], v[106:109]
	v_mfma_f32_16x16x32_bf16 v[110:113], v[218:221], v[202:205], v[110:113]
	v_mfma_f32_16x16x32_bf16 v[114:117], v[226:229], v[202:205], v[114:117]
	v_mfma_f32_16x16x32_bf16 v[94:97], v[218:221], v[210:213], v[94:97]
	v_mfma_f32_16x16x32_bf16 v[98:101], v[226:229], v[210:213], v[98:101]
	v_lshl_add_u64 v[0:1], s[6:7], 0, v[0:1]
	s_mov_b32 m0, s66
	v_lshl_add_u64 v[0:1], v[0:1], 0, v[2:3]
	s_barrier
; #define WAIT_V(n) asm volatile("s_waitcnt vmcnt(" #n ")" ::: "memory")
; #define WAIT_L(n) asm volatile("s_waitcnt lgkmcnt(" #n ")" ::: "memory")
; #define BAR __builtin_amdgcn_s_barrier()
; #define LDA(dst, b, h)                                                                            \
;   _Pragma("unroll") for (int m = 0; m < 4; ++m) _Pragma("unroll") for (int k = 0; k < 2; ++k)                                         \
;     dst[m][k] = *reinterpret_cast<const bf16x8*>((char*)SA(b, h) + lds_byte(wr * 64 + m * 16 + fr, k * 32 + fq * 8))
; #define LDB(dst, b, h)                                                                            \
;   _Pragma("unroll") for (int n = 0; n < 2; ++n) _Pragma("unroll") for (int k = 0; k < 2; ++k)                                         \
;     dst[n][k] = *reinterpret_cast<const bf16x8*>((char*)SB(b, h) + lds_byte(wc * 32 + n * 16 + fr, k * 32 + fq * 8))
; template <int K, bool SWAP>
; __device__ __forceinline__ void gemm_kloop(const bf16* __restrict__ A, const bf16* __restrict__ Bt,
;                                            f32x4 (&acc)[2][2][4][2], bool pref = false) {
;     ...
;   { LDB(B0, 0, 0); LDA(At, 0, 0); STAGE(SA(1, 1), A, HALF, nt - 1);
;     BAR; WAIT_L(0); MMA(0, 0, At, B0); BAR;
;     LDB(B1, 0, 1); BAR; WAIT_L(0); MMA(0, 1, At, B1); BAR;
;     LDA(At, 0, 1); WAIT_V(4); BAR; WAIT_L(0); MMA(1, 0, At, B0); MMA(1, 1, At, B1); BAR; }
	ds_read_b128 v[102:105], v129
	ds_read_b128 v[118:121], v129 offset:1024
	ds_read_b128 v[122:125], v129 offset:2048
	ds_read_b128 v[130:133], v129 offset:3072
	ds_read_b128 v[134:137], v178
	ds_read_b128 v[138:141], v178 offset:1024
	ds_read_b128 v[142:145], v179 offset:2048
	ds_read_b128 v[146:149], v179 offset:3072
	ds_read_b128 v[174:177], v179 offset:4096
	ds_read_b128 v[198:201], v179 offset:5120
	ds_read_b128 v[202:205], v179 offset:6144
	ds_read_b128 v[206:209], v179 offset:7168
	global_load_lds_dwordx4 v[0:1], off
	v_lshl_add_u64 v[0:1], s[6:7], 0, v[4:5]
	v_lshl_add_u64 v[0:1], v[0:1], 0, v[6:7]
	s_mov_b32 m0, s64
	s_nop 0
	global_load_lds_dwordx4 v[0:1], off
	s_barrier
	s_waitcnt lgkmcnt(0)
	v_mfma_f32_16x16x32_bf16 v[0:3], v[102:105], v[134:137], v[12:15]
	v_mfma_f32_16x16x32_bf16 v[4:7], v[122:125], v[134:137], v[66:69]
	v_mfma_f32_16x16x32_bf16 v[12:15], v[102:105], v[142:145], v[70:73]
	v_mfma_f32_16x16x32_bf16 v[64:67], v[122:125], v[142:145], v[74:77]
	v_mfma_f32_16x16x32_bf16 v[68:71], v[102:105], v[174:177], v[78:81]
	v_mfma_f32_16x16x32_bf16 v[72:75], v[122:125], v[174:177], v[82:85]
	v_mfma_f32_16x16x32_bf16 v[76:79], v[102:105], v[202:205], v[86:89]
	v_mfma_f32_16x16x32_bf16 v[80:83], v[122:125], v[202:205], v[90:93]
	v_mfma_f32_16x16x32_bf16 v[0:3], v[118:121], v[138:141], v[0:3]
	v_mfma_f32_16x16x32_bf16 v[4:7], v[130:133], v[138:141], v[4:7]
	v_mfma_f32_16x16x32_bf16 v[12:15], v[118:121], v[146:149], v[12:15]
	v_mfma_f32_16x16x32_bf16 v[64:67], v[130:133], v[146:149], v[64:67]
	v_mfma_f32_16x16x32_bf16 v[68:71], v[118:121], v[198:201], v[68:71]
	v_mfma_f32_16x16x32_bf16 v[72:75], v[130:133], v[198:201], v[72:75]
	v_mfma_f32_16x16x32_bf16 v[76:79], v[118:121], v[206:209], v[76:79]
	v_mfma_f32_16x16x32_bf16 v[84:87], v[130:133], v[206:209], v[80:83]
	s_barrier
	s_nop 0
	ds_read_b128 v[80:83], v186
	ds_read_b128 v[88:91], v186 offset:1024
	ds_read_b128 v[210:213], v186 offset:2048
	ds_read_b128 v[214:217], v186 offset:3072
	s_barrier
	s_waitcnt lgkmcnt(0)
	v_mfma_f32_16x16x32_bf16 v[40:43], v[210:213], v[142:145], v[40:43]
	v_mfma_f32_16x16x32_bf16 v[8:11], v[80:83], v[134:137], v[8:11]
	v_mfma_f32_16x16x32_bf16 v[32:35], v[210:213], v[134:137], v[32:35]
	v_mfma_f32_16x16x32_bf16 v[134:137], v[214:217], v[146:149], v[40:43]
	v_mfma_f32_16x16x32_bf16 v[40:43], v[80:83], v[174:177], v[44:47]
	v_mfma_f32_16x16x32_bf16 v[44:47], v[88:91], v[198:201], v[40:43]
	v_mfma_f32_16x16x32_bf16 v[40:43], v[210:213], v[174:177], v[48:51]
	v_mfma_f32_16x16x32_bf16 v[8:11], v[88:91], v[138:141], v[8:11]
	v_mfma_f32_16x16x32_bf16 v[32:35], v[214:217], v[138:141], v[32:35]
	v_mfma_f32_16x16x32_bf16 v[36:39], v[80:83], v[142:145], v[36:39]
	v_mfma_f32_16x16x32_bf16 v[138:141], v[214:217], v[198:201], v[40:43]
	v_mfma_f32_16x16x32_bf16 v[40:43], v[80:83], v[202:205], v[52:55]
	v_mfma_f32_16x16x32_bf16 v[36:39], v[88:91], v[146:149], v[36:39]
	v_mfma_f32_16x16x32_bf16 v[52:55], v[88:91], v[206:209], v[40:43]
	v_mfma_f32_16x16x32_bf16 v[40:43], v[210:213], v[202:205], v[56:59]
	v_mfma_f32_16x16x32_bf16 v[142:145], v[214:217], v[206:209], v[40:43]
	s_barrier
	s_nop 4
	ds_read_b128 v[40:43], v178 offset:16384
	ds_read_b128 v[48:51], v178 offset:17408
	ds_read_b128 v[56:59], v179 offset:18432
	ds_read_b128 v[146:149], v179 offset:19456
	ds_read_b128 v[174:177], v179 offset:20480
	ds_read_b128 v[198:201], v179 offset:21504
	ds_read_b128 v[202:205], v179 offset:22528
	ds_read_b128 v[206:209], v179 offset:23552
	s_waitcnt vmcnt(4)
	s_barrier
	s_waitcnt lgkmcnt(0)
	v_mfma_f32_16x16x32_bf16 v[16:19], v[102:105], v[202:205], v[16:19]
	v_mfma_f32_16x16x32_bf16 v[218:221], v[118:121], v[206:209], v[16:19]
	v_mfma_f32_16x16x32_bf16 v[16:19], v[122:125], v[202:205], v[20:23]
	v_mfma_f32_16x16x32_bf16 v[150:153], v[102:105], v[40:43], v[150:153]
	v_mfma_f32_16x16x32_bf16 v[154:157], v[122:125], v[40:43], v[154:157]
	v_mfma_f32_16x16x32_bf16 v[158:161], v[102:105], v[56:59], v[158:161]
	v_mfma_f32_16x16x32_bf16 v[162:165], v[122:125], v[56:59], v[162:165]
	v_mfma_f32_16x16x32_bf16 v[166:169], v[102:105], v[174:177], v[166:169]
	v_mfma_f32_16x16x32_bf16 v[170:173], v[122:125], v[174:177], v[170:173]
	v_mfma_f32_16x16x32_bf16 v[20:23], v[130:133], v[206:209], v[16:19]
	v_mfma_f32_16x16x32_bf16 v[150:153], v[118:121], v[48:51], v[150:153]
	v_mfma_f32_16x16x32_bf16 v[154:157], v[130:133], v[48:51], v[154:157]
	v_mfma_f32_16x16x32_bf16 v[158:161], v[118:121], v[146:149], v[158:161]
	v_mfma_f32_16x16x32_bf16 v[162:165], v[130:133], v[146:149], v[162:165]
	v_mfma_f32_16x16x32_bf16 v[166:169], v[118:121], v[198:201], v[166:169]
	v_mfma_f32_16x16x32_bf16 v[170:173], v[130:133], v[198:201], v[170:173]
	v_mfma_f32_16x16x32_bf16 v[16:19], v[80:83], v[40:43], v[24:27]
	v_mfma_f32_16x16x32_bf16 v[130:133], v[88:91], v[48:51], v[16:19]
	v_mfma_f32_16x16x32_bf16 v[16:19], v[210:213], v[40:43], v[28:31]
	v_mfma_f32_16x16x32_bf16 v[28:31], v[214:217], v[48:51], v[16:19]
	v_mfma_f32_16x16x32_bf16 v[16:19], v[80:83], v[56:59], v[60:63]
	v_mfma_f32_16x16x32_bf16 v[222:225], v[88:91], v[146:149], v[16:19]
	v_mfma_f32_16x16x32_bf16 v[16:19], v[210:213], v[56:59], v[106:109]
	v_mfma_f32_16x16x32_bf16 v[146:149], v[214:217], v[146:149], v[16:19]
	v_mfma_f32_16x16x32_bf16 v[16:19], v[80:83], v[174:177], v[110:113]
	v_mfma_f32_16x16x32_bf16 v[226:229], v[88:91], v[198:201], v[16:19]
	v_mfma_f32_16x16x32_bf16 v[16:19], v[210:213], v[174:177], v[114:117]
	v_mfma_f32_16x16x32_bf16 v[174:177], v[214:217], v[198:201], v[16:19]
	v_mfma_f32_16x16x32_bf16 v[16:19], v[80:83], v[202:205], v[94:97]
	v_mfma_f32_16x16x32_bf16 v[198:201], v[88:91], v[206:209], v[16:19]
	v_mfma_f32_16x16x32_bf16 v[16:19], v[210:213], v[202:205], v[98:101]
	v_mfma_f32_16x16x32_bf16 v[202:205], v[214:217], v[206:209], v[16:19]
	s_barrier
; #define WAIT_V(n) asm volatile("s_waitcnt vmcnt(" #n ")" ::: "memory")
; #define WAIT_L(n) asm volatile("s_waitcnt lgkmcnt(" #n ")" ::: "memory")
; #define BAR __builtin_amdgcn_s_barrier()
; #define LDA(dst, b, h)                                                                            \
;   _Pragma("unroll") for (int m = 0; m < 4; ++m) _Pragma("unroll") for (int k = 0; k < 2; ++k)                                         \
;     dst[m][k] = *reinterpret_cast<const bf16x8*>((char*)SA(b, h) + lds_byte(wr * 64 + m * 16 + fr, k * 32 + fq * 8))
; #define LDB(dst, b, h)                                                                            \
;   _Pragma("unroll") for (int n = 0; n < 2; ++n) _Pragma("unroll") for (int k = 0; k < 2; ++k)                                         \
;     dst[n][k] = *reinterpret_cast<const bf16x8*>((char*)SB(b, h) + lds_byte(wc * 32 + n * 16 + fr, k * 32 + fq * 8))
; template <int K, bool SWAP>
; __device__ __forceinline__ void gemm_kloop(const bf16* __restrict__ A, const bf16* __restrict__ Bt,
;                                            f32x4 (&acc)[2][2][4][2], bool pref = false) {
;     ...
;   { LDB(B0, 1, 0); LDA(At, 1, 0); WAIT_V(2); BAR; WAIT_L(0); MMA(0, 0, At, B0); BAR;
;     LDB(B1, 1, 1); WAIT_V(0); BAR; WAIT_L(0); MMA(0, 1, At, B1); BAR;
;     LDA(At, 1, 1); BAR; WAIT_L(0); MMA(1, 0, At, B0); MMA(1, 1, At, B1); BAR; }
;   if (wr == 0) BAR;
	ds_read_b128 v[60:63], v188
	ds_read_b128 v[206:209], v188 offset:1024
	ds_read_b128 v[210:213], v188 offset:2048
	ds_read_b128 v[214:217], v188 offset:3072
	s_nop 0
	ds_read_b128 v[16:19], v178 offset:32768
	ds_read_b128 v[24:27], v178 offset:33792
	ds_read_b128 v[92:95], v179 offset:34816
	ds_read_b128 v[100:103], v179 offset:35840
	ds_read_b128 v[108:111], v179 offset:36864
	ds_read_b128 v[116:119], v179 offset:37888
	ds_read_b128 v[124:127], v179 offset:38912
	ds_read_b128 v[230:233], v179 offset:39936
	s_waitcnt vmcnt(2)
	s_barrier
	s_waitcnt lgkmcnt(0)
	v_mfma_f32_16x16x32_bf16 v[0:3], v[60:63], v[16:19], v[0:3]
	v_mfma_f32_16x16x32_bf16 v[120:123], v[206:209], v[24:27], v[0:3]
	v_mfma_f32_16x16x32_bf16 v[0:3], v[210:213], v[16:19], v[4:7]
	v_mfma_f32_16x16x32_bf16 v[112:115], v[214:217], v[24:27], v[0:3]
	v_mfma_f32_16x16x32_bf16 v[0:3], v[60:63], v[92:95], v[12:15]
	v_mfma_f32_16x16x32_bf16 v[104:107], v[206:209], v[100:103], v[0:3]
	v_mfma_f32_16x16x32_bf16 v[0:3], v[210:213], v[92:95], v[64:67]
	v_mfma_f32_16x16x32_bf16 v[96:99], v[214:217], v[100:103], v[0:3]
	v_mfma_f32_16x16x32_bf16 v[0:3], v[60:63], v[108:111], v[68:71]
	v_mfma_f32_16x16x32_bf16 v[88:91], v[206:209], v[116:119], v[0:3]
	v_mfma_f32_16x16x32_bf16 v[0:3], v[210:213], v[108:111], v[72:75]
	v_mfma_f32_16x16x32_bf16 v[80:83], v[214:217], v[116:119], v[0:3]
	v_mfma_f32_16x16x32_bf16 v[0:3], v[60:63], v[124:127], v[76:79]
	v_mfma_f32_16x16x32_bf16 v[72:75], v[206:209], v[230:233], v[0:3]
	v_mfma_f32_16x16x32_bf16 v[0:3], v[210:213], v[124:127], v[84:87]
	v_mfma_f32_16x16x32_bf16 v[64:67], v[214:217], v[230:233], v[0:3]
	s_barrier
	ds_read_b128 v[4:7], v189
	ds_read_b128 v[12:15], v189 offset:1024
	ds_read_b128 v[234:237], v189 offset:2048
	ds_read_b128 v[238:241], v189 offset:3072
	s_waitcnt vmcnt(0)
	s_barrier
	s_waitcnt lgkmcnt(0)
	v_mfma_f32_16x16x32_bf16 v[0:3], v[4:7], v[16:19], v[8:11]
	v_mfma_f32_16x16x32_bf16 v[56:59], v[12:15], v[24:27], v[0:3]
	v_mfma_f32_16x16x32_bf16 v[0:3], v[234:237], v[16:19], v[32:35]
	v_mfma_f32_16x16x32_bf16 v[48:51], v[238:241], v[24:27], v[0:3]
	v_mfma_f32_16x16x32_bf16 v[0:3], v[4:7], v[92:95], v[36:39]
	v_mfma_f32_16x16x32_bf16 v[40:43], v[12:15], v[100:103], v[0:3]
	v_mfma_f32_16x16x32_bf16 v[0:3], v[234:237], v[92:95], v[134:137]
	v_mfma_f32_16x16x32_bf16 v[32:35], v[238:241], v[100:103], v[0:3]
	v_mfma_f32_16x16x32_bf16 v[0:3], v[4:7], v[108:111], v[44:47]
	v_mfma_f32_16x16x32_bf16 v[24:27], v[12:15], v[116:119], v[0:3]
	v_mfma_f32_16x16x32_bf16 v[0:3], v[234:237], v[108:111], v[138:141]
	v_mfma_f32_16x16x32_bf16 v[16:19], v[238:241], v[116:119], v[0:3]
	v_mfma_f32_16x16x32_bf16 v[0:3], v[4:7], v[124:127], v[52:55]
	v_mfma_f32_16x16x32_bf16 v[8:11], v[12:15], v[230:233], v[0:3]
	v_mfma_f32_16x16x32_bf16 v[0:3], v[234:237], v[124:127], v[142:145]
	v_mfma_f32_16x16x32_bf16 v[0:3], v[238:241], v[230:233], v[0:3]
	s_barrier
	ds_read_b128 v[36:39], v178 offset:49152
	ds_read_b128 v[44:47], v178 offset:50176
	ds_read_b128 v[134:137], v179 offset:51200
	ds_read_b128 v[138:141], v179 offset:52224
	ds_read_b128 v[142:145], v179 offset:53248
	ds_read_b128 v[230:233], v179 offset:54272
	ds_read_b128 v[242:245], v179 offset:55296
	ds_read_b128 v[246:249], v179 offset:56320
	s_barrier
	s_waitcnt lgkmcnt(0)
	v_mfma_f32_16x16x32_bf16 v[52:55], v[60:63], v[36:39], v[150:153]
	v_mfma_f32_16x16x32_bf16 v[124:127], v[206:209], v[44:47], v[52:55]
	v_mfma_f32_16x16x32_bf16 v[52:55], v[210:213], v[36:39], v[154:157]
	v_mfma_f32_16x16x32_bf16 v[116:119], v[214:217], v[44:47], v[52:55]
	v_mfma_f32_16x16x32_bf16 v[52:55], v[60:63], v[134:137], v[158:161]
	v_mfma_f32_16x16x32_bf16 v[108:111], v[206:209], v[138:141], v[52:55]
	v_mfma_f32_16x16x32_bf16 v[52:55], v[210:213], v[134:137], v[162:165]
	v_mfma_f32_16x16x32_bf16 v[100:103], v[214:217], v[138:141], v[52:55]
	v_mfma_f32_16x16x32_bf16 v[52:55], v[60:63], v[142:145], v[166:169]
	v_mfma_f32_16x16x32_bf16 v[92:95], v[206:209], v[230:233], v[52:55]
	v_mfma_f32_16x16x32_bf16 v[52:55], v[210:213], v[142:145], v[170:173]
	v_mfma_f32_16x16x32_bf16 v[84:87], v[214:217], v[230:233], v[52:55]
	v_mfma_f32_16x16x32_bf16 v[52:55], v[60:63], v[242:245], v[218:221]
	v_mfma_f32_16x16x32_bf16 v[20:23], v[210:213], v[242:245], v[20:23]
	v_mfma_f32_16x16x32_bf16 v[76:79], v[206:209], v[246:249], v[52:55]
	v_mfma_f32_16x16x32_bf16 v[68:71], v[214:217], v[246:249], v[20:23]
	v_mfma_f32_16x16x32_bf16 v[20:23], v[4:7], v[36:39], v[130:133]
	v_mfma_f32_16x16x32_bf16 v[60:63], v[12:15], v[44:47], v[20:23]
	v_mfma_f32_16x16x32_bf16 v[20:23], v[234:237], v[36:39], v[28:31]
	v_mfma_f32_16x16x32_bf16 v[52:55], v[238:241], v[44:47], v[20:23]
	v_mfma_f32_16x16x32_bf16 v[20:23], v[4:7], v[134:137], v[222:225]
	v_mfma_f32_16x16x32_bf16 v[44:47], v[12:15], v[138:141], v[20:23]
	v_mfma_f32_16x16x32_bf16 v[20:23], v[234:237], v[134:137], v[146:149]
	v_mfma_f32_16x16x32_bf16 v[36:39], v[238:241], v[138:141], v[20:23]
	v_mfma_f32_16x16x32_bf16 v[20:23], v[4:7], v[142:145], v[226:229]
	v_mfma_f32_16x16x32_bf16 v[4:7], v[4:7], v[242:245], v[198:201]
	v_mfma_f32_16x16x32_bf16 v[28:31], v[12:15], v[230:233], v[20:23]
	v_mfma_f32_16x16x32_bf16 v[20:23], v[234:237], v[142:145], v[174:177]
	v_mfma_f32_16x16x32_bf16 v[12:15], v[12:15], v[246:249], v[4:7]
	v_mfma_f32_16x16x32_bf16 v[4:7], v[234:237], v[242:245], v[202:205]
	v_mfma_f32_16x16x32_bf16 v[20:23], v[238:241], v[230:233], v[20:23]
	v_mfma_f32_16x16x32_bf16 v[4:7], v[238:241], v[246:249], v[4:7]
	s_movk_i32 s0, 0x100
	v_cmp_gt_u32_e32 vcc, s0, v128
	s_barrier
	s_and_saveexec_b64 s[0:1], vcc
	s_cbranch_execz .LBB0_673
	s_barrier

; #define WAIT_V(n) asm volatile("s_waitcnt vmcnt(" #n ")" ::: "memory")
; #define WAIT_L(n) asm volatile("s_waitcnt lgkmcnt(" #n ")" ::: "memory")
; #define BAR __builtin_amdgcn_s_barrier()
; #define SCHED __builtin_amdgcn_sched_barrier(0)
; #define LDA(dst, b, h)                                                                            \
;   _Pragma("unroll") for (int m = 0; m < 4; ++m) _Pragma("unroll") for (int k = 0; k < 2; ++k)                                         \
;     dst[m][k] = *reinterpret_cast<const bf16x8*>((char*)SA(b, h) + lds_byte(wr * 64 + m * 16 + fr, k * 32 + fq * 8))
; #define LDB(dst, b, h)                                                                            \
;   _Pragma("unroll") for (int n = 0; n < 2; ++n) _Pragma("unroll") for (int k = 0; k < 2; ++k)                                         \
;     dst[n][k] = *reinterpret_cast<const bf16x8*>((char*)SB(b, h) + lds_byte(wc * 32 + n * 16 + fr, k * 32 + fq * 8))
; template <int K, bool SWAP>
; __device__ __forceinline__ void gemm_kloop(const bf16* __restrict__ A, const bf16* __restrict__ Bt,
;                                            f32x4 (&acc)[2][2][4][2], bool pref = false) {
;     ...
;   if (wr == 1) BAR;
;   WAIT_V(4); BAR;
;   STAGE(SB(1, 0), Bt, 0, 1); STAGE(SA(1, 0), A, 0, 1); STAGE(SB(1, 1), Bt, HALF, 1);
;   WAIT_V(6); BAR;
;   for (int t = 0; t < nt - 2; t += 2) {
;     LDB(B0, 0, 0); SCHED; LDA(At, 0, 0); STAGE(SA(1, 1), A, HALF, t + 1);
;     WAIT_L(8); BAR; WAIT_L(0); MMA(0, 0, At, B0); BAR; SCHED;
;     LDB(B1, 0, 1); STAGE(SB(0, 0), Bt, 0, t + 2);
.LBB0_719:
	s_or_b64 exec, exec, s[66:67]
	v_add_u32_e32 v0, v15, v0
	v_and_b32_e32 v0, 0xfffffc00, v0
	v_sub_u32_e32 v0, v15, v0
	v_lshrrev_b32_e32 v2, 4, v0
	v_bitop3_b32 v2, v2, v0, 32 bitop3:0x6c
	v_ashrrev_i32_e32 v3, 31, v2
	v_add_u32_e32 v1, v64, v1
	v_lshrrev_b32_e32 v3, 26, v3
	v_ashrrev_i32_e32 v1, 6, v1
	v_add_u32_e32 v3, v2, v3
	v_lshlrev_b32_e32 v0, 3, v1
	v_ashrrev_i32_e32 v4, 6, v3
	v_and_b32_e32 v3, 0xc0, v3
	v_and_b32_e32 v0, -16, v0
	v_lshlrev_b32_e32 v1, 5, v1
	v_sub_u32_e32 v2, v2, v3
	v_add_u32_e32 v0, v4, v0
	v_and_b32_e32 v1, 32, v1
	v_ashrrev_i16_sdwa v2, v193, sext(v2) dst_sel:DWORD dst_unused:UNUSED_PAD src0_sel:DWORD src1_sel:BYTE_0
	v_add_u32_sdwa v2, v1, sext(v2) dst_sel:DWORD dst_unused:UNUSED_PAD src0_sel:DWORD src1_sel:WORD_0
	v_ashrrev_i32_e32 v1, 31, v0
	v_lshlrev_b64 v[0:1], 9, v[0:1]
	v_ashrrev_i32_e32 v3, 31, v2
	v_readlane_b32 s68, v254, 33
	v_lshl_add_u64 v[4:5], s[62:63], 0, v[0:1]
	v_lshlrev_b64 v[2:3], 1, v[2:3]
	v_add_u32_e32 v6, s68, v15
	v_lshl_add_u64 v[8:9], v[4:5], 0, v[2:3]
	s_mov_b64 s[4:5], 0x80
	v_readfirstlane_b32 s20, v6
	v_lshl_add_u64 v[4:5], v[8:9], 0, s[4:5]
	s_mov_b32 m0, s20
	s_waitcnt vmcnt(4)
	s_barrier
	global_load_lds_dwordx4 v[4:5], off
	v_ashrrev_i32_e32 v4, 31, v13
	v_lshrrev_b32_e32 v4, 22, v4
	v_add_u32_e32 v4, v13, v4
	v_ashrrev_i32_e32 v5, 10, v4
	v_mul_i32_i24_e32 v4, 0x400, v5
	v_sub_u32_e32 v4, v13, v4
	v_lshrrev_b32_e32 v6, 4, v4
	v_bitop3_b32 v6, v6, v4, 32 bitop3:0x6c
	v_ashrrev_i32_e32 v7, 31, v6
	v_lshrrev_b32_e32 v7, 26, v7
	v_add_u32_e32 v7, v6, v7
	v_lshlrev_b32_e32 v4, 3, v5
	v_ashrrev_i32_e32 v10, 6, v7
	v_and_b32_e32 v7, 0xc0, v7
	v_and_b32_e32 v4, -16, v4
	v_lshlrev_b32_e32 v5, 5, v5
	v_sub_u32_e32 v6, v6, v7
	v_add_u32_e32 v4, v10, v4
	v_and_b32_e32 v5, 32, v5
	v_ashrrev_i16_sdwa v6, v193, sext(v6) dst_sel:DWORD dst_unused:UNUSED_PAD src0_sel:DWORD src1_sel:BYTE_0
	v_add_u32_sdwa v6, v5, sext(v6) dst_sel:DWORD dst_unused:UNUSED_PAD src0_sel:DWORD src1_sel:WORD_0
	v_ashrrev_i32_e32 v5, 31, v4
	v_lshlrev_b64 v[4:5], 9, v[4:5]
	v_ashrrev_i32_e32 v7, 31, v6
	v_lshl_add_u64 v[10:11], s[62:63], 0, v[4:5]
	v_lshlrev_b64 v[6:7], 1, v[6:7]
	v_add_u32_e32 v17, s68, v13
	v_lshl_add_u64 v[10:11], v[10:11], 0, v[6:7]
	v_readfirstlane_b32 s73, v17
	v_lshl_add_u64 v[18:19], v[10:11], 0, s[4:5]
	s_mov_b32 m0, s73
	v_add_u32_e32 v17, 0x8000, v12
	global_load_lds_dwordx4 v[18:19], off
	v_lshl_add_u64 v[18:19], s[12:13], 0, v[0:1]
	v_readfirstlane_b32 s72, v17
	v_lshl_add_u64 v[18:19], v[18:19], 0, v[2:3]
	s_mov_b32 m0, s72
	v_add_u32_e32 v17, 0xa000, v12
	global_load_lds_dwordx4 v[18:19], off
	v_lshl_add_u64 v[18:19], s[12:13], 0, v[4:5]
	v_readfirstlane_b32 s66, v17
	s_add_u32 vcc_lo, s62, 0x10080
	v_readlane_b32 s5, v254, 34
	v_lshl_add_u64 v[18:19], v[18:19], 0, v[6:7]
	s_mov_b32 m0, s66
	s_addc_u32 vcc_hi, s63, 0
	v_add_u32_e32 v17, s5, v15
	global_load_lds_dwordx4 v[18:19], off
	v_lshl_add_u64 v[18:19], vcc, 0, v[0:1]
	v_readfirstlane_b32 s71, v17
	v_lshl_add_u64 v[18:19], v[18:19], 0, v[2:3]
	s_mov_b32 m0, s71
	v_add_u32_e32 v17, s5, v13
	global_load_lds_dwordx4 v[18:19], off
	v_lshl_add_u64 v[18:19], vcc, 0, v[4:5]
	v_readfirstlane_b32 s67, v17
	v_lshl_add_u64 v[18:19], v[18:19], 0, v[6:7]
	s_mov_b32 m0, s67
	v_and_b32_e32 v17, 15, v64
	global_load_lds_dwordx4 v[18:19], off
	v_lshlrev_b32_e32 v18, 2, v64
	v_and_b32_e32 v42, 48, v64
	v_lshlrev_b32_e32 v17, 6, v17
	v_and_b32_e32 v43, 32, v18
	v_bitop3_b32 v65, v17, v43, v42 bitop3:0x36
	v_lshlrev_b32_e32 v17, 6, v64
	s_add_i32 s65, 0, 0x10000
	v_and_b32_e32 v130, 0x3000, v17
	v_add3_u32 v131, s65, v65, v130
	s_waitcnt vmcnt(6)
	s_barrier
	ds_read_b128 v[18:21], v131
	ds_read_b128 v[22:25], v131 offset:1024
	ds_read_b128 v[26:29], v131 offset:2048
	ds_read_b128 v[30:33], v131 offset:3072
	s_add_u32 vcc_lo, s62, 0x10180
	s_addc_u32 vcc_hi, s63, 0
	v_and_b32_e32 v17, 0x3c0, v17
	v_lshlrev_b32_e32 v16, 13, v16
	v_bitop3_b32 v17, v17, v43, v42 bitop3:0x36
	v_add_u32_e32 v62, 0xc000, v12
	v_add3_u32 v132, 0, v65, v16
	v_add3_u32 v138, 0, v17, v16
	v_lshl_add_u64 v[16:17], s[14:15], 0, v[0:1]
	v_readfirstlane_b32 s70, v62
	v_lshl_add_u64 v[16:17], v[16:17], 0, v[2:3]
	s_mov_b32 m0, s70
	v_add_u32_e32 v62, 0xe000, v12
	ds_read_b128 v[34:37], v132
	ds_read_b128 v[38:41], v132 offset:1024
	ds_read_b128 v[42:45], v138 offset:2048
	ds_read_b128 v[46:49], v138 offset:3072
	ds_read_b128 v[50:53], v138 offset:4096
	ds_read_b128 v[54:57], v138 offset:5120
	ds_read_b128 v[58:61], v138 offset:6144
	ds_read_b128 v[66:69], v138 offset:7168
	global_load_lds_dwordx4 v[16:17], off
	v_lshl_add_u64 v[16:17], s[14:15], 0, v[4:5]
	v_readfirstlane_b32 s41, v62
	v_lshl_add_u64 v[16:17], v[16:17], 0, v[6:7]
	s_mov_b32 m0, s41
	s_add_u32 s62, s62, 0x10100
	global_load_lds_dwordx4 v[16:17], off
	s_waitcnt lgkmcnt(8)
	s_barrier
	s_waitcnt lgkmcnt(0)
	s_addc_u32 s63, s63, 0
	s_waitcnt lgkmcnt(0)
	v_mfma_f32_16x16x32_bf16 v[70:73], v[18:21], v[34:37], 0
	v_mfma_f32_16x16x32_bf16 v[78:81], v[18:21], v[42:45], 0
	v_mfma_f32_16x16x32_bf16 v[86:89], v[18:21], v[50:53], 0
	v_mfma_f32_16x16x32_bf16 v[16:19], v[18:21], v[58:61], 0
	v_mfma_f32_16x16x32_bf16 v[70:73], v[22:25], v[38:41], v[70:73]
	v_mfma_f32_16x16x32_bf16 v[78:81], v[22:25], v[46:49], v[78:81]
	v_mfma_f32_16x16x32_bf16 v[86:89], v[22:25], v[54:57], v[86:89]
	v_mfma_f32_16x16x32_bf16 v[16:19], v[22:25], v[66:69], v[16:19]
	v_mfma_f32_16x16x32_bf16 v[20:23], v[26:29], v[58:61], 0
	v_mfma_f32_16x16x32_bf16 v[74:77], v[26:29], v[34:37], 0
	v_mfma_f32_16x16x32_bf16 v[82:85], v[26:29], v[42:45], 0
	v_mfma_f32_16x16x32_bf16 v[90:93], v[26:29], v[50:53], 0
	v_mfma_f32_16x16x32_bf16 v[20:23], v[30:33], v[66:69], v[20:23]
	v_mfma_f32_16x16x32_bf16 v[74:77], v[30:33], v[38:41], v[74:77]
	v_mfma_f32_16x16x32_bf16 v[82:85], v[30:33], v[46:49], v[82:85]
	v_mfma_f32_16x16x32_bf16 v[90:93], v[30:33], v[54:57], v[90:93]
	s_barrier
; #define WAIT_V(n) asm volatile("s_waitcnt vmcnt(" #n ")" ::: "memory")
; #define WAIT_L(n) asm volatile("s_waitcnt lgkmcnt(" #n ")" ::: "memory")
; #define BAR __builtin_amdgcn_s_barrier()
; #define SCHED __builtin_amdgcn_sched_barrier(0)
; #define LDA(dst, b, h)                                                                            \
;   _Pragma("unroll") for (int m = 0; m < 4; ++m) _Pragma("unroll") for (int k = 0; k < 2; ++k)                                         \
;     dst[m][k] = *reinterpret_cast<const bf16x8*>((char*)SA(b, h) + lds_byte(wr * 64 + m * 16 + fr, k * 32 + fq * 8))
; #define LDB(dst, b, h)                                                                            \
;   _Pragma("unroll") for (int n = 0; n < 2; ++n) _Pragma("unroll") for (int k = 0; k < 2; ++k)                                         \
;     dst[n][k] = *reinterpret_cast<const bf16x8*>((char*)SB(b, h) + lds_byte(wc * 32 + n * 16 + fr, k * 32 + fq * 8))
; template <int K, bool SWAP>
; __device__ __forceinline__ void gemm_kloop(const bf16* __restrict__ A, const bf16* __restrict__ Bt,
;                                            f32x4 (&acc)[2][2][4][2], bool pref = false) {
;     ...
;     LDB(B0, 0, 0); SCHED; LDA(At, 0, 0); STAGE(SA(1, 1), A, HALF, t + 1);
;     WAIT_L(8); BAR; WAIT_L(0); MMA(0, 0, At, B0); BAR; SCHED;
;     LDB(B1, 0, 1); STAGE(SB(0, 0), Bt, 0, t + 2);
;     BAR; WAIT_L(0); MMA(0, 1, At, B1); BAR;
;     LDA(At, 0, 1); STAGE(SA(0, 0), A, 0, t + 2);
;     BAR; WAIT_L(0); MMA(1, 0, At, B0); BAR; SCHED;
;     STAGE(SB(0, 1), Bt, HALF, t + 2);
;     WAIT_V(6); BAR; MMA(1, 1, At, B1); BAR;
;     LDB(B0, 1, 0); SCHED; LDA(At, 1, 0); STAGE(SA(0, 1), A, HALF, t + 2);
;     WAIT_L(8); BAR; WAIT_L(0); MMA(0, 0, At, B0); BAR; SCHED;
;     LDB(B1, 1, 1); STAGE(SB(1, 0), Bt, 0, t + 3);
;     BAR; WAIT_L(0); MMA(0, 1, At, B1); BAR;
;     LDA(At, 1, 1); STAGE(SA(1, 0), A, 0, t + 3);
	v_add_u32_e32 v15, s65, v15
	v_add3_u32 v133, s33, v65, v130
	v_readfirstlane_b32 s4, v15
	v_add_u32_e32 v15, s65, v13
	v_lshl_add_u64 v[32:33], v[8:9], 0, s[44:45]
	s_mov_b32 m0, s4
	v_readfirstlane_b32 s4, v15
	ds_read_b128 v[24:27], v133
	ds_read_b128 v[28:31], v133 offset:1024
	ds_read_b128 v[94:97], v133 offset:2048
	ds_read_b128 v[98:101], v133 offset:3072
	global_load_lds_dwordx4 v[32:33], off
	v_lshl_add_u64 v[32:33], v[10:11], 0, s[44:45]
	s_mov_b32 m0, s4
	s_nop 0
	global_load_lds_dwordx4 v[32:33], off
	s_barrier
	s_waitcnt lgkmcnt(0)
	v_mfma_f32_16x16x32_bf16 v[102:105], v[24:27], v[34:37], 0
	v_mfma_f32_16x16x32_bf16 v[32:35], v[94:97], v[34:37], 0
	v_mfma_f32_16x16x32_bf16 v[102:105], v[28:31], v[38:41], v[102:105]
	v_mfma_f32_16x16x32_bf16 v[32:35], v[98:101], v[38:41], v[32:35]
	v_mfma_f32_16x16x32_bf16 v[36:39], v[24:27], v[42:45], 0
	v_mfma_f32_16x16x32_bf16 v[40:43], v[94:97], v[42:45], 0
	v_mfma_f32_16x16x32_bf16 v[36:39], v[28:31], v[46:49], v[36:39]
	v_mfma_f32_16x16x32_bf16 v[40:43], v[98:101], v[46:49], v[40:43]
	v_mfma_f32_16x16x32_bf16 v[44:47], v[24:27], v[50:53], 0
	v_mfma_f32_16x16x32_bf16 v[24:27], v[24:27], v[58:61], 0
	v_mfma_f32_16x16x32_bf16 v[44:47], v[28:31], v[54:57], v[44:47]
	v_mfma_f32_16x16x32_bf16 v[48:51], v[94:97], v[50:53], 0
	v_mfma_f32_16x16x32_bf16 v[24:27], v[28:31], v[66:69], v[24:27]
	v_mfma_f32_16x16x32_bf16 v[28:31], v[94:97], v[58:61], 0
	v_mfma_f32_16x16x32_bf16 v[48:51], v[98:101], v[54:57], v[48:51]
	v_mfma_f32_16x16x32_bf16 v[28:31], v[98:101], v[66:69], v[28:31]
	v_lshl_add_u64 v[52:53], s[22:23], 0, v[0:1]
	v_readfirstlane_b32 s4, v12
	v_lshl_add_u64 v[52:53], v[52:53], 0, v[2:3]
	s_mov_b32 m0, s4
	v_add_u32_e32 v15, 0x2000, v12
	s_barrier
	global_load_lds_dwordx4 v[52:53], off
	v_lshl_add_u64 v[52:53], s[22:23], 0, v[4:5]
	v_readfirstlane_b32 s4, v15
	v_lshl_add_u64 v[52:53], v[52:53], 0, v[6:7]
	s_mov_b32 m0, s4
	s_nop 0
	global_load_lds_dwordx4 v[52:53], off
	s_barrier
	s_waitcnt lgkmcnt(0)
	s_barrier
	v_lshl_add_u64 v[52:53], s[62:63], 0, v[0:1]
	v_readfirstlane_b32 s4, v14
	v_add_u32_e32 v13, s33, v13
	v_lshl_add_u64 v[52:53], v[52:53], 0, v[2:3]
	s_mov_b32 m0, s4
	v_lshl_add_u64 v[14:15], s[62:63], 0, v[4:5]
	v_readfirstlane_b32 s4, v13
	global_load_lds_dwordx4 v[52:53], off
	v_lshl_add_u64 v[14:15], v[14:15], 0, v[6:7]
	s_mov_b32 m0, s4
	s_nop 0
	global_load_lds_dwordx4 v[14:15], off
	s_waitcnt vmcnt(6)
	s_barrier
	v_add3_u32 v134, s68, v65, v130
	s_barrier
	ds_read_b128 v[52:55], v134
	ds_read_b128 v[56:59], v134 offset:1024
	ds_read_b128 v[60:63], v134 offset:2048
	ds_read_b128 v[66:69], v134 offset:3072
	v_add_u32_e32 v13, 0x4000, v12
	v_lshl_add_u64 v[14:15], s[58:59], 0, v[0:1]
	v_readfirstlane_b32 s4, v13
	v_lshl_add_u64 v[14:15], v[14:15], 0, v[2:3]
	s_mov_b32 m0, s4
	v_add_u32_e32 v12, 0x6000, v12
	ds_read_b128 v[94:97], v132 offset:32768
	ds_read_b128 v[98:101], v132 offset:33792
	ds_read_b128 v[106:109], v138 offset:34816
	ds_read_b128 v[110:113], v138 offset:35840
	ds_read_b128 v[114:117], v138 offset:36864
	ds_read_b128 v[118:121], v138 offset:37888
	ds_read_b128 v[122:125], v138 offset:38912
	ds_read_b128 v[126:129], v138 offset:39936
	global_load_lds_dwordx4 v[14:15], off
	v_lshl_add_u64 v[14:15], s[58:59], 0, v[4:5]
	v_readfirstlane_b32 s4, v12
	v_lshl_add_u64 v[14:15], v[14:15], 0, v[6:7]
	s_mov_b32 m0, s4
	s_nop 0
	global_load_lds_dwordx4 v[14:15], off
	s_waitcnt lgkmcnt(8)
	s_barrier
	s_waitcnt lgkmcnt(0)
	v_mfma_f32_16x16x32_bf16 v[12:15], v[52:55], v[94:97], v[70:73]
	v_mfma_f32_16x16x32_bf16 v[16:19], v[52:55], v[122:125], v[16:19]
	v_mfma_f32_16x16x32_bf16 v[20:23], v[60:63], v[122:125], v[20:23]
	v_mfma_f32_16x16x32_bf16 v[12:15], v[56:59], v[98:101], v[12:15]
	v_mfma_f32_16x16x32_bf16 v[70:73], v[60:63], v[94:97], v[74:77]
	v_mfma_f32_16x16x32_bf16 v[74:77], v[52:55], v[106:109], v[78:81]
	v_mfma_f32_16x16x32_bf16 v[78:81], v[60:63], v[106:109], v[82:85]
	v_mfma_f32_16x16x32_bf16 v[82:85], v[52:55], v[114:117], v[86:89]
	v_mfma_f32_16x16x32_bf16 v[86:89], v[60:63], v[114:117], v[90:93]
	v_mfma_f32_16x16x32_bf16 v[16:19], v[56:59], v[126:129], v[16:19]
	v_mfma_f32_16x16x32_bf16 v[20:23], v[66:69], v[126:129], v[20:23]
	v_mfma_f32_16x16x32_bf16 v[70:73], v[66:69], v[98:101], v[70:73]
	v_mfma_f32_16x16x32_bf16 v[74:77], v[56:59], v[110:113], v[74:77]
	v_mfma_f32_16x16x32_bf16 v[78:81], v[66:69], v[110:113], v[78:81]
	v_mfma_f32_16x16x32_bf16 v[82:85], v[56:59], v[118:121], v[82:85]
	v_mfma_f32_16x16x32_bf16 v[86:89], v[66:69], v[118:121], v[86:89]
	s_barrier
	s_mov_b32 m0, s20
	v_add3_u32 v65, s5, v65, v130
	v_lshl_add_u64 v[8:9], v[8:9], 0, s[52:53]
	ds_read_b128 v[52:55], v65
	ds_read_b128 v[56:59], v65 offset:1024
	ds_read_b128 v[60:63], v65 offset:2048
	ds_read_b128 v[66:69], v65 offset:3072
	global_load_lds_dwordx4 v[8:9], off
	v_lshl_add_u64 v[8:9], v[10:11], 0, s[52:53]
	s_mov_b32 m0, s73
	s_nop 0
	global_load_lds_dwordx4 v[8:9], off
	s_barrier
	s_waitcnt lgkmcnt(0)
	v_mfma_f32_16x16x32_bf16 v[8:11], v[52:55], v[94:97], v[102:105]
	v_mfma_f32_16x16x32_bf16 v[32:35], v[60:63], v[94:97], v[32:35]
	v_mfma_f32_16x16x32_bf16 v[36:39], v[52:55], v[106:109], v[36:39]
	v_mfma_f32_16x16x32_bf16 v[40:43], v[60:63], v[106:109], v[40:43]
	v_mfma_f32_16x16x32_bf16 v[44:47], v[52:55], v[114:117], v[44:47]
	v_mfma_f32_16x16x32_bf16 v[48:51], v[60:63], v[114:117], v[48:51]
	v_mfma_f32_16x16x32_bf16 v[24:27], v[52:55], v[122:125], v[24:27]
	v_mfma_f32_16x16x32_bf16 v[28:31], v[60:63], v[122:125], v[28:31]
	v_mfma_f32_16x16x32_bf16 v[8:11], v[56:59], v[98:101], v[8:11]
	v_mfma_f32_16x16x32_bf16 v[32:35], v[66:69], v[98:101], v[32:35]
	v_mfma_f32_16x16x32_bf16 v[36:39], v[56:59], v[110:113], v[36:39]
	v_mfma_f32_16x16x32_bf16 v[40:43], v[66:69], v[110:113], v[40:43]
	v_mfma_f32_16x16x32_bf16 v[44:47], v[56:59], v[118:121], v[44:47]
	v_mfma_f32_16x16x32_bf16 v[48:51], v[66:69], v[118:121], v[48:51]
	v_mfma_f32_16x16x32_bf16 v[24:27], v[56:59], v[126:129], v[24:27]
	v_mfma_f32_16x16x32_bf16 v[28:31], v[66:69], v[126:129], v[28:31]
	v_lshl_add_u64 v[52:53], s[0:1], 0, v[0:1]
	s_mov_b32 m0, s72
	v_lshl_add_u64 v[52:53], v[52:53], 0, v[2:3]
	s_barrier
; #define WAIT_V(n) asm volatile("s_waitcnt vmcnt(" #n ")" ::: "memory")
; #define WAIT_L(n) asm volatile("s_waitcnt lgkmcnt(" #n ")" ::: "memory")
; #define BAR __builtin_amdgcn_s_barrier()
; #define SCHED __builtin_amdgcn_sched_barrier(0)
; #define LDA(dst, b, h)                                                                            \
;   _Pragma("unroll") for (int m = 0; m < 4; ++m) _Pragma("unroll") for (int k = 0; k < 2; ++k)                                         \
;     dst[m][k] = *reinterpret_cast<const bf16x8*>((char*)SA(b, h) + lds_byte(wr * 64 + m * 16 + fr, k * 32 + fq * 8))
; #define LDB(dst, b, h)                                                                            \
;   _Pragma("unroll") for (int n = 0; n < 2; ++n) _Pragma("unroll") for (int k = 0; k < 2; ++k)                                         \
;     dst[n][k] = *reinterpret_cast<const bf16x8*>((char*)SB(b, h) + lds_byte(wc * 32 + n * 16 + fr, k * 32 + fq * 8))
; template <int K, bool SWAP>
; __device__ __forceinline__ void gemm_kloop(const bf16* __restrict__ A, const bf16* __restrict__ Bt,
;                                            f32x4 (&acc)[2][2][4][2], bool pref = false) {
;     ...
;     LDA(At, 1, 1); STAGE(SA(1, 0), A, 0, t + 3);
;     BAR; WAIT_L(0); MMA(1, 0, At, B0); BAR; SCHED;
;     STAGE(SB(1, 1), Bt, HALF, t + 3);
;     WAIT_V(6); BAR; MMA(1, 1, At, B1); BAR;
;   }
;   { LDB(B0, 0, 0); LDA(At, 0, 0); STAGE(SA(1, 1), A, HALF, nt - 1);
;     BAR; WAIT_L(0); MMA(0, 0, At, B0); BAR;
;     LDB(B1, 0, 1); BAR; WAIT_L(0); MMA(0, 1, At, B1); BAR;
;     LDA(At, 0, 1); WAIT_V(4); BAR; WAIT_L(0); MMA(1, 0, At, B0); MMA(1, 1, At, B1); BAR; }
;   { LDB(B0, 1, 0); LDA(At, 1, 0); WAIT_V(2); BAR; WAIT_L(0); MMA(0, 0, At, B0); BAR;
;     LDB(B1, 1, 1); WAIT_V(0); BAR; WAIT_L(0); MMA(0, 1, At, B1); BAR;
;     LDA(At, 1, 1); BAR; WAIT_L(0); MMA(1, 0, At, B0); MMA(1, 1, At, B1); BAR; }
;   if (wr == 0) BAR;
	global_load_lds_dwordx4 v[52:53], off
	v_lshl_add_u64 v[52:53], s[0:1], 0, v[4:5]
	v_lshl_add_u64 v[52:53], v[52:53], 0, v[6:7]
	s_mov_b32 m0, s66
	s_nop 0
	global_load_lds_dwordx4 v[52:53], off
	s_barrier
	s_waitcnt lgkmcnt(0)
	s_barrier
	v_lshl_add_u64 v[52:53], vcc, 0, v[0:1]
	s_mov_b32 m0, s71
	v_lshl_add_u64 v[52:53], v[52:53], 0, v[2:3]
	global_load_lds_dwordx4 v[52:53], off
	v_lshl_add_u64 v[52:53], vcc, 0, v[4:5]
	v_lshl_add_u64 v[52:53], v[52:53], 0, v[6:7]
	s_mov_b32 m0, s67
	s_nop 0
	global_load_lds_dwordx4 v[52:53], off
	s_waitcnt vmcnt(6)
	s_barrier
	v_lshl_add_u64 v[0:1], s[60:61], 0, v[0:1]
	s_mov_b32 m0, s70
	v_lshl_add_u64 v[0:1], v[0:1], 0, v[2:3]
	s_barrier
	ds_read_b128 v[52:55], v131
	ds_read_b128 v[56:59], v131 offset:1024
	ds_read_b128 v[60:63], v131 offset:2048
	ds_read_b128 v[66:69], v131 offset:3072
	ds_read_b128 v[90:93], v132
	ds_read_b128 v[94:97], v132 offset:1024
	ds_read_b128 v[98:101], v138 offset:2048
	ds_read_b128 v[102:105], v138 offset:3072
	ds_read_b128 v[106:109], v138 offset:4096
	ds_read_b128 v[110:113], v138 offset:5120
	ds_read_b128 v[114:117], v138 offset:6144
	ds_read_b128 v[118:121], v138 offset:7168
	global_load_lds_dwordx4 v[0:1], off
	v_lshl_add_u64 v[0:1], s[60:61], 0, v[4:5]
	v_lshl_add_u64 v[0:1], v[0:1], 0, v[6:7]
	s_mov_b32 m0, s41
	s_nop 0
	global_load_lds_dwordx4 v[0:1], off
	s_barrier
	s_waitcnt lgkmcnt(0)
	v_mfma_f32_16x16x32_bf16 v[0:3], v[52:55], v[90:93], v[12:15]
	v_mfma_f32_16x16x32_bf16 v[4:7], v[60:63], v[90:93], v[70:73]
	v_mfma_f32_16x16x32_bf16 v[12:15], v[52:55], v[98:101], v[74:77]
	v_mfma_f32_16x16x32_bf16 v[16:19], v[52:55], v[114:117], v[16:19]
	v_mfma_f32_16x16x32_bf16 v[20:23], v[60:63], v[114:117], v[20:23]
	v_mfma_f32_16x16x32_bf16 v[0:3], v[56:59], v[94:97], v[0:3]
	v_mfma_f32_16x16x32_bf16 v[4:7], v[66:69], v[94:97], v[4:7]
	v_mfma_f32_16x16x32_bf16 v[12:15], v[56:59], v[102:105], v[12:15]
	v_mfma_f32_16x16x32_bf16 v[70:73], v[60:63], v[98:101], v[78:81]
	v_mfma_f32_16x16x32_bf16 v[74:77], v[52:55], v[106:109], v[82:85]
	v_mfma_f32_16x16x32_bf16 v[78:81], v[60:63], v[106:109], v[86:89]
	v_mfma_f32_16x16x32_bf16 v[16:19], v[56:59], v[118:121], v[16:19]
	v_mfma_f32_16x16x32_bf16 v[20:23], v[66:69], v[118:121], v[20:23]
	v_mfma_f32_16x16x32_bf16 v[70:73], v[66:69], v[102:105], v[70:73]
	v_mfma_f32_16x16x32_bf16 v[74:77], v[56:59], v[110:113], v[74:77]
	v_mfma_f32_16x16x32_bf16 v[78:81], v[66:69], v[110:113], v[78:81]
	s_barrier
	ds_read_b128 v[52:55], v133
	ds_read_b128 v[56:59], v133 offset:1024
	ds_read_b128 v[60:63], v133 offset:2048
	ds_read_b128 v[66:69], v133 offset:3072
	s_barrier
	s_waitcnt lgkmcnt(0)
	v_mfma_f32_16x16x32_bf16 v[32:35], v[60:63], v[90:93], v[32:35]
	v_mfma_f32_16x16x32_bf16 v[82:85], v[66:69], v[94:97], v[32:35]
	v_mfma_f32_16x16x32_bf16 v[32:35], v[52:55], v[98:101], v[36:39]
	v_mfma_f32_16x16x32_bf16 v[86:89], v[56:59], v[102:105], v[32:35]
	v_mfma_f32_16x16x32_bf16 v[32:35], v[60:63], v[98:101], v[40:43]
	v_mfma_f32_16x16x32_bf16 v[8:11], v[52:55], v[90:93], v[8:11]
	v_mfma_f32_16x16x32_bf16 v[90:93], v[66:69], v[102:105], v[32:35]
	v_mfma_f32_16x16x32_bf16 v[32:35], v[52:55], v[106:109], v[44:47]
	v_mfma_f32_16x16x32_bf16 v[24:27], v[52:55], v[114:117], v[24:27]
	v_mfma_f32_16x16x32_bf16 v[8:11], v[56:59], v[94:97], v[8:11]
	v_mfma_f32_16x16x32_bf16 v[94:97], v[56:59], v[110:113], v[32:35]
	v_mfma_f32_16x16x32_bf16 v[32:35], v[60:63], v[106:109], v[48:51]
	v_mfma_f32_16x16x32_bf16 v[102:105], v[56:59], v[118:121], v[24:27]
	v_mfma_f32_16x16x32_bf16 v[24:27], v[60:63], v[114:117], v[28:31]
	v_mfma_f32_16x16x32_bf16 v[98:101], v[66:69], v[110:113], v[32:35]
	v_mfma_f32_16x16x32_bf16 v[66:69], v[66:69], v[118:121], v[24:27]
	s_barrier
	s_waitcnt vmcnt(4)
	s_barrier
	s_waitcnt lgkmcnt(0)
	s_barrier
	ds_read_b128 v[24:27], v134
	ds_read_b128 v[28:31], v134 offset:1024
	ds_read_b128 v[32:35], v134 offset:2048
	ds_read_b128 v[106:109], v134 offset:3072
	ds_read_b128 v[110:113], v132 offset:32768
	ds_read_b128 v[114:117], v132 offset:33792
	ds_read_b128 v[118:121], v138 offset:34816
	ds_read_b128 v[122:125], v138 offset:35840
	ds_read_b128 v[126:129], v138 offset:36864
	ds_read_b128 v[130:133], v138 offset:37888
	ds_read_b128 v[134:137], v138 offset:38912
	ds_read_b128 v[138:141], v138 offset:39936
	s_waitcnt vmcnt(2)
	s_barrier
	s_waitcnt lgkmcnt(0)
	v_mfma_f32_16x16x32_bf16 v[0:3], v[24:27], v[110:113], v[0:3]
	v_mfma_f32_16x16x32_bf16 v[60:63], v[28:31], v[114:117], v[0:3]
	v_mfma_f32_16x16x32_bf16 v[0:3], v[32:35], v[110:113], v[4:7]
	v_mfma_f32_16x16x32_bf16 v[56:59], v[106:109], v[114:117], v[0:3]
	v_mfma_f32_16x16x32_bf16 v[0:3], v[24:27], v[118:121], v[12:15]
	v_mfma_f32_16x16x32_bf16 v[52:55], v[28:31], v[122:125], v[0:3]
	v_mfma_f32_16x16x32_bf16 v[0:3], v[32:35], v[118:121], v[70:73]
	v_mfma_f32_16x16x32_bf16 v[48:51], v[106:109], v[122:125], v[0:3]
	v_mfma_f32_16x16x32_bf16 v[0:3], v[24:27], v[126:129], v[74:77]
	v_mfma_f32_16x16x32_bf16 v[44:47], v[28:31], v[130:133], v[0:3]
	v_mfma_f32_16x16x32_bf16 v[0:3], v[32:35], v[126:129], v[78:81]
	v_mfma_f32_16x16x32_bf16 v[40:43], v[106:109], v[130:133], v[0:3]
	v_mfma_f32_16x16x32_bf16 v[0:3], v[24:27], v[134:137], v[16:19]
	v_mfma_f32_16x16x32_bf16 v[36:39], v[28:31], v[138:141], v[0:3]
	v_mfma_f32_16x16x32_bf16 v[0:3], v[32:35], v[134:137], v[20:23]
	v_mfma_f32_16x16x32_bf16 v[32:35], v[106:109], v[138:141], v[0:3]
	s_barrier
	s_nop 4
	ds_read_b128 v[0:3], v65
	ds_read_b128 v[4:7], v65 offset:1024
	ds_read_b128 v[70:73], v65 offset:2048
	ds_read_b128 v[74:77], v65 offset:3072
	s_waitcnt vmcnt(0)
	s_barrier
	s_waitcnt lgkmcnt(0)
	v_mfma_f32_16x16x32_bf16 v[8:11], v[0:3], v[110:113], v[8:11]
	v_mfma_f32_16x16x32_bf16 v[28:31], v[4:7], v[114:117], v[8:11]
	v_mfma_f32_16x16x32_bf16 v[8:11], v[70:73], v[110:113], v[82:85]
	v_mfma_f32_16x16x32_bf16 v[24:27], v[74:77], v[114:117], v[8:11]
	v_mfma_f32_16x16x32_bf16 v[8:11], v[0:3], v[118:121], v[86:89]
	v_mfma_f32_16x16x32_bf16 v[20:23], v[4:7], v[122:125], v[8:11]
	v_mfma_f32_16x16x32_bf16 v[8:11], v[70:73], v[118:121], v[90:93]
	v_mfma_f32_16x16x32_bf16 v[16:19], v[74:77], v[122:125], v[8:11]
	v_mfma_f32_16x16x32_bf16 v[8:11], v[0:3], v[126:129], v[94:97]
	v_mfma_f32_16x16x32_bf16 v[0:3], v[0:3], v[134:137], v[102:105]
	v_mfma_f32_16x16x32_bf16 v[12:15], v[4:7], v[130:133], v[8:11]
	v_mfma_f32_16x16x32_bf16 v[8:11], v[70:73], v[126:129], v[98:101]
	v_mfma_f32_16x16x32_bf16 v[4:7], v[4:7], v[138:141], v[0:3]
	v_mfma_f32_16x16x32_bf16 v[0:3], v[70:73], v[134:137], v[66:69]
	v_mfma_f32_16x16x32_bf16 v[8:11], v[74:77], v[130:133], v[8:11]
	v_mfma_f32_16x16x32_bf16 v[0:3], v[74:77], v[138:141], v[0:3]
	s_barrier
	s_barrier
	s_waitcnt lgkmcnt(0)
	s_movk_i32 s4, 0x100
	v_cmp_gt_u32_e32 vcc, s4, v64
	s_barrier
	s_and_saveexec_b64 s[62:63], vcc
	s_cbranch_execz .LBB0_721
	s_barrier

; #define WAIT_V(n) asm volatile("s_waitcnt vmcnt(" #n ")" ::: "memory")
; #define WAIT_L(n) asm volatile("s_waitcnt lgkmcnt(" #n ")" ::: "memory")
; #define BAR __builtin_amdgcn_s_barrier()
; #define SCHED __builtin_amdgcn_sched_barrier(0)
; #define LDA(dst, b, h)                                                                            \
;   _Pragma("unroll") for (int m = 0; m < 4; ++m) _Pragma("unroll") for (int k = 0; k < 2; ++k)                                         \
;     dst[m][k] = *reinterpret_cast<const bf16x8*>((char*)SA(b, h) + lds_byte(wr * 64 + m * 16 + fr, k * 32 + fq * 8))
; #define LDB(dst, b, h)                                                                            \
;   _Pragma("unroll") for (int n = 0; n < 2; ++n) _Pragma("unroll") for (int k = 0; k < 2; ++k)                                         \
;     dst[n][k] = *reinterpret_cast<const bf16x8*>((char*)SB(b, h) + lds_byte(wc * 32 + n * 16 + fr, k * 32 + fq * 8))
; template <int K, bool SWAP>
; __device__ __forceinline__ void gemm_kloop(const bf16* __restrict__ A, const bf16* __restrict__ Bt,
;                                            f32x4 (&acc)[2][2][4][2], bool pref = false) {
;     ...
;     LDB(B0, 0, 0); SCHED; LDA(At, 0, 0); STAGE(SA(1, 1), A, HALF, t + 1);
;     WAIT_L(8); BAR; WAIT_L(0); MMA(0, 0, At, B0); BAR; SCHED;
;     LDB(B1, 0, 1); STAGE(SB(0, 0), Bt, 0, t + 2);
;     BAR; WAIT_L(0); MMA(0, 1, At, B1); BAR;
;     LDA(At, 0, 1); STAGE(SA(0, 0), A, 0, t + 2);
;     BAR; WAIT_L(0); MMA(1, 0, At, B0); BAR; SCHED;
;     STAGE(SB(0, 1), Bt, HALF, t + 2);
;     WAIT_V(6); BAR; MMA(1, 1, At, B1); BAR;
.LBB0_791:
	ds_read_b128 v[162:165], v159
	ds_read_b128 v[166:169], v159 offset:1024
	ds_read_b128 v[170:173], v159 offset:2048
	ds_read_b128 v[174:177], v159 offset:3072
	v_add_u32_e32 v160, 0xc000, v145
	v_lshl_add_u64 v[178:179], s[6:7], 0, v[140:141]
	v_readfirstlane_b32 s13, v160
	v_lshl_add_u64 v[188:189], v[178:179], 0, s[74:75]
	s_mov_b32 m0, s13
	v_add_u32_e32 v161, 0xe000, v145
	ds_read_b128 v[198:201], v156
	ds_read_b128 v[202:205], v156 offset:1024
	ds_read_b128 v[206:209], v151
	ds_read_b128 v[210:213], v151 offset:1024
	ds_read_b128 v[214:217], v150
	ds_read_b128 v[218:221], v150 offset:1024
	ds_read_b128 v[222:225], v149
	ds_read_b128 v[226:229], v149 offset:1024
	global_load_lds_dwordx4 v[188:189], off
	v_lshl_add_u64 v[188:189], s[6:7], 0, v[142:143]
	v_readfirstlane_b32 s13, v161
	v_lshl_add_u64 v[230:231], v[188:189], 0, s[74:75]
	s_mov_b32 m0, s13
	s_nop 0
	global_load_lds_dwordx4 v[230:231], off
	s_waitcnt lgkmcnt(8)
	s_barrier
	s_waitcnt lgkmcnt(0)
	v_mfma_f32_16x16x32_bf16 v[124:127], v[162:165], v[198:201], v[124:127]
	v_mfma_f32_16x16x32_bf16 v[120:123], v[170:173], v[198:201], v[120:123]
	v_mfma_f32_16x16x32_bf16 v[112:115], v[170:173], v[206:209], v[112:115]
	v_mfma_f32_16x16x32_bf16 v[116:119], v[162:165], v[206:209], v[116:119]
	v_mfma_f32_16x16x32_bf16 v[108:111], v[162:165], v[214:217], v[108:111]
	v_mfma_f32_16x16x32_bf16 v[104:107], v[170:173], v[214:217], v[104:107]
	v_mfma_f32_16x16x32_bf16 v[96:99], v[170:173], v[222:225], v[96:99]
	v_mfma_f32_16x16x32_bf16 v[100:103], v[162:165], v[222:225], v[100:103]
	v_mfma_f32_16x16x32_bf16 v[124:127], v[166:169], v[202:205], v[124:127]
	v_mfma_f32_16x16x32_bf16 v[120:123], v[174:177], v[202:205], v[120:123]
	v_mfma_f32_16x16x32_bf16 v[112:115], v[174:177], v[210:213], v[112:115]
	v_mfma_f32_16x16x32_bf16 v[116:119], v[166:169], v[210:213], v[116:119]
	v_mfma_f32_16x16x32_bf16 v[108:111], v[166:169], v[218:221], v[108:111]
	v_mfma_f32_16x16x32_bf16 v[104:107], v[174:177], v[218:221], v[104:107]
	v_mfma_f32_16x16x32_bf16 v[96:99], v[174:177], v[226:229], v[96:99]
	v_mfma_f32_16x16x32_bf16 v[100:103], v[166:169], v[226:229], v[100:103]
	s_barrier
	v_add_u32_e32 v186, s9, v144
	v_lshl_add_u64 v[246:247], s[6:7], 0, v[136:137]
	v_readfirstlane_b32 s13, v186
	v_lshl_add_u64 v[248:249], v[246:247], 0, s[76:77]
	s_mov_b32 m0, s13
	v_add_u32_e32 v186, 0x2000, v186
	ds_read_b128 v[230:233], v158
	ds_read_b128 v[234:237], v158 offset:1024
	ds_read_b128 v[238:241], v158 offset:2048
	ds_read_b128 v[242:245], v158 offset:3072
	global_load_lds_dwordx4 v[248:249], off
	v_lshl_add_u64 v[248:249], s[6:7], 0, v[138:139]
	v_readfirstlane_b32 s13, v186
	v_lshl_add_u64 v[250:251], v[248:249], 0, s[76:77]
	s_mov_b32 m0, s13
	s_nop 0
	global_load_lds_dwordx4 v[250:251], off
	s_barrier
	s_waitcnt lgkmcnt(0)
	v_mfma_f32_16x16x32_bf16 v[92:95], v[230:233], v[198:201], v[92:95]
	v_mfma_f32_16x16x32_bf16 v[88:91], v[238:241], v[198:201], v[88:91]
	v_mfma_f32_16x16x32_bf16 v[80:83], v[238:241], v[206:209], v[80:83]
	v_mfma_f32_16x16x32_bf16 v[84:87], v[230:233], v[206:209], v[84:87]
	v_mfma_f32_16x16x32_bf16 v[76:79], v[230:233], v[214:217], v[76:79]
	v_mfma_f32_16x16x32_bf16 v[72:75], v[238:241], v[214:217], v[72:75]
	v_mfma_f32_16x16x32_bf16 v[64:67], v[238:241], v[222:225], v[64:67]
	v_mfma_f32_16x16x32_bf16 v[68:71], v[230:233], v[222:225], v[68:71]
	v_mfma_f32_16x16x32_bf16 v[92:95], v[234:237], v[202:205], v[92:95]
	v_mfma_f32_16x16x32_bf16 v[88:91], v[242:245], v[202:205], v[88:91]
	v_mfma_f32_16x16x32_bf16 v[80:83], v[242:245], v[210:213], v[80:83]
	v_mfma_f32_16x16x32_bf16 v[84:87], v[234:237], v[210:213], v[84:87]
	v_mfma_f32_16x16x32_bf16 v[76:79], v[234:237], v[218:221], v[76:79]
	v_mfma_f32_16x16x32_bf16 v[72:75], v[242:245], v[218:221], v[72:75]
	v_mfma_f32_16x16x32_bf16 v[64:67], v[242:245], v[226:229], v[64:67]
	v_mfma_f32_16x16x32_bf16 v[68:71], v[234:237], v[226:229], v[68:71]
	v_readfirstlane_b32 s13, v145
	v_add_u32_e32 v186, 0x2000, v145
	v_lshl_add_u64 v[250:251], v[178:179], 0, s[46:47]
	s_mov_b32 m0, s13
	v_readfirstlane_b32 s13, v186
	s_barrier
	ds_read_b128 v[198:201], v156 offset:16384
	ds_read_b128 v[202:205], v156 offset:17408
	ds_read_b128 v[206:209], v151 offset:16384
	ds_read_b128 v[210:213], v151 offset:17408
	ds_read_b128 v[214:217], v150 offset:16384
	ds_read_b128 v[218:221], v150 offset:17408
	ds_read_b128 v[222:225], v149 offset:16384
	ds_read_b128 v[226:229], v149 offset:17408
	global_load_lds_dwordx4 v[250:251], off
	v_lshl_add_u64 v[250:251], v[188:189], 0, s[46:47]
	s_mov_b32 m0, s13
	s_nop 0
	global_load_lds_dwordx4 v[250:251], off
	s_barrier
	s_waitcnt lgkmcnt(0)
	v_mfma_f32_16x16x32_bf16 v[60:63], v[162:165], v[198:201], v[60:63]
	v_mfma_f32_16x16x32_bf16 v[56:59], v[170:173], v[198:201], v[56:59]
	v_mfma_f32_16x16x32_bf16 v[48:51], v[170:173], v[206:209], v[48:51]
	v_mfma_f32_16x16x32_bf16 v[52:55], v[162:165], v[206:209], v[52:55]
	v_mfma_f32_16x16x32_bf16 v[44:47], v[162:165], v[214:217], v[44:47]
	v_mfma_f32_16x16x32_bf16 v[40:43], v[170:173], v[214:217], v[40:43]
	v_mfma_f32_16x16x32_bf16 v[32:35], v[170:173], v[222:225], v[32:35]
	v_mfma_f32_16x16x32_bf16 v[36:39], v[162:165], v[222:225], v[36:39]
	v_mfma_f32_16x16x32_bf16 v[60:63], v[166:169], v[202:205], v[60:63]
	v_mfma_f32_16x16x32_bf16 v[56:59], v[174:177], v[202:205], v[56:59]
	v_mfma_f32_16x16x32_bf16 v[48:51], v[174:177], v[210:213], v[48:51]
	v_mfma_f32_16x16x32_bf16 v[52:55], v[166:169], v[210:213], v[52:55]
	v_mfma_f32_16x16x32_bf16 v[44:47], v[166:169], v[218:221], v[44:47]
	v_mfma_f32_16x16x32_bf16 v[40:43], v[174:177], v[218:221], v[40:43]
	v_mfma_f32_16x16x32_bf16 v[32:35], v[174:177], v[226:229], v[32:35]
	v_mfma_f32_16x16x32_bf16 v[36:39], v[166:169], v[226:229], v[36:39]
	s_barrier
; #define WAIT_V(n) asm volatile("s_waitcnt vmcnt(" #n ")" ::: "memory")
; #define WAIT_L(n) asm volatile("s_waitcnt lgkmcnt(" #n ")" ::: "memory")
; #define BAR __builtin_amdgcn_s_barrier()
; #define SCHED __builtin_amdgcn_sched_barrier(0)
; #define LDA(dst, b, h)                                                                            \
;   _Pragma("unroll") for (int m = 0; m < 4; ++m) _Pragma("unroll") for (int k = 0; k < 2; ++k)                                         \
;     dst[m][k] = *reinterpret_cast<const bf16x8*>((char*)SA(b, h) + lds_byte(wr * 64 + m * 16 + fr, k * 32 + fq * 8))
; #define LDB(dst, b, h)                                                                            \
;   _Pragma("unroll") for (int n = 0; n < 2; ++n) _Pragma("unroll") for (int k = 0; k < 2; ++k)                                         \
;     dst[n][k] = *reinterpret_cast<const bf16x8*>((char*)SB(b, h) + lds_byte(wc * 32 + n * 16 + fr, k * 32 + fq * 8))
; template <int K, bool SWAP>
; __device__ __forceinline__ void gemm_kloop(const bf16* __restrict__ A, const bf16* __restrict__ Bt,
;                                            f32x4 (&acc)[2][2][4][2], bool pref = false) {
;     ...
;     WAIT_V(6); BAR; MMA(1, 1, At, B1); BAR;
;     LDB(B0, 1, 0); SCHED; LDA(At, 1, 0); STAGE(SA(0, 1), A, HALF, t + 2);
;     WAIT_L(8); BAR; WAIT_L(0); MMA(0, 0, At, B0); BAR; SCHED;
;     LDB(B1, 1, 1); STAGE(SB(1, 0), Bt, 0, t + 3);
;     BAR; WAIT_L(0); MMA(0, 1, At, B1); BAR;
;     LDA(At, 1, 1); STAGE(SA(1, 0), A, 0, t + 3);
;     BAR; WAIT_L(0); MMA(1, 0, At, B0); BAR; SCHED;
;     STAGE(SB(1, 1), Bt, HALF, t + 3);
	v_readfirstlane_b32 s13, v146
	v_add_u32_e32 v164, 0x2000, v146
	v_lshl_add_u64 v[162:163], v[246:247], 0, s[78:79]
	s_mov_b32 m0, s13
	v_readfirstlane_b32 s13, v164
	global_load_lds_dwordx4 v[162:163], off
	v_lshl_add_u64 v[162:163], v[248:249], 0, s[78:79]
	s_mov_b32 m0, s13
	s_nop 0
	global_load_lds_dwordx4 v[162:163], off
	s_waitcnt vmcnt(6)
	s_barrier
	v_mfma_f32_16x16x32_bf16 v[28:31], v[230:233], v[198:201], v[28:31]
	v_mfma_f32_16x16x32_bf16 v[24:27], v[238:241], v[198:201], v[24:27]
	v_mfma_f32_16x16x32_bf16 v[16:19], v[238:241], v[206:209], v[16:19]
	v_mfma_f32_16x16x32_bf16 v[20:23], v[230:233], v[206:209], v[20:23]
	v_mfma_f32_16x16x32_bf16 v[12:15], v[230:233], v[214:217], v[12:15]
	v_mfma_f32_16x16x32_bf16 v[8:11], v[238:241], v[214:217], v[8:11]
	v_mfma_f32_16x16x32_bf16 v[0:3], v[238:241], v[222:225], v[0:3]
	v_mfma_f32_16x16x32_bf16 v[4:7], v[230:233], v[222:225], v[4:7]
	v_mfma_f32_16x16x32_bf16 v[28:31], v[234:237], v[202:205], v[28:31]
	v_mfma_f32_16x16x32_bf16 v[24:27], v[242:245], v[202:205], v[24:27]
	v_mfma_f32_16x16x32_bf16 v[16:19], v[242:245], v[210:213], v[16:19]
	v_mfma_f32_16x16x32_bf16 v[20:23], v[234:237], v[210:213], v[20:23]
	v_mfma_f32_16x16x32_bf16 v[12:15], v[234:237], v[218:221], v[12:15]
	v_mfma_f32_16x16x32_bf16 v[8:11], v[242:245], v[218:221], v[8:11]
	v_mfma_f32_16x16x32_bf16 v[0:3], v[242:245], v[226:229], v[0:3]
	v_mfma_f32_16x16x32_bf16 v[4:7], v[234:237], v[226:229], v[4:7]
	s_barrier
	ds_read_b128 v[162:165], v147
	ds_read_b128 v[166:169], v147 offset:1024
	ds_read_b128 v[170:173], v147 offset:2048
	ds_read_b128 v[174:177], v147 offset:3072
	v_add_u32_e32 v186, 0x4000, v145
	v_lshl_add_u64 v[230:231], v[178:179], 0, s[80:81]
	v_readfirstlane_b32 s13, v186
	v_add_u32_e32 v186, 0x6000, v145
	s_mov_b32 m0, s13
	v_readfirstlane_b32 s13, v186
	ds_read_b128 v[198:201], v156 offset:32768
	ds_read_b128 v[202:205], v156 offset:33792
	ds_read_b128 v[206:209], v151 offset:32768
	ds_read_b128 v[210:213], v151 offset:33792
	ds_read_b128 v[214:217], v150 offset:32768
	ds_read_b128 v[218:221], v150 offset:33792
	ds_read_b128 v[222:225], v149 offset:32768
	ds_read_b128 v[226:229], v149 offset:33792
	global_load_lds_dwordx4 v[230:231], off
	v_lshl_add_u64 v[230:231], v[188:189], 0, s[80:81]
	s_mov_b32 m0, s13
	s_nop 0
	global_load_lds_dwordx4 v[230:231], off
	s_waitcnt lgkmcnt(8)
	s_barrier
	s_waitcnt lgkmcnt(0)
	v_mfma_f32_16x16x32_bf16 v[124:127], v[162:165], v[198:201], v[124:127]
	v_mfma_f32_16x16x32_bf16 v[120:123], v[170:173], v[198:201], v[120:123]
	v_mfma_f32_16x16x32_bf16 v[112:115], v[170:173], v[206:209], v[112:115]
	v_mfma_f32_16x16x32_bf16 v[116:119], v[162:165], v[206:209], v[116:119]
	v_mfma_f32_16x16x32_bf16 v[108:111], v[162:165], v[214:217], v[108:111]
	v_mfma_f32_16x16x32_bf16 v[104:107], v[170:173], v[214:217], v[104:107]
	v_mfma_f32_16x16x32_bf16 v[96:99], v[170:173], v[222:225], v[96:99]
	v_mfma_f32_16x16x32_bf16 v[100:103], v[162:165], v[222:225], v[100:103]
	v_mfma_f32_16x16x32_bf16 v[124:127], v[166:169], v[202:205], v[124:127]
	v_mfma_f32_16x16x32_bf16 v[120:123], v[174:177], v[202:205], v[120:123]
	v_mfma_f32_16x16x32_bf16 v[112:115], v[174:177], v[210:213], v[112:115]
	v_mfma_f32_16x16x32_bf16 v[116:119], v[166:169], v[210:213], v[116:119]
	v_mfma_f32_16x16x32_bf16 v[108:111], v[166:169], v[218:221], v[108:111]
	v_mfma_f32_16x16x32_bf16 v[104:107], v[174:177], v[218:221], v[104:107]
	v_mfma_f32_16x16x32_bf16 v[96:99], v[174:177], v[226:229], v[96:99]
	v_mfma_f32_16x16x32_bf16 v[100:103], v[166:169], v[226:229], v[100:103]
	s_barrier
	v_readfirstlane_b32 s13, v152
	v_add_u32_e32 v186, 0x2000, v152
	v_lshl_add_u64 v[250:251], v[246:247], 0, s[82:83]
	s_mov_b32 m0, s13
	v_readfirstlane_b32 s13, v186
	ds_read_b128 v[230:233], v157
	ds_read_b128 v[234:237], v157 offset:1024
	ds_read_b128 v[238:241], v157 offset:2048
	ds_read_b128 v[242:245], v157 offset:3072
	global_load_lds_dwordx4 v[250:251], off
	v_lshl_add_u64 v[250:251], v[248:249], 0, s[82:83]
	s_mov_b32 m0, s13
	s_nop 0
	global_load_lds_dwordx4 v[250:251], off
	s_barrier
	s_waitcnt lgkmcnt(0)
	v_mfma_f32_16x16x32_bf16 v[92:95], v[230:233], v[198:201], v[92:95]
	v_mfma_f32_16x16x32_bf16 v[88:91], v[238:241], v[198:201], v[88:91]
	v_mfma_f32_16x16x32_bf16 v[80:83], v[238:241], v[206:209], v[80:83]
	v_mfma_f32_16x16x32_bf16 v[84:87], v[230:233], v[206:209], v[84:87]
	v_mfma_f32_16x16x32_bf16 v[76:79], v[230:233], v[214:217], v[76:79]
	v_mfma_f32_16x16x32_bf16 v[72:75], v[238:241], v[214:217], v[72:75]
	v_mfma_f32_16x16x32_bf16 v[64:67], v[238:241], v[222:225], v[64:67]
	v_mfma_f32_16x16x32_bf16 v[68:71], v[230:233], v[222:225], v[68:71]
	v_mfma_f32_16x16x32_bf16 v[92:95], v[234:237], v[202:205], v[92:95]
	v_mfma_f32_16x16x32_bf16 v[88:91], v[242:245], v[202:205], v[88:91]
	v_mfma_f32_16x16x32_bf16 v[80:83], v[242:245], v[210:213], v[80:83]
	v_mfma_f32_16x16x32_bf16 v[84:87], v[234:237], v[210:213], v[84:87]
	v_mfma_f32_16x16x32_bf16 v[76:79], v[234:237], v[218:221], v[76:79]
	v_mfma_f32_16x16x32_bf16 v[72:75], v[242:245], v[218:221], v[72:75]
	v_mfma_f32_16x16x32_bf16 v[64:67], v[242:245], v[226:229], v[64:67]
	v_mfma_f32_16x16x32_bf16 v[68:71], v[234:237], v[226:229], v[68:71]
	v_readfirstlane_b32 s13, v153
	v_lshl_add_u64 v[178:179], v[178:179], 0, s[54:55]
	s_mov_b32 m0, s13
	v_readfirstlane_b32 s13, v154
	s_barrier
	ds_read_b128 v[198:201], v156 offset:49152
	ds_read_b128 v[202:205], v156 offset:50176
	ds_read_b128 v[206:209], v151 offset:49152
	ds_read_b128 v[210:213], v151 offset:50176
	ds_read_b128 v[214:217], v150 offset:49152
	ds_read_b128 v[218:221], v150 offset:50176
	ds_read_b128 v[222:225], v149 offset:49152
	ds_read_b128 v[226:229], v149 offset:50176
	global_load_lds_dwordx4 v[178:179], off
	v_lshl_add_u64 v[178:179], v[188:189], 0, s[54:55]
	s_mov_b32 m0, s13
	s_nop 0
	global_load_lds_dwordx4 v[178:179], off
	s_barrier
; #define WAIT_V(n) asm volatile("s_waitcnt vmcnt(" #n ")" ::: "memory")
; #define WAIT_L(n) asm volatile("s_waitcnt lgkmcnt(" #n ")" ::: "memory")
; #define BAR __builtin_amdgcn_s_barrier()
; #define LDA(dst, b, h)                                                                            \
;   _Pragma("unroll") for (int m = 0; m < 4; ++m) _Pragma("unroll") for (int k = 0; k < 2; ++k)                                         \
;     dst[m][k] = *reinterpret_cast<const bf16x8*>((char*)SA(b, h) + lds_byte(wr * 64 + m * 16 + fr, k * 32 + fq * 8))
; #define LDB(dst, b, h)                                                                            \
;   _Pragma("unroll") for (int n = 0; n < 2; ++n) _Pragma("unroll") for (int k = 0; k < 2; ++k)                                         \
;     dst[n][k] = *reinterpret_cast<const bf16x8*>((char*)SB(b, h) + lds_byte(wc * 32 + n * 16 + fr, k * 32 + fq * 8))
; template <int K, bool SWAP>
; __device__ __forceinline__ void gemm_kloop(const bf16* __restrict__ A, const bf16* __restrict__ Bt,
;                                            f32x4 (&acc)[2][2][4][2], bool pref = false) {
;     ...
;     STAGE(SB(1, 1), Bt, HALF, t + 3);
;     WAIT_V(6); BAR; MMA(1, 1, At, B1); BAR;
;   }
;   { LDB(B0, 0, 0); LDA(At, 0, 0); STAGE(SA(1, 1), A, HALF, nt - 1);
;     BAR; WAIT_L(0); MMA(0, 0, At, B0); BAR;
	s_waitcnt lgkmcnt(0)
	v_mfma_f32_16x16x32_bf16 v[60:63], v[162:165], v[198:201], v[60:63]
	v_mfma_f32_16x16x32_bf16 v[56:59], v[170:173], v[198:201], v[56:59]
	v_mfma_f32_16x16x32_bf16 v[48:51], v[170:173], v[206:209], v[48:51]
	v_mfma_f32_16x16x32_bf16 v[52:55], v[162:165], v[206:209], v[52:55]
	v_mfma_f32_16x16x32_bf16 v[44:47], v[162:165], v[214:217], v[44:47]
	v_mfma_f32_16x16x32_bf16 v[40:43], v[170:173], v[214:217], v[40:43]
	v_mfma_f32_16x16x32_bf16 v[32:35], v[170:173], v[222:225], v[32:35]
	v_mfma_f32_16x16x32_bf16 v[36:39], v[162:165], v[222:225], v[36:39]
	v_mfma_f32_16x16x32_bf16 v[60:63], v[166:169], v[202:205], v[60:63]
	v_mfma_f32_16x16x32_bf16 v[56:59], v[174:177], v[202:205], v[56:59]
	v_mfma_f32_16x16x32_bf16 v[48:51], v[174:177], v[210:213], v[48:51]
	v_mfma_f32_16x16x32_bf16 v[52:55], v[166:169], v[210:213], v[52:55]
	v_mfma_f32_16x16x32_bf16 v[44:47], v[166:169], v[218:221], v[44:47]
	v_mfma_f32_16x16x32_bf16 v[40:43], v[174:177], v[218:221], v[40:43]
	v_mfma_f32_16x16x32_bf16 v[32:35], v[174:177], v[226:229], v[32:35]
	v_mfma_f32_16x16x32_bf16 v[36:39], v[166:169], v[226:229], v[36:39]
	s_barrier
	v_readfirstlane_b32 s13, v155
	v_add_u32_e32 v164, 0x2000, v155
	v_lshl_add_u64 v[162:163], v[246:247], 0, s[84:85]
	s_mov_b32 m0, s13
	v_readfirstlane_b32 s13, v164
	global_load_lds_dwordx4 v[162:163], off
	v_lshl_add_u64 v[162:163], v[248:249], 0, s[84:85]
	s_mov_b32 m0, s13
	s_nop 0
	global_load_lds_dwordx4 v[162:163], off
	s_waitcnt vmcnt(6)
	s_barrier
	v_mfma_f32_16x16x32_bf16 v[28:31], v[230:233], v[198:201], v[28:31]
	v_mfma_f32_16x16x32_bf16 v[24:27], v[238:241], v[198:201], v[24:27]
	v_mfma_f32_16x16x32_bf16 v[16:19], v[238:241], v[206:209], v[16:19]
	v_mfma_f32_16x16x32_bf16 v[20:23], v[230:233], v[206:209], v[20:23]
	v_mfma_f32_16x16x32_bf16 v[12:15], v[230:233], v[214:217], v[12:15]
	v_mfma_f32_16x16x32_bf16 v[8:11], v[238:241], v[214:217], v[8:11]
	v_mfma_f32_16x16x32_bf16 v[0:3], v[238:241], v[222:225], v[0:3]
	v_mfma_f32_16x16x32_bf16 v[4:7], v[230:233], v[222:225], v[4:7]
	v_mfma_f32_16x16x32_bf16 v[28:31], v[234:237], v[202:205], v[28:31]
	v_mfma_f32_16x16x32_bf16 v[24:27], v[242:245], v[202:205], v[24:27]
	v_mfma_f32_16x16x32_bf16 v[16:19], v[242:245], v[210:213], v[16:19]
	v_mfma_f32_16x16x32_bf16 v[20:23], v[234:237], v[210:213], v[20:23]
	v_mfma_f32_16x16x32_bf16 v[12:15], v[234:237], v[218:221], v[12:15]
	v_mfma_f32_16x16x32_bf16 v[8:11], v[242:245], v[218:221], v[8:11]
	v_mfma_f32_16x16x32_bf16 v[0:3], v[242:245], v[226:229], v[0:3]
	v_mfma_f32_16x16x32_bf16 v[4:7], v[234:237], v[226:229], v[4:7]
	s_add_i32 s12, s12, 2
	v_lshl_add_u64 v[136:137], v[136:137], 0, s[44:45]
	v_lshl_add_u64 v[138:139], v[138:139], 0, s[44:45]
	v_lshl_add_u64 v[140:141], v[140:141], 0, s[44:45]
	s_cmp_lt_u32 s12, 4
	v_lshl_add_u64 v[142:143], v[142:143], 0, s[44:45]
	s_barrier
	s_cbranch_scc1 .LBB0_791
	s_add_u32 s0, s0, 0x20380
	s_addc_u32 s1, s1, 0
	v_lshl_add_u64 v[130:131], s[0:1], 0, v[130:131]
	v_readfirstlane_b32 s12, v160
	v_lshl_add_u64 v[128:129], v[128:129], 1, v[130:131]
	s_mov_b32 m0, s12
	ds_read_b128 v[136:139], v159
	ds_read_b128 v[140:143], v159 offset:1024
	ds_read_b128 v[152:155], v159 offset:2048
	ds_read_b128 v[162:165], v159 offset:3072
	ds_read_b128 v[166:169], v156
	ds_read_b128 v[170:173], v156 offset:1024
	ds_read_b128 v[174:177], v151
	ds_read_b128 v[198:201], v151 offset:1024
	ds_read_b128 v[202:205], v150
	ds_read_b128 v[206:209], v150 offset:1024
	ds_read_b128 v[210:213], v149
	ds_read_b128 v[214:217], v149 offset:1024
	global_load_lds_dwordx4 v[128:129], off
	v_lshl_add_u64 v[128:129], s[0:1], 0, v[134:135]
	v_readfirstlane_b32 s0, v161
	v_lshl_add_u64 v[128:129], v[132:133], 1, v[128:129]
	s_mov_b32 m0, s0
	s_nop 0
	global_load_lds_dwordx4 v[128:129], off
	s_barrier
	s_waitcnt lgkmcnt(0)
	v_mfma_f32_16x16x32_bf16 v[124:127], v[136:139], v[166:169], v[124:127]
	v_mfma_f32_16x16x32_bf16 v[120:123], v[152:155], v[166:169], v[120:123]
	v_mfma_f32_16x16x32_bf16 v[112:115], v[152:155], v[174:177], v[112:115]
	v_mfma_f32_16x16x32_bf16 v[108:111], v[136:139], v[202:205], v[108:111]
	v_mfma_f32_16x16x32_bf16 v[100:103], v[136:139], v[210:213], v[100:103]
	v_mfma_f32_16x16x32_bf16 v[96:99], v[152:155], v[210:213], v[96:99]
	v_mfma_f32_16x16x32_bf16 v[124:127], v[140:143], v[170:173], v[124:127]
	v_mfma_f32_16x16x32_bf16 v[120:123], v[162:165], v[170:173], v[120:123]
	v_mfma_f32_16x16x32_bf16 v[116:119], v[136:139], v[174:177], v[116:119]
	v_mfma_f32_16x16x32_bf16 v[112:115], v[162:165], v[198:201], v[112:115]
	v_mfma_f32_16x16x32_bf16 v[108:111], v[140:143], v[206:209], v[108:111]
	v_mfma_f32_16x16x32_bf16 v[104:107], v[152:155], v[202:205], v[104:107]
	v_mfma_f32_16x16x32_bf16 v[100:103], v[140:143], v[214:217], v[100:103]
	v_mfma_f32_16x16x32_bf16 v[96:99], v[162:165], v[214:217], v[96:99]
	v_mfma_f32_16x16x32_bf16 v[116:119], v[140:143], v[198:201], v[116:119]
	v_mfma_f32_16x16x32_bf16 v[104:107], v[162:165], v[206:209], v[104:107]
	s_barrier
	ds_read_b128 v[128:131], v158
	ds_read_b128 v[132:135], v158 offset:1024
	ds_read_b128 v[218:221], v158 offset:2048
	ds_read_b128 v[158:161], v158 offset:3072
	s_barrier
; #define WAIT_V(n) asm volatile("s_waitcnt vmcnt(" #n ")" ::: "memory")
; #define WAIT_L(n) asm volatile("s_waitcnt lgkmcnt(" #n ")" ::: "memory")
; #define BAR __builtin_amdgcn_s_barrier()
; #define LDA(dst, b, h)                                                                            \
;   _Pragma("unroll") for (int m = 0; m < 4; ++m) _Pragma("unroll") for (int k = 0; k < 2; ++k)                                         \
;     dst[m][k] = *reinterpret_cast<const bf16x8*>((char*)SA(b, h) + lds_byte(wr * 64 + m * 16 + fr, k * 32 + fq * 8))
; #define LDB(dst, b, h)                                                                            \
;   _Pragma("unroll") for (int n = 0; n < 2; ++n) _Pragma("unroll") for (int k = 0; k < 2; ++k)                                         \
;     dst[n][k] = *reinterpret_cast<const bf16x8*>((char*)SB(b, h) + lds_byte(wc * 32 + n * 16 + fr, k * 32 + fq * 8))
; template <int K, bool SWAP>
; __device__ __forceinline__ void gemm_kloop(const bf16* __restrict__ A, const bf16* __restrict__ Bt,
;                                            f32x4 (&acc)[2][2][4][2], bool pref = false) {
;     ...
;     LDB(B1, 0, 1); BAR; WAIT_L(0); MMA(0, 1, At, B1); BAR;
;     LDA(At, 0, 1); WAIT_V(4); BAR; WAIT_L(0); MMA(1, 0, At, B0); MMA(1, 1, At, B1); BAR; }
;   { LDB(B0, 1, 0); LDA(At, 1, 0); WAIT_V(2); BAR; WAIT_L(0); MMA(0, 0, At, B0); BAR;
	s_waitcnt lgkmcnt(0)
	v_mfma_f32_16x16x32_bf16 v[88:91], v[218:221], v[166:169], v[88:91]
	v_mfma_f32_16x16x32_bf16 v[84:87], v[128:131], v[174:177], v[84:87]
	v_mfma_f32_16x16x32_bf16 v[76:79], v[128:131], v[202:205], v[76:79]
	v_mfma_f32_16x16x32_bf16 v[72:75], v[218:221], v[202:205], v[72:75]
	v_mfma_f32_16x16x32_bf16 v[68:71], v[128:131], v[210:213], v[68:71]
	v_mfma_f32_16x16x32_bf16 v[64:67], v[218:221], v[210:213], v[64:67]
	v_mfma_f32_16x16x32_bf16 v[92:95], v[128:131], v[166:169], v[92:95]
	v_mfma_f32_16x16x32_bf16 v[88:91], v[158:161], v[170:173], v[88:91]
	v_mfma_f32_16x16x32_bf16 v[84:87], v[132:135], v[198:201], v[84:87]
	v_mfma_f32_16x16x32_bf16 v[80:83], v[218:221], v[174:177], v[80:83]
	v_mfma_f32_16x16x32_bf16 v[76:79], v[132:135], v[206:209], v[76:79]
	v_mfma_f32_16x16x32_bf16 v[72:75], v[158:161], v[206:209], v[72:75]
	v_mfma_f32_16x16x32_bf16 v[68:71], v[132:135], v[214:217], v[68:71]
	v_mfma_f32_16x16x32_bf16 v[64:67], v[158:161], v[214:217], v[64:67]
	v_mfma_f32_16x16x32_bf16 v[92:95], v[132:135], v[170:173], v[92:95]
	v_mfma_f32_16x16x32_bf16 v[80:83], v[158:161], v[198:201], v[80:83]
	s_barrier
	ds_read_b128 v[166:169], v156 offset:16384
	ds_read_b128 v[170:173], v156 offset:17408
	ds_read_b128 v[174:177], v151 offset:16384
	ds_read_b128 v[198:201], v151 offset:17408
	ds_read_b128 v[202:205], v150 offset:16384
	ds_read_b128 v[206:209], v150 offset:17408
	ds_read_b128 v[210:213], v149 offset:16384
	ds_read_b128 v[214:217], v149 offset:17408
	s_waitcnt vmcnt(4)
	s_barrier
	s_waitcnt lgkmcnt(0)
	v_mfma_f32_16x16x32_bf16 v[60:63], v[136:139], v[166:169], v[60:63]
	v_mfma_f32_16x16x32_bf16 v[56:59], v[152:155], v[166:169], v[56:59]
	v_mfma_f32_16x16x32_bf16 v[48:51], v[152:155], v[174:177], v[48:51]
	v_mfma_f32_16x16x32_bf16 v[52:55], v[136:139], v[174:177], v[52:55]
	v_mfma_f32_16x16x32_bf16 v[44:47], v[136:139], v[202:205], v[44:47]
	v_mfma_f32_16x16x32_bf16 v[40:43], v[152:155], v[202:205], v[40:43]
	v_mfma_f32_16x16x32_bf16 v[32:35], v[152:155], v[210:213], v[32:35]
	v_mfma_f32_16x16x32_bf16 v[36:39], v[136:139], v[210:213], v[36:39]
	v_mfma_f32_16x16x32_bf16 v[60:63], v[140:143], v[170:173], v[60:63]
	v_mfma_f32_16x16x32_bf16 v[56:59], v[162:165], v[170:173], v[56:59]
	v_mfma_f32_16x16x32_bf16 v[48:51], v[162:165], v[198:201], v[48:51]
	v_mfma_f32_16x16x32_bf16 v[52:55], v[140:143], v[198:201], v[52:55]
	v_mfma_f32_16x16x32_bf16 v[44:47], v[140:143], v[206:209], v[44:47]
	v_mfma_f32_16x16x32_bf16 v[40:43], v[162:165], v[206:209], v[40:43]
	v_mfma_f32_16x16x32_bf16 v[32:35], v[162:165], v[214:217], v[32:35]
	v_mfma_f32_16x16x32_bf16 v[36:39], v[140:143], v[214:217], v[36:39]
	v_mfma_f32_16x16x32_bf16 v[28:31], v[128:131], v[166:169], v[28:31]
	v_mfma_f32_16x16x32_bf16 v[24:27], v[218:221], v[166:169], v[24:27]
	v_mfma_f32_16x16x32_bf16 v[16:19], v[218:221], v[174:177], v[16:19]
	v_mfma_f32_16x16x32_bf16 v[20:23], v[128:131], v[174:177], v[20:23]
	v_mfma_f32_16x16x32_bf16 v[12:15], v[128:131], v[202:205], v[12:15]
	v_mfma_f32_16x16x32_bf16 v[8:11], v[218:221], v[202:205], v[8:11]
	v_mfma_f32_16x16x32_bf16 v[0:3], v[218:221], v[210:213], v[0:3]
	v_mfma_f32_16x16x32_bf16 v[4:7], v[128:131], v[210:213], v[4:7]
	v_mfma_f32_16x16x32_bf16 v[28:31], v[132:135], v[170:173], v[28:31]
	v_mfma_f32_16x16x32_bf16 v[24:27], v[158:161], v[170:173], v[24:27]
	v_mfma_f32_16x16x32_bf16 v[16:19], v[158:161], v[198:201], v[16:19]
	v_mfma_f32_16x16x32_bf16 v[20:23], v[132:135], v[198:201], v[20:23]
	v_mfma_f32_16x16x32_bf16 v[12:15], v[132:135], v[206:209], v[12:15]
	v_mfma_f32_16x16x32_bf16 v[8:11], v[158:161], v[206:209], v[8:11]
	v_mfma_f32_16x16x32_bf16 v[0:3], v[158:161], v[214:217], v[0:3]
	v_mfma_f32_16x16x32_bf16 v[4:7], v[132:135], v[214:217], v[4:7]
	s_barrier
	ds_read_b128 v[128:131], v147
	ds_read_b128 v[140:143], v147 offset:1024
	ds_read_b128 v[158:161], v147 offset:2048
	ds_read_b128 v[162:165], v147 offset:3072
	ds_read_b128 v[166:169], v156 offset:32768
	ds_read_b128 v[170:173], v156 offset:33792
	ds_read_b128 v[174:177], v151 offset:32768
	ds_read_b128 v[198:201], v151 offset:33792
	ds_read_b128 v[202:205], v150 offset:32768
	ds_read_b128 v[206:209], v150 offset:33792
	ds_read_b128 v[210:213], v149 offset:32768
	ds_read_b128 v[214:217], v149 offset:33792
	s_waitcnt vmcnt(2)
	s_barrier
; #define WAIT_V(n) asm volatile("s_waitcnt vmcnt(" #n ")" ::: "memory")
; #define WAIT_L(n) asm volatile("s_waitcnt lgkmcnt(" #n ")" ::: "memory")
; #define BAR __builtin_amdgcn_s_barrier()
; #define LDA(dst, b, h)                                                                            \
;   _Pragma("unroll") for (int m = 0; m < 4; ++m) _Pragma("unroll") for (int k = 0; k < 2; ++k)                                         \
;     dst[m][k] = *reinterpret_cast<const bf16x8*>((char*)SA(b, h) + lds_byte(wr * 64 + m * 16 + fr, k * 32 + fq * 8))
; #define LDB(dst, b, h)                                                                            \
;   _Pragma("unroll") for (int n = 0; n < 2; ++n) _Pragma("unroll") for (int k = 0; k < 2; ++k)                                         \
;     dst[n][k] = *reinterpret_cast<const bf16x8*>((char*)SB(b, h) + lds_byte(wc * 32 + n * 16 + fr, k * 32 + fq * 8))
; template <int K, bool SWAP>
; __device__ __forceinline__ void gemm_kloop(const bf16* __restrict__ A, const bf16* __restrict__ Bt,
;                                            f32x4 (&acc)[2][2][4][2], bool pref = false) {
;     ...
;   { LDB(B0, 1, 0); LDA(At, 1, 0); WAIT_V(2); BAR; WAIT_L(0); MMA(0, 0, At, B0); BAR;
;     LDB(B1, 1, 1); WAIT_V(0); BAR; WAIT_L(0); MMA(0, 1, At, B1); BAR;
;     LDA(At, 1, 1); BAR; WAIT_L(0); MMA(1, 0, At, B0); MMA(1, 1, At, B1); BAR; }
;   if (wr == 0) BAR;
	s_waitcnt lgkmcnt(0)
	v_mfma_f32_16x16x32_bf16 v[124:127], v[128:131], v[166:169], v[124:127]
	v_mfma_f32_16x16x32_bf16 v[120:123], v[158:161], v[166:169], v[120:123]
	v_mfma_f32_16x16x32_bf16 v[116:119], v[128:131], v[174:177], v[116:119]
	v_mfma_f32_16x16x32_bf16 v[112:115], v[158:161], v[174:177], v[112:115]
	v_mfma_f32_16x16x32_bf16 v[108:111], v[128:131], v[202:205], v[108:111]
	v_mfma_f32_16x16x32_bf16 v[104:107], v[158:161], v[202:205], v[104:107]
	v_mfma_f32_16x16x32_bf16 v[100:103], v[128:131], v[210:213], v[100:103]
	v_mfma_f32_16x16x32_bf16 v[96:99], v[158:161], v[210:213], v[96:99]
	v_mfma_f32_16x16x32_bf16 v[152:155], v[140:143], v[170:173], v[124:127]
	v_mfma_f32_16x16x32_bf16 v[144:147], v[162:165], v[170:173], v[120:123]
	v_mfma_f32_16x16x32_bf16 v[136:139], v[140:143], v[198:201], v[116:119]
	v_mfma_f32_16x16x32_bf16 v[132:135], v[162:165], v[198:201], v[112:115]
	v_mfma_f32_16x16x32_bf16 v[124:127], v[140:143], v[206:209], v[108:111]
	v_mfma_f32_16x16x32_bf16 v[120:123], v[162:165], v[206:209], v[104:107]
	v_mfma_f32_16x16x32_bf16 v[112:115], v[140:143], v[214:217], v[100:103]
	v_mfma_f32_16x16x32_bf16 v[108:111], v[162:165], v[214:217], v[96:99]
	s_barrier
	ds_read_b128 v[104:107], v157
	ds_read_b128 v[116:119], v157 offset:1024
	ds_read_b128 v[218:221], v157 offset:2048
	ds_read_b128 v[222:225], v157 offset:3072
	s_waitcnt vmcnt(0)
	s_barrier
	s_waitcnt lgkmcnt(0)
	v_mfma_f32_16x16x32_bf16 v[92:95], v[104:107], v[166:169], v[92:95]
	v_mfma_f32_16x16x32_bf16 v[88:91], v[218:221], v[166:169], v[88:91]
	v_mfma_f32_16x16x32_bf16 v[84:87], v[104:107], v[174:177], v[84:87]
	v_mfma_f32_16x16x32_bf16 v[80:83], v[218:221], v[174:177], v[80:83]
	v_mfma_f32_16x16x32_bf16 v[76:79], v[104:107], v[202:205], v[76:79]
	v_mfma_f32_16x16x32_bf16 v[72:75], v[218:221], v[202:205], v[72:75]
	v_mfma_f32_16x16x32_bf16 v[68:71], v[104:107], v[210:213], v[68:71]
	v_mfma_f32_16x16x32_bf16 v[64:67], v[218:221], v[210:213], v[64:67]
	v_mfma_f32_16x16x32_bf16 v[100:103], v[116:119], v[170:173], v[92:95]
	v_mfma_f32_16x16x32_bf16 v[96:99], v[222:225], v[170:173], v[88:91]
	v_mfma_f32_16x16x32_bf16 v[88:91], v[116:119], v[198:201], v[84:87]
	v_mfma_f32_16x16x32_bf16 v[84:87], v[222:225], v[198:201], v[80:83]
	v_mfma_f32_16x16x32_bf16 v[76:79], v[116:119], v[206:209], v[76:79]
	v_mfma_f32_16x16x32_bf16 v[72:75], v[222:225], v[206:209], v[72:75]
	v_mfma_f32_16x16x32_bf16 v[68:71], v[116:119], v[214:217], v[68:71]
	v_mfma_f32_16x16x32_bf16 v[64:67], v[222:225], v[214:217], v[64:67]
	s_barrier
	ds_read_b128 v[80:83], v156 offset:49152
	ds_read_b128 v[92:95], v156 offset:50176
	ds_read_b128 v[166:169], v151 offset:49152
	ds_read_b128 v[170:173], v151 offset:50176
	ds_read_b128 v[174:177], v150 offset:49152
	ds_read_b128 v[198:201], v150 offset:50176
	ds_read_b128 v[202:205], v149 offset:49152
	ds_read_b128 v[206:209], v149 offset:50176
	s_barrier
	s_waitcnt lgkmcnt(0)
	v_mfma_f32_16x16x32_bf16 v[60:63], v[128:131], v[80:83], v[60:63]
	v_mfma_f32_16x16x32_bf16 v[56:59], v[158:161], v[80:83], v[56:59]
	v_mfma_f32_16x16x32_bf16 v[48:51], v[158:161], v[166:169], v[48:51]
	v_mfma_f32_16x16x32_bf16 v[52:55], v[128:131], v[166:169], v[52:55]
	v_mfma_f32_16x16x32_bf16 v[44:47], v[128:131], v[174:177], v[44:47]
	v_mfma_f32_16x16x32_bf16 v[40:43], v[158:161], v[174:177], v[40:43]
	v_mfma_f32_16x16x32_bf16 v[32:35], v[158:161], v[202:205], v[32:35]
	v_mfma_f32_16x16x32_bf16 v[36:39], v[128:131], v[202:205], v[36:39]
	v_mfma_f32_16x16x32_bf16 v[60:63], v[140:143], v[92:95], v[60:63]
	v_mfma_f32_16x16x32_bf16 v[56:59], v[162:165], v[92:95], v[56:59]
	v_mfma_f32_16x16x32_bf16 v[48:51], v[162:165], v[170:173], v[48:51]
	v_mfma_f32_16x16x32_bf16 v[52:55], v[140:143], v[170:173], v[52:55]
	v_mfma_f32_16x16x32_bf16 v[44:47], v[140:143], v[198:201], v[44:47]
	v_mfma_f32_16x16x32_bf16 v[40:43], v[162:165], v[198:201], v[40:43]
	v_mfma_f32_16x16x32_bf16 v[32:35], v[162:165], v[206:209], v[32:35]
	v_mfma_f32_16x16x32_bf16 v[36:39], v[140:143], v[206:209], v[36:39]
	v_mfma_f32_16x16x32_bf16 v[28:31], v[104:107], v[80:83], v[28:31]
	v_mfma_f32_16x16x32_bf16 v[24:27], v[218:221], v[80:83], v[24:27]
	v_mfma_f32_16x16x32_bf16 v[16:19], v[218:221], v[166:169], v[16:19]
	v_mfma_f32_16x16x32_bf16 v[20:23], v[104:107], v[166:169], v[20:23]
	v_mfma_f32_16x16x32_bf16 v[12:15], v[104:107], v[174:177], v[12:15]
	v_mfma_f32_16x16x32_bf16 v[8:11], v[218:221], v[174:177], v[8:11]
	v_mfma_f32_16x16x32_bf16 v[0:3], v[218:221], v[202:205], v[0:3]
	v_mfma_f32_16x16x32_bf16 v[4:7], v[104:107], v[202:205], v[4:7]
	v_mfma_f32_16x16x32_bf16 v[28:31], v[116:119], v[92:95], v[28:31]
	v_mfma_f32_16x16x32_bf16 v[24:27], v[222:225], v[92:95], v[24:27]
	v_mfma_f32_16x16x32_bf16 v[16:19], v[222:225], v[170:173], v[16:19]
	v_mfma_f32_16x16x32_bf16 v[20:23], v[116:119], v[170:173], v[20:23]
	v_mfma_f32_16x16x32_bf16 v[12:15], v[116:119], v[198:201], v[12:15]
	v_mfma_f32_16x16x32_bf16 v[8:11], v[222:225], v[198:201], v[8:11]
	v_mfma_f32_16x16x32_bf16 v[0:3], v[222:225], v[206:209], v[0:3]
	v_mfma_f32_16x16x32_bf16 v[4:7], v[116:119], v[206:209], v[4:7]
	s_movk_i32 s0, 0x100
	v_cmp_gt_u32_e32 vcc, s0, v148
	s_barrier
	s_and_saveexec_b64 s[0:1], vcc
	s_cbranch_execz .LBB0_794
	s_barrier

; #define WAIT_V(n) asm volatile("s_waitcnt vmcnt(" #n ")" ::: "memory")
; #define WAIT_L(n) asm volatile("s_waitcnt lgkmcnt(" #n ")" ::: "memory")
; #define BAR __builtin_amdgcn_s_barrier()
; #define SCHED __builtin_amdgcn_sched_barrier(0)
; #define LDA(dst, b, h)                                                                            \
;   _Pragma("unroll") for (int m = 0; m < 4; ++m) _Pragma("unroll") for (int k = 0; k < 2; ++k)                                         \
;     dst[m][k] = *reinterpret_cast<const bf16x8*>((char*)SA(b, h) + lds_byte(wr * 64 + m * 16 + fr, k * 32 + fq * 8))
; #define LDB(dst, b, h)                                                                            \
;   _Pragma("unroll") for (int n = 0; n < 2; ++n) _Pragma("unroll") for (int k = 0; k < 2; ++k)                                         \
;     dst[n][k] = *reinterpret_cast<const bf16x8*>((char*)SB(b, h) + lds_byte(wc * 32 + n * 16 + fr, k * 32 + fq * 8))
; template <int K, bool SWAP>
; __device__ __forceinline__ void gemm_kloop(const bf16* __restrict__ A, const bf16* __restrict__ Bt,
;                                            f32x4 (&acc)[2][2][4][2], bool pref = false) {
;     ...
;     LDB(B0, 0, 0); SCHED; LDA(At, 0, 0); STAGE(SA(1, 1), A, HALF, t + 1);
;     WAIT_L(8); BAR; WAIT_L(0); MMA(0, 0, At, B0); BAR; SCHED;
;     LDB(B1, 0, 1); STAGE(SB(0, 0), Bt, 0, t + 2);
;     BAR; WAIT_L(0); MMA(0, 1, At, B1); BAR;
;     LDA(At, 0, 1); STAGE(SA(0, 0), A, 0, t + 2);
;     BAR; WAIT_L(0); MMA(1, 0, At, B0); BAR; SCHED;
;     STAGE(SB(0, 1), Bt, HALF, t + 2);
;     WAIT_V(6); BAR; MMA(1, 1, At, B1); BAR;
.LBB0_797:
	ds_read_b128 v[162:165], v158
	ds_read_b128 v[166:169], v158 offset:1024
	ds_read_b128 v[170:173], v158 offset:2048
	ds_read_b128 v[174:177], v158 offset:3072
	v_add_u32_e32 v159, 0xc000, v153
	v_lshl_add_u64 v[178:179], s[6:7], 0, v[140:141]
	v_readfirstlane_b32 s5, v159
	v_lshl_add_u64 v[160:161], v[178:179], 0, s[86:87]
	s_mov_b32 m0, s5
	ds_read_b128 v[198:201], v148
	ds_read_b128 v[202:205], v148 offset:1024
	ds_read_b128 v[206:209], v147
	ds_read_b128 v[210:213], v147 offset:1024
	ds_read_b128 v[214:217], v146
	ds_read_b128 v[218:221], v146 offset:1024
	ds_read_b128 v[222:225], v145
	ds_read_b128 v[226:229], v145 offset:1024
	global_load_lds_dwordx4 v[160:161], off
	v_add_u32_e32 v160, 0xe000, v153
	v_lshl_add_u64 v[188:189], s[6:7], 0, v[142:143]
	v_readfirstlane_b32 s5, v160
	v_lshl_add_u64 v[230:231], v[188:189], 0, s[86:87]
	s_mov_b32 m0, s5
	s_nop 0
	global_load_lds_dwordx4 v[230:231], off
	s_waitcnt lgkmcnt(8)
	s_barrier
	s_waitcnt lgkmcnt(0)
	v_mfma_f32_16x16x32_bf16 v[124:127], v[162:165], v[198:201], v[124:127]
	v_mfma_f32_16x16x32_bf16 v[120:123], v[170:173], v[198:201], v[120:123]
	v_mfma_f32_16x16x32_bf16 v[112:115], v[170:173], v[206:209], v[112:115]
	v_mfma_f32_16x16x32_bf16 v[116:119], v[162:165], v[206:209], v[116:119]
	v_mfma_f32_16x16x32_bf16 v[108:111], v[162:165], v[214:217], v[108:111]
	v_mfma_f32_16x16x32_bf16 v[104:107], v[170:173], v[214:217], v[104:107]
	v_mfma_f32_16x16x32_bf16 v[96:99], v[170:173], v[222:225], v[96:99]
	v_mfma_f32_16x16x32_bf16 v[100:103], v[162:165], v[222:225], v[100:103]
	v_mfma_f32_16x16x32_bf16 v[124:127], v[166:169], v[202:205], v[124:127]
	v_mfma_f32_16x16x32_bf16 v[120:123], v[174:177], v[202:205], v[120:123]
	v_mfma_f32_16x16x32_bf16 v[112:115], v[174:177], v[210:213], v[112:115]
	v_mfma_f32_16x16x32_bf16 v[116:119], v[166:169], v[210:213], v[116:119]
	v_mfma_f32_16x16x32_bf16 v[108:111], v[166:169], v[218:221], v[108:111]
	v_mfma_f32_16x16x32_bf16 v[104:107], v[174:177], v[218:221], v[104:107]
	v_mfma_f32_16x16x32_bf16 v[96:99], v[174:177], v[226:229], v[96:99]
	v_mfma_f32_16x16x32_bf16 v[100:103], v[166:169], v[226:229], v[100:103]
	s_barrier
	v_add_u32_e32 v161, s9, v150
	v_lshl_add_u64 v[246:247], s[6:7], 0, v[136:137]
	v_readfirstlane_b32 s5, v161
	v_lshl_add_u64 v[248:249], v[246:247], 0, s[88:89]
	s_mov_b32 m0, s5
	v_add_u32_e32 v161, 0x2000, v161
	ds_read_b128 v[230:233], v157
	ds_read_b128 v[234:237], v157 offset:1024
	ds_read_b128 v[238:241], v157 offset:2048
	ds_read_b128 v[242:245], v157 offset:3072
	global_load_lds_dwordx4 v[248:249], off
	v_lshl_add_u64 v[248:249], s[6:7], 0, v[138:139]
	v_readfirstlane_b32 s5, v161
	v_lshl_add_u64 v[250:251], v[248:249], 0, s[88:89]
	s_mov_b32 m0, s5
	s_nop 0
	global_load_lds_dwordx4 v[250:251], off
	s_barrier
	s_waitcnt lgkmcnt(0)
	v_mfma_f32_16x16x32_bf16 v[92:95], v[230:233], v[198:201], v[92:95]
	v_mfma_f32_16x16x32_bf16 v[88:91], v[238:241], v[198:201], v[88:91]
	v_mfma_f32_16x16x32_bf16 v[80:83], v[238:241], v[206:209], v[80:83]
	v_mfma_f32_16x16x32_bf16 v[84:87], v[230:233], v[206:209], v[84:87]
	v_mfma_f32_16x16x32_bf16 v[76:79], v[230:233], v[214:217], v[76:79]
	v_mfma_f32_16x16x32_bf16 v[72:75], v[238:241], v[214:217], v[72:75]
	v_mfma_f32_16x16x32_bf16 v[64:67], v[238:241], v[222:225], v[64:67]
	v_mfma_f32_16x16x32_bf16 v[68:71], v[230:233], v[222:225], v[68:71]
	v_mfma_f32_16x16x32_bf16 v[92:95], v[234:237], v[202:205], v[92:95]
	v_mfma_f32_16x16x32_bf16 v[88:91], v[242:245], v[202:205], v[88:91]
	v_mfma_f32_16x16x32_bf16 v[80:83], v[242:245], v[210:213], v[80:83]
	v_mfma_f32_16x16x32_bf16 v[84:87], v[234:237], v[210:213], v[84:87]
	v_mfma_f32_16x16x32_bf16 v[76:79], v[234:237], v[218:221], v[76:79]
	v_mfma_f32_16x16x32_bf16 v[72:75], v[242:245], v[218:221], v[72:75]
	v_mfma_f32_16x16x32_bf16 v[64:67], v[242:245], v[226:229], v[64:67]
	v_mfma_f32_16x16x32_bf16 v[68:71], v[234:237], v[226:229], v[68:71]
	v_readfirstlane_b32 s5, v153
	v_add_u32_e32 v161, 0x2000, v153
	v_lshl_add_u64 v[250:251], v[178:179], 0, s[90:91]
	s_mov_b32 m0, s5
	v_readfirstlane_b32 s5, v161
	s_barrier
	ds_read_b128 v[198:201], v148 offset:16384
	ds_read_b128 v[202:205], v148 offset:17408
	ds_read_b128 v[206:209], v147 offset:16384
	ds_read_b128 v[210:213], v147 offset:17408
	ds_read_b128 v[214:217], v146 offset:16384
	ds_read_b128 v[218:221], v146 offset:17408
	ds_read_b128 v[222:225], v145 offset:16384
	ds_read_b128 v[226:229], v145 offset:17408
	global_load_lds_dwordx4 v[250:251], off
	v_lshl_add_u64 v[250:251], v[188:189], 0, s[90:91]
	s_mov_b32 m0, s5
	s_nop 0
	global_load_lds_dwordx4 v[250:251], off
	s_barrier
	s_waitcnt lgkmcnt(0)
	v_mfma_f32_16x16x32_bf16 v[60:63], v[162:165], v[198:201], v[60:63]
	v_mfma_f32_16x16x32_bf16 v[56:59], v[170:173], v[198:201], v[56:59]
	v_mfma_f32_16x16x32_bf16 v[48:51], v[170:173], v[206:209], v[48:51]
	v_mfma_f32_16x16x32_bf16 v[52:55], v[162:165], v[206:209], v[52:55]
	v_mfma_f32_16x16x32_bf16 v[44:47], v[162:165], v[214:217], v[44:47]
	v_mfma_f32_16x16x32_bf16 v[40:43], v[170:173], v[214:217], v[40:43]
	v_mfma_f32_16x16x32_bf16 v[32:35], v[170:173], v[222:225], v[32:35]
	v_mfma_f32_16x16x32_bf16 v[36:39], v[162:165], v[222:225], v[36:39]
	v_mfma_f32_16x16x32_bf16 v[60:63], v[166:169], v[202:205], v[60:63]
	v_mfma_f32_16x16x32_bf16 v[56:59], v[174:177], v[202:205], v[56:59]
	v_mfma_f32_16x16x32_bf16 v[48:51], v[174:177], v[210:213], v[48:51]
	v_mfma_f32_16x16x32_bf16 v[52:55], v[166:169], v[210:213], v[52:55]
	v_mfma_f32_16x16x32_bf16 v[44:47], v[166:169], v[218:221], v[44:47]
	v_mfma_f32_16x16x32_bf16 v[40:43], v[174:177], v[218:221], v[40:43]
	v_mfma_f32_16x16x32_bf16 v[32:35], v[174:177], v[226:229], v[32:35]
	v_mfma_f32_16x16x32_bf16 v[36:39], v[166:169], v[226:229], v[36:39]
	s_barrier
; #define WAIT_V(n) asm volatile("s_waitcnt vmcnt(" #n ")" ::: "memory")
; #define WAIT_L(n) asm volatile("s_waitcnt lgkmcnt(" #n ")" ::: "memory")
; #define BAR __builtin_amdgcn_s_barrier()
; #define SCHED __builtin_amdgcn_sched_barrier(0)
; #define LDA(dst, b, h)                                                                            \
;   _Pragma("unroll") for (int m = 0; m < 4; ++m) _Pragma("unroll") for (int k = 0; k < 2; ++k)                                         \
;     dst[m][k] = *reinterpret_cast<const bf16x8*>((char*)SA(b, h) + lds_byte(wr * 64 + m * 16 + fr, k * 32 + fq * 8))
; #define LDB(dst, b, h)                                                                            \
;   _Pragma("unroll") for (int n = 0; n < 2; ++n) _Pragma("unroll") for (int k = 0; k < 2; ++k)                                         \
;     dst[n][k] = *reinterpret_cast<const bf16x8*>((char*)SB(b, h) + lds_byte(wc * 32 + n * 16 + fr, k * 32 + fq * 8))
; template <int K, bool SWAP>
; __device__ __forceinline__ void gemm_kloop(const bf16* __restrict__ A, const bf16* __restrict__ Bt,
;                                            f32x4 (&acc)[2][2][4][2], bool pref = false) {
;     ...
;     WAIT_V(6); BAR; MMA(1, 1, At, B1); BAR;
;     LDB(B0, 1, 0); SCHED; LDA(At, 1, 0); STAGE(SA(0, 1), A, HALF, t + 2);
;     WAIT_L(8); BAR; WAIT_L(0); MMA(0, 0, At, B0); BAR; SCHED;
;     LDB(B1, 1, 1); STAGE(SB(1, 0), Bt, 0, t + 3);
;     BAR; WAIT_L(0); MMA(0, 1, At, B1); BAR;
;     LDA(At, 1, 1); STAGE(SA(1, 0), A, 0, t + 3);
;     BAR; WAIT_L(0); MMA(1, 0, At, B0); BAR; SCHED;
;     STAGE(SB(1, 1), Bt, HALF, t + 3);
	v_add_u32_e32 v161, s33, v150
	v_lshl_add_u64 v[162:163], v[246:247], 0, s[92:93]
	v_readfirstlane_b32 s5, v161
	v_add_u32_e32 v161, 0x2000, v161
	s_mov_b32 m0, s5
	v_readfirstlane_b32 s5, v161
	global_load_lds_dwordx4 v[162:163], off
	v_lshl_add_u64 v[162:163], v[248:249], 0, s[92:93]
	s_mov_b32 m0, s5
	s_nop 0
	global_load_lds_dwordx4 v[162:163], off
	s_waitcnt vmcnt(6)
	s_barrier
	v_mfma_f32_16x16x32_bf16 v[28:31], v[230:233], v[198:201], v[28:31]
	v_mfma_f32_16x16x32_bf16 v[24:27], v[238:241], v[198:201], v[24:27]
	v_mfma_f32_16x16x32_bf16 v[16:19], v[238:241], v[206:209], v[16:19]
	v_mfma_f32_16x16x32_bf16 v[20:23], v[230:233], v[206:209], v[20:23]
	v_mfma_f32_16x16x32_bf16 v[12:15], v[230:233], v[214:217], v[12:15]
	v_mfma_f32_16x16x32_bf16 v[8:11], v[238:241], v[214:217], v[8:11]
	v_mfma_f32_16x16x32_bf16 v[0:3], v[238:241], v[222:225], v[0:3]
	v_mfma_f32_16x16x32_bf16 v[4:7], v[230:233], v[222:225], v[4:7]
	v_mfma_f32_16x16x32_bf16 v[28:31], v[234:237], v[202:205], v[28:31]
	v_mfma_f32_16x16x32_bf16 v[24:27], v[242:245], v[202:205], v[24:27]
	v_mfma_f32_16x16x32_bf16 v[16:19], v[242:245], v[210:213], v[16:19]
	v_mfma_f32_16x16x32_bf16 v[20:23], v[234:237], v[210:213], v[20:23]
	v_mfma_f32_16x16x32_bf16 v[12:15], v[234:237], v[218:221], v[12:15]
	v_mfma_f32_16x16x32_bf16 v[8:11], v[242:245], v[218:221], v[8:11]
	v_mfma_f32_16x16x32_bf16 v[0:3], v[242:245], v[226:229], v[0:3]
	v_mfma_f32_16x16x32_bf16 v[4:7], v[234:237], v[226:229], v[4:7]
	s_barrier
	ds_read_b128 v[162:165], v151
	ds_read_b128 v[166:169], v151 offset:1024
	ds_read_b128 v[170:173], v151 offset:2048
	ds_read_b128 v[174:177], v151 offset:3072
	v_add_u32_e32 v161, 0x4000, v153
	v_lshl_add_u64 v[230:231], v[178:179], 0, s[94:95]
	v_readfirstlane_b32 s5, v161
	v_add_u32_e32 v161, 0x6000, v153
	s_mov_b32 m0, s5
	v_readfirstlane_b32 s5, v161
	ds_read_b128 v[198:201], v148 offset:32768
	ds_read_b128 v[202:205], v148 offset:33792
	ds_read_b128 v[206:209], v147 offset:32768
	ds_read_b128 v[210:213], v147 offset:33792
	ds_read_b128 v[214:217], v146 offset:32768
	ds_read_b128 v[218:221], v146 offset:33792
	ds_read_b128 v[222:225], v145 offset:32768
	ds_read_b128 v[226:229], v145 offset:33792
	global_load_lds_dwordx4 v[230:231], off
	v_lshl_add_u64 v[230:231], v[188:189], 0, s[94:95]
	s_mov_b32 m0, s5
	s_nop 0
	global_load_lds_dwordx4 v[230:231], off
	s_waitcnt lgkmcnt(8)
	s_barrier
	s_waitcnt lgkmcnt(0)
	v_mfma_f32_16x16x32_bf16 v[124:127], v[162:165], v[198:201], v[124:127]
	v_mfma_f32_16x16x32_bf16 v[120:123], v[170:173], v[198:201], v[120:123]
	v_mfma_f32_16x16x32_bf16 v[112:115], v[170:173], v[206:209], v[112:115]
	v_mfma_f32_16x16x32_bf16 v[116:119], v[162:165], v[206:209], v[116:119]
	v_mfma_f32_16x16x32_bf16 v[108:111], v[162:165], v[214:217], v[108:111]
	v_mfma_f32_16x16x32_bf16 v[104:107], v[170:173], v[214:217], v[104:107]
	v_mfma_f32_16x16x32_bf16 v[96:99], v[170:173], v[222:225], v[96:99]
	v_mfma_f32_16x16x32_bf16 v[100:103], v[162:165], v[222:225], v[100:103]
	v_mfma_f32_16x16x32_bf16 v[124:127], v[166:169], v[202:205], v[124:127]
	v_mfma_f32_16x16x32_bf16 v[120:123], v[174:177], v[202:205], v[120:123]
	v_mfma_f32_16x16x32_bf16 v[112:115], v[174:177], v[210:213], v[112:115]
	v_mfma_f32_16x16x32_bf16 v[116:119], v[166:169], v[210:213], v[116:119]
	v_mfma_f32_16x16x32_bf16 v[108:111], v[166:169], v[218:221], v[108:111]
	v_mfma_f32_16x16x32_bf16 v[104:107], v[174:177], v[218:221], v[104:107]
	v_mfma_f32_16x16x32_bf16 v[96:99], v[174:177], v[226:229], v[96:99]
	v_mfma_f32_16x16x32_bf16 v[100:103], v[166:169], v[226:229], v[100:103]
	s_barrier
	v_readfirstlane_b32 s5, v152
	v_add_u32_e32 v161, 0x2000, v152
	v_lshl_add_u64 v[250:251], v[246:247], 0, s[96:97]
	s_mov_b32 m0, s5
	v_readfirstlane_b32 s5, v161
	ds_read_b128 v[230:233], v149
	ds_read_b128 v[234:237], v149 offset:1024
	ds_read_b128 v[238:241], v149 offset:2048
	ds_read_b128 v[242:245], v149 offset:3072
	global_load_lds_dwordx4 v[250:251], off
	v_lshl_add_u64 v[250:251], v[248:249], 0, s[96:97]
	s_mov_b32 m0, s5
	s_nop 0
	global_load_lds_dwordx4 v[250:251], off
	s_barrier
	s_waitcnt lgkmcnt(0)
	v_mfma_f32_16x16x32_bf16 v[92:95], v[230:233], v[198:201], v[92:95]
	v_mfma_f32_16x16x32_bf16 v[88:91], v[238:241], v[198:201], v[88:91]
	v_mfma_f32_16x16x32_bf16 v[80:83], v[238:241], v[206:209], v[80:83]
	v_mfma_f32_16x16x32_bf16 v[84:87], v[230:233], v[206:209], v[84:87]
	v_mfma_f32_16x16x32_bf16 v[76:79], v[230:233], v[214:217], v[76:79]
	v_mfma_f32_16x16x32_bf16 v[72:75], v[238:241], v[214:217], v[72:75]
	v_mfma_f32_16x16x32_bf16 v[64:67], v[238:241], v[222:225], v[64:67]
	v_mfma_f32_16x16x32_bf16 v[68:71], v[230:233], v[222:225], v[68:71]
	v_mfma_f32_16x16x32_bf16 v[92:95], v[234:237], v[202:205], v[92:95]
	v_mfma_f32_16x16x32_bf16 v[88:91], v[242:245], v[202:205], v[88:91]
	v_mfma_f32_16x16x32_bf16 v[80:83], v[242:245], v[210:213], v[80:83]
	v_mfma_f32_16x16x32_bf16 v[84:87], v[234:237], v[210:213], v[84:87]
	v_mfma_f32_16x16x32_bf16 v[76:79], v[234:237], v[218:221], v[76:79]
	v_mfma_f32_16x16x32_bf16 v[72:75], v[242:245], v[218:221], v[72:75]
	v_mfma_f32_16x16x32_bf16 v[64:67], v[242:245], v[226:229], v[64:67]
	v_mfma_f32_16x16x32_bf16 v[68:71], v[234:237], v[226:229], v[68:71]
	v_readfirstlane_b32 s5, v154
	v_lshl_add_u64 v[178:179], v[178:179], 0, s[34:35]
	s_mov_b32 m0, s5
	v_readfirstlane_b32 s5, v155
	s_barrier
	ds_read_b128 v[198:201], v148 offset:49152
	ds_read_b128 v[202:205], v148 offset:50176
	ds_read_b128 v[206:209], v147 offset:49152
	ds_read_b128 v[210:213], v147 offset:50176
	ds_read_b128 v[214:217], v146 offset:49152
	ds_read_b128 v[218:221], v146 offset:50176
	ds_read_b128 v[222:225], v145 offset:49152
	ds_read_b128 v[226:229], v145 offset:50176
	global_load_lds_dwordx4 v[178:179], off
	v_lshl_add_u64 v[178:179], v[188:189], 0, s[34:35]
	s_mov_b32 m0, s5
	s_nop 0
	global_load_lds_dwordx4 v[178:179], off
	s_barrier
; #define WAIT_V(n) asm volatile("s_waitcnt vmcnt(" #n ")" ::: "memory")
; #define WAIT_L(n) asm volatile("s_waitcnt lgkmcnt(" #n ")" ::: "memory")
; #define BAR __builtin_amdgcn_s_barrier()
; #define LDA(dst, b, h)                                                                            \
;   _Pragma("unroll") for (int m = 0; m < 4; ++m) _Pragma("unroll") for (int k = 0; k < 2; ++k)                                         \
;     dst[m][k] = *reinterpret_cast<const bf16x8*>((char*)SA(b, h) + lds_byte(wr * 64 + m * 16 + fr, k * 32 + fq * 8))
; #define LDB(dst, b, h)                                                                            \
;   _Pragma("unroll") for (int n = 0; n < 2; ++n) _Pragma("unroll") for (int k = 0; k < 2; ++k)                                         \
;     dst[n][k] = *reinterpret_cast<const bf16x8*>((char*)SB(b, h) + lds_byte(wc * 32 + n * 16 + fr, k * 32 + fq * 8))
; template <int K, bool SWAP>
; __device__ __forceinline__ void gemm_kloop(const bf16* __restrict__ A, const bf16* __restrict__ Bt,
;                                            f32x4 (&acc)[2][2][4][2], bool pref = false) {
;     ...
;     STAGE(SB(1, 1), Bt, HALF, t + 3);
;     WAIT_V(6); BAR; MMA(1, 1, At, B1); BAR;
;   }
;   { LDB(B0, 0, 0); LDA(At, 0, 0); STAGE(SA(1, 1), A, HALF, nt - 1);
;     BAR; WAIT_L(0); MMA(0, 0, At, B0); BAR;
	s_waitcnt lgkmcnt(0)
	v_mfma_f32_16x16x32_bf16 v[60:63], v[162:165], v[198:201], v[60:63]
	v_mfma_f32_16x16x32_bf16 v[56:59], v[170:173], v[198:201], v[56:59]
	v_mfma_f32_16x16x32_bf16 v[48:51], v[170:173], v[206:209], v[48:51]
	v_mfma_f32_16x16x32_bf16 v[52:55], v[162:165], v[206:209], v[52:55]
	v_mfma_f32_16x16x32_bf16 v[44:47], v[162:165], v[214:217], v[44:47]
	v_mfma_f32_16x16x32_bf16 v[40:43], v[170:173], v[214:217], v[40:43]
	v_mfma_f32_16x16x32_bf16 v[32:35], v[170:173], v[222:225], v[32:35]
	v_mfma_f32_16x16x32_bf16 v[36:39], v[162:165], v[222:225], v[36:39]
	v_mfma_f32_16x16x32_bf16 v[60:63], v[166:169], v[202:205], v[60:63]
	v_mfma_f32_16x16x32_bf16 v[56:59], v[174:177], v[202:205], v[56:59]
	v_mfma_f32_16x16x32_bf16 v[48:51], v[174:177], v[210:213], v[48:51]
	v_mfma_f32_16x16x32_bf16 v[52:55], v[166:169], v[210:213], v[52:55]
	v_mfma_f32_16x16x32_bf16 v[44:47], v[166:169], v[218:221], v[44:47]
	v_mfma_f32_16x16x32_bf16 v[40:43], v[174:177], v[218:221], v[40:43]
	v_mfma_f32_16x16x32_bf16 v[32:35], v[174:177], v[226:229], v[32:35]
	v_mfma_f32_16x16x32_bf16 v[36:39], v[166:169], v[226:229], v[36:39]
	s_barrier
	v_readfirstlane_b32 s5, v156
	v_add_u32_e32 v161, 0x2000, v156
	v_lshl_add_u64 v[162:163], v[246:247], 0, s[36:37]
	s_mov_b32 m0, s5
	v_readfirstlane_b32 s5, v161
	global_load_lds_dwordx4 v[162:163], off
	v_lshl_add_u64 v[162:163], v[248:249], 0, s[36:37]
	s_mov_b32 m0, s5
	s_nop 0
	global_load_lds_dwordx4 v[162:163], off
	s_waitcnt vmcnt(6)
	s_barrier
	v_mfma_f32_16x16x32_bf16 v[28:31], v[230:233], v[198:201], v[28:31]
	v_mfma_f32_16x16x32_bf16 v[24:27], v[238:241], v[198:201], v[24:27]
	v_mfma_f32_16x16x32_bf16 v[16:19], v[238:241], v[206:209], v[16:19]
	v_mfma_f32_16x16x32_bf16 v[20:23], v[230:233], v[206:209], v[20:23]
	v_mfma_f32_16x16x32_bf16 v[12:15], v[230:233], v[214:217], v[12:15]
	v_mfma_f32_16x16x32_bf16 v[8:11], v[238:241], v[214:217], v[8:11]
	v_mfma_f32_16x16x32_bf16 v[0:3], v[238:241], v[222:225], v[0:3]
	v_mfma_f32_16x16x32_bf16 v[4:7], v[230:233], v[222:225], v[4:7]
	v_mfma_f32_16x16x32_bf16 v[28:31], v[234:237], v[202:205], v[28:31]
	v_mfma_f32_16x16x32_bf16 v[24:27], v[242:245], v[202:205], v[24:27]
	v_mfma_f32_16x16x32_bf16 v[16:19], v[242:245], v[210:213], v[16:19]
	v_mfma_f32_16x16x32_bf16 v[20:23], v[234:237], v[210:213], v[20:23]
	v_mfma_f32_16x16x32_bf16 v[12:15], v[234:237], v[218:221], v[12:15]
	v_mfma_f32_16x16x32_bf16 v[8:11], v[242:245], v[218:221], v[8:11]
	v_mfma_f32_16x16x32_bf16 v[0:3], v[242:245], v[226:229], v[0:3]
	v_mfma_f32_16x16x32_bf16 v[4:7], v[234:237], v[226:229], v[4:7]
	s_add_i32 s1, s1, 2
	v_lshl_add_u64 v[136:137], v[136:137], 0, s[44:45]
	v_lshl_add_u64 v[138:139], v[138:139], 0, s[44:45]
	v_lshl_add_u64 v[140:141], v[140:141], 0, s[44:45]
	s_cmp_lt_u32 s1, 12
	v_lshl_add_u64 v[142:143], v[142:143], 0, s[44:45]
	s_barrier
	s_cbranch_scc1 .LBB0_797
	s_add_u32 s14, s14, 0x40780
	s_addc_u32 s15, s15, 0
	v_lshl_add_u64 v[130:131], s[14:15], 0, v[130:131]
	v_readfirstlane_b32 s1, v159
	v_lshl_add_u64 v[128:129], v[128:129], 1, v[130:131]
	s_mov_b32 m0, s1
	ds_read_b128 v[136:139], v158
	ds_read_b128 v[140:143], v158 offset:1024
	ds_read_b128 v[152:155], v158 offset:2048
	ds_read_b128 v[162:165], v158 offset:3072
	ds_read_b128 v[166:169], v148
	ds_read_b128 v[170:173], v148 offset:1024
	ds_read_b128 v[174:177], v147
	ds_read_b128 v[198:201], v147 offset:1024
	ds_read_b128 v[202:205], v146
	ds_read_b128 v[206:209], v146 offset:1024
	ds_read_b128 v[210:213], v145
	ds_read_b128 v[214:217], v145 offset:1024
	global_load_lds_dwordx4 v[128:129], off
	v_lshl_add_u64 v[128:129], s[14:15], 0, v[134:135]
	v_readfirstlane_b32 s1, v160
	v_lshl_add_u64 v[128:129], v[132:133], 1, v[128:129]
	s_mov_b32 m0, s1
	s_nop 0
	global_load_lds_dwordx4 v[128:129], off
	s_barrier
	s_waitcnt lgkmcnt(0)
	v_mfma_f32_16x16x32_bf16 v[116:119], v[136:139], v[174:177], v[116:119]
	v_mfma_f32_16x16x32_bf16 v[112:115], v[152:155], v[174:177], v[112:115]
	v_mfma_f32_16x16x32_bf16 v[104:107], v[152:155], v[202:205], v[104:107]
	v_mfma_f32_16x16x32_bf16 v[108:111], v[136:139], v[202:205], v[108:111]
	v_mfma_f32_16x16x32_bf16 v[100:103], v[136:139], v[210:213], v[100:103]
	v_mfma_f32_16x16x32_bf16 v[96:99], v[152:155], v[210:213], v[96:99]
	v_mfma_f32_16x16x32_bf16 v[120:123], v[152:155], v[166:169], v[120:123]
	v_mfma_f32_16x16x32_bf16 v[124:127], v[136:139], v[166:169], v[124:127]
	v_mfma_f32_16x16x32_bf16 v[116:119], v[140:143], v[198:201], v[116:119]
	v_mfma_f32_16x16x32_bf16 v[112:115], v[162:165], v[198:201], v[112:115]
	v_mfma_f32_16x16x32_bf16 v[104:107], v[162:165], v[206:209], v[104:107]
	v_mfma_f32_16x16x32_bf16 v[108:111], v[140:143], v[206:209], v[108:111]
	v_mfma_f32_16x16x32_bf16 v[100:103], v[140:143], v[214:217], v[100:103]
	v_mfma_f32_16x16x32_bf16 v[96:99], v[162:165], v[214:217], v[96:99]
	v_mfma_f32_16x16x32_bf16 v[120:123], v[162:165], v[170:173], v[120:123]
	v_mfma_f32_16x16x32_bf16 v[124:127], v[140:143], v[170:173], v[124:127]
	s_barrier
	ds_read_b128 v[128:131], v157
	ds_read_b128 v[132:135], v157 offset:1024
	ds_read_b128 v[158:161], v157 offset:2048
	ds_read_b128 v[218:221], v157 offset:3072
	s_barrier
; #define WAIT_V(n) asm volatile("s_waitcnt vmcnt(" #n ")" ::: "memory")
; #define WAIT_L(n) asm volatile("s_waitcnt lgkmcnt(" #n ")" ::: "memory")
; #define BAR __builtin_amdgcn_s_barrier()
; #define LDA(dst, b, h)                                                                            \
;   _Pragma("unroll") for (int m = 0; m < 4; ++m) _Pragma("unroll") for (int k = 0; k < 2; ++k)                                         \
;     dst[m][k] = *reinterpret_cast<const bf16x8*>((char*)SA(b, h) + lds_byte(wr * 64 + m * 16 + fr, k * 32 + fq * 8))
; #define LDB(dst, b, h)                                                                            \
;   _Pragma("unroll") for (int n = 0; n < 2; ++n) _Pragma("unroll") for (int k = 0; k < 2; ++k)                                         \
;     dst[n][k] = *reinterpret_cast<const bf16x8*>((char*)SB(b, h) + lds_byte(wc * 32 + n * 16 + fr, k * 32 + fq * 8))
; template <int K, bool SWAP>
; __device__ __forceinline__ void gemm_kloop(const bf16* __restrict__ A, const bf16* __restrict__ Bt,
;                                            f32x4 (&acc)[2][2][4][2], bool pref = false) {
;     ...
;     LDB(B1, 0, 1); BAR; WAIT_L(0); MMA(0, 1, At, B1); BAR;
;     LDA(At, 0, 1); WAIT_V(4); BAR; WAIT_L(0); MMA(1, 0, At, B0); MMA(1, 1, At, B1); BAR; }
;   { LDB(B0, 1, 0); LDA(At, 1, 0); WAIT_V(2); BAR; WAIT_L(0); MMA(0, 0, At, B0); BAR;
	s_waitcnt lgkmcnt(0)
	v_mfma_f32_16x16x32_bf16 v[92:95], v[128:131], v[166:169], v[92:95]
	v_mfma_f32_16x16x32_bf16 v[88:91], v[158:161], v[166:169], v[88:91]
	v_mfma_f32_16x16x32_bf16 v[80:83], v[158:161], v[174:177], v[80:83]
	v_mfma_f32_16x16x32_bf16 v[84:87], v[128:131], v[174:177], v[84:87]
	v_mfma_f32_16x16x32_bf16 v[76:79], v[128:131], v[202:205], v[76:79]
	v_mfma_f32_16x16x32_bf16 v[72:75], v[158:161], v[202:205], v[72:75]
	v_mfma_f32_16x16x32_bf16 v[64:67], v[158:161], v[210:213], v[64:67]
	v_mfma_f32_16x16x32_bf16 v[68:71], v[128:131], v[210:213], v[68:71]
	v_mfma_f32_16x16x32_bf16 v[92:95], v[132:135], v[170:173], v[92:95]
	v_mfma_f32_16x16x32_bf16 v[88:91], v[218:221], v[170:173], v[88:91]
	v_mfma_f32_16x16x32_bf16 v[80:83], v[218:221], v[198:201], v[80:83]
	v_mfma_f32_16x16x32_bf16 v[84:87], v[132:135], v[198:201], v[84:87]
	v_mfma_f32_16x16x32_bf16 v[76:79], v[132:135], v[206:209], v[76:79]
	v_mfma_f32_16x16x32_bf16 v[72:75], v[218:221], v[206:209], v[72:75]
	v_mfma_f32_16x16x32_bf16 v[64:67], v[218:221], v[214:217], v[64:67]
	v_mfma_f32_16x16x32_bf16 v[68:71], v[132:135], v[214:217], v[68:71]
	s_barrier
	ds_read_b128 v[166:169], v148 offset:16384
	ds_read_b128 v[170:173], v148 offset:17408
	ds_read_b128 v[174:177], v147 offset:16384
	ds_read_b128 v[198:201], v147 offset:17408
	ds_read_b128 v[202:205], v146 offset:16384
	ds_read_b128 v[206:209], v146 offset:17408
	ds_read_b128 v[210:213], v145 offset:16384
	ds_read_b128 v[214:217], v145 offset:17408
	s_waitcnt vmcnt(4)
	s_barrier
	s_waitcnt lgkmcnt(0)
	v_mfma_f32_16x16x32_bf16 v[60:63], v[136:139], v[166:169], v[60:63]
	v_mfma_f32_16x16x32_bf16 v[56:59], v[152:155], v[166:169], v[56:59]
	v_mfma_f32_16x16x32_bf16 v[48:51], v[152:155], v[174:177], v[48:51]
	v_mfma_f32_16x16x32_bf16 v[52:55], v[136:139], v[174:177], v[52:55]
	v_mfma_f32_16x16x32_bf16 v[44:47], v[136:139], v[202:205], v[44:47]
	v_mfma_f32_16x16x32_bf16 v[40:43], v[152:155], v[202:205], v[40:43]
	v_mfma_f32_16x16x32_bf16 v[32:35], v[152:155], v[210:213], v[32:35]
	v_mfma_f32_16x16x32_bf16 v[36:39], v[136:139], v[210:213], v[36:39]
	v_mfma_f32_16x16x32_bf16 v[60:63], v[140:143], v[170:173], v[60:63]
	v_mfma_f32_16x16x32_bf16 v[56:59], v[162:165], v[170:173], v[56:59]
	v_mfma_f32_16x16x32_bf16 v[48:51], v[162:165], v[198:201], v[48:51]
	v_mfma_f32_16x16x32_bf16 v[52:55], v[140:143], v[198:201], v[52:55]
	v_mfma_f32_16x16x32_bf16 v[44:47], v[140:143], v[206:209], v[44:47]
	v_mfma_f32_16x16x32_bf16 v[40:43], v[162:165], v[206:209], v[40:43]
	v_mfma_f32_16x16x32_bf16 v[32:35], v[162:165], v[214:217], v[32:35]
	v_mfma_f32_16x16x32_bf16 v[36:39], v[140:143], v[214:217], v[36:39]
	v_mfma_f32_16x16x32_bf16 v[28:31], v[128:131], v[166:169], v[28:31]
	v_mfma_f32_16x16x32_bf16 v[24:27], v[158:161], v[166:169], v[24:27]
	v_mfma_f32_16x16x32_bf16 v[16:19], v[158:161], v[174:177], v[16:19]
	v_mfma_f32_16x16x32_bf16 v[20:23], v[128:131], v[174:177], v[20:23]
	v_mfma_f32_16x16x32_bf16 v[12:15], v[128:131], v[202:205], v[12:15]
	v_mfma_f32_16x16x32_bf16 v[8:11], v[158:161], v[202:205], v[8:11]
	v_mfma_f32_16x16x32_bf16 v[0:3], v[158:161], v[210:213], v[0:3]
	v_mfma_f32_16x16x32_bf16 v[4:7], v[128:131], v[210:213], v[4:7]
	v_mfma_f32_16x16x32_bf16 v[28:31], v[132:135], v[170:173], v[28:31]
	v_mfma_f32_16x16x32_bf16 v[24:27], v[218:221], v[170:173], v[24:27]
	v_mfma_f32_16x16x32_bf16 v[16:19], v[218:221], v[198:201], v[16:19]
	v_mfma_f32_16x16x32_bf16 v[20:23], v[132:135], v[198:201], v[20:23]
	v_mfma_f32_16x16x32_bf16 v[12:15], v[132:135], v[206:209], v[12:15]
	v_mfma_f32_16x16x32_bf16 v[8:11], v[218:221], v[206:209], v[8:11]
	v_mfma_f32_16x16x32_bf16 v[0:3], v[218:221], v[214:217], v[0:3]
	v_mfma_f32_16x16x32_bf16 v[4:7], v[132:135], v[214:217], v[4:7]
	s_barrier
	ds_read_b128 v[136:139], v151
	ds_read_b128 v[140:143], v151 offset:1024
	ds_read_b128 v[152:155], v151 offset:2048
	ds_read_b128 v[156:159], v151 offset:3072
	ds_read_b128 v[160:163], v148 offset:32768
	ds_read_b128 v[164:167], v148 offset:33792
	ds_read_b128 v[168:171], v147 offset:32768
	ds_read_b128 v[172:175], v147 offset:33792
	ds_read_b128 v[176:179], v146 offset:32768
	ds_read_b128 v[198:201], v146 offset:33792
	ds_read_b128 v[202:205], v145 offset:32768
	ds_read_b128 v[206:209], v145 offset:33792
	s_waitcnt vmcnt(2)
	s_barrier
; #define WAIT_V(n) asm volatile("s_waitcnt vmcnt(" #n ")" ::: "memory")
; #define WAIT_L(n) asm volatile("s_waitcnt lgkmcnt(" #n ")" ::: "memory")
; #define BAR __builtin_amdgcn_s_barrier()
; #define LDA(dst, b, h)                                                                            \
;   _Pragma("unroll") for (int m = 0; m < 4; ++m) _Pragma("unroll") for (int k = 0; k < 2; ++k)                                         \
;     dst[m][k] = *reinterpret_cast<const bf16x8*>((char*)SA(b, h) + lds_byte(wr * 64 + m * 16 + fr, k * 32 + fq * 8))
; #define LDB(dst, b, h)                                                                            \
;   _Pragma("unroll") for (int n = 0; n < 2; ++n) _Pragma("unroll") for (int k = 0; k < 2; ++k)                                         \
;     dst[n][k] = *reinterpret_cast<const bf16x8*>((char*)SB(b, h) + lds_byte(wc * 32 + n * 16 + fr, k * 32 + fq * 8))
; template <int K, bool SWAP>
; __device__ __forceinline__ void gemm_kloop(const bf16* __restrict__ A, const bf16* __restrict__ Bt,
;                                            f32x4 (&acc)[2][2][4][2], bool pref = false) {
;     ...
;   { LDB(B0, 1, 0); LDA(At, 1, 0); WAIT_V(2); BAR; WAIT_L(0); MMA(0, 0, At, B0); BAR;
;     LDB(B1, 1, 1); WAIT_V(0); BAR; WAIT_L(0); MMA(0, 1, At, B1); BAR;
;     LDA(At, 1, 1); BAR; WAIT_L(0); MMA(1, 0, At, B0); MMA(1, 1, At, B1); BAR; }
;   if (wr == 0) BAR;
	s_waitcnt lgkmcnt(0)
	v_mfma_f32_16x16x32_bf16 v[124:127], v[136:139], v[160:163], v[124:127]
	v_mfma_f32_16x16x32_bf16 v[120:123], v[152:155], v[160:163], v[120:123]
	v_mfma_f32_16x16x32_bf16 v[116:119], v[136:139], v[168:171], v[116:119]
	v_mfma_f32_16x16x32_bf16 v[112:115], v[152:155], v[168:171], v[112:115]
	v_mfma_f32_16x16x32_bf16 v[108:111], v[136:139], v[176:179], v[108:111]
	v_mfma_f32_16x16x32_bf16 v[104:107], v[152:155], v[176:179], v[104:107]
	v_mfma_f32_16x16x32_bf16 v[100:103], v[136:139], v[202:205], v[100:103]
	v_mfma_f32_16x16x32_bf16 v[96:99], v[152:155], v[202:205], v[96:99]
	v_mfma_f32_16x16x32_bf16 v[132:135], v[140:143], v[164:167], v[124:127]
	v_mfma_f32_16x16x32_bf16 v[128:131], v[156:159], v[164:167], v[120:123]
	v_mfma_f32_16x16x32_bf16 v[116:119], v[140:143], v[172:175], v[116:119]
	v_mfma_f32_16x16x32_bf16 v[112:115], v[156:159], v[172:175], v[112:115]
	v_mfma_f32_16x16x32_bf16 v[108:111], v[140:143], v[198:201], v[108:111]
	v_mfma_f32_16x16x32_bf16 v[104:107], v[156:159], v[198:201], v[104:107]
	v_mfma_f32_16x16x32_bf16 v[100:103], v[140:143], v[206:209], v[100:103]
	v_mfma_f32_16x16x32_bf16 v[96:99], v[156:159], v[206:209], v[96:99]
	s_barrier
	ds_read_b128 v[120:123], v149
	ds_read_b128 v[124:127], v149 offset:1024
	ds_read_b128 v[210:213], v149 offset:2048
	ds_read_b128 v[214:217], v149 offset:3072
	s_waitcnt vmcnt(0)
	s_barrier
	s_waitcnt lgkmcnt(0)
	v_mfma_f32_16x16x32_bf16 v[92:95], v[120:123], v[160:163], v[92:95]
	v_mfma_f32_16x16x32_bf16 v[88:91], v[210:213], v[160:163], v[88:91]
	v_mfma_f32_16x16x32_bf16 v[80:83], v[210:213], v[168:171], v[80:83]
	v_mfma_f32_16x16x32_bf16 v[84:87], v[120:123], v[168:171], v[84:87]
	v_mfma_f32_16x16x32_bf16 v[76:79], v[120:123], v[176:179], v[76:79]
	v_mfma_f32_16x16x32_bf16 v[72:75], v[210:213], v[176:179], v[72:75]
	v_mfma_f32_16x16x32_bf16 v[64:67], v[210:213], v[202:205], v[64:67]
	v_mfma_f32_16x16x32_bf16 v[68:71], v[120:123], v[202:205], v[68:71]
	v_mfma_f32_16x16x32_bf16 v[92:95], v[124:127], v[164:167], v[92:95]
	v_mfma_f32_16x16x32_bf16 v[88:91], v[214:217], v[164:167], v[88:91]
	v_mfma_f32_16x16x32_bf16 v[80:83], v[214:217], v[172:175], v[80:83]
	v_mfma_f32_16x16x32_bf16 v[84:87], v[124:127], v[172:175], v[84:87]
	v_mfma_f32_16x16x32_bf16 v[76:79], v[124:127], v[198:201], v[76:79]
	v_mfma_f32_16x16x32_bf16 v[72:75], v[214:217], v[198:201], v[72:75]
	v_mfma_f32_16x16x32_bf16 v[64:67], v[214:217], v[206:209], v[64:67]
	v_mfma_f32_16x16x32_bf16 v[68:71], v[124:127], v[206:209], v[68:71]
	s_barrier
	ds_read_b128 v[160:163], v148 offset:49152
	ds_read_b128 v[148:151], v148 offset:50176
	ds_read_b128 v[164:167], v147 offset:49152
	ds_read_b128 v[168:171], v147 offset:50176
	ds_read_b128 v[172:175], v146 offset:49152
	ds_read_b128 v[176:179], v146 offset:50176
	ds_read_b128 v[198:201], v145 offset:49152
	ds_read_b128 v[202:205], v145 offset:50176
	s_barrier
	s_waitcnt lgkmcnt(0)
	v_mfma_f32_16x16x32_bf16 v[60:63], v[136:139], v[160:163], v[60:63]
	v_mfma_f32_16x16x32_bf16 v[56:59], v[152:155], v[160:163], v[56:59]
	v_mfma_f32_16x16x32_bf16 v[48:51], v[152:155], v[164:167], v[48:51]
	v_mfma_f32_16x16x32_bf16 v[52:55], v[136:139], v[164:167], v[52:55]
	v_mfma_f32_16x16x32_bf16 v[44:47], v[136:139], v[172:175], v[44:47]
	v_mfma_f32_16x16x32_bf16 v[40:43], v[152:155], v[172:175], v[40:43]
	v_mfma_f32_16x16x32_bf16 v[32:35], v[152:155], v[198:201], v[32:35]
	v_mfma_f32_16x16x32_bf16 v[36:39], v[136:139], v[198:201], v[36:39]
	v_mfma_f32_16x16x32_bf16 v[60:63], v[140:143], v[148:151], v[60:63]
	v_mfma_f32_16x16x32_bf16 v[56:59], v[156:159], v[148:151], v[56:59]
	v_mfma_f32_16x16x32_bf16 v[48:51], v[156:159], v[168:171], v[48:51]
	v_mfma_f32_16x16x32_bf16 v[52:55], v[140:143], v[168:171], v[52:55]
	v_mfma_f32_16x16x32_bf16 v[44:47], v[140:143], v[176:179], v[44:47]
	v_mfma_f32_16x16x32_bf16 v[40:43], v[156:159], v[176:179], v[40:43]
	v_mfma_f32_16x16x32_bf16 v[32:35], v[156:159], v[202:205], v[32:35]
	v_mfma_f32_16x16x32_bf16 v[36:39], v[140:143], v[202:205], v[36:39]
	v_mfma_f32_16x16x32_bf16 v[28:31], v[120:123], v[160:163], v[28:31]
	v_mfma_f32_16x16x32_bf16 v[24:27], v[210:213], v[160:163], v[24:27]
	v_mfma_f32_16x16x32_bf16 v[16:19], v[210:213], v[164:167], v[16:19]
	v_mfma_f32_16x16x32_bf16 v[20:23], v[120:123], v[164:167], v[20:23]
	v_mfma_f32_16x16x32_bf16 v[12:15], v[120:123], v[172:175], v[12:15]
	v_mfma_f32_16x16x32_bf16 v[8:11], v[210:213], v[172:175], v[8:11]
	v_mfma_f32_16x16x32_bf16 v[0:3], v[210:213], v[198:201], v[0:3]
	v_mfma_f32_16x16x32_bf16 v[4:7], v[120:123], v[198:201], v[4:7]
	v_mfma_f32_16x16x32_bf16 v[28:31], v[124:127], v[148:151], v[28:31]
	v_mfma_f32_16x16x32_bf16 v[24:27], v[214:217], v[148:151], v[24:27]
	v_mfma_f32_16x16x32_bf16 v[16:19], v[214:217], v[168:171], v[16:19]
	v_mfma_f32_16x16x32_bf16 v[20:23], v[124:127], v[168:171], v[20:23]
	v_mfma_f32_16x16x32_bf16 v[12:15], v[124:127], v[176:179], v[12:15]
	v_mfma_f32_16x16x32_bf16 v[8:11], v[214:217], v[176:179], v[8:11]
	v_mfma_f32_16x16x32_bf16 v[0:3], v[214:217], v[202:205], v[0:3]
	v_mfma_f32_16x16x32_bf16 v[4:7], v[124:127], v[202:205], v[4:7]
	s_movk_i32 s1, 0x100
	v_cmp_gt_u32_e32 vcc, s1, v144
	s_barrier
	s_and_saveexec_b64 s[14:15], vcc
	s_mov_b32 s62, s68
	s_mov_b32 s63, s69
	s_cbranch_execz .LBB0_800
	s_barrier

; #define WAIT_V(n) asm volatile("s_waitcnt vmcnt(" #n ")" ::: "memory")
; #define WAIT_L(n) asm volatile("s_waitcnt lgkmcnt(" #n ")" ::: "memory")
; #define BAR __builtin_amdgcn_s_barrier()
; #define SCHED __builtin_amdgcn_sched_barrier(0)
; #define LDA(dst, b, h)                                                                            \
;   _Pragma("unroll") for (int m = 0; m < 4; ++m) _Pragma("unroll") for (int k = 0; k < 2; ++k)                                         \
;     dst[m][k] = *reinterpret_cast<const bf16x8*>((char*)SA(b, h) + lds_byte(wr * 64 + m * 16 + fr, k * 32 + fq * 8))
; #define LDB(dst, b, h)                                                                            \
;   _Pragma("unroll") for (int n = 0; n < 2; ++n) _Pragma("unroll") for (int k = 0; k < 2; ++k)                                         \
;     dst[n][k] = *reinterpret_cast<const bf16x8*>((char*)SB(b, h) + lds_byte(wc * 32 + n * 16 + fr, k * 32 + fq * 8))
; template <int K, bool SWAP>
; __device__ __forceinline__ void gemm_kloop(const bf16* __restrict__ A, const bf16* __restrict__ Bt,
;                                            f32x4 (&acc)[2][2][4][2], bool pref = false) {
;     ...
;     LDB(B0, 0, 0); SCHED; LDA(At, 0, 0); STAGE(SA(1, 1), A, HALF, t + 1);
;     WAIT_L(8); BAR; WAIT_L(0); MMA(0, 0, At, B0); BAR; SCHED;
;     LDB(B1, 0, 1); STAGE(SB(0, 0), Bt, 0, t + 2);
;     BAR; WAIT_L(0); MMA(0, 1, At, B1); BAR;
;     LDA(At, 0, 1); STAGE(SA(0, 0), A, 0, t + 2);
;     BAR; WAIT_L(0); MMA(1, 0, At, B0); BAR; SCHED;
;     STAGE(SB(0, 1), Bt, HALF, t + 2);
;     WAIT_V(6); BAR; MMA(1, 1, At, B1); BAR;
.LBB0_844:
	ds_read_b128 v[162:165], v159
	ds_read_b128 v[166:169], v159 offset:1024
	ds_read_b128 v[170:173], v159 offset:2048
	ds_read_b128 v[174:177], v159 offset:3072
	v_add_u32_e32 v160, 0xc000, v146
	v_lshl_add_u64 v[178:179], s[6:7], 0, v[140:141]
	v_readfirstlane_b32 s14, v160
	v_lshl_add_u64 v[188:189], v[178:179], 0, s[38:39]
	s_mov_b32 m0, s14
	v_add_u32_e32 v161, 0xe000, v146
	ds_read_b128 v[198:201], v151
	ds_read_b128 v[202:205], v151 offset:1024
	ds_read_b128 v[206:209], v150
	ds_read_b128 v[210:213], v150 offset:1024
	ds_read_b128 v[214:217], v149
	ds_read_b128 v[218:221], v149 offset:1024
	ds_read_b128 v[222:225], v148
	ds_read_b128 v[226:229], v148 offset:1024
	global_load_lds_dwordx4 v[188:189], off
	v_lshl_add_u64 v[188:189], s[6:7], 0, v[142:143]
	v_readfirstlane_b32 s14, v161
	v_lshl_add_u64 v[230:231], v[188:189], 0, s[38:39]
	s_mov_b32 m0, s14
	s_nop 0
	global_load_lds_dwordx4 v[230:231], off
	s_waitcnt lgkmcnt(8)
	s_barrier
	s_waitcnt lgkmcnt(0)
	v_mfma_f32_16x16x32_bf16 v[124:127], v[162:165], v[198:201], v[124:127]
	v_mfma_f32_16x16x32_bf16 v[120:123], v[170:173], v[198:201], v[120:123]
	v_mfma_f32_16x16x32_bf16 v[112:115], v[170:173], v[206:209], v[112:115]
	v_mfma_f32_16x16x32_bf16 v[116:119], v[162:165], v[206:209], v[116:119]
	v_mfma_f32_16x16x32_bf16 v[108:111], v[162:165], v[214:217], v[108:111]
	v_mfma_f32_16x16x32_bf16 v[104:107], v[170:173], v[214:217], v[104:107]
	v_mfma_f32_16x16x32_bf16 v[96:99], v[170:173], v[222:225], v[96:99]
	v_mfma_f32_16x16x32_bf16 v[100:103], v[162:165], v[222:225], v[100:103]
	v_mfma_f32_16x16x32_bf16 v[124:127], v[166:169], v[202:205], v[124:127]
	v_mfma_f32_16x16x32_bf16 v[120:123], v[174:177], v[202:205], v[120:123]
	v_mfma_f32_16x16x32_bf16 v[112:115], v[174:177], v[210:213], v[112:115]
	v_mfma_f32_16x16x32_bf16 v[116:119], v[166:169], v[210:213], v[116:119]
	v_mfma_f32_16x16x32_bf16 v[108:111], v[166:169], v[218:221], v[108:111]
	v_mfma_f32_16x16x32_bf16 v[104:107], v[174:177], v[218:221], v[104:107]
	v_mfma_f32_16x16x32_bf16 v[96:99], v[174:177], v[226:229], v[96:99]
	v_mfma_f32_16x16x32_bf16 v[100:103], v[166:169], v[226:229], v[100:103]
	s_barrier
	v_add_u32_e32 v186, s9, v145
	v_lshl_add_u64 v[246:247], s[6:7], 0, v[136:137]
	v_readfirstlane_b32 s14, v186
	v_lshl_add_u64 v[248:249], v[246:247], 0, s[18:19]
	s_mov_b32 m0, s14
	v_add_u32_e32 v186, 0x2000, v186
	ds_read_b128 v[230:233], v158
	ds_read_b128 v[234:237], v158 offset:1024
	ds_read_b128 v[238:241], v158 offset:2048
	ds_read_b128 v[242:245], v158 offset:3072
	global_load_lds_dwordx4 v[248:249], off
	v_lshl_add_u64 v[248:249], s[6:7], 0, v[138:139]
	v_readfirstlane_b32 s14, v186
	v_lshl_add_u64 v[250:251], v[248:249], 0, s[18:19]
	s_mov_b32 m0, s14
	s_nop 0
	global_load_lds_dwordx4 v[250:251], off
	s_barrier
	s_waitcnt lgkmcnt(0)
	v_mfma_f32_16x16x32_bf16 v[92:95], v[230:233], v[198:201], v[92:95]
	v_mfma_f32_16x16x32_bf16 v[88:91], v[238:241], v[198:201], v[88:91]
	v_mfma_f32_16x16x32_bf16 v[80:83], v[238:241], v[206:209], v[80:83]
	v_mfma_f32_16x16x32_bf16 v[84:87], v[230:233], v[206:209], v[84:87]
	v_mfma_f32_16x16x32_bf16 v[76:79], v[230:233], v[214:217], v[76:79]
	v_mfma_f32_16x16x32_bf16 v[72:75], v[238:241], v[214:217], v[72:75]
	v_mfma_f32_16x16x32_bf16 v[64:67], v[238:241], v[222:225], v[64:67]
	v_mfma_f32_16x16x32_bf16 v[68:71], v[230:233], v[222:225], v[68:71]
	v_mfma_f32_16x16x32_bf16 v[92:95], v[234:237], v[202:205], v[92:95]
	v_mfma_f32_16x16x32_bf16 v[88:91], v[242:245], v[202:205], v[88:91]
	v_mfma_f32_16x16x32_bf16 v[80:83], v[242:245], v[210:213], v[80:83]
	v_mfma_f32_16x16x32_bf16 v[84:87], v[234:237], v[210:213], v[84:87]
	v_mfma_f32_16x16x32_bf16 v[76:79], v[234:237], v[218:221], v[76:79]
	v_mfma_f32_16x16x32_bf16 v[72:75], v[242:245], v[218:221], v[72:75]
	v_mfma_f32_16x16x32_bf16 v[64:67], v[242:245], v[226:229], v[64:67]
	v_mfma_f32_16x16x32_bf16 v[68:71], v[234:237], v[226:229], v[68:71]
	v_readfirstlane_b32 s14, v146
	v_add_u32_e32 v186, 0x2000, v146
	v_lshl_add_u64 v[250:251], v[178:179], 0, s[26:27]
	s_mov_b32 m0, s14
	v_readfirstlane_b32 s14, v186
	s_barrier
	ds_read_b128 v[198:201], v151 offset:16384
	ds_read_b128 v[202:205], v151 offset:17408
	ds_read_b128 v[206:209], v150 offset:16384
	ds_read_b128 v[210:213], v150 offset:17408
	ds_read_b128 v[214:217], v149 offset:16384
	ds_read_b128 v[218:221], v149 offset:17408
	ds_read_b128 v[222:225], v148 offset:16384
	ds_read_b128 v[226:229], v148 offset:17408
	global_load_lds_dwordx4 v[250:251], off
	v_lshl_add_u64 v[250:251], v[188:189], 0, s[26:27]
	s_mov_b32 m0, s14
	s_nop 0
	global_load_lds_dwordx4 v[250:251], off
	s_barrier
	s_waitcnt lgkmcnt(0)
	v_mfma_f32_16x16x32_bf16 v[60:63], v[162:165], v[198:201], v[60:63]
	v_mfma_f32_16x16x32_bf16 v[56:59], v[170:173], v[198:201], v[56:59]
	v_mfma_f32_16x16x32_bf16 v[48:51], v[170:173], v[206:209], v[48:51]
	v_mfma_f32_16x16x32_bf16 v[52:55], v[162:165], v[206:209], v[52:55]
	v_mfma_f32_16x16x32_bf16 v[44:47], v[162:165], v[214:217], v[44:47]
	v_mfma_f32_16x16x32_bf16 v[40:43], v[170:173], v[214:217], v[40:43]
	v_mfma_f32_16x16x32_bf16 v[32:35], v[170:173], v[222:225], v[32:35]
	v_mfma_f32_16x16x32_bf16 v[36:39], v[162:165], v[222:225], v[36:39]
	v_mfma_f32_16x16x32_bf16 v[60:63], v[166:169], v[202:205], v[60:63]
	v_mfma_f32_16x16x32_bf16 v[56:59], v[174:177], v[202:205], v[56:59]
	v_mfma_f32_16x16x32_bf16 v[48:51], v[174:177], v[210:213], v[48:51]
	v_mfma_f32_16x16x32_bf16 v[52:55], v[166:169], v[210:213], v[52:55]
	v_mfma_f32_16x16x32_bf16 v[44:47], v[166:169], v[218:221], v[44:47]
	v_mfma_f32_16x16x32_bf16 v[40:43], v[174:177], v[218:221], v[40:43]
	v_mfma_f32_16x16x32_bf16 v[32:35], v[174:177], v[226:229], v[32:35]
	v_mfma_f32_16x16x32_bf16 v[36:39], v[166:169], v[226:229], v[36:39]
	s_barrier
; #define WAIT_V(n) asm volatile("s_waitcnt vmcnt(" #n ")" ::: "memory")
; #define WAIT_L(n) asm volatile("s_waitcnt lgkmcnt(" #n ")" ::: "memory")
; #define BAR __builtin_amdgcn_s_barrier()
; #define SCHED __builtin_amdgcn_sched_barrier(0)
; #define LDA(dst, b, h)                                                                            \
;   _Pragma("unroll") for (int m = 0; m < 4; ++m) _Pragma("unroll") for (int k = 0; k < 2; ++k)                                         \
;     dst[m][k] = *reinterpret_cast<const bf16x8*>((char*)SA(b, h) + lds_byte(wr * 64 + m * 16 + fr, k * 32 + fq * 8))
; #define LDB(dst, b, h)                                                                            \
;   _Pragma("unroll") for (int n = 0; n < 2; ++n) _Pragma("unroll") for (int k = 0; k < 2; ++k)                                         \
;     dst[n][k] = *reinterpret_cast<const bf16x8*>((char*)SB(b, h) + lds_byte(wc * 32 + n * 16 + fr, k * 32 + fq * 8))
; template <int K, bool SWAP>
; __device__ __forceinline__ void gemm_kloop(const bf16* __restrict__ A, const bf16* __restrict__ Bt,
;                                            f32x4 (&acc)[2][2][4][2], bool pref = false) {
;     ...
;     WAIT_V(6); BAR; MMA(1, 1, At, B1); BAR;
;     LDB(B0, 1, 0); SCHED; LDA(At, 1, 0); STAGE(SA(0, 1), A, HALF, t + 2);
;     WAIT_L(8); BAR; WAIT_L(0); MMA(0, 0, At, B0); BAR; SCHED;
;     LDB(B1, 1, 1); STAGE(SB(1, 0), Bt, 0, t + 3);
;     BAR; WAIT_L(0); MMA(0, 1, At, B1); BAR;
;     LDA(At, 1, 1); STAGE(SA(1, 0), A, 0, t + 3);
;     BAR; WAIT_L(0); MMA(1, 0, At, B0); BAR; SCHED;
;     STAGE(SB(1, 1), Bt, HALF, t + 3);
	v_readfirstlane_b32 s14, v147
	v_add_u32_e32 v164, 0x2000, v147
	v_lshl_add_u64 v[162:163], v[246:247], 0, s[30:31]
	s_mov_b32 m0, s14
	v_readfirstlane_b32 s14, v164
	global_load_lds_dwordx4 v[162:163], off
	v_lshl_add_u64 v[162:163], v[248:249], 0, s[30:31]
	s_mov_b32 m0, s14
	s_nop 0
	global_load_lds_dwordx4 v[162:163], off
	s_waitcnt vmcnt(6)
	s_barrier
	v_mfma_f32_16x16x32_bf16 v[28:31], v[230:233], v[198:201], v[28:31]
	v_mfma_f32_16x16x32_bf16 v[24:27], v[238:241], v[198:201], v[24:27]
	v_mfma_f32_16x16x32_bf16 v[16:19], v[238:241], v[206:209], v[16:19]
	v_mfma_f32_16x16x32_bf16 v[20:23], v[230:233], v[206:209], v[20:23]
	v_mfma_f32_16x16x32_bf16 v[12:15], v[230:233], v[214:217], v[12:15]
	v_mfma_f32_16x16x32_bf16 v[8:11], v[238:241], v[214:217], v[8:11]
	v_mfma_f32_16x16x32_bf16 v[0:3], v[238:241], v[222:225], v[0:3]
	v_mfma_f32_16x16x32_bf16 v[4:7], v[230:233], v[222:225], v[4:7]
	v_mfma_f32_16x16x32_bf16 v[28:31], v[234:237], v[202:205], v[28:31]
	v_mfma_f32_16x16x32_bf16 v[24:27], v[242:245], v[202:205], v[24:27]
	v_mfma_f32_16x16x32_bf16 v[16:19], v[242:245], v[210:213], v[16:19]
	v_mfma_f32_16x16x32_bf16 v[20:23], v[234:237], v[210:213], v[20:23]
	v_mfma_f32_16x16x32_bf16 v[12:15], v[234:237], v[218:221], v[12:15]
	v_mfma_f32_16x16x32_bf16 v[8:11], v[242:245], v[218:221], v[8:11]
	v_mfma_f32_16x16x32_bf16 v[0:3], v[242:245], v[226:229], v[0:3]
	v_mfma_f32_16x16x32_bf16 v[4:7], v[234:237], v[226:229], v[4:7]
	s_barrier
	ds_read_b128 v[162:165], v153
	ds_read_b128 v[166:169], v153 offset:1024
	ds_read_b128 v[170:173], v153 offset:2048
	ds_read_b128 v[174:177], v153 offset:3072
	v_add_u32_e32 v186, 0x4000, v146
	v_lshl_add_u64 v[230:231], v[178:179], 0, s[16:17]
	v_readfirstlane_b32 s14, v186
	v_add_u32_e32 v186, 0x6000, v146
	s_mov_b32 m0, s14
	v_readfirstlane_b32 s14, v186
	ds_read_b128 v[198:201], v151 offset:32768
	ds_read_b128 v[202:205], v151 offset:33792
	ds_read_b128 v[206:209], v150 offset:32768
	ds_read_b128 v[210:213], v150 offset:33792
	ds_read_b128 v[214:217], v149 offset:32768
	ds_read_b128 v[218:221], v149 offset:33792
	ds_read_b128 v[222:225], v148 offset:32768
	ds_read_b128 v[226:229], v148 offset:33792
	global_load_lds_dwordx4 v[230:231], off
	v_lshl_add_u64 v[230:231], v[188:189], 0, s[16:17]
	s_mov_b32 m0, s14
	s_nop 0
	global_load_lds_dwordx4 v[230:231], off
	s_waitcnt lgkmcnt(8)
	s_barrier
	s_waitcnt lgkmcnt(0)
	v_mfma_f32_16x16x32_bf16 v[124:127], v[162:165], v[198:201], v[124:127]
	v_mfma_f32_16x16x32_bf16 v[120:123], v[170:173], v[198:201], v[120:123]
	v_mfma_f32_16x16x32_bf16 v[112:115], v[170:173], v[206:209], v[112:115]
	v_mfma_f32_16x16x32_bf16 v[116:119], v[162:165], v[206:209], v[116:119]
	v_mfma_f32_16x16x32_bf16 v[108:111], v[162:165], v[214:217], v[108:111]
	v_mfma_f32_16x16x32_bf16 v[104:107], v[170:173], v[214:217], v[104:107]
	v_mfma_f32_16x16x32_bf16 v[96:99], v[170:173], v[222:225], v[96:99]
	v_mfma_f32_16x16x32_bf16 v[100:103], v[162:165], v[222:225], v[100:103]
	v_mfma_f32_16x16x32_bf16 v[124:127], v[166:169], v[202:205], v[124:127]
	v_mfma_f32_16x16x32_bf16 v[120:123], v[174:177], v[202:205], v[120:123]
	v_mfma_f32_16x16x32_bf16 v[112:115], v[174:177], v[210:213], v[112:115]
	v_mfma_f32_16x16x32_bf16 v[116:119], v[166:169], v[210:213], v[116:119]
	v_mfma_f32_16x16x32_bf16 v[108:111], v[166:169], v[218:221], v[108:111]
	v_mfma_f32_16x16x32_bf16 v[104:107], v[174:177], v[218:221], v[104:107]
	v_mfma_f32_16x16x32_bf16 v[96:99], v[174:177], v[226:229], v[96:99]
	v_mfma_f32_16x16x32_bf16 v[100:103], v[166:169], v[226:229], v[100:103]
	s_barrier
	v_readfirstlane_b32 s14, v154
	v_add_u32_e32 v186, 0x2000, v154
	v_lshl_add_u64 v[250:251], v[246:247], 0, s[28:29]
	s_mov_b32 m0, s14
	v_readfirstlane_b32 s14, v186
	ds_read_b128 v[230:233], v152
	ds_read_b128 v[234:237], v152 offset:1024
	ds_read_b128 v[238:241], v152 offset:2048
	ds_read_b128 v[242:245], v152 offset:3072
	global_load_lds_dwordx4 v[250:251], off
	v_lshl_add_u64 v[250:251], v[248:249], 0, s[28:29]
	s_mov_b32 m0, s14
	s_nop 0
	global_load_lds_dwordx4 v[250:251], off
	s_barrier
	s_waitcnt lgkmcnt(0)
	v_mfma_f32_16x16x32_bf16 v[92:95], v[230:233], v[198:201], v[92:95]
	v_mfma_f32_16x16x32_bf16 v[88:91], v[238:241], v[198:201], v[88:91]
	v_mfma_f32_16x16x32_bf16 v[80:83], v[238:241], v[206:209], v[80:83]
	v_mfma_f32_16x16x32_bf16 v[84:87], v[230:233], v[206:209], v[84:87]
	v_mfma_f32_16x16x32_bf16 v[76:79], v[230:233], v[214:217], v[76:79]
	v_mfma_f32_16x16x32_bf16 v[72:75], v[238:241], v[214:217], v[72:75]
	v_mfma_f32_16x16x32_bf16 v[64:67], v[238:241], v[222:225], v[64:67]
	v_mfma_f32_16x16x32_bf16 v[68:71], v[230:233], v[222:225], v[68:71]
	v_mfma_f32_16x16x32_bf16 v[92:95], v[234:237], v[202:205], v[92:95]
	v_mfma_f32_16x16x32_bf16 v[88:91], v[242:245], v[202:205], v[88:91]
	v_mfma_f32_16x16x32_bf16 v[80:83], v[242:245], v[210:213], v[80:83]
	v_mfma_f32_16x16x32_bf16 v[84:87], v[234:237], v[210:213], v[84:87]
	v_mfma_f32_16x16x32_bf16 v[76:79], v[234:237], v[218:221], v[76:79]
	v_mfma_f32_16x16x32_bf16 v[72:75], v[242:245], v[218:221], v[72:75]
	v_mfma_f32_16x16x32_bf16 v[64:67], v[242:245], v[226:229], v[64:67]
	v_mfma_f32_16x16x32_bf16 v[68:71], v[234:237], v[226:229], v[68:71]
	v_readfirstlane_b32 s14, v155
	v_lshl_add_u64 v[178:179], v[178:179], 0, s[24:25]
	s_mov_b32 m0, s14
	v_readfirstlane_b32 s14, v156
	s_barrier
	ds_read_b128 v[198:201], v151 offset:49152
	ds_read_b128 v[202:205], v151 offset:50176
	ds_read_b128 v[206:209], v150 offset:49152
	ds_read_b128 v[210:213], v150 offset:50176
	ds_read_b128 v[214:217], v149 offset:49152
	ds_read_b128 v[218:221], v149 offset:50176
	ds_read_b128 v[222:225], v148 offset:49152
	ds_read_b128 v[226:229], v148 offset:50176
	global_load_lds_dwordx4 v[178:179], off
	v_lshl_add_u64 v[178:179], v[188:189], 0, s[24:25]
	s_mov_b32 m0, s14
	s_nop 0
	global_load_lds_dwordx4 v[178:179], off
	s_barrier
; #define WAIT_V(n) asm volatile("s_waitcnt vmcnt(" #n ")" ::: "memory")
; #define WAIT_L(n) asm volatile("s_waitcnt lgkmcnt(" #n ")" ::: "memory")
; #define BAR __builtin_amdgcn_s_barrier()
; #define SCHED __builtin_amdgcn_sched_barrier(0)
; #define LDA(dst, b, h)                                                                            \
;   _Pragma("unroll") for (int m = 0; m < 4; ++m) _Pragma("unroll") for (int k = 0; k < 2; ++k)                                         \
;     dst[m][k] = *reinterpret_cast<const bf16x8*>((char*)SA(b, h) + lds_byte(wr * 64 + m * 16 + fr, k * 32 + fq * 8))
; #define LDB(dst, b, h)                                                                            \
;   _Pragma("unroll") for (int n = 0; n < 2; ++n) _Pragma("unroll") for (int k = 0; k < 2; ++k)                                         \
;     dst[n][k] = *reinterpret_cast<const bf16x8*>((char*)SB(b, h) + lds_byte(wc * 32 + n * 16 + fr, k * 32 + fq * 8))
; template <int K, bool SWAP>
; __device__ __forceinline__ void gemm_kloop(const bf16* __restrict__ A, const bf16* __restrict__ Bt,
;                                            f32x4 (&acc)[2][2][4][2], bool pref = false) {
;     ...
;     BAR; WAIT_L(0); MMA(1, 0, At, B0); BAR; SCHED;
;     STAGE(SB(1, 1), Bt, HALF, t + 3);
;     WAIT_V(6); BAR; MMA(1, 1, At, B1); BAR;
;   }
;   { LDB(B0, 0, 0); LDA(At, 0, 0); STAGE(SA(1, 1), A, HALF, nt - 1);
;     BAR; WAIT_L(0); MMA(0, 0, At, B0); BAR;
	s_waitcnt lgkmcnt(0)
	v_mfma_f32_16x16x32_bf16 v[60:63], v[162:165], v[198:201], v[60:63]
	v_mfma_f32_16x16x32_bf16 v[56:59], v[170:173], v[198:201], v[56:59]
	v_mfma_f32_16x16x32_bf16 v[48:51], v[170:173], v[206:209], v[48:51]
	v_mfma_f32_16x16x32_bf16 v[52:55], v[162:165], v[206:209], v[52:55]
	v_mfma_f32_16x16x32_bf16 v[44:47], v[162:165], v[214:217], v[44:47]
	v_mfma_f32_16x16x32_bf16 v[40:43], v[170:173], v[214:217], v[40:43]
	v_mfma_f32_16x16x32_bf16 v[32:35], v[170:173], v[222:225], v[32:35]
	v_mfma_f32_16x16x32_bf16 v[36:39], v[162:165], v[222:225], v[36:39]
	v_mfma_f32_16x16x32_bf16 v[60:63], v[166:169], v[202:205], v[60:63]
	v_mfma_f32_16x16x32_bf16 v[56:59], v[174:177], v[202:205], v[56:59]
	v_mfma_f32_16x16x32_bf16 v[48:51], v[174:177], v[210:213], v[48:51]
	v_mfma_f32_16x16x32_bf16 v[52:55], v[166:169], v[210:213], v[52:55]
	v_mfma_f32_16x16x32_bf16 v[44:47], v[166:169], v[218:221], v[44:47]
	v_mfma_f32_16x16x32_bf16 v[40:43], v[174:177], v[218:221], v[40:43]
	v_mfma_f32_16x16x32_bf16 v[32:35], v[174:177], v[226:229], v[32:35]
	v_mfma_f32_16x16x32_bf16 v[36:39], v[166:169], v[226:229], v[36:39]
	s_barrier
	v_readfirstlane_b32 s14, v157
	v_add_u32_e32 v164, 0x2000, v157
	v_lshl_add_u64 v[162:163], v[246:247], 0, s[2:3]
	s_mov_b32 m0, s14
	v_readfirstlane_b32 s14, v164
	global_load_lds_dwordx4 v[162:163], off
	v_lshl_add_u64 v[162:163], v[248:249], 0, s[2:3]
	s_mov_b32 m0, s14
	s_nop 0
	global_load_lds_dwordx4 v[162:163], off
	s_waitcnt vmcnt(6)
	s_barrier
	v_mfma_f32_16x16x32_bf16 v[28:31], v[230:233], v[198:201], v[28:31]
	v_mfma_f32_16x16x32_bf16 v[24:27], v[238:241], v[198:201], v[24:27]
	v_mfma_f32_16x16x32_bf16 v[16:19], v[238:241], v[206:209], v[16:19]
	v_mfma_f32_16x16x32_bf16 v[20:23], v[230:233], v[206:209], v[20:23]
	v_mfma_f32_16x16x32_bf16 v[12:15], v[230:233], v[214:217], v[12:15]
	v_mfma_f32_16x16x32_bf16 v[8:11], v[238:241], v[214:217], v[8:11]
	v_mfma_f32_16x16x32_bf16 v[0:3], v[238:241], v[222:225], v[0:3]
	v_mfma_f32_16x16x32_bf16 v[4:7], v[230:233], v[222:225], v[4:7]
	v_mfma_f32_16x16x32_bf16 v[28:31], v[234:237], v[202:205], v[28:31]
	v_mfma_f32_16x16x32_bf16 v[24:27], v[242:245], v[202:205], v[24:27]
	v_mfma_f32_16x16x32_bf16 v[16:19], v[242:245], v[210:213], v[16:19]
	v_mfma_f32_16x16x32_bf16 v[20:23], v[234:237], v[210:213], v[20:23]
	v_mfma_f32_16x16x32_bf16 v[12:15], v[234:237], v[218:221], v[12:15]
	v_mfma_f32_16x16x32_bf16 v[8:11], v[242:245], v[218:221], v[8:11]
	v_mfma_f32_16x16x32_bf16 v[0:3], v[242:245], v[226:229], v[0:3]
	v_mfma_f32_16x16x32_bf16 v[4:7], v[234:237], v[226:229], v[4:7]
	s_add_i32 s11, s11, 2
	v_lshl_add_u64 v[136:137], v[136:137], 0, s[44:45]
	v_lshl_add_u64 v[138:139], v[138:139], 0, s[44:45]
	v_lshl_add_u64 v[140:141], v[140:141], 0, s[44:45]
	s_cmp_lt_u32 s11, 12
	v_lshl_add_u64 v[142:143], v[142:143], 0, s[44:45]
	s_barrier
	s_cbranch_scc1 .LBB0_844
	s_add_u32 s12, s12, 0x40780
	s_addc_u32 s13, s13, 0
	v_lshl_add_u64 v[130:131], s[12:13], 0, v[130:131]
	v_readfirstlane_b32 s11, v160
	v_lshl_add_u64 v[128:129], v[128:129], 1, v[130:131]
	s_mov_b32 m0, s11
	ds_read_b128 v[136:139], v159
	ds_read_b128 v[140:143], v159 offset:1024
	ds_read_b128 v[154:157], v159 offset:2048
	ds_read_b128 v[162:165], v159 offset:3072
	ds_read_b128 v[166:169], v151
	ds_read_b128 v[170:173], v151 offset:1024
	ds_read_b128 v[174:177], v150
	ds_read_b128 v[198:201], v150 offset:1024
	ds_read_b128 v[202:205], v149
	ds_read_b128 v[206:209], v149 offset:1024
	ds_read_b128 v[210:213], v148
	ds_read_b128 v[214:217], v148 offset:1024
	global_load_lds_dwordx4 v[128:129], off
	v_lshl_add_u64 v[128:129], s[12:13], 0, v[134:135]
	v_readfirstlane_b32 s11, v161
	v_lshl_add_u64 v[128:129], v[132:133], 1, v[128:129]
	s_mov_b32 m0, s11
	s_nop 0
	global_load_lds_dwordx4 v[128:129], off
	s_barrier
	s_waitcnt lgkmcnt(0)
	v_mfma_f32_16x16x32_bf16 v[124:127], v[136:139], v[166:169], v[124:127]
	v_mfma_f32_16x16x32_bf16 v[120:123], v[154:157], v[166:169], v[120:123]
	v_mfma_f32_16x16x32_bf16 v[112:115], v[154:157], v[174:177], v[112:115]
	v_mfma_f32_16x16x32_bf16 v[116:119], v[136:139], v[174:177], v[116:119]
	v_mfma_f32_16x16x32_bf16 v[108:111], v[136:139], v[202:205], v[108:111]
	v_mfma_f32_16x16x32_bf16 v[104:107], v[154:157], v[202:205], v[104:107]
	v_mfma_f32_16x16x32_bf16 v[96:99], v[154:157], v[210:213], v[96:99]
	v_mfma_f32_16x16x32_bf16 v[100:103], v[136:139], v[210:213], v[100:103]
	v_mfma_f32_16x16x32_bf16 v[124:127], v[140:143], v[170:173], v[124:127]
	v_mfma_f32_16x16x32_bf16 v[120:123], v[162:165], v[170:173], v[120:123]
	v_mfma_f32_16x16x32_bf16 v[112:115], v[162:165], v[198:201], v[112:115]
	v_mfma_f32_16x16x32_bf16 v[116:119], v[140:143], v[198:201], v[116:119]
	v_mfma_f32_16x16x32_bf16 v[108:111], v[140:143], v[206:209], v[108:111]
	v_mfma_f32_16x16x32_bf16 v[104:107], v[162:165], v[206:209], v[104:107]
	v_mfma_f32_16x16x32_bf16 v[96:99], v[162:165], v[214:217], v[96:99]
	v_mfma_f32_16x16x32_bf16 v[100:103], v[140:143], v[214:217], v[100:103]
	s_barrier
	ds_read_b128 v[128:131], v158
	ds_read_b128 v[132:135], v158 offset:1024
	ds_read_b128 v[218:221], v158 offset:2048
	ds_read_b128 v[158:161], v158 offset:3072
	s_barrier
; #define WAIT_V(n) asm volatile("s_waitcnt vmcnt(" #n ")" ::: "memory")
; #define WAIT_L(n) asm volatile("s_waitcnt lgkmcnt(" #n ")" ::: "memory")
; #define BAR __builtin_amdgcn_s_barrier()
; #define LDA(dst, b, h)                                                                            \
;   _Pragma("unroll") for (int m = 0; m < 4; ++m) _Pragma("unroll") for (int k = 0; k < 2; ++k)                                         \
;     dst[m][k] = *reinterpret_cast<const bf16x8*>((char*)SA(b, h) + lds_byte(wr * 64 + m * 16 + fr, k * 32 + fq * 8))
; #define LDB(dst, b, h)                                                                            \
;   _Pragma("unroll") for (int n = 0; n < 2; ++n) _Pragma("unroll") for (int k = 0; k < 2; ++k)                                         \
;     dst[n][k] = *reinterpret_cast<const bf16x8*>((char*)SB(b, h) + lds_byte(wc * 32 + n * 16 + fr, k * 32 + fq * 8))
; template <int K, bool SWAP>
; __device__ __forceinline__ void gemm_kloop(const bf16* __restrict__ A, const bf16* __restrict__ Bt,
;                                            f32x4 (&acc)[2][2][4][2], bool pref = false) {
;     ...
;     LDB(B1, 0, 1); BAR; WAIT_L(0); MMA(0, 1, At, B1); BAR;
;     LDA(At, 0, 1); WAIT_V(4); BAR; WAIT_L(0); MMA(1, 0, At, B0); MMA(1, 1, At, B1); BAR; }
;   { LDB(B0, 1, 0); LDA(At, 1, 0); WAIT_V(2); BAR; WAIT_L(0); MMA(0, 0, At, B0); BAR;
	s_waitcnt lgkmcnt(0)
	v_mfma_f32_16x16x32_bf16 v[88:91], v[218:221], v[166:169], v[88:91]
	v_mfma_f32_16x16x32_bf16 v[84:87], v[128:131], v[174:177], v[84:87]
	v_mfma_f32_16x16x32_bf16 v[80:83], v[218:221], v[174:177], v[80:83]
	v_mfma_f32_16x16x32_bf16 v[76:79], v[128:131], v[202:205], v[76:79]
	v_mfma_f32_16x16x32_bf16 v[72:75], v[218:221], v[202:205], v[72:75]
	v_mfma_f32_16x16x32_bf16 v[68:71], v[128:131], v[210:213], v[68:71]
	v_mfma_f32_16x16x32_bf16 v[64:67], v[218:221], v[210:213], v[64:67]
	v_mfma_f32_16x16x32_bf16 v[92:95], v[128:131], v[166:169], v[92:95]
	v_mfma_f32_16x16x32_bf16 v[88:91], v[158:161], v[170:173], v[88:91]
	v_mfma_f32_16x16x32_bf16 v[84:87], v[132:135], v[198:201], v[84:87]
	v_mfma_f32_16x16x32_bf16 v[80:83], v[158:161], v[198:201], v[80:83]
	v_mfma_f32_16x16x32_bf16 v[76:79], v[132:135], v[206:209], v[76:79]
	v_mfma_f32_16x16x32_bf16 v[72:75], v[158:161], v[206:209], v[72:75]
	v_mfma_f32_16x16x32_bf16 v[68:71], v[132:135], v[214:217], v[68:71]
	v_mfma_f32_16x16x32_bf16 v[64:67], v[158:161], v[214:217], v[64:67]
	v_mfma_f32_16x16x32_bf16 v[222:225], v[132:135], v[170:173], v[92:95]
	s_barrier
	s_nop 0
	ds_read_b128 v[92:95], v151 offset:16384
	ds_read_b128 v[166:169], v151 offset:17408
	ds_read_b128 v[170:173], v150 offset:16384
	ds_read_b128 v[174:177], v150 offset:17408
	ds_read_b128 v[198:201], v149 offset:16384
	ds_read_b128 v[202:205], v149 offset:17408
	ds_read_b128 v[206:209], v148 offset:16384
	ds_read_b128 v[210:213], v148 offset:17408
	s_waitcnt vmcnt(4)
	s_barrier
	s_waitcnt lgkmcnt(0)
	v_mfma_f32_16x16x32_bf16 v[60:63], v[136:139], v[92:95], v[60:63]
	v_mfma_f32_16x16x32_bf16 v[56:59], v[154:157], v[92:95], v[56:59]
	v_mfma_f32_16x16x32_bf16 v[48:51], v[154:157], v[170:173], v[48:51]
	v_mfma_f32_16x16x32_bf16 v[52:55], v[136:139], v[170:173], v[52:55]
	v_mfma_f32_16x16x32_bf16 v[44:47], v[136:139], v[198:201], v[44:47]
	v_mfma_f32_16x16x32_bf16 v[40:43], v[154:157], v[198:201], v[40:43]
	v_mfma_f32_16x16x32_bf16 v[32:35], v[154:157], v[206:209], v[32:35]
	v_mfma_f32_16x16x32_bf16 v[36:39], v[136:139], v[206:209], v[36:39]
	v_mfma_f32_16x16x32_bf16 v[60:63], v[140:143], v[166:169], v[60:63]
	v_mfma_f32_16x16x32_bf16 v[56:59], v[162:165], v[166:169], v[56:59]
	v_mfma_f32_16x16x32_bf16 v[48:51], v[162:165], v[174:177], v[48:51]
	v_mfma_f32_16x16x32_bf16 v[52:55], v[140:143], v[174:177], v[52:55]
	v_mfma_f32_16x16x32_bf16 v[44:47], v[140:143], v[202:205], v[44:47]
	v_mfma_f32_16x16x32_bf16 v[40:43], v[162:165], v[202:205], v[40:43]
	v_mfma_f32_16x16x32_bf16 v[32:35], v[162:165], v[210:213], v[32:35]
	v_mfma_f32_16x16x32_bf16 v[36:39], v[140:143], v[210:213], v[36:39]
	v_mfma_f32_16x16x32_bf16 v[28:31], v[128:131], v[92:95], v[28:31]
	v_mfma_f32_16x16x32_bf16 v[24:27], v[218:221], v[92:95], v[24:27]
	v_mfma_f32_16x16x32_bf16 v[16:19], v[218:221], v[170:173], v[16:19]
	v_mfma_f32_16x16x32_bf16 v[20:23], v[128:131], v[170:173], v[20:23]
	v_mfma_f32_16x16x32_bf16 v[12:15], v[128:131], v[198:201], v[12:15]
	v_mfma_f32_16x16x32_bf16 v[8:11], v[218:221], v[198:201], v[8:11]
	v_mfma_f32_16x16x32_bf16 v[0:3], v[218:221], v[206:209], v[0:3]
	v_mfma_f32_16x16x32_bf16 v[4:7], v[128:131], v[206:209], v[4:7]
	v_mfma_f32_16x16x32_bf16 v[28:31], v[132:135], v[166:169], v[28:31]
	v_mfma_f32_16x16x32_bf16 v[24:27], v[158:161], v[166:169], v[24:27]
	v_mfma_f32_16x16x32_bf16 v[16:19], v[158:161], v[174:177], v[16:19]
	v_mfma_f32_16x16x32_bf16 v[20:23], v[132:135], v[174:177], v[20:23]
	v_mfma_f32_16x16x32_bf16 v[12:15], v[132:135], v[202:205], v[12:15]
	v_mfma_f32_16x16x32_bf16 v[8:11], v[158:161], v[202:205], v[8:11]
	v_mfma_f32_16x16x32_bf16 v[0:3], v[158:161], v[210:213], v[0:3]
	v_mfma_f32_16x16x32_bf16 v[4:7], v[132:135], v[210:213], v[4:7]
	s_barrier
	ds_read_b128 v[128:131], v153
	ds_read_b128 v[132:135], v153 offset:1024
	ds_read_b128 v[136:139], v153 offset:2048
	ds_read_b128 v[140:143], v153 offset:3072
	ds_read_b128 v[154:157], v151 offset:32768
	ds_read_b128 v[158:161], v151 offset:33792
	ds_read_b128 v[162:165], v150 offset:32768
	ds_read_b128 v[166:169], v150 offset:33792
	ds_read_b128 v[170:173], v149 offset:32768
	ds_read_b128 v[174:177], v149 offset:33792
	ds_read_b128 v[198:201], v148 offset:32768
	ds_read_b128 v[202:205], v148 offset:33792
	s_waitcnt vmcnt(2)
	s_barrier
; #define WAIT_V(n) asm volatile("s_waitcnt vmcnt(" #n ")" ::: "memory")
; #define WAIT_L(n) asm volatile("s_waitcnt lgkmcnt(" #n ")" ::: "memory")
; #define BAR __builtin_amdgcn_s_barrier()
; #define LDA(dst, b, h)                                                                            \
;   _Pragma("unroll") for (int m = 0; m < 4; ++m) _Pragma("unroll") for (int k = 0; k < 2; ++k)                                         \
;     dst[m][k] = *reinterpret_cast<const bf16x8*>((char*)SA(b, h) + lds_byte(wr * 64 + m * 16 + fr, k * 32 + fq * 8))
; #define LDB(dst, b, h)                                                                            \
;   _Pragma("unroll") for (int n = 0; n < 2; ++n) _Pragma("unroll") for (int k = 0; k < 2; ++k)                                         \
;     dst[n][k] = *reinterpret_cast<const bf16x8*>((char*)SB(b, h) + lds_byte(wc * 32 + n * 16 + fr, k * 32 + fq * 8))
; template <int K, bool SWAP>
; __device__ __forceinline__ void gemm_kloop(const bf16* __restrict__ A, const bf16* __restrict__ Bt,
;                                            f32x4 (&acc)[2][2][4][2], bool pref = false) {
;     ...
;   { LDB(B0, 1, 0); LDA(At, 1, 0); WAIT_V(2); BAR; WAIT_L(0); MMA(0, 0, At, B0); BAR;
;     LDB(B1, 1, 1); WAIT_V(0); BAR; WAIT_L(0); MMA(0, 1, At, B1); BAR;
;     LDA(At, 1, 1); BAR; WAIT_L(0); MMA(1, 0, At, B0); MMA(1, 1, At, B1); BAR; }
;   if (wr == 0) BAR;
	s_waitcnt lgkmcnt(0)
	v_mfma_f32_16x16x32_bf16 v[92:95], v[128:131], v[154:157], v[124:127]
	v_mfma_f32_16x16x32_bf16 v[124:127], v[132:135], v[158:161], v[92:95]
	v_mfma_f32_16x16x32_bf16 v[92:95], v[136:139], v[154:157], v[120:123]
	v_mfma_f32_16x16x32_bf16 v[120:123], v[140:143], v[158:161], v[92:95]
	v_mfma_f32_16x16x32_bf16 v[92:95], v[128:131], v[162:165], v[116:119]
	v_mfma_f32_16x16x32_bf16 v[116:119], v[132:135], v[166:169], v[92:95]
	v_mfma_f32_16x16x32_bf16 v[92:95], v[136:139], v[162:165], v[112:115]
	v_mfma_f32_16x16x32_bf16 v[112:115], v[140:143], v[166:169], v[92:95]
	v_mfma_f32_16x16x32_bf16 v[92:95], v[128:131], v[170:173], v[108:111]
	v_mfma_f32_16x16x32_bf16 v[108:111], v[132:135], v[174:177], v[92:95]
	v_mfma_f32_16x16x32_bf16 v[92:95], v[136:139], v[170:173], v[104:107]
	v_mfma_f32_16x16x32_bf16 v[104:107], v[140:143], v[174:177], v[92:95]
	v_mfma_f32_16x16x32_bf16 v[92:95], v[128:131], v[198:201], v[100:103]
	v_mfma_f32_16x16x32_bf16 v[100:103], v[132:135], v[202:205], v[92:95]
	v_mfma_f32_16x16x32_bf16 v[92:95], v[136:139], v[198:201], v[96:99]
	v_mfma_f32_16x16x32_bf16 v[92:95], v[140:143], v[202:205], v[92:95]
	s_barrier
	ds_read_b128 v[206:209], v152
	ds_read_b128 v[210:213], v152 offset:1024
	ds_read_b128 v[214:217], v152 offset:2048
	ds_read_b128 v[218:221], v152 offset:3072
	s_waitcnt vmcnt(0)
	s_barrier
	s_waitcnt lgkmcnt(0)
	v_mfma_f32_16x16x32_bf16 v[96:99], v[206:209], v[154:157], v[222:225]
	v_mfma_f32_16x16x32_bf16 v[88:91], v[214:217], v[154:157], v[88:91]
	v_mfma_f32_16x16x32_bf16 v[84:87], v[206:209], v[162:165], v[84:87]
	v_mfma_f32_16x16x32_bf16 v[80:83], v[214:217], v[162:165], v[80:83]
	v_mfma_f32_16x16x32_bf16 v[76:79], v[206:209], v[170:173], v[76:79]
	v_mfma_f32_16x16x32_bf16 v[72:75], v[214:217], v[170:173], v[72:75]
	v_mfma_f32_16x16x32_bf16 v[68:71], v[206:209], v[198:201], v[68:71]
	v_mfma_f32_16x16x32_bf16 v[64:67], v[214:217], v[198:201], v[64:67]
	v_mfma_f32_16x16x32_bf16 v[96:99], v[210:213], v[158:161], v[96:99]
	v_mfma_f32_16x16x32_bf16 v[88:91], v[218:221], v[158:161], v[88:91]
	v_mfma_f32_16x16x32_bf16 v[84:87], v[210:213], v[166:169], v[84:87]
	v_mfma_f32_16x16x32_bf16 v[80:83], v[218:221], v[166:169], v[80:83]
	v_mfma_f32_16x16x32_bf16 v[76:79], v[210:213], v[174:177], v[76:79]
	v_mfma_f32_16x16x32_bf16 v[72:75], v[218:221], v[174:177], v[72:75]
	v_mfma_f32_16x16x32_bf16 v[68:71], v[210:213], v[202:205], v[68:71]
	v_mfma_f32_16x16x32_bf16 v[64:67], v[218:221], v[202:205], v[64:67]
	s_barrier
	ds_read_b128 v[152:155], v151 offset:49152
	ds_read_b128 v[156:159], v151 offset:50176
	ds_read_b128 v[160:163], v150 offset:49152
	ds_read_b128 v[164:167], v150 offset:50176
	ds_read_b128 v[168:171], v149 offset:49152
	ds_read_b128 v[172:175], v149 offset:50176
	ds_read_b128 v[176:179], v148 offset:49152
	ds_read_b128 v[146:149], v148 offset:50176
	s_barrier
	s_waitcnt lgkmcnt(0)
	v_mfma_f32_16x16x32_bf16 v[60:63], v[128:131], v[152:155], v[60:63]
	v_mfma_f32_16x16x32_bf16 v[56:59], v[136:139], v[152:155], v[56:59]
	v_mfma_f32_16x16x32_bf16 v[48:51], v[136:139], v[160:163], v[48:51]
	v_mfma_f32_16x16x32_bf16 v[52:55], v[128:131], v[160:163], v[52:55]
	v_mfma_f32_16x16x32_bf16 v[44:47], v[128:131], v[168:171], v[44:47]
	v_mfma_f32_16x16x32_bf16 v[40:43], v[136:139], v[168:171], v[40:43]
	v_mfma_f32_16x16x32_bf16 v[32:35], v[136:139], v[176:179], v[32:35]
	v_mfma_f32_16x16x32_bf16 v[36:39], v[128:131], v[176:179], v[36:39]
	v_mfma_f32_16x16x32_bf16 v[60:63], v[132:135], v[156:159], v[60:63]
	v_mfma_f32_16x16x32_bf16 v[56:59], v[140:143], v[156:159], v[56:59]
	v_mfma_f32_16x16x32_bf16 v[48:51], v[140:143], v[164:167], v[48:51]
	v_mfma_f32_16x16x32_bf16 v[52:55], v[132:135], v[164:167], v[52:55]
	v_mfma_f32_16x16x32_bf16 v[44:47], v[132:135], v[172:175], v[44:47]
	v_mfma_f32_16x16x32_bf16 v[40:43], v[140:143], v[172:175], v[40:43]
	v_mfma_f32_16x16x32_bf16 v[32:35], v[140:143], v[146:149], v[32:35]
	v_mfma_f32_16x16x32_bf16 v[36:39], v[132:135], v[146:149], v[36:39]
	v_mfma_f32_16x16x32_bf16 v[28:31], v[206:209], v[152:155], v[28:31]
	v_mfma_f32_16x16x32_bf16 v[24:27], v[214:217], v[152:155], v[24:27]
	v_mfma_f32_16x16x32_bf16 v[16:19], v[214:217], v[160:163], v[16:19]
	v_mfma_f32_16x16x32_bf16 v[20:23], v[206:209], v[160:163], v[20:23]
	v_mfma_f32_16x16x32_bf16 v[12:15], v[206:209], v[168:171], v[12:15]
	v_mfma_f32_16x16x32_bf16 v[8:11], v[214:217], v[168:171], v[8:11]
	v_mfma_f32_16x16x32_bf16 v[0:3], v[214:217], v[176:179], v[0:3]
	v_mfma_f32_16x16x32_bf16 v[4:7], v[206:209], v[176:179], v[4:7]
	v_mfma_f32_16x16x32_bf16 v[28:31], v[210:213], v[156:159], v[28:31]
	v_mfma_f32_16x16x32_bf16 v[24:27], v[218:221], v[156:159], v[24:27]
	v_mfma_f32_16x16x32_bf16 v[16:19], v[218:221], v[164:167], v[16:19]
	v_mfma_f32_16x16x32_bf16 v[20:23], v[210:213], v[164:167], v[20:23]
	v_mfma_f32_16x16x32_bf16 v[12:15], v[210:213], v[172:175], v[12:15]
	v_mfma_f32_16x16x32_bf16 v[8:11], v[218:221], v[172:175], v[8:11]
	v_mfma_f32_16x16x32_bf16 v[0:3], v[218:221], v[146:149], v[0:3]
	v_mfma_f32_16x16x32_bf16 v[4:7], v[210:213], v[146:149], v[4:7]
	s_movk_i32 s11, 0x100
	v_cmp_gt_u32_e32 vcc, s11, v144
	s_barrier
	s_and_saveexec_b64 s[12:13], vcc
	s_cbranch_execz .LBB0_847
	s_barrier
